# re-measure v27: pre-scaled recurrence + page-table reuse + three nt decode waves beside the recurrence
# speedup vs baseline: 1.0206x; 1.0206x over previous
; __device__ __forceinline__ float bf2f(bf16_t b) { return __uint_as_float(((unsigned)b) << 16); }
; template <int NB>
; __device__ __forceinline__ void sb_decode_task(const Params& P, float* lds, int task) {
;     ...
;     constexpr int NBT = 32 / NB;
;     const int h = task % SH, bj = task / SH, b = bj / NPAGES;
;     const int page = P.page_table[bj];
;     const float* Kp = P.cache_k + ((size_t)page * PAGE * SH + h) * HD + 4 * c;
;     const float* Vp = P.cache_v + ((size_t)page * PAGE * SH + h) * HD + 4 * c;
;     const bf16_t* qp = qb + (size_t)(NTOK + b) * SBW + h * 64 + 4 * c;
;     const float q0 = bf2f(qp[0]), q1 = bf2f(qp[1]), q2 = bf2f(qp[2]), q3 = bf2f(qp[3]);
;     const float bias = P.sb_bias[h] * LOG2E;
;     float4 cur[NB], nx[NB];
; #pragma unroll
;     for (int i = 0; i < NB; ++i) cur[i] = *(const float4*)(Kp + (size_t)(4 * i + g) * (SH * HD));
; #pragma unroll
;     for (int kb = 0; kb < NBT; ++kb) {
;         const float* np = (kb + 1 < NBT) ? Kp + (size_t)(4 * NB * (kb + 1)) * (SH * HD) : Vp;
; #pragma unroll
;         for (int i = 0; i < NB; ++i) nx[i] = *(const float4*)(np + (size_t)(4 * i + g) * (SH * HD));
; #pragma unroll
;         for (int i = 0; i < NB; ++i) { const int s = 4 * NB * kb + 4 * i + g;
;             float part = q0 * cur[i].x + q1 * cur[i].y + q2 * cur[i].z + q3 * cur[i].w; part = sum16(part);
;             if (c == 0) zl[s] = part + bias; }
.LBB0_956:
	s_or_b64 exec, exec, s[0:1]
	v_readlane_b32 s36, v252, 48
	v_readlane_b32 s37, v252, 49
	s_mul_hi_i32 s1, s34, 0x2aaaaaab
	s_load_dwordx16 s[56:71], s[36:37], 0x0
	s_lshr_b32 s3, s1, 31
	s_add_i32 s0, s1, s3
	s_ashr_i32 s1, s1, 7
	s_mul_i32 s2, s0, 6
	s_add_i32 s33, s1, s3
	s_ashr_i32 s1, s0, 31
	s_sub_i32 s2, s34, s2
	s_lshl_b64 s[0:1], s[0:1], 2
	s_waitcnt lgkmcnt(0)
	s_add_u32 s0, s66, s0
	s_addc_u32 s1, s67, s1
	global_load_dword v2, v83, s[0:1]
	s_add_i32 s0, s33, 0x4000
	s_ashr_i32 s3, s2, 31
	s_mul_hi_i32 s1, s0, 0x300
	s_mulk_i32 s0, 0x300
	s_add_u32 s33, s38, s0
	s_addc_u32 s35, s39, s1
	s_lshl_b32 s0, s2, 6
	s_ashr_i32 s1, s0, 31
	s_lshl_b64 s[0:1], s[0:1], 1
	s_add_u32 s0, s33, s0
	s_addc_u32 s1, s35, s1
	v_readlane_b32 s56, v252, 16
	v_readlane_b32 s57, v252, 17
	v_readlane_b32 s64, v252, 24
	v_readlane_b32 s65, v252, 25
	s_mov_b64 s[56:57], s[64:65]
	v_mov_b32_e32 v91, v83
	v_readlane_b32 s58, v252, 18
	v_readlane_b32 s59, v252, 19
	v_readlane_b32 s60, v252, 20
	v_readlane_b32 s61, v252, 21
	v_readlane_b32 s62, v252, 22
	v_readlane_b32 s63, v252, 23
	v_readlane_b32 s66, v252, 26
	v_readlane_b32 s67, v252, 27
	v_readlane_b32 s68, v252, 28
	v_readlane_b32 s69, v252, 29
	v_readlane_b32 s70, v252, 30
	v_readlane_b32 s71, v252, 31
	s_waitcnt vmcnt(0)
	v_mov_b32_e32 v253, v2
	v_mul_hi_i32 v3, v2, s42
	v_mul_lo_u32 v2, v2, s42
	v_lshl_add_u64 v[92:93], v[2:3], 0, s[2:3]
	v_lshlrev_b64 v[2:3], 8, v[92:93]
	v_lshl_add_u64 v[66:67], v[84:85], 0, v[2:3]
	global_load_dwordx2 v[2:3], v99, s[0:1]
	s_lshl_b64 s[0:1], s[2:3], 2
	s_add_u32 s0, s56, s0
	s_addc_u32 s1, s57, s1
	global_load_dword v22, v83, s[0:1]
	v_lshl_add_u64 v[18:19], v[66:67], 0, v[82:83]
	v_lshl_add_u64 v[20:21], v[66:67], 0, v[90:91]
	global_load_dwordx4 v[14:17], v[18:19], off nt
	global_load_dwordx4 v[62:65], v[20:21], off nt
	s_waitcnt vmcnt(3)
	v_lshlrev_b32_e32 v105, 16, v2
	v_and_b32_e32 v107, 0xffff0000, v2
	v_add_co_u32_e32 v2, vcc, s44, v18
	v_lshlrev_b32_e32 v106, 16, v3
	v_and_b32_e32 v104, 0xffff0000, v3
	v_addc_co_u32_e32 v3, vcc, 0, v19, vcc
	global_load_dwordx4 v[10:13], v[2:3], off offset:2048 nt
	v_add_co_u32_e32 v2, vcc, s45, v18
	s_waitcnt vmcnt(3)
	v_mul_f32_e32 v108, 0x3fb8aa3b, v22
	v_addc_co_u32_e32 v3, vcc, 0, v19, vcc
	global_load_dwordx4 v[6:9], v[2:3], off nt
	v_add_co_u32_e32 v2, vcc, s43, v18
	v_lshl_add_u64 v[22:23], v[66:67], 0, s[26:27]
	s_nop 0
	v_addc_co_u32_e32 v3, vcc, 0, v19, vcc
	v_add_co_u32_e32 v20, vcc, s46, v18
	v_lshl_add_u64 v[30:31], v[22:23], 0, v[82:83]
	s_nop 0
	v_addc_co_u32_e32 v21, vcc, 0, v19, vcc
	global_load_dwordx4 v[58:61], v[20:21], off offset:2048 nt
	v_add_co_u32_e32 v20, vcc, s47, v18
	v_lshl_add_u64 v[22:23], v[22:23], 0, v[90:91]
	s_nop 0
	v_addc_co_u32_e32 v21, vcc, 0, v19, vcc
	v_add_co_u32_e32 v18, vcc, s48, v18
	global_load_dwordx4 v[54:57], v[20:21], off nt
	s_nop 0
	v_addc_co_u32_e32 v19, vcc, 0, v19, vcc
	global_load_dwordx4 v[50:53], v[18:19], off offset:2048 nt
	v_add_co_u32_e32 v18, vcc, s44, v30
	global_load_dwordx4 v[22:25], v[22:23], off nt
	s_nop 0
	v_addc_co_u32_e32 v19, vcc, 0, v31, vcc
	global_load_dwordx4 v[34:37], v[18:19], off offset:2048 nt
	v_add_co_u32_e32 v18, vcc, s45, v30
	global_load_dwordx4 v[2:5], v[2:3], off offset:2048 nt
	s_nop 0
	v_addc_co_u32_e32 v19, vcc, 0, v31, vcc
	global_load_dwordx4 v[26:29], v[18:19], off nt
	v_add_co_u32_e32 v18, vcc, s43, v30
	global_load_dwordx4 v[46:49], v[30:31], off nt
	s_nop 0
	v_addc_co_u32_e32 v19, vcc, 0, v31, vcc
	v_add_co_u32_e32 v32, vcc, s46, v30
	global_load_dwordx4 v[18:21], v[18:19], off offset:2048 nt
	s_nop 0
	v_addc_co_u32_e32 v33, vcc, 0, v31, vcc
	global_load_dwordx4 v[38:41], v[32:33], off offset:2048 nt
	v_add_co_u32_e32 v32, vcc, s47, v30
	s_waitcnt vmcnt(13)
	v_mul_f32_e32 v15, v15, v107
	v_addc_co_u32_e32 v33, vcc, 0, v31, vcc
	v_add_co_u32_e32 v30, vcc, s48, v30
	global_load_dwordx4 v[42:45], v[32:33], off nt
	s_nop 0
	v_addc_co_u32_e32 v31, vcc, 0, v31, vcc
	global_load_dwordx4 v[30:33], v[30:31], off offset:2048 nt
	v_fmac_f32_e32 v15, v14, v105
	v_fmac_f32_e32 v15, v16, v106
	v_fmac_f32_e32 v15, v17, v104
	s_nop 1
	v_add_f32_dpp v14, v15, v15 quad_perm:[1,0,3,2] row_mask:0xf bank_mask:0xf bound_ctrl:1
	s_nop 1
	v_add_f32_dpp v14, v14, v14 quad_perm:[2,3,0,1] row_mask:0xf bank_mask:0xf bound_ctrl:1
	s_nop 1
	v_add_f32_dpp v14, v14, v14 row_ror:4 row_mask:0xf bank_mask:0xf bound_ctrl:1
	s_nop 1
	v_mov_b32_dpp v15, v14 row_ror:8 row_mask:0xf bank_mask:0xf bound_ctrl:1
	s_and_saveexec_b64 s[0:1], s[6:7]
	v_add_f32_e32 v14, v14, v15
	v_add_f32_e32 v14, v108, v14
	ds_write_b32 v96, v14
	s_or_b64 exec, exec, s[0:1]
	s_waitcnt vmcnt(13)
	v_mul_f32_e32 v11, v11, v107
	v_fmac_f32_e32 v11, v10, v105
	v_fmac_f32_e32 v11, v12, v106
	v_fmac_f32_e32 v11, v13, v104
	s_nop 1
	v_add_f32_dpp v10, v11, v11 quad_perm:[1,0,3,2] row_mask:0xf bank_mask:0xf bound_ctrl:1
	s_nop 1
	v_add_f32_dpp v10, v10, v10 quad_perm:[2,3,0,1] row_mask:0xf bank_mask:0xf bound_ctrl:1
	s_nop 1
	v_add_f32_dpp v10, v10, v10 row_ror:4 row_mask:0xf bank_mask:0xf bound_ctrl:1
	s_nop 1
	v_mov_b32_dpp v11, v10 row_ror:8 row_mask:0xf bank_mask:0xf bound_ctrl:1
	s_and_saveexec_b64 s[0:1], s[6:7]
	v_add_f32_e32 v10, v10, v11
	v_add_f32_e32 v10, v108, v10
	ds_write_b32 v96, v10 offset:16
	s_or_b64 exec, exec, s[0:1]
	s_waitcnt vmcnt(12)
	v_mul_f32_e32 v7, v7, v107
	v_fmac_f32_e32 v7, v6, v105
	v_fmac_f32_e32 v7, v8, v106
	v_fmac_f32_e32 v7, v9, v104
	s_nop 1
	v_add_f32_dpp v6, v7, v7 quad_perm:[1,0,3,2] row_mask:0xf bank_mask:0xf bound_ctrl:1
	s_nop 1
	v_add_f32_dpp v6, v6, v6 quad_perm:[2,3,0,1] row_mask:0xf bank_mask:0xf bound_ctrl:1
	s_nop 1
	v_add_f32_dpp v6, v6, v6 row_ror:4 row_mask:0xf bank_mask:0xf bound_ctrl:1
	s_nop 1
	v_mov_b32_dpp v7, v6 row_ror:8 row_mask:0xf bank_mask:0xf bound_ctrl:1
	s_and_saveexec_b64 s[0:1], s[6:7]
	v_add_f32_e32 v6, v6, v7
	v_add_f32_e32 v6, v108, v6
	ds_write_b32 v96, v6 offset:32
	s_or_b64 exec, exec, s[0:1]
	s_waitcnt vmcnt(6)
; template <int NB>
; __device__ __forceinline__ void sb_decode_task(const Params& P, float* lds, int task) {
;     ...
;     for (int i = 0; i < NB; ++i) cur[i] = *(const float4*)(Kp + (size_t)(4 * i + g) * (SH * HD));
; #pragma unroll
;     for (int kb = 0; kb < NBT; ++kb) {
;         const float* np = (kb + 1 < NBT) ? Kp + (size_t)(4 * NB * (kb + 1)) * (SH * HD) : Vp;
; #pragma unroll
;         for (int i = 0; i < NB; ++i) nx[i] = *(const float4*)(np + (size_t)(4 * i + g) * (SH * HD));
; #pragma unroll
;         for (int i = 0; i < NB; ++i) { const int s = 4 * NB * kb + 4 * i + g;
;             float part = q0 * cur[i].x + q1 * cur[i].y + q2 * cur[i].z + q3 * cur[i].w; part = sum16(part);
;             if (c == 0) zl[s] = part + bias; }
; #pragma unroll
;         for (int i = 0; i < NB; ++i) cur[i] = nx[i];
	v_mul_f32_e32 v3, v3, v107
	v_fmac_f32_e32 v3, v2, v105
	v_fmac_f32_e32 v3, v4, v106
	v_fmac_f32_e32 v3, v5, v104
	s_nop 1
	v_add_f32_dpp v2, v3, v3 quad_perm:[1,0,3,2] row_mask:0xf bank_mask:0xf bound_ctrl:1
	s_nop 1
	v_add_f32_dpp v2, v2, v2 quad_perm:[2,3,0,1] row_mask:0xf bank_mask:0xf bound_ctrl:1
	s_nop 1
	v_add_f32_dpp v2, v2, v2 row_ror:4 row_mask:0xf bank_mask:0xf bound_ctrl:1
	s_nop 1
	v_mov_b32_dpp v3, v2 row_ror:8 row_mask:0xf bank_mask:0xf bound_ctrl:1
	s_and_saveexec_b64 s[0:1], s[6:7]
	v_add_f32_e32 v2, v2, v3
	v_add_f32_e32 v2, v108, v2
	ds_write_b32 v96, v2 offset:48
	s_or_b64 exec, exec, s[0:1]
	v_mul_f32_e32 v2, v63, v107
	v_fmac_f32_e32 v2, v62, v105
	v_fmac_f32_e32 v2, v64, v106
	v_fmac_f32_e32 v2, v65, v104
	s_nop 1
	v_add_f32_dpp v2, v2, v2 quad_perm:[1,0,3,2] row_mask:0xf bank_mask:0xf bound_ctrl:1
	s_nop 1
	v_add_f32_dpp v2, v2, v2 quad_perm:[2,3,0,1] row_mask:0xf bank_mask:0xf bound_ctrl:1
	s_nop 1
	v_add_f32_dpp v2, v2, v2 row_ror:4 row_mask:0xf bank_mask:0xf bound_ctrl:1
	s_nop 1
	v_mov_b32_dpp v3, v2 row_ror:8 row_mask:0xf bank_mask:0xf bound_ctrl:1
	s_and_saveexec_b64 s[0:1], s[6:7]
	v_add_f32_e32 v2, v2, v3
	v_add_f32_e32 v2, v108, v2
	ds_write_b32 v96, v2 offset:64
	s_or_b64 exec, exec, s[0:1]
	v_mul_f32_e32 v2, v59, v107
	v_fmac_f32_e32 v2, v58, v105
	v_fmac_f32_e32 v2, v60, v106
	v_fmac_f32_e32 v2, v61, v104
	s_nop 1
	v_add_f32_dpp v2, v2, v2 quad_perm:[1,0,3,2] row_mask:0xf bank_mask:0xf bound_ctrl:1
	s_nop 1
	v_add_f32_dpp v2, v2, v2 quad_perm:[2,3,0,1] row_mask:0xf bank_mask:0xf bound_ctrl:1
	s_nop 1
	v_add_f32_dpp v2, v2, v2 row_ror:4 row_mask:0xf bank_mask:0xf bound_ctrl:1
	s_nop 1
	v_mov_b32_dpp v3, v2 row_ror:8 row_mask:0xf bank_mask:0xf bound_ctrl:1
	s_and_saveexec_b64 s[0:1], s[6:7]
	v_add_f32_e32 v2, v2, v3
	v_add_f32_e32 v2, v108, v2
	ds_write_b32 v96, v2 offset:80
	s_or_b64 exec, exec, s[0:1]
	v_mul_f32_e32 v2, v55, v107
	v_fmac_f32_e32 v2, v54, v105
	v_fmac_f32_e32 v2, v56, v106
	v_fmac_f32_e32 v2, v57, v104
	s_nop 1
	v_add_f32_dpp v2, v2, v2 quad_perm:[1,0,3,2] row_mask:0xf bank_mask:0xf bound_ctrl:1
	s_nop 1
	v_add_f32_dpp v2, v2, v2 quad_perm:[2,3,0,1] row_mask:0xf bank_mask:0xf bound_ctrl:1
	s_nop 1
	v_add_f32_dpp v2, v2, v2 row_ror:4 row_mask:0xf bank_mask:0xf bound_ctrl:1
	s_nop 1
	v_mov_b32_dpp v3, v2 row_ror:8 row_mask:0xf bank_mask:0xf bound_ctrl:1
	s_and_saveexec_b64 s[0:1], s[6:7]
	v_add_f32_e32 v2, v2, v3
	v_add_f32_e32 v2, v108, v2
	ds_write_b32 v96, v2 offset:96
	s_or_b64 exec, exec, s[0:1]
	v_mul_f32_e32 v2, v51, v107
	v_fmac_f32_e32 v2, v50, v105
	v_fmac_f32_e32 v2, v52, v106
	v_fmac_f32_e32 v2, v53, v104
	s_nop 1
	v_add_f32_dpp v2, v2, v2 quad_perm:[1,0,3,2] row_mask:0xf bank_mask:0xf bound_ctrl:1
	s_nop 1
	v_add_f32_dpp v2, v2, v2 quad_perm:[2,3,0,1] row_mask:0xf bank_mask:0xf bound_ctrl:1
	s_nop 1
	v_add_f32_dpp v2, v2, v2 row_ror:4 row_mask:0xf bank_mask:0xf bound_ctrl:1
	s_nop 1
	v_mov_b32_dpp v3, v2 row_ror:8 row_mask:0xf bank_mask:0xf bound_ctrl:1
	s_and_saveexec_b64 s[0:1], s[6:7]
	v_add_f32_e32 v2, v2, v3
	v_add_f32_e32 v2, v108, v2
	ds_write_b32 v96, v2 offset:112
	s_or_b64 exec, exec, s[0:1]
	v_lshl_add_u64 v[2:3], v[66:67], 0, s[28:29]
	v_lshl_add_u64 v[4:5], v[2:3], 0, v[82:83]
	v_add_co_u32_e32 v6, vcc, 0x1000, v4
	v_mov_b32_e32 v91, v83
	s_nop 0
	v_addc_co_u32_e32 v7, vcc, 0, v5, vcc
	global_load_dwordx4 v[78:81], v[4:5], off nt
	global_load_dwordx4 v[70:73], v[6:7], off offset:2048 nt
	v_add_co_u32_e32 v6, vcc, 0x3000, v4
	v_lshl_add_u64 v[2:3], v[2:3], 0, v[90:91]
	s_nop 0
	v_addc_co_u32_e32 v7, vcc, 0, v5, vcc
	v_add_co_u32_e32 v8, vcc, s43, v4
	s_waitcnt vmcnt(6)
	v_mul_f32_e32 v47, v47, v107
	v_addc_co_u32_e32 v9, vcc, 0, v5, vcc
	global_load_dwordx4 v[62:65], v[6:7], off nt
	global_load_dwordx4 v[54:57], v[8:9], off offset:2048 nt
	v_add_co_u32_e32 v6, vcc, 0x7000, v4
	v_fmac_f32_e32 v47, v46, v105
	s_nop 0
	v_addc_co_u32_e32 v7, vcc, 0, v5, vcc
	global_load_dwordx4 v[14:17], v[2:3], off nt
	global_load_dwordx4 v[10:13], v[6:7], off offset:2048 nt
	v_add_co_u32_e32 v2, vcc, 0x9000, v4
	v_fmac_f32_e32 v47, v48, v106
	s_nop 0
	v_addc_co_u32_e32 v3, vcc, 0, v5, vcc
	v_add_co_u32_e32 v4, vcc, 0xa000, v4
	v_fmac_f32_e32 v47, v49, v104
	s_nop 0
	v_addc_co_u32_e32 v5, vcc, 0, v5, vcc
	global_load_dwordx4 v[6:9], v[2:3], off nt
	s_nop 0
	global_load_dwordx4 v[2:5], v[4:5], off offset:2048 nt
	v_add_f32_dpp v46, v47, v47 quad_perm:[1,0,3,2] row_mask:0xf bank_mask:0xf bound_ctrl:1
	s_nop 1
	v_add_f32_dpp v46, v46, v46 quad_perm:[2,3,0,1] row_mask:0xf bank_mask:0xf bound_ctrl:1
	s_nop 1
	v_add_f32_dpp v46, v46, v46 row_ror:4 row_mask:0xf bank_mask:0xf bound_ctrl:1
	s_nop 1
	v_mov_b32_dpp v47, v46 row_ror:8 row_mask:0xf bank_mask:0xf bound_ctrl:1
	s_and_saveexec_b64 s[0:1], s[6:7]
	v_add_f32_e32 v46, v46, v47
	v_add_f32_e32 v46, v108, v46
	ds_write_b32 v96, v46 offset:128
	s_or_b64 exec, exec, s[0:1]
	v_mul_f32_e32 v35, v35, v107
	v_fmac_f32_e32 v35, v34, v105
	v_fmac_f32_e32 v35, v36, v106
	v_fmac_f32_e32 v35, v37, v104
	s_nop 1
	v_add_f32_dpp v34, v35, v35 quad_perm:[1,0,3,2] row_mask:0xf bank_mask:0xf bound_ctrl:1
	s_nop 1
	v_add_f32_dpp v34, v34, v34 quad_perm:[2,3,0,1] row_mask:0xf bank_mask:0xf bound_ctrl:1
	s_nop 1
	v_add_f32_dpp v34, v34, v34 row_ror:4 row_mask:0xf bank_mask:0xf bound_ctrl:1
	s_nop 1
	v_mov_b32_dpp v35, v34 row_ror:8 row_mask:0xf bank_mask:0xf bound_ctrl:1
	s_and_saveexec_b64 s[0:1], s[6:7]
	v_add_f32_e32 v34, v34, v35
	v_add_f32_e32 v34, v108, v34
	ds_write_b32 v96, v34 offset:144
	s_or_b64 exec, exec, s[0:1]
	v_mul_f32_e32 v27, v27, v107
	v_fmac_f32_e32 v27, v26, v105
	v_fmac_f32_e32 v27, v28, v106
	v_fmac_f32_e32 v27, v29, v104
	s_nop 1
	v_add_f32_dpp v26, v27, v27 quad_perm:[1,0,3,2] row_mask:0xf bank_mask:0xf bound_ctrl:1
	s_nop 1
	v_add_f32_dpp v26, v26, v26 quad_perm:[2,3,0,1] row_mask:0xf bank_mask:0xf bound_ctrl:1
	s_nop 1
	v_add_f32_dpp v26, v26, v26 row_ror:4 row_mask:0xf bank_mask:0xf bound_ctrl:1
	s_nop 1
	v_mov_b32_dpp v27, v26 row_ror:8 row_mask:0xf bank_mask:0xf bound_ctrl:1
	s_and_saveexec_b64 s[0:1], s[6:7]
	v_add_f32_e32 v26, v26, v27
	v_add_f32_e32 v26, v108, v26
	ds_write_b32 v96, v26 offset:160
	s_or_b64 exec, exec, s[0:1]
	s_waitcnt vmcnt(11)
; template <int NB>
; __device__ __forceinline__ void sb_decode_task(const Params& P, float* lds, int task) {
;     ...
;     for (int i = 0; i < NB; ++i) cur[i] = *(const float4*)(Kp + (size_t)(4 * i + g) * (SH * HD));
; #pragma unroll
;     for (int kb = 0; kb < NBT; ++kb) {
;         const float* np = (kb + 1 < NBT) ? Kp + (size_t)(4 * NB * (kb + 1)) * (SH * HD) : Vp;
; #pragma unroll
;         for (int i = 0; i < NB; ++i) nx[i] = *(const float4*)(np + (size_t)(4 * i + g) * (SH * HD));
; #pragma unroll
;         for (int i = 0; i < NB; ++i) { const int s = 4 * NB * kb + 4 * i + g;
;             float part = q0 * cur[i].x + q1 * cur[i].y + q2 * cur[i].z + q3 * cur[i].w; part = sum16(part);
;             if (c == 0) zl[s] = part + bias; }
; #pragma unroll
;         for (int i = 0; i < NB; ++i) cur[i] = nx[i];
	v_mul_f32_e32 v19, v19, v107
	v_fmac_f32_e32 v19, v18, v105
	v_fmac_f32_e32 v19, v20, v106
	v_fmac_f32_e32 v19, v21, v104
	s_nop 1
	v_add_f32_dpp v18, v19, v19 quad_perm:[1,0,3,2] row_mask:0xf bank_mask:0xf bound_ctrl:1
	s_nop 1
	v_add_f32_dpp v18, v18, v18 quad_perm:[2,3,0,1] row_mask:0xf bank_mask:0xf bound_ctrl:1
	s_nop 1
	v_add_f32_dpp v18, v18, v18 row_ror:4 row_mask:0xf bank_mask:0xf bound_ctrl:1
	s_nop 1
	v_mov_b32_dpp v19, v18 row_ror:8 row_mask:0xf bank_mask:0xf bound_ctrl:1
	s_and_saveexec_b64 s[0:1], s[6:7]
	v_add_f32_e32 v18, v18, v19
	v_add_f32_e32 v18, v108, v18
	ds_write_b32 v96, v18 offset:176
	s_or_b64 exec, exec, s[0:1]
	v_mul_f32_e32 v18, v23, v107
	v_fmac_f32_e32 v18, v22, v105
	v_fmac_f32_e32 v18, v24, v106
	v_fmac_f32_e32 v18, v25, v104
	s_nop 1
	v_add_f32_dpp v18, v18, v18 quad_perm:[1,0,3,2] row_mask:0xf bank_mask:0xf bound_ctrl:1
	s_nop 1
	v_add_f32_dpp v18, v18, v18 quad_perm:[2,3,0,1] row_mask:0xf bank_mask:0xf bound_ctrl:1
	s_nop 1
	v_add_f32_dpp v18, v18, v18 row_ror:4 row_mask:0xf bank_mask:0xf bound_ctrl:1
	s_nop 1
	v_mov_b32_dpp v19, v18 row_ror:8 row_mask:0xf bank_mask:0xf bound_ctrl:1
	s_and_saveexec_b64 s[0:1], s[6:7]
	v_add_f32_e32 v18, v18, v19
	v_add_f32_e32 v18, v108, v18
	ds_write_b32 v96, v18 offset:192
	s_or_b64 exec, exec, s[0:1]
	s_waitcnt vmcnt(10)
	v_mul_f32_e32 v18, v39, v107
	v_fmac_f32_e32 v18, v38, v105
	v_fmac_f32_e32 v18, v40, v106
	v_fmac_f32_e32 v18, v41, v104
	s_nop 1
	v_add_f32_dpp v18, v18, v18 quad_perm:[1,0,3,2] row_mask:0xf bank_mask:0xf bound_ctrl:1
	s_nop 1
	v_add_f32_dpp v18, v18, v18 quad_perm:[2,3,0,1] row_mask:0xf bank_mask:0xf bound_ctrl:1
	s_nop 1
	v_add_f32_dpp v18, v18, v18 row_ror:4 row_mask:0xf bank_mask:0xf bound_ctrl:1
	s_nop 1
	v_mov_b32_dpp v19, v18 row_ror:8 row_mask:0xf bank_mask:0xf bound_ctrl:1
	s_and_saveexec_b64 s[0:1], s[6:7]
	v_add_f32_e32 v18, v18, v19
	v_add_f32_e32 v18, v108, v18
	ds_write_b32 v96, v18 offset:208
	s_or_b64 exec, exec, s[0:1]
	s_waitcnt vmcnt(9)
	v_mul_f32_e32 v18, v43, v107
	v_fmac_f32_e32 v18, v42, v105
	v_fmac_f32_e32 v18, v44, v106
	v_fmac_f32_e32 v18, v45, v104
	s_nop 1
	v_add_f32_dpp v18, v18, v18 quad_perm:[1,0,3,2] row_mask:0xf bank_mask:0xf bound_ctrl:1
	s_nop 1
	v_add_f32_dpp v18, v18, v18 quad_perm:[2,3,0,1] row_mask:0xf bank_mask:0xf bound_ctrl:1
	s_nop 1
	v_add_f32_dpp v18, v18, v18 row_ror:4 row_mask:0xf bank_mask:0xf bound_ctrl:1
	s_nop 1
	v_mov_b32_dpp v19, v18 row_ror:8 row_mask:0xf bank_mask:0xf bound_ctrl:1
	s_and_saveexec_b64 s[0:1], s[6:7]
	v_add_f32_e32 v18, v18, v19
	v_add_f32_e32 v18, v108, v18
	ds_write_b32 v96, v18 offset:224
	s_or_b64 exec, exec, s[0:1]
	s_waitcnt vmcnt(8)
	v_mul_f32_e32 v18, v31, v107
	v_fmac_f32_e32 v18, v30, v105
	v_fmac_f32_e32 v18, v32, v106
	v_fmac_f32_e32 v18, v33, v104
	s_nop 1
	v_add_f32_dpp v18, v18, v18 quad_perm:[1,0,3,2] row_mask:0xf bank_mask:0xf bound_ctrl:1
	s_nop 1
	v_add_f32_dpp v18, v18, v18 quad_perm:[2,3,0,1] row_mask:0xf bank_mask:0xf bound_ctrl:1
	s_nop 1
	v_add_f32_dpp v18, v18, v18 row_ror:4 row_mask:0xf bank_mask:0xf bound_ctrl:1
	s_nop 1
	v_mov_b32_dpp v19, v18 row_ror:8 row_mask:0xf bank_mask:0xf bound_ctrl:1
	s_and_saveexec_b64 s[0:1], s[6:7]
	v_add_f32_e32 v18, v18, v19
	v_add_f32_e32 v18, v108, v18
	ds_write_b32 v96, v18 offset:240
	s_or_b64 exec, exec, s[0:1]
	v_lshl_add_u64 v[18:19], v[66:67], 0, s[30:31]
	v_lshl_add_u64 v[20:21], v[18:19], 0, v[82:83]
	v_add_co_u32_e32 v22, vcc, 0x1000, v20
	v_mov_b32_e32 v91, v83
	s_nop 0
	v_addc_co_u32_e32 v23, vcc, 0, v21, vcc
	global_load_dwordx4 v[74:77], v[20:21], off nt
	global_load_dwordx4 v[66:69], v[22:23], off offset:2048 nt
	v_add_co_u32_e32 v22, vcc, 0x3000, v20
	v_lshl_add_u64 v[18:19], v[18:19], 0, v[90:91]
	s_nop 0
	v_addc_co_u32_e32 v23, vcc, 0, v21, vcc
	v_add_co_u32_e32 v24, vcc, s43, v20
	s_nop 1
	v_addc_co_u32_e32 v25, vcc, 0, v21, vcc
	global_load_dwordx4 v[58:61], v[22:23], off nt
	global_load_dwordx4 v[50:53], v[24:25], off offset:2048 nt
	v_add_co_u32_e32 v22, vcc, 0x7000, v20
	s_nop 1
	v_addc_co_u32_e32 v23, vcc, 0, v21, vcc
	global_load_dwordx4 v[46:49], v[18:19], off nt
	global_load_dwordx4 v[42:45], v[22:23], off offset:2048 nt
	v_add_co_u32_e32 v18, vcc, 0x9000, v20
	s_nop 1
	v_addc_co_u32_e32 v19, vcc, 0, v21, vcc
	v_add_co_u32_e32 v20, vcc, 0xa000, v20
	s_nop 1
	v_addc_co_u32_e32 v21, vcc, 0, v21, vcc
	global_load_dwordx4 v[38:41], v[18:19], off nt
	global_load_dwordx4 v[34:37], v[20:21], off offset:2048 nt
	s_waitcnt vmcnt(15)
	v_mul_f32_e32 v18, v79, v107
	v_fmac_f32_e32 v18, v78, v105
	v_fmac_f32_e32 v18, v80, v106
	v_fmac_f32_e32 v18, v81, v104
	s_nop 1
	v_add_f32_dpp v18, v18, v18 quad_perm:[1,0,3,2] row_mask:0xf bank_mask:0xf bound_ctrl:1
	s_nop 1
	v_add_f32_dpp v18, v18, v18 quad_perm:[2,3,0,1] row_mask:0xf bank_mask:0xf bound_ctrl:1
	s_nop 1
	v_add_f32_dpp v18, v18, v18 row_ror:4 row_mask:0xf bank_mask:0xf bound_ctrl:1
	s_nop 1
	v_mov_b32_dpp v19, v18 row_ror:8 row_mask:0xf bank_mask:0xf bound_ctrl:1
	s_and_saveexec_b64 s[0:1], s[6:7]
	v_add_f32_e32 v18, v18, v19
	v_add_f32_e32 v18, v108, v18
	ds_write_b32 v96, v18 offset:256
	s_or_b64 exec, exec, s[0:1]
	s_waitcnt vmcnt(14)
	v_mul_f32_e32 v18, v71, v107
	v_fmac_f32_e32 v18, v70, v105
	v_fmac_f32_e32 v18, v72, v106
	v_fmac_f32_e32 v18, v73, v104
	s_nop 1
	v_add_f32_dpp v18, v18, v18 quad_perm:[1,0,3,2] row_mask:0xf bank_mask:0xf bound_ctrl:1
	s_nop 1
	v_add_f32_dpp v18, v18, v18 quad_perm:[2,3,0,1] row_mask:0xf bank_mask:0xf bound_ctrl:1
	s_nop 1
	v_add_f32_dpp v18, v18, v18 row_ror:4 row_mask:0xf bank_mask:0xf bound_ctrl:1
	s_nop 1
	v_mov_b32_dpp v19, v18 row_ror:8 row_mask:0xf bank_mask:0xf bound_ctrl:1
	s_and_saveexec_b64 s[0:1], s[6:7]
	v_add_f32_e32 v18, v18, v19
	v_add_f32_e32 v18, v108, v18
	ds_write_b32 v96, v18 offset:272
	s_or_b64 exec, exec, s[0:1]
	s_waitcnt vmcnt(13)
; template <int NB>
; __device__ __forceinline__ void sb_decode_task(const Params& P, float* lds, int task) {
;     ...
;     for (int i = 0; i < NB; ++i) cur[i] = *(const float4*)(Kp + (size_t)(4 * i + g) * (SH * HD));
; #pragma unroll
;     for (int kb = 0; kb < NBT; ++kb) {
;         const float* np = (kb + 1 < NBT) ? Kp + (size_t)(4 * NB * (kb + 1)) * (SH * HD) : Vp;
; #pragma unroll
;         for (int i = 0; i < NB; ++i) nx[i] = *(const float4*)(np + (size_t)(4 * i + g) * (SH * HD));
; #pragma unroll
;         for (int i = 0; i < NB; ++i) { const int s = 4 * NB * kb + 4 * i + g;
;             float part = q0 * cur[i].x + q1 * cur[i].y + q2 * cur[i].z + q3 * cur[i].w; part = sum16(part);
;             if (c == 0) zl[s] = part + bias; }
; #pragma unroll
;         for (int i = 0; i < NB; ++i) cur[i] = nx[i];
	v_mul_f32_e32 v18, v63, v107
	v_fmac_f32_e32 v18, v62, v105
	v_fmac_f32_e32 v18, v64, v106
	v_fmac_f32_e32 v18, v65, v104
	s_nop 1
	v_add_f32_dpp v18, v18, v18 quad_perm:[1,0,3,2] row_mask:0xf bank_mask:0xf bound_ctrl:1
	s_nop 1
	v_add_f32_dpp v18, v18, v18 quad_perm:[2,3,0,1] row_mask:0xf bank_mask:0xf bound_ctrl:1
	s_nop 1
	v_add_f32_dpp v18, v18, v18 row_ror:4 row_mask:0xf bank_mask:0xf bound_ctrl:1
	s_nop 1
	v_mov_b32_dpp v19, v18 row_ror:8 row_mask:0xf bank_mask:0xf bound_ctrl:1
	s_and_saveexec_b64 s[0:1], s[6:7]
	v_add_f32_e32 v18, v18, v19
	v_add_f32_e32 v18, v108, v18
	ds_write_b32 v96, v18 offset:288
	s_or_b64 exec, exec, s[0:1]
	s_waitcnt vmcnt(12)
	v_mul_f32_e32 v18, v55, v107
	v_fmac_f32_e32 v18, v54, v105
	v_fmac_f32_e32 v18, v56, v106
	v_fmac_f32_e32 v18, v57, v104
	s_nop 1
	v_add_f32_dpp v18, v18, v18 quad_perm:[1,0,3,2] row_mask:0xf bank_mask:0xf bound_ctrl:1
	s_nop 1
	v_add_f32_dpp v18, v18, v18 quad_perm:[2,3,0,1] row_mask:0xf bank_mask:0xf bound_ctrl:1
	s_nop 1
	v_add_f32_dpp v18, v18, v18 row_ror:4 row_mask:0xf bank_mask:0xf bound_ctrl:1
	s_nop 1
	v_mov_b32_dpp v19, v18 row_ror:8 row_mask:0xf bank_mask:0xf bound_ctrl:1
	s_and_saveexec_b64 s[0:1], s[6:7]
	v_add_f32_e32 v18, v18, v19
	v_add_f32_e32 v18, v108, v18
	ds_write_b32 v96, v18 offset:304
	s_or_b64 exec, exec, s[0:1]
	s_waitcnt vmcnt(11)
	v_mul_f32_e32 v15, v15, v107
	v_fmac_f32_e32 v15, v14, v105
	v_fmac_f32_e32 v15, v16, v106
	v_fmac_f32_e32 v15, v17, v104
	s_nop 1
	v_add_f32_dpp v14, v15, v15 quad_perm:[1,0,3,2] row_mask:0xf bank_mask:0xf bound_ctrl:1
	s_nop 1
	v_add_f32_dpp v14, v14, v14 quad_perm:[2,3,0,1] row_mask:0xf bank_mask:0xf bound_ctrl:1
	s_nop 1
	v_add_f32_dpp v14, v14, v14 row_ror:4 row_mask:0xf bank_mask:0xf bound_ctrl:1
	s_nop 1
	v_mov_b32_dpp v15, v14 row_ror:8 row_mask:0xf bank_mask:0xf bound_ctrl:1
	s_and_saveexec_b64 s[0:1], s[6:7]
	v_add_f32_e32 v14, v14, v15
	v_add_f32_e32 v14, v108, v14
	ds_write_b32 v96, v14 offset:320
	s_or_b64 exec, exec, s[0:1]
	s_waitcnt vmcnt(10)
	v_mul_f32_e32 v11, v11, v107
	v_fmac_f32_e32 v11, v10, v105
	v_fmac_f32_e32 v11, v12, v106
	v_fmac_f32_e32 v11, v13, v104
	s_nop 1
	v_add_f32_dpp v10, v11, v11 quad_perm:[1,0,3,2] row_mask:0xf bank_mask:0xf bound_ctrl:1
	s_nop 1
	v_add_f32_dpp v10, v10, v10 quad_perm:[2,3,0,1] row_mask:0xf bank_mask:0xf bound_ctrl:1
	s_nop 1
	v_add_f32_dpp v10, v10, v10 row_ror:4 row_mask:0xf bank_mask:0xf bound_ctrl:1
	s_nop 1
	v_mov_b32_dpp v11, v10 row_ror:8 row_mask:0xf bank_mask:0xf bound_ctrl:1
	s_and_saveexec_b64 s[0:1], s[6:7]
	v_add_f32_e32 v10, v10, v11
	v_add_f32_e32 v10, v108, v10
	ds_write_b32 v96, v10 offset:336
	s_or_b64 exec, exec, s[0:1]
	s_waitcnt vmcnt(9)
	v_mul_f32_e32 v7, v7, v107
	v_fmac_f32_e32 v7, v6, v105
	v_fmac_f32_e32 v7, v8, v106
	v_fmac_f32_e32 v7, v9, v104
	s_nop 1
	v_add_f32_dpp v6, v7, v7 quad_perm:[1,0,3,2] row_mask:0xf bank_mask:0xf bound_ctrl:1
	s_nop 1
	v_add_f32_dpp v6, v6, v6 quad_perm:[2,3,0,1] row_mask:0xf bank_mask:0xf bound_ctrl:1
	s_nop 1
	v_add_f32_dpp v6, v6, v6 row_ror:4 row_mask:0xf bank_mask:0xf bound_ctrl:1
	s_nop 1
	v_mov_b32_dpp v7, v6 row_ror:8 row_mask:0xf bank_mask:0xf bound_ctrl:1
	s_and_saveexec_b64 s[0:1], s[6:7]
	v_add_f32_e32 v6, v6, v7
	v_add_f32_e32 v6, v108, v6
	ds_write_b32 v96, v6 offset:352
	s_or_b64 exec, exec, s[0:1]
	s_waitcnt vmcnt(8)
	v_mul_f32_e32 v3, v3, v107
	v_fmac_f32_e32 v3, v2, v105
	v_fmac_f32_e32 v3, v4, v106
	v_fmac_f32_e32 v3, v5, v104
	s_nop 1
	v_add_f32_dpp v2, v3, v3 quad_perm:[1,0,3,2] row_mask:0xf bank_mask:0xf bound_ctrl:1
	s_nop 1
	v_add_f32_dpp v2, v2, v2 quad_perm:[2,3,0,1] row_mask:0xf bank_mask:0xf bound_ctrl:1
	s_nop 1
	v_add_f32_dpp v2, v2, v2 row_ror:4 row_mask:0xf bank_mask:0xf bound_ctrl:1
	s_nop 1
	v_mov_b32_dpp v3, v2 row_ror:8 row_mask:0xf bank_mask:0xf bound_ctrl:1
	s_and_saveexec_b64 s[0:1], s[6:7]
	v_add_f32_e32 v2, v2, v3
	v_add_f32_e32 v2, v108, v2
	ds_write_b32 v96, v2 offset:368
	s_or_b64 exec, exec, s[0:1]
	v_lshlrev_b64 v[2:3], 6, v[92:93]
	v_lshl_add_u64 v[6:7], v[2:3], 2, v[86:87]
	v_lshl_add_u64 v[54:55], v[6:7], 0, v[82:83]
	v_add_co_u32_e32 v2, vcc, 0x1000, v54
	v_mov_b32_e32 v91, v83
	s_nop 0
	v_addc_co_u32_e32 v3, vcc, 0, v55, vcc
	v_add_co_u32_e32 v8, vcc, 0x3000, v54
	v_lshl_add_u64 v[10:11], v[6:7], 0, v[90:91]
	s_nop 0
	v_addc_co_u32_e32 v9, vcc, 0, v55, vcc
	v_add_co_u32_e32 v14, vcc, s43, v54
	global_load_dwordx4 v[30:33], v[54:55], off nt
	s_nop 0
	global_load_dwordx4 v[2:5], v[2:3], off offset:2048 nt
	v_addc_co_u32_e32 v15, vcc, 0, v55, vcc
	v_add_co_u32_e32 v18, vcc, 0x7000, v54
	global_load_dwordx4 v[6:9], v[8:9], off nt
	s_nop 0
	global_load_dwordx4 v[10:13], v[10:11], off nt
	v_addc_co_u32_e32 v19, vcc, 0, v55, vcc
	v_add_co_u32_e32 v22, vcc, 0x9000, v54
	global_load_dwordx4 v[14:17], v[14:15], off offset:2048 nt
	s_nop 0
	global_load_dwordx4 v[18:21], v[18:19], off offset:2048 nt
	v_addc_co_u32_e32 v23, vcc, 0, v55, vcc
	v_add_co_u32_e32 v26, vcc, 0xa000, v54
	s_waitcnt vmcnt(13)
	v_mul_f32_e32 v56, v75, v107
	v_addc_co_u32_e32 v27, vcc, 0, v55, vcc
	global_load_dwordx4 v[22:25], v[22:23], off nt
	s_nop 0
	global_load_dwordx4 v[26:29], v[26:27], off offset:2048 nt
	v_fmac_f32_e32 v56, v74, v105
	v_fmac_f32_e32 v56, v76, v106
	v_fmac_f32_e32 v56, v77, v104
	s_nop 1
	v_add_f32_dpp v56, v56, v56 quad_perm:[1,0,3,2] row_mask:0xf bank_mask:0xf bound_ctrl:1
	s_nop 1
	v_add_f32_dpp v56, v56, v56 quad_perm:[2,3,0,1] row_mask:0xf bank_mask:0xf bound_ctrl:1
	s_nop 1
	v_add_f32_dpp v56, v56, v56 row_ror:4 row_mask:0xf bank_mask:0xf bound_ctrl:1
	s_nop 1
	v_mov_b32_dpp v57, v56 row_ror:8 row_mask:0xf bank_mask:0xf bound_ctrl:1
	s_and_saveexec_b64 s[0:1], s[6:7]
	v_add_f32_e32 v56, v56, v57
	v_add_f32_e32 v56, v108, v56
	ds_write_b32 v96, v56 offset:384
	s_or_b64 exec, exec, s[0:1]
	s_waitcnt vmcnt(14)
; template <int NB>
; __device__ __forceinline__ void sb_decode_task(const Params& P, float* lds, int task) {
;     ...
;         for (int i = 0; i < NB; ++i) { const int s = 4 * NB * kb + 4 * i + g;
;             float part = q0 * cur[i].x + q1 * cur[i].y + q2 * cur[i].z + q3 * cur[i].w; part = sum16(part);
;             if (c == 0) zl[s] = part + bias; }
; #pragma unroll
;         for (int i = 0; i < NB; ++i) cur[i] = nx[i];
;     }
;     asm volatile("s_waitcnt lgkmcnt(0)" ::: "memory");
;     __builtin_amdgcn_wave_barrier();
;     const float z0 = zl[2 * lane], z1 = zl[2 * lane + 1];
	v_mul_f32_e32 v56, v67, v107
	v_fmac_f32_e32 v56, v66, v105
	v_fmac_f32_e32 v56, v68, v106
	v_fmac_f32_e32 v56, v69, v104
	s_nop 1
	v_add_f32_dpp v56, v56, v56 quad_perm:[1,0,3,2] row_mask:0xf bank_mask:0xf bound_ctrl:1
	s_nop 1
	v_add_f32_dpp v56, v56, v56 quad_perm:[2,3,0,1] row_mask:0xf bank_mask:0xf bound_ctrl:1
	s_nop 1
	v_add_f32_dpp v56, v56, v56 row_ror:4 row_mask:0xf bank_mask:0xf bound_ctrl:1
	s_nop 1
	v_mov_b32_dpp v57, v56 row_ror:8 row_mask:0xf bank_mask:0xf bound_ctrl:1
	s_and_saveexec_b64 s[0:1], s[6:7]
	v_add_f32_e32 v56, v56, v57
	v_add_f32_e32 v56, v108, v56
	ds_write_b32 v96, v56 offset:400
	s_or_b64 exec, exec, s[0:1]
	s_waitcnt vmcnt(13)
	v_mul_f32_e32 v56, v59, v107
	v_fmac_f32_e32 v56, v58, v105
	v_fmac_f32_e32 v56, v60, v106
	v_fmac_f32_e32 v56, v61, v104
	s_nop 1
	v_add_f32_dpp v56, v56, v56 quad_perm:[1,0,3,2] row_mask:0xf bank_mask:0xf bound_ctrl:1
	s_nop 1
	v_add_f32_dpp v56, v56, v56 quad_perm:[2,3,0,1] row_mask:0xf bank_mask:0xf bound_ctrl:1
	s_nop 1
	v_add_f32_dpp v56, v56, v56 row_ror:4 row_mask:0xf bank_mask:0xf bound_ctrl:1
	s_nop 1
	v_mov_b32_dpp v57, v56 row_ror:8 row_mask:0xf bank_mask:0xf bound_ctrl:1
	s_and_saveexec_b64 s[0:1], s[6:7]
	v_add_f32_e32 v56, v56, v57
	v_add_f32_e32 v56, v108, v56
	ds_write_b32 v96, v56 offset:416
	s_or_b64 exec, exec, s[0:1]
	s_waitcnt vmcnt(12)
	v_mul_f32_e32 v51, v51, v107
	v_fmac_f32_e32 v51, v50, v105
	v_fmac_f32_e32 v51, v52, v106
	v_fmac_f32_e32 v51, v53, v104
	s_nop 1
	v_add_f32_dpp v50, v51, v51 quad_perm:[1,0,3,2] row_mask:0xf bank_mask:0xf bound_ctrl:1
	s_nop 1
	v_add_f32_dpp v50, v50, v50 quad_perm:[2,3,0,1] row_mask:0xf bank_mask:0xf bound_ctrl:1
	s_nop 1
	v_add_f32_dpp v50, v50, v50 row_ror:4 row_mask:0xf bank_mask:0xf bound_ctrl:1
	s_nop 1
	v_mov_b32_dpp v51, v50 row_ror:8 row_mask:0xf bank_mask:0xf bound_ctrl:1
	s_and_saveexec_b64 s[0:1], s[6:7]
	v_add_f32_e32 v50, v50, v51
	v_add_f32_e32 v50, v108, v50
	ds_write_b32 v96, v50 offset:432
	s_or_b64 exec, exec, s[0:1]
	s_waitcnt vmcnt(11)
	v_mul_f32_e32 v47, v47, v107
	v_fmac_f32_e32 v47, v46, v105
	v_fmac_f32_e32 v47, v48, v106
	v_fmac_f32_e32 v47, v49, v104
	s_nop 1
	v_add_f32_dpp v46, v47, v47 quad_perm:[1,0,3,2] row_mask:0xf bank_mask:0xf bound_ctrl:1
	s_nop 1
	v_add_f32_dpp v46, v46, v46 quad_perm:[2,3,0,1] row_mask:0xf bank_mask:0xf bound_ctrl:1
	s_nop 1
	v_add_f32_dpp v46, v46, v46 row_ror:4 row_mask:0xf bank_mask:0xf bound_ctrl:1
	s_nop 1
	v_mov_b32_dpp v47, v46 row_ror:8 row_mask:0xf bank_mask:0xf bound_ctrl:1
	s_and_saveexec_b64 s[0:1], s[6:7]
	v_add_f32_e32 v46, v46, v47
	v_add_f32_e32 v46, v108, v46
	ds_write_b32 v96, v46 offset:448
	s_or_b64 exec, exec, s[0:1]
	s_waitcnt vmcnt(10)
	v_mul_f32_e32 v43, v43, v107
	v_fmac_f32_e32 v43, v42, v105
	v_fmac_f32_e32 v43, v44, v106
	v_fmac_f32_e32 v43, v45, v104
	s_nop 1
	v_add_f32_dpp v42, v43, v43 quad_perm:[1,0,3,2] row_mask:0xf bank_mask:0xf bound_ctrl:1
	s_nop 1
	v_add_f32_dpp v42, v42, v42 quad_perm:[2,3,0,1] row_mask:0xf bank_mask:0xf bound_ctrl:1
	s_nop 1
	v_add_f32_dpp v42, v42, v42 row_ror:4 row_mask:0xf bank_mask:0xf bound_ctrl:1
	s_nop 1
	v_mov_b32_dpp v43, v42 row_ror:8 row_mask:0xf bank_mask:0xf bound_ctrl:1
	s_and_saveexec_b64 s[0:1], s[6:7]
	v_add_f32_e32 v42, v42, v43
	v_add_f32_e32 v42, v108, v42
	ds_write_b32 v96, v42 offset:464
	s_or_b64 exec, exec, s[0:1]
	s_waitcnt vmcnt(9)
	v_mul_f32_e32 v39, v39, v107
	v_fmac_f32_e32 v39, v38, v105
	v_fmac_f32_e32 v39, v40, v106
	v_fmac_f32_e32 v39, v41, v104
	s_nop 1
	v_add_f32_dpp v38, v39, v39 quad_perm:[1,0,3,2] row_mask:0xf bank_mask:0xf bound_ctrl:1
	s_nop 1
	v_add_f32_dpp v38, v38, v38 quad_perm:[2,3,0,1] row_mask:0xf bank_mask:0xf bound_ctrl:1
	s_nop 1
	v_add_f32_dpp v38, v38, v38 row_ror:4 row_mask:0xf bank_mask:0xf bound_ctrl:1
	s_nop 1
	v_mov_b32_dpp v39, v38 row_ror:8 row_mask:0xf bank_mask:0xf bound_ctrl:1
	s_and_saveexec_b64 s[0:1], s[6:7]
	v_add_f32_e32 v38, v38, v39
	v_add_f32_e32 v38, v108, v38
	ds_write_b32 v96, v38 offset:480
	s_or_b64 exec, exec, s[0:1]
	s_waitcnt vmcnt(8)
	v_mul_f32_e32 v35, v35, v107
	v_fmac_f32_e32 v35, v34, v105
	v_fmac_f32_e32 v35, v36, v106
	v_fmac_f32_e32 v35, v37, v104
	s_nop 1
	v_add_f32_dpp v34, v35, v35 quad_perm:[1,0,3,2] row_mask:0xf bank_mask:0xf bound_ctrl:1
	s_nop 1
	v_add_f32_dpp v34, v34, v34 quad_perm:[2,3,0,1] row_mask:0xf bank_mask:0xf bound_ctrl:1
	s_nop 1
	v_add_f32_dpp v34, v34, v34 row_ror:4 row_mask:0xf bank_mask:0xf bound_ctrl:1
	s_nop 1
	v_mov_b32_dpp v35, v34 row_ror:8 row_mask:0xf bank_mask:0xf bound_ctrl:1
	s_and_saveexec_b64 s[0:1], s[6:7]
	v_add_f32_e32 v34, v34, v35
	v_add_f32_e32 v34, v108, v34
	ds_write_b32 v96, v34 offset:496
	s_or_b64 exec, exec, s[0:1]
	s_waitcnt lgkmcnt(0)
	ds_read_b64 v[34:35], v97
	s_waitcnt lgkmcnt(0)
; __device__ __forceinline__ float softplus2_(float z2) { return fmaxf(z2, 0.f) + log1pf(exp2f(-fabsf(z2))) * LOG2E; }
; template <int NB>
; __device__ __forceinline__ void sb_decode_task(const Params& P, float* lds, int task) {
;     ...
;     const float sp0 = softplus2_(z0), sp1 = softplus2_(z1);
;     float incl = sp0 + sp1;
	v_cmp_gt_f32_e64 vcc, |v34|, s49
	s_nop 1
	v_cndmask_b32_e32 v37, 0, v101, vcc
	v_sub_f32_e64 v37, v37, |v34|
	v_exp_f32_e32 v37, v37
	v_max_f32_e32 v36, v34, v34
	v_max_f32_e32 v38, 0, v36
	v_cndmask_b32_e32 v36, 0, v100, vcc
	v_ldexp_f32 v39, v37, v36
	v_add_f32_e32 v40, 1.0, v39
	v_add_f32_e32 v36, -1.0, v40
	v_sub_f32_e32 v37, v36, v40
	v_add_f32_e32 v37, 1.0, v37
	v_sub_f32_e32 v36, v39, v36
	v_add_f32_e32 v41, v36, v37
	v_frexp_mant_f32_e32 v36, v40
	v_cmp_gt_f32_e32 vcc, s50, v36
	v_cvt_f64_f32_e32 v[36:37], v40
	v_frexp_exp_i32_f64_e32 v36, v[36:37]
	v_subbrev_co_u32_e32 v36, vcc, 0, v36, vcc
	v_sub_u32_e32 v37, 0, v36
	v_ldexp_f32 v40, v40, v37
	v_ldexp_f32 v37, v41, v37
	v_add_f32_e32 v41, -1.0, v40
	v_add_f32_e32 v42, 1.0, v41
	v_sub_f32_e32 v42, v40, v42
	v_add_f32_e32 v42, v37, v42
	v_add_f32_e32 v43, v41, v42
	v_sub_f32_e32 v41, v41, v43
	v_add_f32_e32 v41, v42, v41
	v_add_f32_e32 v42, 1.0, v40
	v_add_f32_e32 v44, -1.0, v42
	v_sub_f32_e32 v40, v40, v44
	v_add_f32_e32 v37, v37, v40
	v_add_f32_e32 v40, v42, v37
	v_sub_f32_e32 v42, v42, v40
	v_add_f32_e32 v37, v37, v42
	v_rcp_f32_e32 v42, v40
	v_cvt_f32_i32_e32 v36, v36
	v_cmp_neq_f32_e32 vcc, s52, v39
	v_mul_f32_e32 v44, v43, v42
	v_mul_f32_e32 v45, v40, v44
	v_fma_f32 v46, v44, v40, -v45
	v_fmac_f32_e32 v46, v44, v37
	v_add_f32_e32 v47, v45, v46
	v_sub_f32_e32 v48, v43, v47
	v_sub_f32_e32 v43, v43, v48
	v_sub_f32_e32 v45, v47, v45
	v_sub_f32_e32 v43, v43, v47
	v_add_f32_e32 v41, v41, v43
	v_sub_f32_e32 v43, v45, v46
	v_add_f32_e32 v41, v43, v41
	v_add_f32_e32 v43, v48, v41
	v_mul_f32_e32 v45, v42, v43
	v_mul_f32_e32 v46, v40, v45
	v_fma_f32 v40, v45, v40, -v46
	v_fmac_f32_e32 v40, v45, v37
	v_sub_f32_e32 v37, v48, v43
	v_add_f32_e32 v37, v41, v37
	v_add_f32_e32 v41, v46, v40
	v_sub_f32_e32 v47, v43, v41
	v_sub_f32_e32 v43, v43, v47
	v_sub_f32_e32 v46, v41, v46
	v_sub_f32_e32 v41, v43, v41
	v_add_f32_e32 v37, v37, v41
	v_sub_f32_e32 v40, v46, v40
	v_add_f32_e32 v37, v40, v37
	v_add_f32_e32 v40, v44, v45
	v_add_f32_e32 v37, v47, v37
	v_sub_f32_e32 v41, v40, v44
	v_mul_f32_e32 v37, v42, v37
	v_sub_f32_e32 v41, v45, v41
	v_add_f32_e32 v37, v41, v37
	v_mul_f32_e32 v44, 0x3f317218, v36
	v_add_f32_e32 v41, v40, v37
	v_fma_f32 v45, v36, s51, -v44
	v_mul_f32_e32 v42, v41, v41
	v_fmac_f32_e32 v45, 0xb102e308, v36
	v_sub_f32_e32 v36, v41, v40
	v_fmamk_f32 v43, v42, 0x3e9b6dac, v98
	v_sub_f32_e32 v36, v37, v36
	v_add_f32_e32 v37, v44, v45
	v_fmaak_f32 v43, v42, v43, 0x3f2aaada
	v_sub_f32_e32 v40, v37, v44
	v_ldexp_f32 v44, v41, 1
	v_mul_f32_e32 v41, v41, v42
	v_mul_f32_e32 v41, v41, v43
	v_add_f32_e32 v42, v44, v41
	v_sub_f32_e32 v43, v42, v44
	v_ldexp_f32 v36, v36, 1
	v_sub_f32_e32 v41, v41, v43
	v_add_f32_e32 v36, v36, v41
	v_add_f32_e32 v41, v42, v36
	v_sub_f32_e32 v42, v41, v42
	v_sub_f32_e32 v36, v36, v42
	v_add_f32_e32 v42, v37, v41
	v_sub_f32_e32 v43, v42, v37
	v_sub_f32_e32 v44, v42, v43
	v_sub_f32_e32 v40, v45, v40
	v_sub_f32_e32 v37, v37, v44
	v_sub_f32_e32 v41, v41, v43
	v_add_f32_e32 v37, v41, v37
	v_add_f32_e32 v41, v40, v36
	v_sub_f32_e32 v43, v41, v40
	v_sub_f32_e32 v44, v41, v43
	v_sub_f32_e32 v40, v40, v44
	v_sub_f32_e32 v36, v36, v43
	v_add_f32_e32 v37, v41, v37
	v_add_f32_e32 v36, v36, v40
	v_add_f32_e32 v40, v42, v37
	v_sub_f32_e32 v41, v40, v42
	v_sub_f32_e32 v37, v37, v41
	v_add_f32_e32 v36, v36, v37
	v_add_f32_e32 v36, v40, v36
	v_cndmask_b32_e32 v36, v102, v36, vcc
	v_cmp_lt_f32_e64 vcc, |v39|, s53
	s_nop 1
	v_cndmask_b32_e32 v36, v36, v39, vcc
	v_cmp_gt_f32_e64 vcc, |v35|, s49
	v_fmac_f32_e32 v38, 0x3fb8aa3b, v36
	v_max_f32_e32 v36, v35, v35
	v_cndmask_b32_e32 v37, 0, v101, vcc
	v_sub_f32_e64 v37, v37, |v35|
	v_exp_f32_e32 v37, v37
	v_max_f32_e32 v39, 0, v36
	v_cndmask_b32_e32 v36, 0, v100, vcc
	v_sub_f32_e32 v34, v34, v38
	v_ldexp_f32 v40, v37, v36
	v_add_f32_e32 v41, 1.0, v40
	v_add_f32_e32 v36, -1.0, v41
	v_sub_f32_e32 v37, v36, v41
	v_add_f32_e32 v37, 1.0, v37
	v_sub_f32_e32 v36, v40, v36
	v_add_f32_e32 v42, v36, v37
	v_frexp_mant_f32_e32 v36, v41
	v_cmp_gt_f32_e32 vcc, s50, v36
	v_cvt_f64_f32_e32 v[36:37], v41
	v_frexp_exp_i32_f64_e32 v36, v[36:37]
	v_subbrev_co_u32_e32 v36, vcc, 0, v36, vcc
	v_sub_u32_e32 v37, 0, v36
	v_ldexp_f32 v41, v41, v37
	v_ldexp_f32 v37, v42, v37
	v_add_f32_e32 v42, -1.0, v41
	v_add_f32_e32 v43, 1.0, v42
	v_sub_f32_e32 v43, v41, v43
	v_add_f32_e32 v43, v37, v43
	v_add_f32_e32 v44, v42, v43
	v_sub_f32_e32 v42, v42, v44
	v_add_f32_e32 v42, v43, v42
	v_add_f32_e32 v43, 1.0, v41
	v_add_f32_e32 v45, -1.0, v43
	v_sub_f32_e32 v41, v41, v45
	v_add_f32_e32 v37, v37, v41
	v_add_f32_e32 v41, v43, v37
	v_sub_f32_e32 v43, v43, v41
	v_add_f32_e32 v37, v37, v43
	v_rcp_f32_e32 v43, v41
	v_cvt_f32_i32_e32 v36, v36
	v_cmp_neq_f32_e32 vcc, s52, v40
	v_mul_f32_e32 v45, v44, v43
	v_mul_f32_e32 v46, v41, v45
	v_fma_f32 v47, v45, v41, -v46
	v_fmac_f32_e32 v47, v45, v37
	v_add_f32_e32 v48, v46, v47
	v_sub_f32_e32 v49, v44, v48
	v_sub_f32_e32 v44, v44, v49
	v_sub_f32_e32 v46, v48, v46
	v_sub_f32_e32 v44, v44, v48
	v_add_f32_e32 v42, v42, v44
	v_sub_f32_e32 v44, v46, v47
	v_add_f32_e32 v42, v44, v42
	v_add_f32_e32 v44, v49, v42
	v_mul_f32_e32 v46, v43, v44
	v_mul_f32_e32 v47, v41, v46
	v_fma_f32 v41, v46, v41, -v47
	v_fmac_f32_e32 v41, v46, v37
	v_sub_f32_e32 v37, v49, v44
	v_add_f32_e32 v37, v42, v37
	v_add_f32_e32 v42, v47, v41
	v_sub_f32_e32 v48, v44, v42
	v_sub_f32_e32 v44, v44, v48
	v_sub_f32_e32 v47, v42, v47
	v_sub_f32_e32 v42, v44, v42
	v_add_f32_e32 v37, v37, v42
	v_sub_f32_e32 v41, v47, v41
	v_add_f32_e32 v37, v41, v37
	v_add_f32_e32 v41, v45, v46
	v_add_f32_e32 v37, v48, v37
	v_sub_f32_e32 v42, v41, v45
	v_mul_f32_e32 v37, v43, v37
; __device__ __forceinline__ float softplus2_(float z2) { return fmaxf(z2, 0.f) + log1pf(exp2f(-fabsf(z2))) * LOG2E; }
; template <int NB>
; __device__ __forceinline__ void sb_decode_task(const Params& P, float* lds, int task) {
;     ...
;     const float sp0 = softplus2_(z0), sp1 = softplus2_(z1);
;     float incl = sp0 + sp1;
; #pragma unroll
;     for (int off = 1; off < 64; off <<= 1) { const float t = __shfl_down(incl, off); if (lane + off < 64) incl += t; }
;     const float excl = incl - (sp0 + sp1);
;     wl[2 * lane] = exp2f(z0 - sp0 - (excl + sp1));
;     wl[2 * lane + 1] = exp2f(z1 - sp1 - excl);
;     const float Ltot = __shfl(incl, 0);
;     asm volatile("s_waitcnt lgkmcnt(0)" ::: "memory");
;     __builtin_amdgcn_wave_barrier();
;     float4 o4 = make_float4(0.f, 0.f, 0.f, 0.f);
; #pragma unroll
;     for (int vb = 0; vb < NBT; ++vb) {
;         if (vb + 1 < NBT) {
; #pragma unroll
;             for (int i = 0; i < NB; ++i) nx[i] = *(const float4*)(Vp + (size_t)(4 * NB * (vb + 1) + 4 * i + g) * (SH * HD)); }
; #pragma unroll
;         for (int i = 0; i < NB; ++i) { const float w = wl[4 * NB * vb + 4 * i + g]; o4.x += w * cur[i].x; o4.y += w * cur[i].y; o4.z += w * cur[i].z; o4.w += w * cur[i].w; }
	v_sub_f32_e32 v42, v46, v42
	v_add_f32_e32 v37, v42, v37
	v_mul_f32_e32 v45, 0x3f317218, v36
	v_add_f32_e32 v42, v41, v37
	v_fma_f32 v46, v36, s51, -v45
	v_mul_f32_e32 v43, v42, v42
	v_fmac_f32_e32 v46, 0xb102e308, v36
	v_sub_f32_e32 v36, v42, v41
	v_fmamk_f32 v44, v43, 0x3e9b6dac, v98
	v_sub_f32_e32 v36, v37, v36
	v_add_f32_e32 v37, v45, v46
	v_fmaak_f32 v44, v43, v44, 0x3f2aaada
	v_sub_f32_e32 v41, v37, v45
	v_ldexp_f32 v45, v42, 1
	v_mul_f32_e32 v42, v42, v43
	v_mul_f32_e32 v42, v42, v44
	v_add_f32_e32 v43, v45, v42
	v_sub_f32_e32 v44, v43, v45
	v_ldexp_f32 v36, v36, 1
	v_sub_f32_e32 v42, v42, v44
	v_add_f32_e32 v36, v36, v42
	v_add_f32_e32 v42, v43, v36
	v_sub_f32_e32 v43, v42, v43
	v_sub_f32_e32 v36, v36, v43
	v_add_f32_e32 v43, v37, v42
	v_sub_f32_e32 v44, v43, v37
	v_sub_f32_e32 v45, v43, v44
	v_sub_f32_e32 v41, v46, v41
	v_sub_f32_e32 v37, v37, v45
	v_sub_f32_e32 v42, v42, v44
	v_add_f32_e32 v37, v42, v37
	v_add_f32_e32 v42, v41, v36
	v_sub_f32_e32 v44, v42, v41
	v_sub_f32_e32 v45, v42, v44
	v_sub_f32_e32 v41, v41, v45
	v_sub_f32_e32 v36, v36, v44
	v_add_f32_e32 v37, v42, v37
	v_add_f32_e32 v36, v36, v41
	v_add_f32_e32 v41, v43, v37
	v_sub_f32_e32 v42, v41, v43
	v_sub_f32_e32 v37, v37, v42
	v_add_f32_e32 v36, v36, v37
	v_add_f32_e32 v36, v41, v36
	v_cndmask_b32_e32 v36, v102, v36, vcc
	v_cmp_lt_f32_e64 vcc, |v40|, s53
	v_and_b32_e32 v37, 63, v103
	s_nop 0
	v_cndmask_b32_e32 v36, v36, v40, vcc
	v_cmp_ne_u32_e32 vcc, 63, v37
	v_fmac_f32_e32 v39, 0x3fb8aa3b, v36
	v_add_f32_e32 v36, v38, v39
	v_addc_co_u32_e32 v40, vcc, 0, v103, vcc
	v_lshlrev_b32_e32 v106, 2, v40
	ds_bpermute_b32 v40, v106, v36
	v_cmp_gt_u32_e32 vcc, 62, v37
	v_sub_f32_e32 v35, v35, v39
	s_waitcnt lgkmcnt(0)
	v_add_f32_e32 v40, v36, v40
	v_cndmask_b32_e64 v41, 0, 2, vcc
	v_cndmask_b32_e64 v40, v40, v36, s[8:9]
	v_add_lshl_u32 v107, v41, v103, 2
	ds_bpermute_b32 v41, v107, v40
	v_cmp_gt_u32_e32 vcc, 60, v37
	s_waitcnt lgkmcnt(0)
	v_add_f32_e32 v41, v40, v41
	v_cndmask_b32_e64 v40, v40, v41, s[10:11]
	v_cndmask_b32_e64 v41, 0, 4, vcc
	v_add_lshl_u32 v108, v41, v103, 2
	ds_bpermute_b32 v41, v108, v40
	v_cmp_gt_u32_e32 vcc, 56, v37
	s_waitcnt lgkmcnt(0)
	v_add_f32_e32 v41, v40, v41
	v_cndmask_b32_e64 v40, v40, v41, s[12:13]
	v_cndmask_b32_e64 v41, 0, 8, vcc
	v_add_lshl_u32 v109, v41, v103, 2
	ds_bpermute_b32 v41, v109, v40
	v_cmp_gt_u32_e32 vcc, 48, v37
	s_waitcnt lgkmcnt(0)
	v_add_f32_e32 v41, v40, v41
	v_cndmask_b32_e64 v37, 0, 16, vcc
	v_cndmask_b32_e64 v40, v40, v41, s[14:15]
	v_add_lshl_u32 v110, v37, v103, 2
	ds_bpermute_b32 v37, v110, v40
	s_waitcnt lgkmcnt(0)
	v_add_f32_e32 v37, v40, v37
	v_cndmask_b32_e64 v37, v40, v37, s[16:17]
	v_lshlrev_b32_e32 v40, 2, v103
	v_or_b32_e32 v111, 0x80, v40
	ds_bpermute_b32 v41, v111, v37
	v_and_b32_e32 v104, 0x100, v40
	s_waitcnt lgkmcnt(0)
	v_add_f32_e32 v41, v37, v41
	v_cndmask_b32_e64 v44, v37, v41, s[18:19]
	v_sub_f32_e32 v36, v44, v36
	v_add_f32_e32 v37, v39, v36
	v_sub_f32_e32 v34, v34, v37
	v_cmp_gt_f32_e32 vcc, s54, v34
	v_sub_f32_e32 v35, v35, v36
	s_nop 0
	v_cndmask_b32_e32 v37, 0, v101, vcc
	v_add_f32_e32 v34, v34, v37
	v_cndmask_b32_e32 v37, 0, v100, vcc
	v_cmp_gt_f32_e32 vcc, s54, v35
	v_exp_f32_e32 v34, v34
	s_nop 0
	v_cndmask_b32_e32 v36, 0, v101, vcc
	v_add_f32_e32 v35, v35, v36
	v_exp_f32_e32 v35, v35
	v_cndmask_b32_e32 v36, 0, v100, vcc
	v_ldexp_f32 v34, v34, v37
	v_ldexp_f32 v35, v35, v36
	ds_write_b64 v97, v[34:35] offset:512
	s_waitcnt lgkmcnt(0)
	ds_read2_b32 v[34:35], v96 offset0:128 offset1:132
	ds_read2_b32 v[42:43], v96 offset0:136 offset1:140
	ds_read2_b32 v[66:67], v96 offset0:144 offset1:148
	ds_read2_b32 v[68:69], v96 offset0:152 offset1:156
	ds_read2_b32 v[74:75], v96 offset0:160 offset1:164
	ds_read2_b32 v[76:77], v96 offset0:168 offset1:172
	ds_read2_b32 v[38:39], v96 offset0:176 offset1:180
	ds_read2_b32 v[40:41], v96 offset0:184 offset1:188
	s_waitcnt vmcnt(7) lgkmcnt(7)
	v_pk_fma_f32 v[70:71], v[30:31], v[34:35], 0 op_sel_hi:[1,0,0]
	v_add_co_u32_e32 v30, vcc, s55, v54
	v_pk_fma_f32 v[72:73], v[32:33], v[34:35], 0 op_sel_hi:[1,0,0]
	s_nop 0
	v_addc_co_u32_e32 v31, vcc, 0, v55, vcc
	v_add_co_u32_e32 v34, vcc, s83, v54
	v_mov_b32_e32 v64, v35
	s_nop 0
	v_addc_co_u32_e32 v35, vcc, 0, v55, vcc
	v_add_co_u32_e32 v46, vcc, s86, v54
	s_waitcnt vmcnt(6)
	v_pk_fma_f32 v[2:3], v[2:3], v[64:65], v[70:71] op_sel_hi:[1,0,1]
	v_addc_co_u32_e32 v47, vcc, 0, v55, vcc
	v_add_co_u32_e32 v50, vcc, s87, v54
	global_load_dwordx4 v[46:49], v[46:47], off nt
	s_nop 0
	v_addc_co_u32_e32 v51, vcc, 0, v55, vcc
	v_add_co_u32_e32 v56, vcc, s88, v54
	global_load_dwordx4 v[50:53], v[50:51], off offset:2048 nt
	s_nop 0
	v_addc_co_u32_e32 v57, vcc, 0, v55, vcc
	v_add_co_u32_e32 v60, vcc, s89, v54
	global_load_dwordx4 v[56:59], v[56:57], off nt
	s_nop 0
	v_addc_co_u32_e32 v61, vcc, 0, v55, vcc
	global_load_dwordx4 v[60:63], v[60:61], off offset:2048 nt
	s_waitcnt lgkmcnt(6)
	v_mov_b32_e32 v78, v43
	s_waitcnt vmcnt(9)
	v_pk_fma_f32 v[2:3], v[6:7], v[42:43], v[2:3] op_sel_hi:[1,0,1]
	s_waitcnt lgkmcnt(5)
	v_mov_b32_e32 v80, v67
	s_waitcnt vmcnt(7)
	v_pk_fma_f32 v[2:3], v[14:15], v[78:79], v[2:3] op_sel_hi:[1,0,1]
	s_waitcnt lgkmcnt(4)
	v_mov_b32_e32 v92, v69
	v_pk_fma_f32 v[2:3], v[10:11], v[66:67], v[2:3] op_sel_hi:[1,0,1]
	s_waitcnt lgkmcnt(3)
	v_mov_b32_e32 v10, v75
	s_waitcnt vmcnt(6)
	v_pk_fma_f32 v[2:3], v[18:19], v[80:81], v[2:3] op_sel_hi:[1,0,1]
	s_waitcnt lgkmcnt(2)
	v_mov_b32_e32 v14, v77
	s_waitcnt vmcnt(5)
	v_pk_fma_f32 v[2:3], v[22:23], v[68:69], v[2:3] op_sel_hi:[1,0,1]
	global_load_dwordx4 v[30:33], v[30:31], off nt
	s_waitcnt vmcnt(5)
; template <int NB>
; __device__ __forceinline__ void sb_decode_task(const Params& P, float* lds, int task) {
;     ...
;     for (int vb = 0; vb < NBT; ++vb) {
;         if (vb + 1 < NBT) {
; #pragma unroll
;             for (int i = 0; i < NB; ++i) nx[i] = *(const float4*)(Vp + (size_t)(4 * NB * (vb + 1) + 4 * i + g) * (SH * HD)); }
; #pragma unroll
;         for (int i = 0; i < NB; ++i) { const float w = wl[4 * NB * vb + 4 * i + g]; o4.x += w * cur[i].x; o4.y += w * cur[i].y; o4.z += w * cur[i].z; o4.w += w * cur[i].w; }
; #pragma unroll
;         for (int i = 0; i < NB; ++i) cur[i] = nx[i];
;     }
	v_pk_fma_f32 v[2:3], v[26:27], v[92:93], v[2:3] op_sel_hi:[1,0,1]
	global_load_dwordx4 v[34:37], v[34:35], off offset:2048 nt
	s_waitcnt vmcnt(5)
	v_pk_fma_f32 v[2:3], v[46:47], v[74:75], v[2:3] op_sel_hi:[1,0,1]
	s_waitcnt vmcnt(4)
	v_pk_fma_f32 v[2:3], v[50:51], v[10:11], v[2:3] op_sel_hi:[1,0,1]
	s_waitcnt vmcnt(3)
	v_pk_fma_f32 v[2:3], v[56:57], v[76:77], v[2:3] op_sel_hi:[1,0,1]
	s_waitcnt vmcnt(2)
	v_pk_fma_f32 v[6:7], v[60:61], v[14:15], v[2:3] op_sel_hi:[1,0,1]
	v_pk_fma_f32 v[2:3], v[4:5], v[64:65], v[72:73] op_sel_hi:[1,0,1]
	v_add_co_u32_e32 v4, vcc, s90, v54
	v_pk_fma_f32 v[2:3], v[8:9], v[42:43], v[2:3] op_sel_hi:[1,0,1]
	s_nop 0
	v_addc_co_u32_e32 v5, vcc, 0, v55, vcc
	v_pk_fma_f32 v[2:3], v[16:17], v[78:79], v[2:3] op_sel_hi:[1,0,1]
	s_waitcnt lgkmcnt(0)
	v_mov_b32_e32 v42, v41
	v_pk_fma_f32 v[2:3], v[12:13], v[66:67], v[2:3] op_sel_hi:[1,0,1]
	s_waitcnt vmcnt(1)
	v_pk_fma_f32 v[6:7], v[30:31], v[38:39], v[6:7] op_sel_hi:[1,0,1]
	v_pk_fma_f32 v[2:3], v[20:21], v[80:81], v[2:3] op_sel_hi:[1,0,1]
	s_nop 0
	v_pk_fma_f32 v[2:3], v[24:25], v[68:69], v[2:3] op_sel_hi:[1,0,1]
	s_nop 0
	v_pk_fma_f32 v[2:3], v[28:29], v[92:93], v[2:3] op_sel_hi:[1,0,1]
	v_mov_b32_e32 v28, v39
	v_pk_fma_f32 v[2:3], v[48:49], v[74:75], v[2:3] op_sel_hi:[1,0,1]
	s_waitcnt vmcnt(0)
	v_pk_fma_f32 v[6:7], v[34:35], v[28:29], v[6:7] op_sel_hi:[1,0,1]
	v_pk_fma_f32 v[2:3], v[52:53], v[10:11], v[2:3] op_sel_hi:[1,0,1]
	s_nop 0
	v_pk_fma_f32 v[2:3], v[58:59], v[76:77], v[2:3] op_sel_hi:[1,0,1]
	s_nop 0
	v_pk_fma_f32 v[2:3], v[62:63], v[14:15], v[2:3] op_sel_hi:[1,0,1]
	ds_read2_b32 v[14:15], v96 offset0:192 offset1:196
	ds_read2_b32 v[12:13], v96 offset0:200 offset1:204
	ds_read2_b32 v[10:11], v96 offset0:208 offset1:212
	ds_read2_b32 v[8:9], v96 offset0:216 offset1:220
	global_load_dwordx4 v[16:19], v[4:5], off nt
	v_add_co_u32_e32 v4, vcc, s91, v54
	v_pk_fma_f32 v[2:3], v[32:33], v[38:39], v[2:3] op_sel_hi:[1,0,1]
	s_nop 0
	v_addc_co_u32_e32 v5, vcc, 0, v55, vcc
	global_load_dwordx4 v[20:23], v[4:5], off offset:2048 nt
	v_add_co_u32_e32 v4, vcc, s92, v54
	v_pk_fma_f32 v[2:3], v[36:37], v[28:29], v[2:3] op_sel_hi:[1,0,1]
	s_nop 0
	v_addc_co_u32_e32 v5, vcc, 0, v55, vcc
	global_load_dwordx4 v[24:27], v[4:5], off nt
	v_add_co_u32_e32 v4, vcc, s93, v54
	s_waitcnt lgkmcnt(0)
	v_mov_b32_e32 v36, v9
	v_addc_co_u32_e32 v5, vcc, 0, v55, vcc
	global_load_dwordx4 v[46:49], v[4:5], off offset:2048 nt
	v_add_co_u32_e32 v4, vcc, s94, v54
	ds_read2_b32 v[30:31], v96 offset0:224 offset1:228
	s_nop 0
	v_addc_co_u32_e32 v5, vcc, 0, v55, vcc
	global_load_dwordx4 v[50:53], v[4:5], off nt
	v_add_co_u32_e32 v4, vcc, s95, v54
	s_waitcnt vmcnt(4)
	v_pk_fma_f32 v[2:3], v[18:19], v[40:41], v[2:3] op_sel_hi:[1,0,1]
	v_addc_co_u32_e32 v5, vcc, 0, v55, vcc
	global_load_dwordx4 v[56:59], v[4:5], off offset:2048 nt
	v_add_co_u32_e32 v4, vcc, s96, v54
	s_waitcnt vmcnt(4)
	v_pk_fma_f32 v[2:3], v[22:23], v[42:43], v[2:3] op_sel_hi:[1,0,1]
	v_addc_co_u32_e32 v5, vcc, 0, v55, vcc
	global_load_dwordx4 v[60:63], v[4:5], off nt
	v_add_co_u32_e32 v4, vcc, s97, v54
	s_waitcnt vmcnt(4)
	v_pk_fma_f32 v[2:3], v[26:27], v[14:15], v[2:3] op_sel_hi:[1,0,1]
	v_addc_co_u32_e32 v5, vcc, 0, v55, vcc
	global_load_dwordx4 v[64:67], v[4:5], off offset:2048 nt
	v_add_co_u32_e32 v4, vcc, s22, v54
	v_mov_b32_e32 v18, v15
	s_nop 0
	v_addc_co_u32_e32 v5, vcc, 0, v55, vcc
	global_load_dwordx4 v[68:71], v[4:5], off nt
	v_pk_fma_f32 v[6:7], v[16:17], v[40:41], v[6:7] op_sel_hi:[1,0,1]
	s_waitcnt vmcnt(5)
	v_pk_fma_f32 v[2:3], v[48:49], v[18:19], v[2:3] op_sel_hi:[1,0,1]
	v_pk_fma_f32 v[6:7], v[20:21], v[42:43], v[6:7] op_sel_hi:[1,0,1]
	s_waitcnt vmcnt(4)
	v_pk_fma_f32 v[2:3], v[52:53], v[12:13], v[2:3] op_sel_hi:[1,0,1]
	v_mov_b32_e32 v22, v13
	v_pk_fma_f32 v[6:7], v[24:25], v[14:15], v[6:7] op_sel_hi:[1,0,1]
	v_mov_b32_e32 v26, v11
	v_pk_fma_f32 v[6:7], v[46:47], v[18:19], v[6:7] op_sel_hi:[1,0,1]
	s_waitcnt vmcnt(3)
	v_pk_fma_f32 v[2:3], v[58:59], v[22:23], v[2:3] op_sel_hi:[1,0,1]
	v_pk_fma_f32 v[6:7], v[50:51], v[12:13], v[6:7] op_sel_hi:[1,0,1]
	s_waitcnt vmcnt(2)
	v_pk_fma_f32 v[2:3], v[62:63], v[10:11], v[2:3] op_sel_hi:[1,0,1]
	v_pk_fma_f32 v[6:7], v[56:57], v[22:23], v[6:7] op_sel_hi:[1,0,1]
	s_waitcnt vmcnt(1)
; template <int NB>
; __device__ __forceinline__ void sb_decode_task(const Params& P, float* lds, int task) {
;     ...
;     for (int vb = 0; vb < NBT; ++vb) {
;         if (vb + 1 < NBT) {
; #pragma unroll
;             for (int i = 0; i < NB; ++i) nx[i] = *(const float4*)(Vp + (size_t)(4 * NB * (vb + 1) + 4 * i + g) * (SH * HD)); }
; #pragma unroll
;         for (int i = 0; i < NB; ++i) { const float w = wl[4 * NB * vb + 4 * i + g]; o4.x += w * cur[i].x; o4.y += w * cur[i].y; o4.z += w * cur[i].z; o4.w += w * cur[i].w; }
; #pragma unroll
;         for (int i = 0; i < NB; ++i) cur[i] = nx[i];
;     }
; #pragma unroll
;     for (int off = 16; off < 64; off <<= 1) { o4.x += __shfl_xor(o4.x, off); o4.y += __shfl_xor(o4.y, off); o4.z += __shfl_xor(o4.z, off); o4.w += __shfl_xor(o4.w, off); }
;     if (g == 0) *(float4*)(dpart + (size_t)task * HD + 4 * c) = o4;
	v_pk_fma_f32 v[2:3], v[66:67], v[26:27], v[2:3] op_sel_hi:[1,0,1]
	v_pk_fma_f32 v[6:7], v[60:61], v[10:11], v[6:7] op_sel_hi:[1,0,1]
	v_and_b32_e32 v10, 64, v103
	v_pk_fma_f32 v[6:7], v[64:65], v[26:27], v[6:7] op_sel_hi:[1,0,1]
	v_add_u32_e32 v37, 64, v10
	v_xor_b32_e32 v10, 16, v103
	s_waitcnt vmcnt(0)
	v_pk_fma_f32 v[32:33], v[70:71], v[8:9], v[2:3] op_sel_hi:[1,0,1]
	v_add_co_u32_e32 v2, vcc, s23, v54
	v_pk_fma_f32 v[34:35], v[68:69], v[8:9], v[6:7] op_sel_hi:[1,0,1]
	s_nop 0
	v_addc_co_u32_e32 v3, vcc, 0, v55, vcc
	v_add_co_u32_e32 v6, vcc, s24, v54
	global_load_dwordx4 v[2:5], v[2:3], off offset:2048 nt
	s_nop 0
	v_addc_co_u32_e32 v7, vcc, 0, v55, vcc
	v_cmp_lt_i32_e32 vcc, v10, v37
	global_load_dwordx4 v[6:9], v[6:7], off nt
	ds_read2_b32 v[42:43], v96 offset0:232 offset1:236
	ds_read2_b32 v[40:41], v96 offset0:240 offset1:244
	ds_read2_b32 v[38:39], v96 offset0:248 offset1:252
	v_cndmask_b32_e32 v10, v103, v10, vcc
	v_lshlrev_b32_e32 v105, 2, v10
	v_add_co_u32_e32 v10, vcc, s72, v54
	s_waitcnt lgkmcnt(1)
	v_mov_b32_e32 v56, v41
	v_addc_co_u32_e32 v11, vcc, 0, v55, vcc
	v_add_co_u32_e32 v14, vcc, s73, v54
	global_load_dwordx4 v[10:13], v[10:11], off offset:2048 nt
	s_nop 0
	v_addc_co_u32_e32 v15, vcc, 0, v55, vcc
	v_add_co_u32_e32 v18, vcc, s74, v54
	global_load_dwordx4 v[14:17], v[14:15], off nt
	s_nop 0
	v_addc_co_u32_e32 v19, vcc, 0, v55, vcc
	v_add_co_u32_e32 v22, vcc, s75, v54
	global_load_dwordx4 v[18:21], v[18:19], off offset:2048 nt
	s_nop 0
	v_addc_co_u32_e32 v23, vcc, 0, v55, vcc
	v_add_co_u32_e32 v26, vcc, s80, v54
	global_load_dwordx4 v[22:25], v[22:23], off nt
	s_nop 0
	v_addc_co_u32_e32 v27, vcc, 0, v55, vcc
	v_add_co_u32_e32 v46, vcc, s81, v54
	global_load_dwordx4 v[26:29], v[26:27], off offset:2048 nt
	s_nop 0
	v_addc_co_u32_e32 v47, vcc, 0, v55, vcc
	v_add_co_u32_e32 v50, vcc, s82, v54
	global_load_dwordx4 v[46:49], v[46:47], off nt
	s_nop 0
	v_addc_co_u32_e32 v51, vcc, 0, v55, vcc
	global_load_dwordx4 v[50:53], v[50:51], off offset:2048 nt
	v_mov_b32_e32 v54, v43
	s_waitcnt lgkmcnt(0)
	v_mov_b32_e32 v58, v39
	s_waitcnt vmcnt(8)
	v_pk_fma_f32 v[2:3], v[2:3], v[36:37], v[34:35] op_sel_hi:[1,0,1]
	v_mov_b32_e32 v34, v31
	v_pk_fma_f32 v[4:5], v[4:5], v[36:37], v[32:33] op_sel_hi:[1,0,1]
	s_waitcnt vmcnt(7)
	v_pk_fma_f32 v[2:3], v[6:7], v[30:31], v[2:3] op_sel_hi:[1,0,1]
	v_pk_fma_f32 v[4:5], v[8:9], v[30:31], v[4:5] op_sel_hi:[1,0,1]
	s_waitcnt vmcnt(6)
	v_pk_fma_f32 v[2:3], v[10:11], v[34:35], v[2:3] op_sel_hi:[1,0,1]
	v_pk_fma_f32 v[4:5], v[12:13], v[34:35], v[4:5] op_sel_hi:[1,0,1]
	ds_bpermute_b32 v10, v104, v44
	s_waitcnt vmcnt(5)
	v_pk_fma_f32 v[2:3], v[14:15], v[42:43], v[2:3] op_sel_hi:[1,0,1]
	v_pk_fma_f32 v[4:5], v[16:17], v[42:43], v[4:5] op_sel_hi:[1,0,1]
	s_waitcnt vmcnt(4)
	v_pk_fma_f32 v[2:3], v[18:19], v[54:55], v[2:3] op_sel_hi:[1,0,1]
	v_pk_fma_f32 v[4:5], v[20:21], v[54:55], v[4:5] op_sel_hi:[1,0,1]
	s_waitcnt vmcnt(3)
	v_pk_fma_f32 v[2:3], v[22:23], v[40:41], v[2:3] op_sel_hi:[1,0,1]
	v_pk_fma_f32 v[4:5], v[24:25], v[40:41], v[4:5] op_sel_hi:[1,0,1]
	s_waitcnt vmcnt(2)
	v_pk_fma_f32 v[2:3], v[26:27], v[56:57], v[2:3] op_sel_hi:[1,0,1]
	v_pk_fma_f32 v[4:5], v[28:29], v[56:57], v[4:5] op_sel_hi:[1,0,1]
	s_waitcnt vmcnt(1)
	v_pk_fma_f32 v[2:3], v[46:47], v[38:39], v[2:3] op_sel_hi:[1,0,1]
	v_pk_fma_f32 v[4:5], v[48:49], v[38:39], v[4:5] op_sel_hi:[1,0,1]
	s_waitcnt vmcnt(0)
	v_pk_fma_f32 v[2:3], v[50:51], v[58:59], v[2:3] op_sel_hi:[1,0,1]
	ds_bpermute_b32 v6, v105, v2
	ds_bpermute_b32 v7, v105, v3
	v_pk_fma_f32 v[4:5], v[52:53], v[58:59], v[4:5] op_sel_hi:[1,0,1]
	s_waitcnt lgkmcnt(0)
	v_pk_add_f32 v[2:3], v[2:3], v[6:7]
	ds_bpermute_b32 v6, v105, v4
	ds_bpermute_b32 v7, v105, v5
	s_waitcnt lgkmcnt(0)
	v_pk_add_f32 v[4:5], v[4:5], v[6:7]
	v_xor_b32_e32 v6, 32, v103
	v_cmp_lt_i32_e32 vcc, v6, v37
	s_nop 1
	v_cndmask_b32_e32 v6, v103, v6, vcc
	v_lshlrev_b32_e32 v112, 2, v6
	ds_bpermute_b32 v6, v112, v2
	ds_bpermute_b32 v7, v112, v3
	ds_bpermute_b32 v8, v112, v4
	ds_bpermute_b32 v9, v112, v5
	s_and_saveexec_b64 s[0:1], s[20:21]
	s_cbranch_execz .LBB0_1022
	s_ashr_i32 s35, s34, 31
	s_lshl_b64 s[2:3], s[34:35], 8
	v_lshl_add_u64 v[12:13], v[88:89], 0, s[2:3]
	s_waitcnt lgkmcnt(2)
	v_pk_add_f32 v[2:3], v[2:3], v[6:7]
	s_waitcnt lgkmcnt(0)
	v_pk_add_f32 v[4:5], v[4:5], v[8:9]
	global_store_dwordx4 v[12:13], v[2:5], off

; __device__ __forceinline__ float bf2f(bf16_t b) { return __uint_as_float(((unsigned)b) << 16); }
; template <int NB>
; __device__ __forceinline__ void sb_decode_task(const Params& P, float* lds, int task) {
;     ...
;     constexpr int NBT = 32 / NB;
;     const int h = task % SH, bj = task / SH, b = bj / NPAGES;
;     const int page = P.page_table[bj];
;     const float* Kp = P.cache_k + ((size_t)page * PAGE * SH + h) * HD + 4 * c;
;     const float* Vp = P.cache_v + ((size_t)page * PAGE * SH + h) * HD + 4 * c;
;     const bf16_t* qp = qb + (size_t)(NTOK + b) * SBW + h * 64 + 4 * c;
;     const float q0 = bf2f(qp[0]), q1 = bf2f(qp[1]), q2 = bf2f(qp[2]), q3 = bf2f(qp[3]);
;     const float bias = P.sb_bias[h] * LOG2E;
;     float4 cur[NB], nx[NB];
; #pragma unroll
;     for (int i = 0; i < NB; ++i) cur[i] = *(const float4*)(Kp + (size_t)(4 * i + g) * (SH * HD));
; #pragma unroll
;     for (int kb = 0; kb < NBT; ++kb) {
;         const float* np = (kb + 1 < NBT) ? Kp + (size_t)(4 * NB * (kb + 1)) * (SH * HD) : Vp;
; #pragma unroll
;         for (int i = 0; i < NB; ++i) nx[i] = *(const float4*)(np + (size_t)(4 * i + g) * (SH * HD));
; #pragma unroll
;         for (int i = 0; i < NB; ++i) { const int s = 4 * NB * kb + 4 * i + g;
;             float part = q0 * cur[i].x + q1 * cur[i].y + q2 * cur[i].z + q3 * cur[i].w; part = sum16(part);
;             if (c == 0) zl[s] = part + bias; }
.LBB0_1024:
	s_or_b64 exec, exec, s[0:1]
	v_readlane_b32 s36, v252, 48
	s_add_i32 s34, s34, 1
	v_readlane_b32 s37, v252, 49
	s_mul_hi_i32 s1, s34, 0x2aaaaaab
	s_load_dwordx16 s[56:71], s[36:37], 0x0
	s_lshr_b32 s3, s1, 31
	s_add_i32 s0, s1, s3
	s_ashr_i32 s1, s1, 7
	s_mul_i32 s2, s0, 6
	s_add_i32 s33, s1, s3
	s_ashr_i32 s1, s0, 31
	s_sub_i32 s2, s34, s2
	s_lshl_b64 s[0:1], s[0:1], 2
	s_waitcnt lgkmcnt(0)
	s_add_u32 s0, s66, s0
	s_addc_u32 s1, s67, s1
	v_mov_b32_e32 v2, v253
	s_add_i32 s0, s33, 0x4000
	s_ashr_i32 s3, s2, 31
	s_mul_hi_i32 s1, s0, 0x300
	s_mulk_i32 s0, 0x300
	s_add_u32 s33, s38, s0
	s_addc_u32 s35, s39, s1
	s_lshl_b32 s0, s2, 6
	s_ashr_i32 s1, s0, 31
	s_lshl_b64 s[0:1], s[0:1], 1
	s_add_u32 s0, s33, s0
	s_addc_u32 s1, s35, s1
	v_readlane_b32 s56, v252, 16
	v_readlane_b32 s57, v252, 17
	v_readlane_b32 s64, v252, 24
	v_readlane_b32 s65, v252, 25
	s_mov_b64 s[56:57], s[64:65]
	v_mov_b32_e32 v91, v83
	v_readlane_b32 s58, v252, 18
	v_readlane_b32 s59, v252, 19
	v_readlane_b32 s60, v252, 20
	v_readlane_b32 s61, v252, 21
	v_readlane_b32 s62, v252, 22
	v_readlane_b32 s63, v252, 23
	v_readlane_b32 s66, v252, 26
	v_readlane_b32 s67, v252, 27
	v_readlane_b32 s68, v252, 28
	v_readlane_b32 s69, v252, 29
	v_readlane_b32 s70, v252, 30
	v_readlane_b32 s71, v252, 31
	v_mul_hi_i32 v3, v2, s42
	v_mul_lo_u32 v2, v2, s42
	v_lshl_add_u64 v[92:93], v[2:3], 0, s[2:3]
	v_lshlrev_b64 v[2:3], 8, v[92:93]
	v_lshl_add_u64 v[66:67], v[84:85], 0, v[2:3]
	global_load_dwordx2 v[2:3], v99, s[0:1]
	s_lshl_b64 s[0:1], s[2:3], 2
	s_add_u32 s0, s56, s0
	s_addc_u32 s1, s57, s1
	global_load_dword v22, v83, s[0:1]
	v_lshl_add_u64 v[18:19], v[66:67], 0, v[82:83]
	v_lshl_add_u64 v[20:21], v[66:67], 0, v[90:91]
	global_load_dwordx4 v[14:17], v[18:19], off nt
	global_load_dwordx4 v[62:65], v[20:21], off nt
	s_waitcnt vmcnt(3)
	v_lshlrev_b32_e32 v114, 16, v2
	v_and_b32_e32 v116, 0xffff0000, v2
	v_add_co_u32_e32 v2, vcc, s44, v18
	v_lshlrev_b32_e32 v115, 16, v3
	v_and_b32_e32 v113, 0xffff0000, v3
	v_addc_co_u32_e32 v3, vcc, 0, v19, vcc
	global_load_dwordx4 v[10:13], v[2:3], off offset:2048 nt
	v_add_co_u32_e32 v2, vcc, s45, v18
	s_waitcnt vmcnt(3)
	v_mul_f32_e32 v117, 0x3fb8aa3b, v22
	v_addc_co_u32_e32 v3, vcc, 0, v19, vcc
	global_load_dwordx4 v[6:9], v[2:3], off nt
	v_add_co_u32_e32 v2, vcc, s43, v18
	v_lshl_add_u64 v[22:23], v[66:67], 0, s[26:27]
	s_nop 0
	v_addc_co_u32_e32 v3, vcc, 0, v19, vcc
	v_add_co_u32_e32 v20, vcc, s46, v18
	v_lshl_add_u64 v[30:31], v[22:23], 0, v[82:83]
	s_nop 0
	v_addc_co_u32_e32 v21, vcc, 0, v19, vcc
	global_load_dwordx4 v[58:61], v[20:21], off offset:2048 nt
	v_add_co_u32_e32 v20, vcc, s47, v18
	v_lshl_add_u64 v[22:23], v[22:23], 0, v[90:91]
	s_nop 0
	v_addc_co_u32_e32 v21, vcc, 0, v19, vcc
	v_add_co_u32_e32 v18, vcc, s48, v18
	global_load_dwordx4 v[54:57], v[20:21], off nt
	s_nop 0
	v_addc_co_u32_e32 v19, vcc, 0, v19, vcc
	global_load_dwordx4 v[50:53], v[18:19], off offset:2048 nt
	v_add_co_u32_e32 v18, vcc, s44, v30
	global_load_dwordx4 v[22:25], v[22:23], off nt
	s_nop 0
	v_addc_co_u32_e32 v19, vcc, 0, v31, vcc
	global_load_dwordx4 v[34:37], v[18:19], off offset:2048 nt
	v_add_co_u32_e32 v18, vcc, s45, v30
	global_load_dwordx4 v[2:5], v[2:3], off offset:2048 nt
	s_nop 0
	v_addc_co_u32_e32 v19, vcc, 0, v31, vcc
	global_load_dwordx4 v[26:29], v[18:19], off nt
	v_add_co_u32_e32 v18, vcc, s43, v30
	global_load_dwordx4 v[46:49], v[30:31], off nt
	s_nop 0
	v_addc_co_u32_e32 v19, vcc, 0, v31, vcc
	v_add_co_u32_e32 v32, vcc, s46, v30
	global_load_dwordx4 v[18:21], v[18:19], off offset:2048 nt
	s_nop 0
	v_addc_co_u32_e32 v33, vcc, 0, v31, vcc
	global_load_dwordx4 v[38:41], v[32:33], off offset:2048 nt
	v_add_co_u32_e32 v32, vcc, s47, v30
	s_waitcnt vmcnt(13)
	v_mul_f32_e32 v15, v15, v116
	v_addc_co_u32_e32 v33, vcc, 0, v31, vcc
	v_add_co_u32_e32 v30, vcc, s48, v30
	global_load_dwordx4 v[42:45], v[32:33], off nt
	s_nop 0
	v_addc_co_u32_e32 v31, vcc, 0, v31, vcc
	global_load_dwordx4 v[30:33], v[30:31], off offset:2048 nt
	v_fmac_f32_e32 v15, v14, v114
	v_fmac_f32_e32 v15, v16, v115
	v_fmac_f32_e32 v15, v17, v113
	s_nop 1
	v_add_f32_dpp v14, v15, v15 quad_perm:[1,0,3,2] row_mask:0xf bank_mask:0xf bound_ctrl:1
	s_nop 1
	v_add_f32_dpp v14, v14, v14 quad_perm:[2,3,0,1] row_mask:0xf bank_mask:0xf bound_ctrl:1
	s_nop 1
	v_add_f32_dpp v14, v14, v14 row_ror:4 row_mask:0xf bank_mask:0xf bound_ctrl:1
	s_nop 1
	v_mov_b32_dpp v15, v14 row_ror:8 row_mask:0xf bank_mask:0xf bound_ctrl:1
	s_and_saveexec_b64 s[0:1], s[6:7]
	v_add_f32_e32 v14, v14, v15
	v_add_f32_e32 v14, v117, v14
	ds_write_b32 v96, v14
	s_or_b64 exec, exec, s[0:1]
	s_waitcnt vmcnt(13)
	v_mul_f32_e32 v11, v11, v116
	v_fmac_f32_e32 v11, v10, v114
	v_fmac_f32_e32 v11, v12, v115
	v_fmac_f32_e32 v11, v13, v113
	s_nop 1
	v_add_f32_dpp v10, v11, v11 quad_perm:[1,0,3,2] row_mask:0xf bank_mask:0xf bound_ctrl:1
	s_nop 1
	v_add_f32_dpp v10, v10, v10 quad_perm:[2,3,0,1] row_mask:0xf bank_mask:0xf bound_ctrl:1
	s_nop 1
	v_add_f32_dpp v10, v10, v10 row_ror:4 row_mask:0xf bank_mask:0xf bound_ctrl:1
	s_nop 1
	v_mov_b32_dpp v11, v10 row_ror:8 row_mask:0xf bank_mask:0xf bound_ctrl:1
	s_and_saveexec_b64 s[0:1], s[6:7]
	v_add_f32_e32 v10, v10, v11
	v_add_f32_e32 v10, v117, v10
	ds_write_b32 v96, v10 offset:16
	s_or_b64 exec, exec, s[0:1]
	s_waitcnt vmcnt(12)
	v_mul_f32_e32 v7, v7, v116
	v_fmac_f32_e32 v7, v6, v114
	v_fmac_f32_e32 v7, v8, v115
	v_fmac_f32_e32 v7, v9, v113
	s_nop 1
	v_add_f32_dpp v6, v7, v7 quad_perm:[1,0,3,2] row_mask:0xf bank_mask:0xf bound_ctrl:1
	s_nop 1
	v_add_f32_dpp v6, v6, v6 quad_perm:[2,3,0,1] row_mask:0xf bank_mask:0xf bound_ctrl:1
	s_nop 1
	v_add_f32_dpp v6, v6, v6 row_ror:4 row_mask:0xf bank_mask:0xf bound_ctrl:1
	s_nop 1
	v_mov_b32_dpp v7, v6 row_ror:8 row_mask:0xf bank_mask:0xf bound_ctrl:1
	s_and_saveexec_b64 s[0:1], s[6:7]
	v_add_f32_e32 v6, v6, v7
	v_add_f32_e32 v6, v117, v6
	ds_write_b32 v96, v6 offset:32
	s_or_b64 exec, exec, s[0:1]
	s_waitcnt vmcnt(6)
; template <int NB>
; __device__ __forceinline__ void sb_decode_task(const Params& P, float* lds, int task) {
;     ...
;     for (int kb = 0; kb < NBT; ++kb) {
;         const float* np = (kb + 1 < NBT) ? Kp + (size_t)(4 * NB * (kb + 1)) * (SH * HD) : Vp;
; #pragma unroll
;         for (int i = 0; i < NB; ++i) nx[i] = *(const float4*)(np + (size_t)(4 * i + g) * (SH * HD));
; #pragma unroll
;         for (int i = 0; i < NB; ++i) { const int s = 4 * NB * kb + 4 * i + g;
;             float part = q0 * cur[i].x + q1 * cur[i].y + q2 * cur[i].z + q3 * cur[i].w; part = sum16(part);
;             if (c == 0) zl[s] = part + bias; }
	v_mul_f32_e32 v3, v3, v116
	v_fmac_f32_e32 v3, v2, v114
	v_fmac_f32_e32 v3, v4, v115
	v_fmac_f32_e32 v3, v5, v113
	s_nop 1
	v_add_f32_dpp v2, v3, v3 quad_perm:[1,0,3,2] row_mask:0xf bank_mask:0xf bound_ctrl:1
	s_nop 1
	v_add_f32_dpp v2, v2, v2 quad_perm:[2,3,0,1] row_mask:0xf bank_mask:0xf bound_ctrl:1
	s_nop 1
	v_add_f32_dpp v2, v2, v2 row_ror:4 row_mask:0xf bank_mask:0xf bound_ctrl:1
	s_nop 1
	v_mov_b32_dpp v3, v2 row_ror:8 row_mask:0xf bank_mask:0xf bound_ctrl:1
	s_and_saveexec_b64 s[0:1], s[6:7]
	v_add_f32_e32 v2, v2, v3
	v_add_f32_e32 v2, v117, v2
	ds_write_b32 v96, v2 offset:48
	s_or_b64 exec, exec, s[0:1]
	v_mul_f32_e32 v2, v63, v116
	v_fmac_f32_e32 v2, v62, v114
	v_fmac_f32_e32 v2, v64, v115
	v_fmac_f32_e32 v2, v65, v113
	s_nop 1
	v_add_f32_dpp v2, v2, v2 quad_perm:[1,0,3,2] row_mask:0xf bank_mask:0xf bound_ctrl:1
	s_nop 1
	v_add_f32_dpp v2, v2, v2 quad_perm:[2,3,0,1] row_mask:0xf bank_mask:0xf bound_ctrl:1
	s_nop 1
	v_add_f32_dpp v2, v2, v2 row_ror:4 row_mask:0xf bank_mask:0xf bound_ctrl:1
	s_nop 1
	v_mov_b32_dpp v3, v2 row_ror:8 row_mask:0xf bank_mask:0xf bound_ctrl:1
	s_and_saveexec_b64 s[0:1], s[6:7]
	v_add_f32_e32 v2, v2, v3
	v_add_f32_e32 v2, v117, v2
	ds_write_b32 v96, v2 offset:64
	s_or_b64 exec, exec, s[0:1]
	v_mul_f32_e32 v2, v59, v116
	v_fmac_f32_e32 v2, v58, v114
	v_fmac_f32_e32 v2, v60, v115
	v_fmac_f32_e32 v2, v61, v113
	s_nop 1
	v_add_f32_dpp v2, v2, v2 quad_perm:[1,0,3,2] row_mask:0xf bank_mask:0xf bound_ctrl:1
	s_nop 1
	v_add_f32_dpp v2, v2, v2 quad_perm:[2,3,0,1] row_mask:0xf bank_mask:0xf bound_ctrl:1
	s_nop 1
	v_add_f32_dpp v2, v2, v2 row_ror:4 row_mask:0xf bank_mask:0xf bound_ctrl:1
	s_nop 1
	v_mov_b32_dpp v3, v2 row_ror:8 row_mask:0xf bank_mask:0xf bound_ctrl:1
	s_and_saveexec_b64 s[0:1], s[6:7]
	v_add_f32_e32 v2, v2, v3
	v_add_f32_e32 v2, v117, v2
	ds_write_b32 v96, v2 offset:80
	s_or_b64 exec, exec, s[0:1]
	v_mul_f32_e32 v2, v55, v116
	v_fmac_f32_e32 v2, v54, v114
	v_fmac_f32_e32 v2, v56, v115
	v_fmac_f32_e32 v2, v57, v113
	s_nop 1
	v_add_f32_dpp v2, v2, v2 quad_perm:[1,0,3,2] row_mask:0xf bank_mask:0xf bound_ctrl:1
	s_nop 1
	v_add_f32_dpp v2, v2, v2 quad_perm:[2,3,0,1] row_mask:0xf bank_mask:0xf bound_ctrl:1
	s_nop 1
	v_add_f32_dpp v2, v2, v2 row_ror:4 row_mask:0xf bank_mask:0xf bound_ctrl:1
	s_nop 1
	v_mov_b32_dpp v3, v2 row_ror:8 row_mask:0xf bank_mask:0xf bound_ctrl:1
	s_and_saveexec_b64 s[0:1], s[6:7]
	v_add_f32_e32 v2, v2, v3
	v_add_f32_e32 v2, v117, v2
	ds_write_b32 v96, v2 offset:96
	s_or_b64 exec, exec, s[0:1]
	v_mul_f32_e32 v2, v51, v116
	v_fmac_f32_e32 v2, v50, v114
	v_fmac_f32_e32 v2, v52, v115
	v_fmac_f32_e32 v2, v53, v113
	s_nop 1
	v_add_f32_dpp v2, v2, v2 quad_perm:[1,0,3,2] row_mask:0xf bank_mask:0xf bound_ctrl:1
	s_nop 1
	v_add_f32_dpp v2, v2, v2 quad_perm:[2,3,0,1] row_mask:0xf bank_mask:0xf bound_ctrl:1
	s_nop 1
	v_add_f32_dpp v2, v2, v2 row_ror:4 row_mask:0xf bank_mask:0xf bound_ctrl:1
	s_nop 1
	v_mov_b32_dpp v3, v2 row_ror:8 row_mask:0xf bank_mask:0xf bound_ctrl:1
	s_and_saveexec_b64 s[0:1], s[6:7]
	v_add_f32_e32 v2, v2, v3
	v_add_f32_e32 v2, v117, v2
	ds_write_b32 v96, v2 offset:112
	s_or_b64 exec, exec, s[0:1]
	v_lshl_add_u64 v[2:3], v[66:67], 0, s[28:29]
	v_lshl_add_u64 v[4:5], v[2:3], 0, v[82:83]
	v_add_co_u32_e32 v6, vcc, 0x1000, v4
	v_mov_b32_e32 v91, v83
	s_nop 0
	v_addc_co_u32_e32 v7, vcc, 0, v5, vcc
	global_load_dwordx4 v[78:81], v[4:5], off nt
	global_load_dwordx4 v[70:73], v[6:7], off offset:2048 nt
	v_add_co_u32_e32 v6, vcc, 0x3000, v4
	v_lshl_add_u64 v[2:3], v[2:3], 0, v[90:91]
	s_nop 0
	v_addc_co_u32_e32 v7, vcc, 0, v5, vcc
	v_add_co_u32_e32 v8, vcc, s43, v4
	s_waitcnt vmcnt(6)
	v_mul_f32_e32 v47, v47, v116
	v_addc_co_u32_e32 v9, vcc, 0, v5, vcc
	global_load_dwordx4 v[62:65], v[6:7], off nt
	global_load_dwordx4 v[54:57], v[8:9], off offset:2048 nt
	v_add_co_u32_e32 v6, vcc, 0x7000, v4
	v_fmac_f32_e32 v47, v46, v114
	s_nop 0
	v_addc_co_u32_e32 v7, vcc, 0, v5, vcc
	global_load_dwordx4 v[14:17], v[2:3], off nt
	global_load_dwordx4 v[10:13], v[6:7], off offset:2048 nt
	v_add_co_u32_e32 v2, vcc, 0x9000, v4
	v_fmac_f32_e32 v47, v48, v115
	s_nop 0
	v_addc_co_u32_e32 v3, vcc, 0, v5, vcc
	v_add_co_u32_e32 v4, vcc, 0xa000, v4
	v_fmac_f32_e32 v47, v49, v113
	s_nop 0
	v_addc_co_u32_e32 v5, vcc, 0, v5, vcc
	global_load_dwordx4 v[6:9], v[2:3], off nt
	s_nop 0
	global_load_dwordx4 v[2:5], v[4:5], off offset:2048 nt
	v_add_f32_dpp v46, v47, v47 quad_perm:[1,0,3,2] row_mask:0xf bank_mask:0xf bound_ctrl:1
	s_nop 1
	v_add_f32_dpp v46, v46, v46 quad_perm:[2,3,0,1] row_mask:0xf bank_mask:0xf bound_ctrl:1
	s_nop 1
	v_add_f32_dpp v46, v46, v46 row_ror:4 row_mask:0xf bank_mask:0xf bound_ctrl:1
	s_nop 1
	v_mov_b32_dpp v47, v46 row_ror:8 row_mask:0xf bank_mask:0xf bound_ctrl:1
	s_and_saveexec_b64 s[0:1], s[6:7]
	v_add_f32_e32 v46, v46, v47
	v_add_f32_e32 v46, v117, v46
	ds_write_b32 v96, v46 offset:128
	s_or_b64 exec, exec, s[0:1]
	v_mul_f32_e32 v35, v35, v116
	v_fmac_f32_e32 v35, v34, v114
	v_fmac_f32_e32 v35, v36, v115
	v_fmac_f32_e32 v35, v37, v113
	s_nop 1
	v_add_f32_dpp v34, v35, v35 quad_perm:[1,0,3,2] row_mask:0xf bank_mask:0xf bound_ctrl:1
	s_nop 1
	v_add_f32_dpp v34, v34, v34 quad_perm:[2,3,0,1] row_mask:0xf bank_mask:0xf bound_ctrl:1
	s_nop 1
	v_add_f32_dpp v34, v34, v34 row_ror:4 row_mask:0xf bank_mask:0xf bound_ctrl:1
	s_nop 1
	v_mov_b32_dpp v35, v34 row_ror:8 row_mask:0xf bank_mask:0xf bound_ctrl:1
	s_and_saveexec_b64 s[0:1], s[6:7]
	v_add_f32_e32 v34, v34, v35
	v_add_f32_e32 v34, v117, v34
	ds_write_b32 v96, v34 offset:144
	s_or_b64 exec, exec, s[0:1]
	v_mul_f32_e32 v27, v27, v116
	v_fmac_f32_e32 v27, v26, v114
	v_fmac_f32_e32 v27, v28, v115
	v_fmac_f32_e32 v27, v29, v113
	s_nop 1
	v_add_f32_dpp v26, v27, v27 quad_perm:[1,0,3,2] row_mask:0xf bank_mask:0xf bound_ctrl:1
	s_nop 1
	v_add_f32_dpp v26, v26, v26 quad_perm:[2,3,0,1] row_mask:0xf bank_mask:0xf bound_ctrl:1
	s_nop 1
	v_add_f32_dpp v26, v26, v26 row_ror:4 row_mask:0xf bank_mask:0xf bound_ctrl:1
	s_nop 1
	v_mov_b32_dpp v27, v26 row_ror:8 row_mask:0xf bank_mask:0xf bound_ctrl:1
	s_and_saveexec_b64 s[0:1], s[6:7]
	v_add_f32_e32 v26, v26, v27
	v_add_f32_e32 v26, v117, v26
	ds_write_b32 v96, v26 offset:160
	s_or_b64 exec, exec, s[0:1]
	s_waitcnt vmcnt(11)
; template <int NB>
; __device__ __forceinline__ void sb_decode_task(const Params& P, float* lds, int task) {
;     ...
;     for (int kb = 0; kb < NBT; ++kb) {
;         const float* np = (kb + 1 < NBT) ? Kp + (size_t)(4 * NB * (kb + 1)) * (SH * HD) : Vp;
; #pragma unroll
;         for (int i = 0; i < NB; ++i) nx[i] = *(const float4*)(np + (size_t)(4 * i + g) * (SH * HD));
; #pragma unroll
;         for (int i = 0; i < NB; ++i) { const int s = 4 * NB * kb + 4 * i + g;
;             float part = q0 * cur[i].x + q1 * cur[i].y + q2 * cur[i].z + q3 * cur[i].w; part = sum16(part);
;             if (c == 0) zl[s] = part + bias; }
	v_mul_f32_e32 v19, v19, v116
	v_fmac_f32_e32 v19, v18, v114
	v_fmac_f32_e32 v19, v20, v115
	v_fmac_f32_e32 v19, v21, v113
	s_nop 1
	v_add_f32_dpp v18, v19, v19 quad_perm:[1,0,3,2] row_mask:0xf bank_mask:0xf bound_ctrl:1
	s_nop 1
	v_add_f32_dpp v18, v18, v18 quad_perm:[2,3,0,1] row_mask:0xf bank_mask:0xf bound_ctrl:1
	s_nop 1
	v_add_f32_dpp v18, v18, v18 row_ror:4 row_mask:0xf bank_mask:0xf bound_ctrl:1
	s_nop 1
	v_mov_b32_dpp v19, v18 row_ror:8 row_mask:0xf bank_mask:0xf bound_ctrl:1
	s_and_saveexec_b64 s[0:1], s[6:7]
	v_add_f32_e32 v18, v18, v19
	v_add_f32_e32 v18, v117, v18
	ds_write_b32 v96, v18 offset:176
	s_or_b64 exec, exec, s[0:1]
	v_mul_f32_e32 v18, v23, v116
	v_fmac_f32_e32 v18, v22, v114
	v_fmac_f32_e32 v18, v24, v115
	v_fmac_f32_e32 v18, v25, v113
	s_nop 1
	v_add_f32_dpp v18, v18, v18 quad_perm:[1,0,3,2] row_mask:0xf bank_mask:0xf bound_ctrl:1
	s_nop 1
	v_add_f32_dpp v18, v18, v18 quad_perm:[2,3,0,1] row_mask:0xf bank_mask:0xf bound_ctrl:1
	s_nop 1
	v_add_f32_dpp v18, v18, v18 row_ror:4 row_mask:0xf bank_mask:0xf bound_ctrl:1
	s_nop 1
	v_mov_b32_dpp v19, v18 row_ror:8 row_mask:0xf bank_mask:0xf bound_ctrl:1
	s_and_saveexec_b64 s[0:1], s[6:7]
	v_add_f32_e32 v18, v18, v19
	v_add_f32_e32 v18, v117, v18
	ds_write_b32 v96, v18 offset:192
	s_or_b64 exec, exec, s[0:1]
	s_waitcnt vmcnt(10)
	v_mul_f32_e32 v18, v39, v116
	v_fmac_f32_e32 v18, v38, v114
	v_fmac_f32_e32 v18, v40, v115
	v_fmac_f32_e32 v18, v41, v113
	s_nop 1
	v_add_f32_dpp v18, v18, v18 quad_perm:[1,0,3,2] row_mask:0xf bank_mask:0xf bound_ctrl:1
	s_nop 1
	v_add_f32_dpp v18, v18, v18 quad_perm:[2,3,0,1] row_mask:0xf bank_mask:0xf bound_ctrl:1
	s_nop 1
	v_add_f32_dpp v18, v18, v18 row_ror:4 row_mask:0xf bank_mask:0xf bound_ctrl:1
	s_nop 1
	v_mov_b32_dpp v19, v18 row_ror:8 row_mask:0xf bank_mask:0xf bound_ctrl:1
	s_and_saveexec_b64 s[0:1], s[6:7]
	v_add_f32_e32 v18, v18, v19
	v_add_f32_e32 v18, v117, v18
	ds_write_b32 v96, v18 offset:208
	s_or_b64 exec, exec, s[0:1]
	s_waitcnt vmcnt(9)
	v_mul_f32_e32 v18, v43, v116
	v_fmac_f32_e32 v18, v42, v114
	v_fmac_f32_e32 v18, v44, v115
	v_fmac_f32_e32 v18, v45, v113
	s_nop 1
	v_add_f32_dpp v18, v18, v18 quad_perm:[1,0,3,2] row_mask:0xf bank_mask:0xf bound_ctrl:1
	s_nop 1
	v_add_f32_dpp v18, v18, v18 quad_perm:[2,3,0,1] row_mask:0xf bank_mask:0xf bound_ctrl:1
	s_nop 1
	v_add_f32_dpp v18, v18, v18 row_ror:4 row_mask:0xf bank_mask:0xf bound_ctrl:1
	s_nop 1
	v_mov_b32_dpp v19, v18 row_ror:8 row_mask:0xf bank_mask:0xf bound_ctrl:1
	s_and_saveexec_b64 s[0:1], s[6:7]
	v_add_f32_e32 v18, v18, v19
	v_add_f32_e32 v18, v117, v18
	ds_write_b32 v96, v18 offset:224
	s_or_b64 exec, exec, s[0:1]
	s_waitcnt vmcnt(8)
	v_mul_f32_e32 v18, v31, v116
	v_fmac_f32_e32 v18, v30, v114
	v_fmac_f32_e32 v18, v32, v115
	v_fmac_f32_e32 v18, v33, v113
	s_nop 1
	v_add_f32_dpp v18, v18, v18 quad_perm:[1,0,3,2] row_mask:0xf bank_mask:0xf bound_ctrl:1
	s_nop 1
	v_add_f32_dpp v18, v18, v18 quad_perm:[2,3,0,1] row_mask:0xf bank_mask:0xf bound_ctrl:1
	s_nop 1
	v_add_f32_dpp v18, v18, v18 row_ror:4 row_mask:0xf bank_mask:0xf bound_ctrl:1
	s_nop 1
	v_mov_b32_dpp v19, v18 row_ror:8 row_mask:0xf bank_mask:0xf bound_ctrl:1
	s_and_saveexec_b64 s[0:1], s[6:7]
	v_add_f32_e32 v18, v18, v19
	v_add_f32_e32 v18, v117, v18
	ds_write_b32 v96, v18 offset:240
	s_or_b64 exec, exec, s[0:1]
	v_lshl_add_u64 v[18:19], v[66:67], 0, s[30:31]
	v_lshl_add_u64 v[20:21], v[18:19], 0, v[82:83]
	v_add_co_u32_e32 v22, vcc, 0x1000, v20
	v_mov_b32_e32 v91, v83
	s_nop 0
	v_addc_co_u32_e32 v23, vcc, 0, v21, vcc
	global_load_dwordx4 v[74:77], v[20:21], off nt
	global_load_dwordx4 v[66:69], v[22:23], off offset:2048 nt
	v_add_co_u32_e32 v22, vcc, 0x3000, v20
	v_lshl_add_u64 v[18:19], v[18:19], 0, v[90:91]
	s_nop 0
	v_addc_co_u32_e32 v23, vcc, 0, v21, vcc
	v_add_co_u32_e32 v24, vcc, s43, v20
	s_nop 1
	v_addc_co_u32_e32 v25, vcc, 0, v21, vcc
	global_load_dwordx4 v[58:61], v[22:23], off nt
	global_load_dwordx4 v[50:53], v[24:25], off offset:2048 nt
	v_add_co_u32_e32 v22, vcc, 0x7000, v20
	s_nop 1
	v_addc_co_u32_e32 v23, vcc, 0, v21, vcc
	global_load_dwordx4 v[46:49], v[18:19], off nt
	global_load_dwordx4 v[42:45], v[22:23], off offset:2048 nt
	v_add_co_u32_e32 v18, vcc, 0x9000, v20
	s_nop 1
	v_addc_co_u32_e32 v19, vcc, 0, v21, vcc
	v_add_co_u32_e32 v20, vcc, 0xa000, v20
	s_nop 1
	v_addc_co_u32_e32 v21, vcc, 0, v21, vcc
	global_load_dwordx4 v[38:41], v[18:19], off nt
	global_load_dwordx4 v[34:37], v[20:21], off offset:2048 nt
	s_waitcnt vmcnt(15)
	v_mul_f32_e32 v18, v79, v116
	v_fmac_f32_e32 v18, v78, v114
	v_fmac_f32_e32 v18, v80, v115
	v_fmac_f32_e32 v18, v81, v113
	s_nop 1
	v_add_f32_dpp v18, v18, v18 quad_perm:[1,0,3,2] row_mask:0xf bank_mask:0xf bound_ctrl:1
	s_nop 1
	v_add_f32_dpp v18, v18, v18 quad_perm:[2,3,0,1] row_mask:0xf bank_mask:0xf bound_ctrl:1
	s_nop 1
	v_add_f32_dpp v18, v18, v18 row_ror:4 row_mask:0xf bank_mask:0xf bound_ctrl:1
	s_nop 1
	v_mov_b32_dpp v19, v18 row_ror:8 row_mask:0xf bank_mask:0xf bound_ctrl:1
	s_and_saveexec_b64 s[0:1], s[6:7]
	v_add_f32_e32 v18, v18, v19
	v_add_f32_e32 v18, v117, v18
	ds_write_b32 v96, v18 offset:256
	s_or_b64 exec, exec, s[0:1]
	s_waitcnt vmcnt(14)
	v_mul_f32_e32 v18, v71, v116
	v_fmac_f32_e32 v18, v70, v114
	v_fmac_f32_e32 v18, v72, v115
	v_fmac_f32_e32 v18, v73, v113
	s_nop 1
	v_add_f32_dpp v18, v18, v18 quad_perm:[1,0,3,2] row_mask:0xf bank_mask:0xf bound_ctrl:1
	s_nop 1
	v_add_f32_dpp v18, v18, v18 quad_perm:[2,3,0,1] row_mask:0xf bank_mask:0xf bound_ctrl:1
	s_nop 1
	v_add_f32_dpp v18, v18, v18 row_ror:4 row_mask:0xf bank_mask:0xf bound_ctrl:1
	s_nop 1
	v_mov_b32_dpp v19, v18 row_ror:8 row_mask:0xf bank_mask:0xf bound_ctrl:1
	s_and_saveexec_b64 s[0:1], s[6:7]
	v_add_f32_e32 v18, v18, v19
	v_add_f32_e32 v18, v117, v18
	ds_write_b32 v96, v18 offset:272
	s_or_b64 exec, exec, s[0:1]
	s_waitcnt vmcnt(13)
; template <int NB>
; __device__ __forceinline__ void sb_decode_task(const Params& P, float* lds, int task) {
;     ...
;     for (int kb = 0; kb < NBT; ++kb) {
;         const float* np = (kb + 1 < NBT) ? Kp + (size_t)(4 * NB * (kb + 1)) * (SH * HD) : Vp;
; #pragma unroll
;         for (int i = 0; i < NB; ++i) nx[i] = *(const float4*)(np + (size_t)(4 * i + g) * (SH * HD));
; #pragma unroll
;         for (int i = 0; i < NB; ++i) { const int s = 4 * NB * kb + 4 * i + g;
;             float part = q0 * cur[i].x + q1 * cur[i].y + q2 * cur[i].z + q3 * cur[i].w; part = sum16(part);
;             if (c == 0) zl[s] = part + bias; }
	v_mul_f32_e32 v18, v63, v116
	v_fmac_f32_e32 v18, v62, v114
	v_fmac_f32_e32 v18, v64, v115
	v_fmac_f32_e32 v18, v65, v113
	s_nop 1
	v_add_f32_dpp v18, v18, v18 quad_perm:[1,0,3,2] row_mask:0xf bank_mask:0xf bound_ctrl:1
	s_nop 1
	v_add_f32_dpp v18, v18, v18 quad_perm:[2,3,0,1] row_mask:0xf bank_mask:0xf bound_ctrl:1
	s_nop 1
	v_add_f32_dpp v18, v18, v18 row_ror:4 row_mask:0xf bank_mask:0xf bound_ctrl:1
	s_nop 1
	v_mov_b32_dpp v19, v18 row_ror:8 row_mask:0xf bank_mask:0xf bound_ctrl:1
	s_and_saveexec_b64 s[0:1], s[6:7]
	v_add_f32_e32 v18, v18, v19
	v_add_f32_e32 v18, v117, v18
	ds_write_b32 v96, v18 offset:288
	s_or_b64 exec, exec, s[0:1]
	s_waitcnt vmcnt(12)
	v_mul_f32_e32 v18, v55, v116
	v_fmac_f32_e32 v18, v54, v114
	v_fmac_f32_e32 v18, v56, v115
	v_fmac_f32_e32 v18, v57, v113
	s_nop 1
	v_add_f32_dpp v18, v18, v18 quad_perm:[1,0,3,2] row_mask:0xf bank_mask:0xf bound_ctrl:1
	s_nop 1
	v_add_f32_dpp v18, v18, v18 quad_perm:[2,3,0,1] row_mask:0xf bank_mask:0xf bound_ctrl:1
	s_nop 1
	v_add_f32_dpp v18, v18, v18 row_ror:4 row_mask:0xf bank_mask:0xf bound_ctrl:1
	s_nop 1
	v_mov_b32_dpp v19, v18 row_ror:8 row_mask:0xf bank_mask:0xf bound_ctrl:1
	s_and_saveexec_b64 s[0:1], s[6:7]
	v_add_f32_e32 v18, v18, v19
	v_add_f32_e32 v18, v117, v18
	ds_write_b32 v96, v18 offset:304
	s_or_b64 exec, exec, s[0:1]
	s_waitcnt vmcnt(11)
	v_mul_f32_e32 v15, v15, v116
	v_fmac_f32_e32 v15, v14, v114
	v_fmac_f32_e32 v15, v16, v115
	v_fmac_f32_e32 v15, v17, v113
	s_nop 1
	v_add_f32_dpp v14, v15, v15 quad_perm:[1,0,3,2] row_mask:0xf bank_mask:0xf bound_ctrl:1
	s_nop 1
	v_add_f32_dpp v14, v14, v14 quad_perm:[2,3,0,1] row_mask:0xf bank_mask:0xf bound_ctrl:1
	s_nop 1
	v_add_f32_dpp v14, v14, v14 row_ror:4 row_mask:0xf bank_mask:0xf bound_ctrl:1
	s_nop 1
	v_mov_b32_dpp v15, v14 row_ror:8 row_mask:0xf bank_mask:0xf bound_ctrl:1
	s_and_saveexec_b64 s[0:1], s[6:7]
	v_add_f32_e32 v14, v14, v15
	v_add_f32_e32 v14, v117, v14
	ds_write_b32 v96, v14 offset:320
	s_or_b64 exec, exec, s[0:1]
	s_waitcnt vmcnt(10)
	v_mul_f32_e32 v11, v11, v116
	v_fmac_f32_e32 v11, v10, v114
	v_fmac_f32_e32 v11, v12, v115
	v_fmac_f32_e32 v11, v13, v113
	s_nop 1
	v_add_f32_dpp v10, v11, v11 quad_perm:[1,0,3,2] row_mask:0xf bank_mask:0xf bound_ctrl:1
	s_nop 1
	v_add_f32_dpp v10, v10, v10 quad_perm:[2,3,0,1] row_mask:0xf bank_mask:0xf bound_ctrl:1
	s_nop 1
	v_add_f32_dpp v10, v10, v10 row_ror:4 row_mask:0xf bank_mask:0xf bound_ctrl:1
	s_nop 1
	v_mov_b32_dpp v11, v10 row_ror:8 row_mask:0xf bank_mask:0xf bound_ctrl:1
	s_and_saveexec_b64 s[0:1], s[6:7]
	v_add_f32_e32 v10, v10, v11
	v_add_f32_e32 v10, v117, v10
	ds_write_b32 v96, v10 offset:336
	s_or_b64 exec, exec, s[0:1]
	s_waitcnt vmcnt(9)
	v_mul_f32_e32 v7, v7, v116
	v_fmac_f32_e32 v7, v6, v114
	v_fmac_f32_e32 v7, v8, v115
	v_fmac_f32_e32 v7, v9, v113
	s_nop 1
	v_add_f32_dpp v6, v7, v7 quad_perm:[1,0,3,2] row_mask:0xf bank_mask:0xf bound_ctrl:1
	s_nop 1
	v_add_f32_dpp v6, v6, v6 quad_perm:[2,3,0,1] row_mask:0xf bank_mask:0xf bound_ctrl:1
	s_nop 1
	v_add_f32_dpp v6, v6, v6 row_ror:4 row_mask:0xf bank_mask:0xf bound_ctrl:1
	s_nop 1
	v_mov_b32_dpp v7, v6 row_ror:8 row_mask:0xf bank_mask:0xf bound_ctrl:1
	s_and_saveexec_b64 s[0:1], s[6:7]
	v_add_f32_e32 v6, v6, v7
	v_add_f32_e32 v6, v117, v6
	ds_write_b32 v96, v6 offset:352
	s_or_b64 exec, exec, s[0:1]
	s_waitcnt vmcnt(8)
	v_mul_f32_e32 v3, v3, v116
	v_fmac_f32_e32 v3, v2, v114
	v_fmac_f32_e32 v3, v4, v115
	v_fmac_f32_e32 v3, v5, v113
	s_nop 1
	v_add_f32_dpp v2, v3, v3 quad_perm:[1,0,3,2] row_mask:0xf bank_mask:0xf bound_ctrl:1
	s_nop 1
	v_add_f32_dpp v2, v2, v2 quad_perm:[2,3,0,1] row_mask:0xf bank_mask:0xf bound_ctrl:1
	s_nop 1
	v_add_f32_dpp v2, v2, v2 row_ror:4 row_mask:0xf bank_mask:0xf bound_ctrl:1
	s_nop 1
	v_mov_b32_dpp v3, v2 row_ror:8 row_mask:0xf bank_mask:0xf bound_ctrl:1
	s_and_saveexec_b64 s[0:1], s[6:7]
	v_add_f32_e32 v2, v2, v3
	v_add_f32_e32 v2, v117, v2
	ds_write_b32 v96, v2 offset:368
	s_or_b64 exec, exec, s[0:1]
	v_lshlrev_b64 v[2:3], 6, v[92:93]
	v_lshl_add_u64 v[6:7], v[2:3], 2, v[86:87]
	v_lshl_add_u64 v[54:55], v[6:7], 0, v[82:83]
	v_add_co_u32_e32 v2, vcc, 0x1000, v54
	v_mov_b32_e32 v91, v83
	s_nop 0
	v_addc_co_u32_e32 v3, vcc, 0, v55, vcc
	v_add_co_u32_e32 v8, vcc, 0x3000, v54
	v_lshl_add_u64 v[10:11], v[6:7], 0, v[90:91]
	s_nop 0
	v_addc_co_u32_e32 v9, vcc, 0, v55, vcc
	v_add_co_u32_e32 v14, vcc, s43, v54
	global_load_dwordx4 v[30:33], v[54:55], off nt
	s_nop 0
	global_load_dwordx4 v[2:5], v[2:3], off offset:2048 nt
	v_addc_co_u32_e32 v15, vcc, 0, v55, vcc
	v_add_co_u32_e32 v18, vcc, 0x7000, v54
	global_load_dwordx4 v[6:9], v[8:9], off nt
	s_nop 0
	global_load_dwordx4 v[10:13], v[10:11], off nt
	v_addc_co_u32_e32 v19, vcc, 0, v55, vcc
	v_add_co_u32_e32 v22, vcc, 0x9000, v54
	global_load_dwordx4 v[14:17], v[14:15], off offset:2048 nt
	s_nop 0
	global_load_dwordx4 v[18:21], v[18:19], off offset:2048 nt
	v_addc_co_u32_e32 v23, vcc, 0, v55, vcc
	v_add_co_u32_e32 v26, vcc, 0xa000, v54
	s_waitcnt vmcnt(13)
	v_mul_f32_e32 v56, v75, v116
	v_addc_co_u32_e32 v27, vcc, 0, v55, vcc
	global_load_dwordx4 v[22:25], v[22:23], off nt
	s_nop 0
	global_load_dwordx4 v[26:29], v[26:27], off offset:2048 nt
	v_fmac_f32_e32 v56, v74, v114
	v_fmac_f32_e32 v56, v76, v115
	v_fmac_f32_e32 v56, v77, v113
	s_nop 1
	v_add_f32_dpp v56, v56, v56 quad_perm:[1,0,3,2] row_mask:0xf bank_mask:0xf bound_ctrl:1
	s_nop 1
	v_add_f32_dpp v56, v56, v56 quad_perm:[2,3,0,1] row_mask:0xf bank_mask:0xf bound_ctrl:1
	s_nop 1
	v_add_f32_dpp v56, v56, v56 row_ror:4 row_mask:0xf bank_mask:0xf bound_ctrl:1
	s_nop 1
	v_mov_b32_dpp v57, v56 row_ror:8 row_mask:0xf bank_mask:0xf bound_ctrl:1
	s_and_saveexec_b64 s[0:1], s[6:7]
	v_add_f32_e32 v56, v56, v57
	v_add_f32_e32 v56, v117, v56
	ds_write_b32 v96, v56 offset:384
	s_or_b64 exec, exec, s[0:1]
	s_waitcnt vmcnt(14)
; template <int NB>
; __device__ __forceinline__ void sb_decode_task(const Params& P, float* lds, int task) {
;     ...
;         for (int i = 0; i < NB; ++i) { const int s = 4 * NB * kb + 4 * i + g;
;             float part = q0 * cur[i].x + q1 * cur[i].y + q2 * cur[i].z + q3 * cur[i].w; part = sum16(part);
;             if (c == 0) zl[s] = part + bias; }
; #pragma unroll
;         for (int i = 0; i < NB; ++i) cur[i] = nx[i];
;     }
;     asm volatile("s_waitcnt lgkmcnt(0)" ::: "memory");
;     __builtin_amdgcn_wave_barrier();
;     const float z0 = zl[2 * lane], z1 = zl[2 * lane + 1];
	v_mul_f32_e32 v56, v67, v116
	v_fmac_f32_e32 v56, v66, v114
	v_fmac_f32_e32 v56, v68, v115
	v_fmac_f32_e32 v56, v69, v113
	s_nop 1
	v_add_f32_dpp v56, v56, v56 quad_perm:[1,0,3,2] row_mask:0xf bank_mask:0xf bound_ctrl:1
	s_nop 1
	v_add_f32_dpp v56, v56, v56 quad_perm:[2,3,0,1] row_mask:0xf bank_mask:0xf bound_ctrl:1
	s_nop 1
	v_add_f32_dpp v56, v56, v56 row_ror:4 row_mask:0xf bank_mask:0xf bound_ctrl:1
	s_nop 1
	v_mov_b32_dpp v57, v56 row_ror:8 row_mask:0xf bank_mask:0xf bound_ctrl:1
	s_and_saveexec_b64 s[0:1], s[6:7]
	v_add_f32_e32 v56, v56, v57
	v_add_f32_e32 v56, v117, v56
	ds_write_b32 v96, v56 offset:400
	s_or_b64 exec, exec, s[0:1]
	s_waitcnt vmcnt(13)
	v_mul_f32_e32 v56, v59, v116
	v_fmac_f32_e32 v56, v58, v114
	v_fmac_f32_e32 v56, v60, v115
	v_fmac_f32_e32 v56, v61, v113
	s_nop 1
	v_add_f32_dpp v56, v56, v56 quad_perm:[1,0,3,2] row_mask:0xf bank_mask:0xf bound_ctrl:1
	s_nop 1
	v_add_f32_dpp v56, v56, v56 quad_perm:[2,3,0,1] row_mask:0xf bank_mask:0xf bound_ctrl:1
	s_nop 1
	v_add_f32_dpp v56, v56, v56 row_ror:4 row_mask:0xf bank_mask:0xf bound_ctrl:1
	s_nop 1
	v_mov_b32_dpp v57, v56 row_ror:8 row_mask:0xf bank_mask:0xf bound_ctrl:1
	s_and_saveexec_b64 s[0:1], s[6:7]
	v_add_f32_e32 v56, v56, v57
	v_add_f32_e32 v56, v117, v56
	ds_write_b32 v96, v56 offset:416
	s_or_b64 exec, exec, s[0:1]
	s_waitcnt vmcnt(12)
	v_mul_f32_e32 v51, v51, v116
	v_fmac_f32_e32 v51, v50, v114
	v_fmac_f32_e32 v51, v52, v115
	v_fmac_f32_e32 v51, v53, v113
	s_nop 1
	v_add_f32_dpp v50, v51, v51 quad_perm:[1,0,3,2] row_mask:0xf bank_mask:0xf bound_ctrl:1
	s_nop 1
	v_add_f32_dpp v50, v50, v50 quad_perm:[2,3,0,1] row_mask:0xf bank_mask:0xf bound_ctrl:1
	s_nop 1
	v_add_f32_dpp v50, v50, v50 row_ror:4 row_mask:0xf bank_mask:0xf bound_ctrl:1
	s_nop 1
	v_mov_b32_dpp v51, v50 row_ror:8 row_mask:0xf bank_mask:0xf bound_ctrl:1
	s_and_saveexec_b64 s[0:1], s[6:7]
	v_add_f32_e32 v50, v50, v51
	v_add_f32_e32 v50, v117, v50
	ds_write_b32 v96, v50 offset:432
	s_or_b64 exec, exec, s[0:1]
	s_waitcnt vmcnt(11)
	v_mul_f32_e32 v47, v47, v116
	v_fmac_f32_e32 v47, v46, v114
	v_fmac_f32_e32 v47, v48, v115
	v_fmac_f32_e32 v47, v49, v113
	s_nop 1
	v_add_f32_dpp v46, v47, v47 quad_perm:[1,0,3,2] row_mask:0xf bank_mask:0xf bound_ctrl:1
	s_nop 1
	v_add_f32_dpp v46, v46, v46 quad_perm:[2,3,0,1] row_mask:0xf bank_mask:0xf bound_ctrl:1
	s_nop 1
	v_add_f32_dpp v46, v46, v46 row_ror:4 row_mask:0xf bank_mask:0xf bound_ctrl:1
	s_nop 1
	v_mov_b32_dpp v47, v46 row_ror:8 row_mask:0xf bank_mask:0xf bound_ctrl:1
	s_and_saveexec_b64 s[0:1], s[6:7]
	v_add_f32_e32 v46, v46, v47
	v_add_f32_e32 v46, v117, v46
	ds_write_b32 v96, v46 offset:448
	s_or_b64 exec, exec, s[0:1]
	s_waitcnt vmcnt(10)
	v_mul_f32_e32 v43, v43, v116
	v_fmac_f32_e32 v43, v42, v114
	v_fmac_f32_e32 v43, v44, v115
	v_fmac_f32_e32 v43, v45, v113
	s_nop 1
	v_add_f32_dpp v42, v43, v43 quad_perm:[1,0,3,2] row_mask:0xf bank_mask:0xf bound_ctrl:1
	s_nop 1
	v_add_f32_dpp v42, v42, v42 quad_perm:[2,3,0,1] row_mask:0xf bank_mask:0xf bound_ctrl:1
	s_nop 1
	v_add_f32_dpp v42, v42, v42 row_ror:4 row_mask:0xf bank_mask:0xf bound_ctrl:1
	s_nop 1
	v_mov_b32_dpp v43, v42 row_ror:8 row_mask:0xf bank_mask:0xf bound_ctrl:1
	s_and_saveexec_b64 s[0:1], s[6:7]
	v_add_f32_e32 v42, v42, v43
	v_add_f32_e32 v42, v117, v42
	ds_write_b32 v96, v42 offset:464
	s_or_b64 exec, exec, s[0:1]
	s_waitcnt vmcnt(9)
	v_mul_f32_e32 v39, v39, v116
	v_fmac_f32_e32 v39, v38, v114
	v_fmac_f32_e32 v39, v40, v115
	v_fmac_f32_e32 v39, v41, v113
	s_nop 1
	v_add_f32_dpp v38, v39, v39 quad_perm:[1,0,3,2] row_mask:0xf bank_mask:0xf bound_ctrl:1
	s_nop 1
	v_add_f32_dpp v38, v38, v38 quad_perm:[2,3,0,1] row_mask:0xf bank_mask:0xf bound_ctrl:1
	s_nop 1
	v_add_f32_dpp v38, v38, v38 row_ror:4 row_mask:0xf bank_mask:0xf bound_ctrl:1
	s_nop 1
	v_mov_b32_dpp v39, v38 row_ror:8 row_mask:0xf bank_mask:0xf bound_ctrl:1
	s_and_saveexec_b64 s[0:1], s[6:7]
	v_add_f32_e32 v38, v38, v39
	v_add_f32_e32 v38, v117, v38
	ds_write_b32 v96, v38 offset:480
	s_or_b64 exec, exec, s[0:1]
	s_waitcnt vmcnt(8)
	v_mul_f32_e32 v35, v35, v116
	v_fmac_f32_e32 v35, v34, v114
	v_fmac_f32_e32 v35, v36, v115
	v_fmac_f32_e32 v35, v37, v113
	s_nop 1
	v_add_f32_dpp v34, v35, v35 quad_perm:[1,0,3,2] row_mask:0xf bank_mask:0xf bound_ctrl:1
	s_nop 1
	v_add_f32_dpp v34, v34, v34 quad_perm:[2,3,0,1] row_mask:0xf bank_mask:0xf bound_ctrl:1
	s_nop 1
	v_add_f32_dpp v34, v34, v34 row_ror:4 row_mask:0xf bank_mask:0xf bound_ctrl:1
	s_nop 1
	v_mov_b32_dpp v35, v34 row_ror:8 row_mask:0xf bank_mask:0xf bound_ctrl:1
	s_and_saveexec_b64 s[0:1], s[6:7]
	v_add_f32_e32 v34, v34, v35
	v_add_f32_e32 v34, v117, v34
	ds_write_b32 v96, v34 offset:496
	s_or_b64 exec, exec, s[0:1]
	s_waitcnt lgkmcnt(0)
	ds_read_b64 v[34:35], v97
	s_waitcnt lgkmcnt(0)
; __device__ __forceinline__ float softplus2_(float z2) { return fmaxf(z2, 0.f) + log1pf(exp2f(-fabsf(z2))) * LOG2E; }
; template <int NB>
; __device__ __forceinline__ void sb_decode_task(const Params& P, float* lds, int task) {
;     ...
;     const float z0 = zl[2 * lane], z1 = zl[2 * lane + 1];
;     const float sp0 = softplus2_(z0), sp1 = softplus2_(z1);
;     float incl = sp0 + sp1;
; #pragma unroll
;     for (int off = 1; off < 64; off <<= 1) { const float t = __shfl_down(incl, off); if (lane + off < 64) incl += t; }
;     const float excl = incl - (sp0 + sp1);
	v_cmp_gt_f32_e64 vcc, |v34|, s49
	s_nop 1
	v_cndmask_b32_e32 v37, 0, v101, vcc
	v_sub_f32_e64 v37, v37, |v34|
	v_exp_f32_e32 v37, v37
	v_max_f32_e32 v36, v34, v34
	v_max_f32_e32 v38, 0, v36
	v_cndmask_b32_e32 v36, 0, v100, vcc
	v_ldexp_f32 v39, v37, v36
	v_add_f32_e32 v40, 1.0, v39
	v_add_f32_e32 v36, -1.0, v40
	v_sub_f32_e32 v37, v36, v40
	v_add_f32_e32 v37, 1.0, v37
	v_sub_f32_e32 v36, v39, v36
	v_add_f32_e32 v41, v36, v37
	v_frexp_mant_f32_e32 v36, v40
	v_cmp_gt_f32_e32 vcc, s50, v36
	v_cvt_f64_f32_e32 v[36:37], v40
	v_frexp_exp_i32_f64_e32 v36, v[36:37]
	v_subbrev_co_u32_e32 v36, vcc, 0, v36, vcc
	v_sub_u32_e32 v37, 0, v36
	v_ldexp_f32 v40, v40, v37
	v_ldexp_f32 v37, v41, v37
	v_add_f32_e32 v41, -1.0, v40
	v_add_f32_e32 v42, 1.0, v41
	v_sub_f32_e32 v42, v40, v42
	v_add_f32_e32 v42, v37, v42
	v_add_f32_e32 v43, v41, v42
	v_sub_f32_e32 v41, v41, v43
	v_add_f32_e32 v41, v42, v41
	v_add_f32_e32 v42, 1.0, v40
	v_add_f32_e32 v44, -1.0, v42
	v_sub_f32_e32 v40, v40, v44
	v_add_f32_e32 v37, v37, v40
	v_add_f32_e32 v40, v42, v37
	v_sub_f32_e32 v42, v42, v40
	v_add_f32_e32 v37, v37, v42
	v_rcp_f32_e32 v42, v40
	v_cvt_f32_i32_e32 v36, v36
	v_cmp_neq_f32_e32 vcc, s52, v39
	v_mul_f32_e32 v44, v43, v42
	v_mul_f32_e32 v45, v40, v44
	v_fma_f32 v46, v44, v40, -v45
	v_fmac_f32_e32 v46, v44, v37
	v_add_f32_e32 v47, v45, v46
	v_sub_f32_e32 v48, v43, v47
	v_sub_f32_e32 v43, v43, v48
	v_sub_f32_e32 v45, v47, v45
	v_sub_f32_e32 v43, v43, v47
	v_add_f32_e32 v41, v41, v43
	v_sub_f32_e32 v43, v45, v46
	v_add_f32_e32 v41, v43, v41
	v_add_f32_e32 v43, v48, v41
	v_mul_f32_e32 v45, v42, v43
	v_mul_f32_e32 v46, v40, v45
	v_fma_f32 v40, v45, v40, -v46
	v_fmac_f32_e32 v40, v45, v37
	v_sub_f32_e32 v37, v48, v43
	v_add_f32_e32 v37, v41, v37
	v_add_f32_e32 v41, v46, v40
	v_sub_f32_e32 v47, v43, v41
	v_sub_f32_e32 v43, v43, v47
	v_sub_f32_e32 v46, v41, v46
	v_sub_f32_e32 v41, v43, v41
	v_add_f32_e32 v37, v37, v41
	v_sub_f32_e32 v40, v46, v40
	v_add_f32_e32 v37, v40, v37
	v_add_f32_e32 v40, v44, v45
	v_add_f32_e32 v37, v47, v37
	v_sub_f32_e32 v41, v40, v44
	v_mul_f32_e32 v37, v42, v37
	v_sub_f32_e32 v41, v45, v41
	v_add_f32_e32 v37, v41, v37
	v_mul_f32_e32 v44, 0x3f317218, v36
	v_add_f32_e32 v41, v40, v37
	v_fma_f32 v45, v36, s51, -v44
	v_mul_f32_e32 v42, v41, v41
	v_fmac_f32_e32 v45, 0xb102e308, v36
	v_sub_f32_e32 v36, v41, v40
	v_fmamk_f32 v43, v42, 0x3e9b6dac, v98
	v_sub_f32_e32 v36, v37, v36
	v_add_f32_e32 v37, v44, v45
	v_fmaak_f32 v43, v42, v43, 0x3f2aaada
	v_sub_f32_e32 v40, v37, v44
	v_ldexp_f32 v44, v41, 1
	v_mul_f32_e32 v41, v41, v42
	v_mul_f32_e32 v41, v41, v43
	v_add_f32_e32 v42, v44, v41
	v_sub_f32_e32 v43, v42, v44
	v_ldexp_f32 v36, v36, 1
	v_sub_f32_e32 v41, v41, v43
	v_add_f32_e32 v36, v36, v41
	v_add_f32_e32 v41, v42, v36
	v_sub_f32_e32 v42, v41, v42
	v_sub_f32_e32 v36, v36, v42
	v_add_f32_e32 v42, v37, v41
	v_sub_f32_e32 v43, v42, v37
	v_sub_f32_e32 v44, v42, v43
	v_sub_f32_e32 v40, v45, v40
	v_sub_f32_e32 v37, v37, v44
	v_sub_f32_e32 v41, v41, v43
	v_add_f32_e32 v37, v41, v37
	v_add_f32_e32 v41, v40, v36
	v_sub_f32_e32 v43, v41, v40
	v_sub_f32_e32 v44, v41, v43
	v_sub_f32_e32 v40, v40, v44
	v_sub_f32_e32 v36, v36, v43
	v_add_f32_e32 v37, v41, v37
	v_add_f32_e32 v36, v36, v40
	v_add_f32_e32 v40, v42, v37
	v_sub_f32_e32 v41, v40, v42
	v_sub_f32_e32 v37, v37, v41
	v_add_f32_e32 v36, v36, v37
	v_add_f32_e32 v36, v40, v36
	v_cndmask_b32_e32 v36, v102, v36, vcc
	v_cmp_lt_f32_e64 vcc, |v39|, s53
	s_nop 1
	v_cndmask_b32_e32 v36, v36, v39, vcc
	v_cmp_gt_f32_e64 vcc, |v35|, s49
	v_fmac_f32_e32 v38, 0x3fb8aa3b, v36
	v_max_f32_e32 v36, v35, v35
	v_cndmask_b32_e32 v37, 0, v101, vcc
	v_sub_f32_e64 v37, v37, |v35|
	v_exp_f32_e32 v37, v37
	v_max_f32_e32 v39, 0, v36
	v_cndmask_b32_e32 v36, 0, v100, vcc
	v_sub_f32_e32 v34, v34, v38
	v_ldexp_f32 v40, v37, v36
	v_add_f32_e32 v41, 1.0, v40
	v_add_f32_e32 v36, -1.0, v41
	v_sub_f32_e32 v37, v36, v41
	v_add_f32_e32 v37, 1.0, v37
	v_sub_f32_e32 v36, v40, v36
	v_add_f32_e32 v42, v36, v37
	v_frexp_mant_f32_e32 v36, v41
	v_cmp_gt_f32_e32 vcc, s50, v36
	v_cvt_f64_f32_e32 v[36:37], v41
	v_frexp_exp_i32_f64_e32 v36, v[36:37]
	v_subbrev_co_u32_e32 v36, vcc, 0, v36, vcc
	v_sub_u32_e32 v37, 0, v36
	v_ldexp_f32 v41, v41, v37
	v_ldexp_f32 v37, v42, v37
	v_add_f32_e32 v42, -1.0, v41
	v_add_f32_e32 v43, 1.0, v42
	v_sub_f32_e32 v43, v41, v43
	v_add_f32_e32 v43, v37, v43
	v_add_f32_e32 v44, v42, v43
	v_sub_f32_e32 v42, v42, v44
	v_add_f32_e32 v42, v43, v42
	v_add_f32_e32 v43, 1.0, v41
	v_add_f32_e32 v45, -1.0, v43
	v_sub_f32_e32 v41, v41, v45
	v_add_f32_e32 v37, v37, v41
	v_add_f32_e32 v41, v43, v37
	v_sub_f32_e32 v43, v43, v41
	v_add_f32_e32 v37, v37, v43
	v_rcp_f32_e32 v43, v41
	v_cvt_f32_i32_e32 v36, v36
	v_cmp_neq_f32_e32 vcc, s52, v40
	v_mul_f32_e32 v45, v44, v43
	v_mul_f32_e32 v46, v41, v45
	v_fma_f32 v47, v45, v41, -v46
	v_fmac_f32_e32 v47, v45, v37
	v_add_f32_e32 v48, v46, v47
	v_sub_f32_e32 v49, v44, v48
	v_sub_f32_e32 v44, v44, v49
	v_sub_f32_e32 v46, v48, v46
	v_sub_f32_e32 v44, v44, v48
	v_add_f32_e32 v42, v42, v44
	v_sub_f32_e32 v44, v46, v47
	v_add_f32_e32 v42, v44, v42
	v_add_f32_e32 v44, v49, v42
	v_mul_f32_e32 v46, v43, v44
	v_mul_f32_e32 v47, v41, v46
	v_fma_f32 v41, v46, v41, -v47
	v_fmac_f32_e32 v41, v46, v37
	v_sub_f32_e32 v37, v49, v44
	v_add_f32_e32 v37, v42, v37
	v_add_f32_e32 v42, v47, v41
	v_sub_f32_e32 v48, v44, v42
	v_sub_f32_e32 v44, v44, v48
	v_sub_f32_e32 v47, v42, v47
	v_sub_f32_e32 v42, v44, v42
	v_add_f32_e32 v37, v37, v42
	v_sub_f32_e32 v41, v47, v41
	v_add_f32_e32 v37, v41, v37
	v_add_f32_e32 v41, v45, v46
	v_add_f32_e32 v37, v48, v37
	v_sub_f32_e32 v42, v41, v45
	v_mul_f32_e32 v37, v43, v37
; template <int NB>
; __device__ __forceinline__ void sb_decode_task(const Params& P, float* lds, int task) {
;     ...
;     float incl = sp0 + sp1;
; #pragma unroll
;     for (int off = 1; off < 64; off <<= 1) { const float t = __shfl_down(incl, off); if (lane + off < 64) incl += t; }
;     const float excl = incl - (sp0 + sp1);
;     wl[2 * lane] = exp2f(z0 - sp0 - (excl + sp1));
;     wl[2 * lane + 1] = exp2f(z1 - sp1 - excl);
;     const float Ltot = __shfl(incl, 0);
;     asm volatile("s_waitcnt lgkmcnt(0)" ::: "memory");
;     __builtin_amdgcn_wave_barrier();
;     float4 o4 = make_float4(0.f, 0.f, 0.f, 0.f);
; #pragma unroll
;     for (int vb = 0; vb < NBT; ++vb) {
;         if (vb + 1 < NBT) {
; #pragma unroll
;             for (int i = 0; i < NB; ++i) nx[i] = *(const float4*)(Vp + (size_t)(4 * NB * (vb + 1) + 4 * i + g) * (SH * HD)); }
; #pragma unroll
;         for (int i = 0; i < NB; ++i) { const float w = wl[4 * NB * vb + 4 * i + g]; o4.x += w * cur[i].x; o4.y += w * cur[i].y; o4.z += w * cur[i].z; o4.w += w * cur[i].w; }
	v_sub_f32_e32 v42, v46, v42
	v_add_f32_e32 v37, v42, v37
	v_mul_f32_e32 v45, 0x3f317218, v36
	v_add_f32_e32 v42, v41, v37
	v_fma_f32 v46, v36, s51, -v45
	v_mul_f32_e32 v43, v42, v42
	v_fmac_f32_e32 v46, 0xb102e308, v36
	v_sub_f32_e32 v36, v42, v41
	v_fmamk_f32 v44, v43, 0x3e9b6dac, v98
	v_sub_f32_e32 v36, v37, v36
	v_add_f32_e32 v37, v45, v46
	v_fmaak_f32 v44, v43, v44, 0x3f2aaada
	v_sub_f32_e32 v41, v37, v45
	v_ldexp_f32 v45, v42, 1
	v_mul_f32_e32 v42, v42, v43
	v_mul_f32_e32 v42, v42, v44
	v_add_f32_e32 v43, v45, v42
	v_sub_f32_e32 v44, v43, v45
	v_ldexp_f32 v36, v36, 1
	v_sub_f32_e32 v42, v42, v44
	v_add_f32_e32 v36, v36, v42
	v_add_f32_e32 v42, v43, v36
	v_sub_f32_e32 v43, v42, v43
	v_sub_f32_e32 v36, v36, v43
	v_add_f32_e32 v43, v37, v42
	v_sub_f32_e32 v44, v43, v37
	v_sub_f32_e32 v45, v43, v44
	v_sub_f32_e32 v41, v46, v41
	v_sub_f32_e32 v37, v37, v45
	v_sub_f32_e32 v42, v42, v44
	v_add_f32_e32 v37, v42, v37
	v_add_f32_e32 v42, v41, v36
	v_sub_f32_e32 v44, v42, v41
	v_sub_f32_e32 v45, v42, v44
	v_sub_f32_e32 v41, v41, v45
	v_sub_f32_e32 v36, v36, v44
	v_add_f32_e32 v37, v42, v37
	v_add_f32_e32 v36, v36, v41
	v_add_f32_e32 v41, v43, v37
	v_sub_f32_e32 v42, v41, v43
	v_sub_f32_e32 v37, v37, v42
	v_add_f32_e32 v36, v36, v37
	v_add_f32_e32 v36, v41, v36
	v_cndmask_b32_e32 v36, v102, v36, vcc
	v_cmp_lt_f32_e64 vcc, |v40|, s53
	s_nop 1
	v_cndmask_b32_e32 v36, v36, v40, vcc
	v_fmac_f32_e32 v39, 0x3fb8aa3b, v36
	v_add_f32_e32 v36, v38, v39
	ds_bpermute_b32 v37, v106, v36
	v_sub_f32_e32 v35, v35, v39
	s_waitcnt lgkmcnt(0)
	v_add_f32_e32 v37, v36, v37
	v_cndmask_b32_e64 v37, v37, v36, s[8:9]
	ds_bpermute_b32 v40, v107, v37
	s_waitcnt lgkmcnt(0)
	v_add_f32_e32 v40, v37, v40
	v_cndmask_b32_e64 v37, v37, v40, s[10:11]
	ds_bpermute_b32 v40, v108, v37
	s_waitcnt lgkmcnt(0)
	v_add_f32_e32 v40, v37, v40
	v_cndmask_b32_e64 v37, v37, v40, s[12:13]
	ds_bpermute_b32 v40, v109, v37
	s_waitcnt lgkmcnt(0)
	v_add_f32_e32 v40, v37, v40
	v_cndmask_b32_e64 v37, v37, v40, s[14:15]
	ds_bpermute_b32 v40, v110, v37
	s_waitcnt lgkmcnt(0)
	v_add_f32_e32 v40, v37, v40
	v_cndmask_b32_e64 v37, v37, v40, s[16:17]
	ds_bpermute_b32 v40, v111, v37
	s_waitcnt lgkmcnt(0)
	v_add_f32_e32 v40, v37, v40
	v_cndmask_b32_e64 v44, v37, v40, s[18:19]
	v_sub_f32_e32 v36, v44, v36
	v_add_f32_e32 v37, v39, v36
	v_sub_f32_e32 v34, v34, v37
	v_cmp_gt_f32_e32 vcc, s54, v34
	v_sub_f32_e32 v35, v35, v36
	s_nop 0
	v_cndmask_b32_e32 v37, 0, v101, vcc
	v_add_f32_e32 v34, v34, v37
	v_cndmask_b32_e32 v37, 0, v100, vcc
	v_cmp_gt_f32_e32 vcc, s54, v35
	v_exp_f32_e32 v34, v34
	s_nop 0
	v_cndmask_b32_e32 v36, 0, v101, vcc
	v_add_f32_e32 v35, v35, v36
	v_exp_f32_e32 v35, v35
	v_cndmask_b32_e32 v36, 0, v100, vcc
	v_ldexp_f32 v34, v34, v37
	v_ldexp_f32 v35, v35, v36
	ds_write_b64 v97, v[34:35] offset:512
	s_waitcnt lgkmcnt(0)
	ds_read2_b32 v[34:35], v96 offset0:128 offset1:132
	ds_read2_b32 v[42:43], v96 offset0:136 offset1:140
	ds_read2_b32 v[66:67], v96 offset0:144 offset1:148
	ds_read2_b32 v[68:69], v96 offset0:152 offset1:156
	ds_read2_b32 v[74:75], v96 offset0:160 offset1:164
	ds_read2_b32 v[76:77], v96 offset0:168 offset1:172
	ds_read2_b32 v[38:39], v96 offset0:176 offset1:180
	ds_read2_b32 v[40:41], v96 offset0:184 offset1:188
	s_waitcnt vmcnt(7) lgkmcnt(7)
	v_pk_fma_f32 v[70:71], v[30:31], v[34:35], 0 op_sel_hi:[1,0,0]
	v_add_co_u32_e32 v30, vcc, s55, v54
	v_pk_fma_f32 v[72:73], v[32:33], v[34:35], 0 op_sel_hi:[1,0,0]
	s_nop 0
	v_addc_co_u32_e32 v31, vcc, 0, v55, vcc
	v_add_co_u32_e32 v34, vcc, s83, v54
	v_mov_b32_e32 v64, v35
	s_nop 0
	v_addc_co_u32_e32 v35, vcc, 0, v55, vcc
	v_add_co_u32_e32 v46, vcc, s86, v54
	s_waitcnt vmcnt(6)
	v_pk_fma_f32 v[2:3], v[2:3], v[64:65], v[70:71] op_sel_hi:[1,0,1]
	v_addc_co_u32_e32 v47, vcc, 0, v55, vcc
	v_add_co_u32_e32 v50, vcc, s87, v54
	global_load_dwordx4 v[46:49], v[46:47], off nt
	s_nop 0
	v_addc_co_u32_e32 v51, vcc, 0, v55, vcc
	v_add_co_u32_e32 v56, vcc, s88, v54
	global_load_dwordx4 v[50:53], v[50:51], off offset:2048 nt
	s_nop 0
	v_addc_co_u32_e32 v57, vcc, 0, v55, vcc
	v_add_co_u32_e32 v60, vcc, s89, v54
	global_load_dwordx4 v[56:59], v[56:57], off nt
	s_nop 0
	v_addc_co_u32_e32 v61, vcc, 0, v55, vcc
	global_load_dwordx4 v[60:63], v[60:61], off offset:2048 nt
	s_waitcnt lgkmcnt(6)
	v_mov_b32_e32 v78, v43
	s_waitcnt vmcnt(9)
	v_pk_fma_f32 v[2:3], v[6:7], v[42:43], v[2:3] op_sel_hi:[1,0,1]
	s_waitcnt lgkmcnt(5)
	v_mov_b32_e32 v80, v67
	s_waitcnt vmcnt(7)
	v_pk_fma_f32 v[2:3], v[14:15], v[78:79], v[2:3] op_sel_hi:[1,0,1]
	s_waitcnt lgkmcnt(4)
	v_mov_b32_e32 v92, v69
	v_pk_fma_f32 v[2:3], v[10:11], v[66:67], v[2:3] op_sel_hi:[1,0,1]
	s_waitcnt lgkmcnt(3)
	v_mov_b32_e32 v10, v75
	s_waitcnt vmcnt(6)
	v_pk_fma_f32 v[2:3], v[18:19], v[80:81], v[2:3] op_sel_hi:[1,0,1]
	s_waitcnt lgkmcnt(2)
	v_mov_b32_e32 v14, v77
	s_waitcnt vmcnt(5)
	v_pk_fma_f32 v[2:3], v[22:23], v[68:69], v[2:3] op_sel_hi:[1,0,1]
	global_load_dwordx4 v[30:33], v[30:31], off nt
	s_waitcnt vmcnt(5)
	v_pk_fma_f32 v[2:3], v[26:27], v[92:93], v[2:3] op_sel_hi:[1,0,1]
	global_load_dwordx4 v[34:37], v[34:35], off offset:2048 nt
	s_waitcnt vmcnt(5)
	v_pk_fma_f32 v[2:3], v[46:47], v[74:75], v[2:3] op_sel_hi:[1,0,1]
	s_waitcnt vmcnt(4)
	v_pk_fma_f32 v[2:3], v[50:51], v[10:11], v[2:3] op_sel_hi:[1,0,1]
	s_waitcnt vmcnt(3)
	v_pk_fma_f32 v[2:3], v[56:57], v[76:77], v[2:3] op_sel_hi:[1,0,1]
	s_waitcnt vmcnt(2)
	v_pk_fma_f32 v[6:7], v[60:61], v[14:15], v[2:3] op_sel_hi:[1,0,1]
	v_pk_fma_f32 v[2:3], v[4:5], v[64:65], v[72:73] op_sel_hi:[1,0,1]
	v_add_co_u32_e32 v4, vcc, s90, v54
	v_pk_fma_f32 v[2:3], v[8:9], v[42:43], v[2:3] op_sel_hi:[1,0,1]
	s_nop 0
	v_addc_co_u32_e32 v5, vcc, 0, v55, vcc
	v_pk_fma_f32 v[2:3], v[16:17], v[78:79], v[2:3] op_sel_hi:[1,0,1]
	s_waitcnt lgkmcnt(0)
; template <int NB>
; __device__ __forceinline__ void sb_decode_task(const Params& P, float* lds, int task) {
;     ...
;     for (int vb = 0; vb < NBT; ++vb) {
;         if (vb + 1 < NBT) {
; #pragma unroll
;             for (int i = 0; i < NB; ++i) nx[i] = *(const float4*)(Vp + (size_t)(4 * NB * (vb + 1) + 4 * i + g) * (SH * HD)); }
; #pragma unroll
;         for (int i = 0; i < NB; ++i) { const float w = wl[4 * NB * vb + 4 * i + g]; o4.x += w * cur[i].x; o4.y += w * cur[i].y; o4.z += w * cur[i].z; o4.w += w * cur[i].w; }
; #pragma unroll
;         for (int i = 0; i < NB; ++i) cur[i] = nx[i];
	v_mov_b32_e32 v42, v41
	v_pk_fma_f32 v[2:3], v[12:13], v[66:67], v[2:3] op_sel_hi:[1,0,1]
	s_waitcnt vmcnt(1)
	v_pk_fma_f32 v[6:7], v[30:31], v[38:39], v[6:7] op_sel_hi:[1,0,1]
	v_pk_fma_f32 v[2:3], v[20:21], v[80:81], v[2:3] op_sel_hi:[1,0,1]
	s_nop 0
	v_pk_fma_f32 v[2:3], v[24:25], v[68:69], v[2:3] op_sel_hi:[1,0,1]
	s_nop 0
	v_pk_fma_f32 v[2:3], v[28:29], v[92:93], v[2:3] op_sel_hi:[1,0,1]
	v_mov_b32_e32 v28, v39
	v_pk_fma_f32 v[2:3], v[48:49], v[74:75], v[2:3] op_sel_hi:[1,0,1]
	s_waitcnt vmcnt(0)
	v_pk_fma_f32 v[6:7], v[34:35], v[28:29], v[6:7] op_sel_hi:[1,0,1]
	v_pk_fma_f32 v[2:3], v[52:53], v[10:11], v[2:3] op_sel_hi:[1,0,1]
	s_nop 0
	v_pk_fma_f32 v[2:3], v[58:59], v[76:77], v[2:3] op_sel_hi:[1,0,1]
	s_nop 0
	v_pk_fma_f32 v[2:3], v[62:63], v[14:15], v[2:3] op_sel_hi:[1,0,1]
	ds_read2_b32 v[14:15], v96 offset0:192 offset1:196
	ds_read2_b32 v[12:13], v96 offset0:200 offset1:204
	ds_read2_b32 v[10:11], v96 offset0:208 offset1:212
	ds_read2_b32 v[8:9], v96 offset0:216 offset1:220
	global_load_dwordx4 v[16:19], v[4:5], off nt
	v_add_co_u32_e32 v4, vcc, s91, v54
	v_pk_fma_f32 v[2:3], v[32:33], v[38:39], v[2:3] op_sel_hi:[1,0,1]
	s_nop 0
	v_addc_co_u32_e32 v5, vcc, 0, v55, vcc
	global_load_dwordx4 v[20:23], v[4:5], off offset:2048 nt
	v_add_co_u32_e32 v4, vcc, s92, v54
	v_pk_fma_f32 v[2:3], v[36:37], v[28:29], v[2:3] op_sel_hi:[1,0,1]
	s_nop 0
	v_addc_co_u32_e32 v5, vcc, 0, v55, vcc
	global_load_dwordx4 v[24:27], v[4:5], off nt
	v_add_co_u32_e32 v4, vcc, s93, v54
	s_waitcnt lgkmcnt(0)
	v_mov_b32_e32 v36, v9
	v_addc_co_u32_e32 v5, vcc, 0, v55, vcc
	global_load_dwordx4 v[46:49], v[4:5], off offset:2048 nt
	v_add_co_u32_e32 v4, vcc, s94, v54
	ds_read2_b32 v[30:31], v96 offset0:224 offset1:228
	s_nop 0
	v_addc_co_u32_e32 v5, vcc, 0, v55, vcc
	global_load_dwordx4 v[50:53], v[4:5], off nt
	v_add_co_u32_e32 v4, vcc, s95, v54
	s_waitcnt vmcnt(4)
	v_pk_fma_f32 v[2:3], v[18:19], v[40:41], v[2:3] op_sel_hi:[1,0,1]
	v_addc_co_u32_e32 v5, vcc, 0, v55, vcc
	global_load_dwordx4 v[56:59], v[4:5], off offset:2048 nt
	v_add_co_u32_e32 v4, vcc, s96, v54
	s_waitcnt vmcnt(4)
	v_pk_fma_f32 v[2:3], v[22:23], v[42:43], v[2:3] op_sel_hi:[1,0,1]
	v_addc_co_u32_e32 v5, vcc, 0, v55, vcc
	global_load_dwordx4 v[60:63], v[4:5], off nt
	v_add_co_u32_e32 v4, vcc, s97, v54
	s_waitcnt vmcnt(4)
	v_pk_fma_f32 v[2:3], v[26:27], v[14:15], v[2:3] op_sel_hi:[1,0,1]
	v_addc_co_u32_e32 v5, vcc, 0, v55, vcc
	global_load_dwordx4 v[64:67], v[4:5], off offset:2048 nt
	v_add_co_u32_e32 v4, vcc, s22, v54
	v_mov_b32_e32 v18, v15
	s_nop 0
	v_addc_co_u32_e32 v5, vcc, 0, v55, vcc
	global_load_dwordx4 v[68:71], v[4:5], off nt
	v_pk_fma_f32 v[6:7], v[16:17], v[40:41], v[6:7] op_sel_hi:[1,0,1]
	s_waitcnt vmcnt(5)
	v_pk_fma_f32 v[2:3], v[48:49], v[18:19], v[2:3] op_sel_hi:[1,0,1]
	v_pk_fma_f32 v[6:7], v[20:21], v[42:43], v[6:7] op_sel_hi:[1,0,1]
	s_waitcnt vmcnt(4)
	v_pk_fma_f32 v[2:3], v[52:53], v[12:13], v[2:3] op_sel_hi:[1,0,1]
	v_mov_b32_e32 v22, v13
	v_pk_fma_f32 v[6:7], v[24:25], v[14:15], v[6:7] op_sel_hi:[1,0,1]
	v_mov_b32_e32 v26, v11
	v_pk_fma_f32 v[6:7], v[46:47], v[18:19], v[6:7] op_sel_hi:[1,0,1]
	s_waitcnt vmcnt(3)
	v_pk_fma_f32 v[2:3], v[58:59], v[22:23], v[2:3] op_sel_hi:[1,0,1]
	v_pk_fma_f32 v[6:7], v[50:51], v[12:13], v[6:7] op_sel_hi:[1,0,1]
	s_waitcnt vmcnt(2)
	v_pk_fma_f32 v[2:3], v[62:63], v[10:11], v[2:3] op_sel_hi:[1,0,1]
	v_pk_fma_f32 v[6:7], v[56:57], v[22:23], v[6:7] op_sel_hi:[1,0,1]
	s_waitcnt vmcnt(1)
	v_pk_fma_f32 v[2:3], v[66:67], v[26:27], v[2:3] op_sel_hi:[1,0,1]
	v_pk_fma_f32 v[6:7], v[60:61], v[10:11], v[6:7] op_sel_hi:[1,0,1]
	s_waitcnt vmcnt(0)
; template <int NB>
; __device__ __forceinline__ void sb_decode_task(const Params& P, float* lds, int task) {
;     ...
;     for (int vb = 0; vb < NBT; ++vb) {
;         if (vb + 1 < NBT) {
; #pragma unroll
;             for (int i = 0; i < NB; ++i) nx[i] = *(const float4*)(Vp + (size_t)(4 * NB * (vb + 1) + 4 * i + g) * (SH * HD)); }
; #pragma unroll
;         for (int i = 0; i < NB; ++i) { const float w = wl[4 * NB * vb + 4 * i + g]; o4.x += w * cur[i].x; o4.y += w * cur[i].y; o4.z += w * cur[i].z; o4.w += w * cur[i].w; }
; #pragma unroll
;         for (int i = 0; i < NB; ++i) cur[i] = nx[i];
;     }
; #pragma unroll
;     for (int off = 16; off < 64; off <<= 1) { o4.x += __shfl_xor(o4.x, off); o4.y += __shfl_xor(o4.y, off); o4.z += __shfl_xor(o4.z, off); o4.w += __shfl_xor(o4.w, off); }
;     if (g == 0) *(float4*)(dpart + (size_t)task * HD + 4 * c) = o4;
	v_pk_fma_f32 v[32:33], v[70:71], v[8:9], v[2:3] op_sel_hi:[1,0,1]
	v_add_co_u32_e32 v2, vcc, s23, v54
	v_pk_fma_f32 v[6:7], v[64:65], v[26:27], v[6:7] op_sel_hi:[1,0,1]
	s_nop 0
	v_addc_co_u32_e32 v3, vcc, 0, v55, vcc
	v_pk_fma_f32 v[34:35], v[68:69], v[8:9], v[6:7] op_sel_hi:[1,0,1]
	v_add_co_u32_e32 v6, vcc, s24, v54
	global_load_dwordx4 v[2:5], v[2:3], off offset:2048 nt
	s_nop 0
	v_addc_co_u32_e32 v7, vcc, 0, v55, vcc
	v_add_co_u32_e32 v10, vcc, s72, v54
	global_load_dwordx4 v[6:9], v[6:7], off nt
	s_nop 0
	v_addc_co_u32_e32 v11, vcc, 0, v55, vcc
	v_add_co_u32_e32 v14, vcc, s73, v54
	ds_read2_b32 v[42:43], v96 offset0:232 offset1:236
	ds_read2_b32 v[40:41], v96 offset0:240 offset1:244
	ds_read2_b32 v[38:39], v96 offset0:248 offset1:252
	v_addc_co_u32_e32 v15, vcc, 0, v55, vcc
	v_add_co_u32_e32 v18, vcc, s74, v54
	global_load_dwordx4 v[10:13], v[10:11], off offset:2048 nt
	s_nop 0
	v_addc_co_u32_e32 v19, vcc, 0, v55, vcc
	v_add_co_u32_e32 v22, vcc, s75, v54
	global_load_dwordx4 v[14:17], v[14:15], off nt
	s_nop 0
	v_addc_co_u32_e32 v23, vcc, 0, v55, vcc
	v_add_co_u32_e32 v26, vcc, s80, v54
	global_load_dwordx4 v[18:21], v[18:19], off offset:2048 nt
	s_nop 0
	v_addc_co_u32_e32 v27, vcc, 0, v55, vcc
	v_add_co_u32_e32 v46, vcc, s81, v54
	global_load_dwordx4 v[22:25], v[22:23], off nt
	s_nop 0
	v_addc_co_u32_e32 v47, vcc, 0, v55, vcc
	global_load_dwordx4 v[26:29], v[26:27], off offset:2048 nt
	v_add_co_u32_e32 v50, vcc, s82, v54
	global_load_dwordx4 v[46:49], v[46:47], off nt
	s_nop 0
	v_addc_co_u32_e32 v51, vcc, 0, v55, vcc
	global_load_dwordx4 v[50:53], v[50:51], off offset:2048 nt
	s_waitcnt lgkmcnt(2)
	v_mov_b32_e32 v54, v43
	s_waitcnt lgkmcnt(1)
	v_mov_b32_e32 v56, v41
	s_waitcnt lgkmcnt(0)
	v_mov_b32_e32 v58, v39
	s_waitcnt vmcnt(8)
	v_pk_fma_f32 v[2:3], v[2:3], v[36:37], v[34:35] op_sel_hi:[1,0,1]
	v_mov_b32_e32 v34, v31
	v_pk_fma_f32 v[4:5], v[4:5], v[36:37], v[32:33] op_sel_hi:[1,0,1]
	s_waitcnt vmcnt(7)
	v_pk_fma_f32 v[2:3], v[6:7], v[30:31], v[2:3] op_sel_hi:[1,0,1]
	v_pk_fma_f32 v[4:5], v[8:9], v[30:31], v[4:5] op_sel_hi:[1,0,1]
	s_waitcnt vmcnt(6)
	v_pk_fma_f32 v[2:3], v[10:11], v[34:35], v[2:3] op_sel_hi:[1,0,1]
	v_pk_fma_f32 v[4:5], v[12:13], v[34:35], v[4:5] op_sel_hi:[1,0,1]
	ds_bpermute_b32 v10, v104, v44
	s_waitcnt vmcnt(5)
	v_pk_fma_f32 v[2:3], v[14:15], v[42:43], v[2:3] op_sel_hi:[1,0,1]
	v_pk_fma_f32 v[4:5], v[16:17], v[42:43], v[4:5] op_sel_hi:[1,0,1]
	s_waitcnt vmcnt(4)
	v_pk_fma_f32 v[2:3], v[18:19], v[54:55], v[2:3] op_sel_hi:[1,0,1]
	v_pk_fma_f32 v[4:5], v[20:21], v[54:55], v[4:5] op_sel_hi:[1,0,1]
	s_waitcnt vmcnt(3)
	v_pk_fma_f32 v[2:3], v[22:23], v[40:41], v[2:3] op_sel_hi:[1,0,1]
	v_pk_fma_f32 v[4:5], v[24:25], v[40:41], v[4:5] op_sel_hi:[1,0,1]
	s_waitcnt vmcnt(2)
	v_pk_fma_f32 v[2:3], v[26:27], v[56:57], v[2:3] op_sel_hi:[1,0,1]
	v_pk_fma_f32 v[4:5], v[28:29], v[56:57], v[4:5] op_sel_hi:[1,0,1]
	s_waitcnt vmcnt(1)
	v_pk_fma_f32 v[2:3], v[46:47], v[38:39], v[2:3] op_sel_hi:[1,0,1]
	v_pk_fma_f32 v[4:5], v[48:49], v[38:39], v[4:5] op_sel_hi:[1,0,1]
	s_waitcnt vmcnt(0)
	v_pk_fma_f32 v[2:3], v[50:51], v[58:59], v[2:3] op_sel_hi:[1,0,1]
	ds_bpermute_b32 v6, v105, v2
	ds_bpermute_b32 v7, v105, v3
	v_pk_fma_f32 v[4:5], v[52:53], v[58:59], v[4:5] op_sel_hi:[1,0,1]
	s_waitcnt lgkmcnt(0)
	v_pk_add_f32 v[2:3], v[2:3], v[6:7]
	ds_bpermute_b32 v6, v105, v4
	ds_bpermute_b32 v7, v105, v5
	s_waitcnt lgkmcnt(0)
	v_pk_add_f32 v[4:5], v[4:5], v[6:7]
	ds_bpermute_b32 v6, v112, v2
	ds_bpermute_b32 v7, v112, v3
	ds_bpermute_b32 v8, v112, v4
	ds_bpermute_b32 v9, v112, v5
	s_and_saveexec_b64 s[0:1], s[20:21]
	s_cbranch_execz .LBB0_1090
	s_ashr_i32 s35, s34, 31
	s_lshl_b64 s[2:3], s[34:35], 8
	v_lshl_add_u64 v[12:13], v[88:89], 0, s[2:3]
	s_waitcnt lgkmcnt(2)
	v_pk_add_f32 v[2:3], v[2:3], v[6:7]
	s_waitcnt lgkmcnt(0)
	v_pk_add_f32 v[4:5], v[4:5], v[8:9]
	global_store_dwordx4 v[12:13], v[2:5], off

; __device__ __forceinline__ float bf2f(bf16_t b) { return __uint_as_float(((unsigned)b) << 16); }
; template <int NB>
; __device__ __forceinline__ void sb_decode_task(const Params& P, float* lds, int task) {
;     ...
;     constexpr int NBT = 32 / NB;
;     const int h = task % SH, bj = task / SH, b = bj / NPAGES;
;     const int page = P.page_table[bj];
;     const float* Kp = P.cache_k + ((size_t)page * PAGE * SH + h) * HD + 4 * c;
;     const float* Vp = P.cache_v + ((size_t)page * PAGE * SH + h) * HD + 4 * c;
;     const bf16_t* qp = qb + (size_t)(NTOK + b) * SBW + h * 64 + 4 * c;
;     const float q0 = bf2f(qp[0]), q1 = bf2f(qp[1]), q2 = bf2f(qp[2]), q3 = bf2f(qp[3]);
;     const float bias = P.sb_bias[h] * LOG2E;
;     float4 cur[NB], nx[NB];
; #pragma unroll
;     for (int i = 0; i < NB; ++i) cur[i] = *(const float4*)(Kp + (size_t)(4 * i + g) * (SH * HD));
; #pragma unroll
;     for (int kb = 0; kb < NBT; ++kb) {
;         const float* np = (kb + 1 < NBT) ? Kp + (size_t)(4 * NB * (kb + 1)) * (SH * HD) : Vp;
; #pragma unroll
;         for (int i = 0; i < NB; ++i) nx[i] = *(const float4*)(np + (size_t)(4 * i + g) * (SH * HD));
; #pragma unroll
;         for (int i = 0; i < NB; ++i) { const int s = 4 * NB * kb + 4 * i + g;
;             float part = q0 * cur[i].x + q1 * cur[i].y + q2 * cur[i].z + q3 * cur[i].w; part = sum16(part);
;             if (c == 0) zl[s] = part + bias; }
.LBB0_1281:
	v_readlane_b32 s90, v252, 48
	s_lshr_b32 s1, s2, 31
	v_readlane_b32 s91, v252, 49
	s_add_i32 s0, s2, s1
	s_load_dwordx16 s[52:67], s[90:91], 0x0
	s_mul_i32 s3, s0, 6
	s_sub_i32 s36, s34, s3
	s_ashr_i32 s3, s2, 7
	s_add_i32 s3, s3, s1
	s_ashr_i32 s1, s0, 31
	s_lshl_b64 s[0:1], s[0:1], 2
	s_waitcnt lgkmcnt(0)
	s_add_u32 s0, s62, s0
	s_addc_u32 s1, s63, s1
	global_load_dword v2, v83, s[0:1]
	s_add_i32 s0, s3, 0x4000
	s_ashr_i32 s37, s36, 31
	s_mul_hi_i32 s1, s0, 0x300
	s_mulk_i32 s0, 0x300
	s_add_u32 s3, s38, s0
	s_addc_u32 s33, s39, s1
	s_lshl_b32 s0, s36, 6
	s_ashr_i32 s1, s0, 31
	s_lshl_b64 s[0:1], s[0:1], 1
	s_add_u32 s0, s3, s0
	s_addc_u32 s1, s33, s1
	v_readlane_b32 s52, v252, 16
	v_readlane_b32 s53, v252, 17
	v_readlane_b32 s60, v252, 24
	v_readlane_b32 s61, v252, 25
	s_mov_b64 s[52:53], s[60:61]
	v_mov_b32_e32 v93, v83
	v_readlane_b32 s54, v252, 18
	v_readlane_b32 s55, v252, 19
	v_readlane_b32 s56, v252, 20
	v_readlane_b32 s57, v252, 21
	v_readlane_b32 s58, v252, 22
	v_readlane_b32 s59, v252, 23
	v_readlane_b32 s62, v252, 26
	v_readlane_b32 s63, v252, 27
	v_readlane_b32 s64, v252, 28
	v_readlane_b32 s65, v252, 29
	v_readlane_b32 s66, v252, 30
	v_readlane_b32 s67, v252, 31
	s_waitcnt vmcnt(0)
	v_mov_b32_e32 v253, v2
	v_mul_hi_i32 v3, v2, s48
	v_mul_lo_u32 v2, v2, s48
	v_lshl_add_u64 v[94:95], v[2:3], 0, s[36:37]
	v_lshlrev_b64 v[2:3], 8, v[94:95]
	v_lshl_add_u64 v[70:71], v[84:85], 0, v[2:3]
	global_load_dwordx2 v[2:3], v101, s[0:1]
	s_lshl_b64 s[0:1], s[36:37], 2
	s_add_u32 s0, s52, s0
	s_addc_u32 s1, s53, s1
	global_load_dword v22, v83, s[0:1]
	v_lshl_add_u64 v[14:15], v[70:71], 0, v[82:83]
	v_lshl_add_u64 v[16:17], v[70:71], 0, v[92:93]
	global_load_dwordx4 v[18:21], v[14:15], off nt
	s_mov_b64 s[0:1], 0xc000
	global_load_dwordx4 v[62:65], v[16:17], off nt
	s_waitcnt vmcnt(3)
	v_lshlrev_b32_e32 v107, 16, v2
	v_and_b32_e32 v109, 0xffff0000, v2
	v_add_co_u32_e32 v2, vcc, s50, v14
	v_lshlrev_b32_e32 v108, 16, v3
	v_and_b32_e32 v106, 0xffff0000, v3
	v_addc_co_u32_e32 v3, vcc, 0, v15, vcc
	global_load_dwordx4 v[10:13], v[2:3], off offset:2048 nt
	v_add_co_u32_e32 v2, vcc, s51, v14
	s_waitcnt vmcnt(3)
	v_mul_f32_e32 v110, 0x3fb8aa3b, v22
	v_addc_co_u32_e32 v3, vcc, 0, v15, vcc
	global_load_dwordx4 v[6:9], v[2:3], off nt
	v_add_co_u32_e32 v2, vcc, s49, v14
	v_lshl_add_u64 v[22:23], v[70:71], 0, s[0:1]
	s_nop 0
	v_addc_co_u32_e32 v3, vcc, 0, v15, vcc
	v_add_co_u32_e32 v16, vcc, s92, v14
	v_lshl_add_u64 v[30:31], v[22:23], 0, v[82:83]
	s_nop 0
	v_addc_co_u32_e32 v17, vcc, 0, v15, vcc
	global_load_dwordx4 v[58:61], v[16:17], off offset:2048 nt
	v_add_co_u32_e32 v16, vcc, s93, v14
	v_lshl_add_u64 v[22:23], v[22:23], 0, v[92:93]
	s_nop 0
	v_addc_co_u32_e32 v17, vcc, 0, v15, vcc
	v_add_co_u32_e32 v14, vcc, s96, v14
	global_load_dwordx4 v[54:57], v[16:17], off nt
	s_nop 0
	v_addc_co_u32_e32 v15, vcc, 0, v15, vcc
	global_load_dwordx4 v[50:53], v[14:15], off offset:2048 nt
	v_add_co_u32_e32 v14, vcc, s50, v30
	global_load_dwordx4 v[22:25], v[22:23], off nt
	s_nop 0
	v_addc_co_u32_e32 v15, vcc, 0, v31, vcc
	global_load_dwordx4 v[34:37], v[14:15], off offset:2048 nt
	v_add_co_u32_e32 v14, vcc, s51, v30
	global_load_dwordx4 v[2:5], v[2:3], off offset:2048 nt
	s_nop 0
	v_addc_co_u32_e32 v15, vcc, 0, v31, vcc
	global_load_dwordx4 v[26:29], v[14:15], off nt
	v_add_co_u32_e32 v14, vcc, s49, v30
	global_load_dwordx4 v[46:49], v[30:31], off nt
	s_nop 0
	v_addc_co_u32_e32 v15, vcc, 0, v31, vcc
	v_add_co_u32_e32 v32, vcc, s92, v30
	global_load_dwordx4 v[14:17], v[14:15], off offset:2048 nt
	s_nop 0
	v_addc_co_u32_e32 v33, vcc, 0, v31, vcc
	global_load_dwordx4 v[38:41], v[32:33], off offset:2048 nt
	v_add_co_u32_e32 v32, vcc, s93, v30
	s_waitcnt vmcnt(13)
	v_mul_f32_e32 v19, v19, v109
	v_addc_co_u32_e32 v33, vcc, 0, v31, vcc
	v_add_co_u32_e32 v30, vcc, s96, v30
	global_load_dwordx4 v[42:45], v[32:33], off nt
	s_nop 0
	v_addc_co_u32_e32 v31, vcc, 0, v31, vcc
	global_load_dwordx4 v[30:33], v[30:31], off offset:2048 nt
	v_fmac_f32_e32 v19, v18, v107
	v_fmac_f32_e32 v19, v20, v108
	v_fmac_f32_e32 v19, v21, v106
	s_nop 1
	v_add_f32_dpp v18, v19, v19 quad_perm:[1,0,3,2] row_mask:0xf bank_mask:0xf bound_ctrl:1
	s_nop 1
	v_add_f32_dpp v18, v18, v18 quad_perm:[2,3,0,1] row_mask:0xf bank_mask:0xf bound_ctrl:1
	s_nop 1
	v_add_f32_dpp v18, v18, v18 row_ror:4 row_mask:0xf bank_mask:0xf bound_ctrl:1
	s_nop 1
	v_mov_b32_dpp v19, v18 row_ror:8 row_mask:0xf bank_mask:0xf bound_ctrl:1
	s_and_saveexec_b64 s[0:1], s[6:7]
	v_add_f32_e32 v18, v18, v19
	v_add_f32_e32 v18, v110, v18
	ds_write_b32 v99, v18
	s_or_b64 exec, exec, s[0:1]
	s_waitcnt vmcnt(13)
	v_mul_f32_e32 v11, v11, v109
	v_fmac_f32_e32 v11, v10, v107
	v_fmac_f32_e32 v11, v12, v108
	v_fmac_f32_e32 v11, v13, v106
	s_nop 1
	v_add_f32_dpp v10, v11, v11 quad_perm:[1,0,3,2] row_mask:0xf bank_mask:0xf bound_ctrl:1
	s_nop 1
	v_add_f32_dpp v10, v10, v10 quad_perm:[2,3,0,1] row_mask:0xf bank_mask:0xf bound_ctrl:1
	s_nop 1
	v_add_f32_dpp v10, v10, v10 row_ror:4 row_mask:0xf bank_mask:0xf bound_ctrl:1
	s_nop 1
	v_mov_b32_dpp v11, v10 row_ror:8 row_mask:0xf bank_mask:0xf bound_ctrl:1
	s_and_saveexec_b64 s[0:1], s[6:7]
	v_add_f32_e32 v10, v10, v11
	v_add_f32_e32 v10, v110, v10
	ds_write_b32 v99, v10 offset:16
	s_or_b64 exec, exec, s[0:1]
	s_waitcnt vmcnt(12)
	v_mul_f32_e32 v7, v7, v109
	v_fmac_f32_e32 v7, v6, v107
	v_fmac_f32_e32 v7, v8, v108
	v_fmac_f32_e32 v7, v9, v106
	s_nop 1
	v_add_f32_dpp v6, v7, v7 quad_perm:[1,0,3,2] row_mask:0xf bank_mask:0xf bound_ctrl:1
	s_nop 1
	v_add_f32_dpp v6, v6, v6 quad_perm:[2,3,0,1] row_mask:0xf bank_mask:0xf bound_ctrl:1
	s_nop 1
	v_add_f32_dpp v6, v6, v6 row_ror:4 row_mask:0xf bank_mask:0xf bound_ctrl:1
	s_nop 1
	v_mov_b32_dpp v7, v6 row_ror:8 row_mask:0xf bank_mask:0xf bound_ctrl:1
	s_and_saveexec_b64 s[0:1], s[6:7]
	v_add_f32_e32 v6, v6, v7
	v_add_f32_e32 v6, v110, v6
	ds_write_b32 v99, v6 offset:32
	s_or_b64 exec, exec, s[0:1]
	s_waitcnt vmcnt(6)
; template <int NB>
; __device__ __forceinline__ void sb_decode_task(const Params& P, float* lds, int task) {
;     ...
;     for (int kb = 0; kb < NBT; ++kb) {
;         const float* np = (kb + 1 < NBT) ? Kp + (size_t)(4 * NB * (kb + 1)) * (SH * HD) : Vp;
; #pragma unroll
;         for (int i = 0; i < NB; ++i) nx[i] = *(const float4*)(np + (size_t)(4 * i + g) * (SH * HD));
; #pragma unroll
;         for (int i = 0; i < NB; ++i) { const int s = 4 * NB * kb + 4 * i + g;
;             float part = q0 * cur[i].x + q1 * cur[i].y + q2 * cur[i].z + q3 * cur[i].w; part = sum16(part);
;             if (c == 0) zl[s] = part + bias; }
	v_mul_f32_e32 v3, v3, v109
	v_fmac_f32_e32 v3, v2, v107
	v_fmac_f32_e32 v3, v4, v108
	v_fmac_f32_e32 v3, v5, v106
	s_nop 1
	v_add_f32_dpp v2, v3, v3 quad_perm:[1,0,3,2] row_mask:0xf bank_mask:0xf bound_ctrl:1
	s_nop 1
	v_add_f32_dpp v2, v2, v2 quad_perm:[2,3,0,1] row_mask:0xf bank_mask:0xf bound_ctrl:1
	s_nop 1
	v_add_f32_dpp v2, v2, v2 row_ror:4 row_mask:0xf bank_mask:0xf bound_ctrl:1
	s_nop 1
	v_mov_b32_dpp v3, v2 row_ror:8 row_mask:0xf bank_mask:0xf bound_ctrl:1
	s_and_saveexec_b64 s[0:1], s[6:7]
	v_add_f32_e32 v2, v2, v3
	v_add_f32_e32 v2, v110, v2
	ds_write_b32 v99, v2 offset:48
	s_or_b64 exec, exec, s[0:1]
	v_mul_f32_e32 v2, v63, v109
	v_fmac_f32_e32 v2, v62, v107
	v_fmac_f32_e32 v2, v64, v108
	v_fmac_f32_e32 v2, v65, v106
	s_nop 1
	v_add_f32_dpp v2, v2, v2 quad_perm:[1,0,3,2] row_mask:0xf bank_mask:0xf bound_ctrl:1
	s_nop 1
	v_add_f32_dpp v2, v2, v2 quad_perm:[2,3,0,1] row_mask:0xf bank_mask:0xf bound_ctrl:1
	s_nop 1
	v_add_f32_dpp v2, v2, v2 row_ror:4 row_mask:0xf bank_mask:0xf bound_ctrl:1
	s_nop 1
	v_mov_b32_dpp v3, v2 row_ror:8 row_mask:0xf bank_mask:0xf bound_ctrl:1
	s_and_saveexec_b64 s[0:1], s[6:7]
	v_add_f32_e32 v2, v2, v3
	v_add_f32_e32 v2, v110, v2
	ds_write_b32 v99, v2 offset:64
	s_or_b64 exec, exec, s[0:1]
	v_mul_f32_e32 v2, v59, v109
	v_fmac_f32_e32 v2, v58, v107
	v_fmac_f32_e32 v2, v60, v108
	v_fmac_f32_e32 v2, v61, v106
	s_nop 1
	v_add_f32_dpp v2, v2, v2 quad_perm:[1,0,3,2] row_mask:0xf bank_mask:0xf bound_ctrl:1
	s_nop 1
	v_add_f32_dpp v2, v2, v2 quad_perm:[2,3,0,1] row_mask:0xf bank_mask:0xf bound_ctrl:1
	s_nop 1
	v_add_f32_dpp v2, v2, v2 row_ror:4 row_mask:0xf bank_mask:0xf bound_ctrl:1
	s_nop 1
	v_mov_b32_dpp v3, v2 row_ror:8 row_mask:0xf bank_mask:0xf bound_ctrl:1
	s_and_saveexec_b64 s[0:1], s[6:7]
	v_add_f32_e32 v2, v2, v3
	v_add_f32_e32 v2, v110, v2
	ds_write_b32 v99, v2 offset:80
	s_or_b64 exec, exec, s[0:1]
	v_mul_f32_e32 v2, v55, v109
	v_fmac_f32_e32 v2, v54, v107
	v_fmac_f32_e32 v2, v56, v108
	v_fmac_f32_e32 v2, v57, v106
	s_nop 1
	v_add_f32_dpp v2, v2, v2 quad_perm:[1,0,3,2] row_mask:0xf bank_mask:0xf bound_ctrl:1
	s_nop 1
	v_add_f32_dpp v2, v2, v2 quad_perm:[2,3,0,1] row_mask:0xf bank_mask:0xf bound_ctrl:1
	s_nop 1
	v_add_f32_dpp v2, v2, v2 row_ror:4 row_mask:0xf bank_mask:0xf bound_ctrl:1
	s_nop 1
	v_mov_b32_dpp v3, v2 row_ror:8 row_mask:0xf bank_mask:0xf bound_ctrl:1
	s_and_saveexec_b64 s[0:1], s[6:7]
	v_add_f32_e32 v2, v2, v3
	v_add_f32_e32 v2, v110, v2
	ds_write_b32 v99, v2 offset:96
	s_or_b64 exec, exec, s[0:1]
	v_mul_f32_e32 v2, v51, v109
	v_fmac_f32_e32 v2, v50, v107
	v_fmac_f32_e32 v2, v52, v108
	v_fmac_f32_e32 v2, v53, v106
	s_nop 1
	v_add_f32_dpp v2, v2, v2 quad_perm:[1,0,3,2] row_mask:0xf bank_mask:0xf bound_ctrl:1
	s_nop 1
	v_add_f32_dpp v2, v2, v2 quad_perm:[2,3,0,1] row_mask:0xf bank_mask:0xf bound_ctrl:1
	s_nop 1
	v_add_f32_dpp v2, v2, v2 row_ror:4 row_mask:0xf bank_mask:0xf bound_ctrl:1
	s_nop 1
	v_mov_b32_dpp v3, v2 row_ror:8 row_mask:0xf bank_mask:0xf bound_ctrl:1
	s_and_saveexec_b64 s[0:1], s[6:7]
	v_add_f32_e32 v2, v2, v3
	v_add_f32_e32 v2, v110, v2
	ds_write_b32 v99, v2 offset:112
	s_or_b64 exec, exec, s[0:1]
	s_mov_b64 s[0:1], 0x18000
	v_lshl_add_u64 v[2:3], v[70:71], 0, s[0:1]
	v_lshl_add_u64 v[4:5], v[2:3], 0, v[82:83]
	v_add_co_u32_e32 v6, vcc, 0x1000, v4
	v_mov_b32_e32 v93, v83
	s_nop 0
	v_addc_co_u32_e32 v7, vcc, 0, v5, vcc
	global_load_dwordx4 v[74:77], v[4:5], off nt
	global_load_dwordx4 v[66:69], v[6:7], off offset:2048 nt
	v_add_co_u32_e32 v6, vcc, 0x3000, v4
	v_lshl_add_u64 v[2:3], v[2:3], 0, v[92:93]
	s_nop 0
	v_addc_co_u32_e32 v7, vcc, 0, v5, vcc
	v_add_co_u32_e32 v8, vcc, s49, v4
	s_waitcnt vmcnt(6)
	v_mul_f32_e32 v47, v47, v109
	v_addc_co_u32_e32 v9, vcc, 0, v5, vcc
	global_load_dwordx4 v[58:61], v[6:7], off nt
	global_load_dwordx4 v[50:53], v[8:9], off offset:2048 nt
	v_add_co_u32_e32 v6, vcc, 0x7000, v4
	v_fmac_f32_e32 v47, v46, v107
	s_nop 0
	v_addc_co_u32_e32 v7, vcc, 0, v5, vcc
	global_load_dwordx4 v[18:21], v[2:3], off nt
	global_load_dwordx4 v[10:13], v[6:7], off offset:2048 nt
	v_add_co_u32_e32 v2, vcc, 0x9000, v4
	v_fmac_f32_e32 v47, v48, v108
	s_nop 0
	v_addc_co_u32_e32 v3, vcc, 0, v5, vcc
	v_add_co_u32_e32 v4, vcc, 0xa000, v4
	v_fmac_f32_e32 v47, v49, v106
	s_nop 0
	v_addc_co_u32_e32 v5, vcc, 0, v5, vcc
	global_load_dwordx4 v[6:9], v[2:3], off nt
	s_nop 0
	global_load_dwordx4 v[2:5], v[4:5], off offset:2048 nt
	v_add_f32_dpp v46, v47, v47 quad_perm:[1,0,3,2] row_mask:0xf bank_mask:0xf bound_ctrl:1
	s_nop 1
	v_add_f32_dpp v46, v46, v46 quad_perm:[2,3,0,1] row_mask:0xf bank_mask:0xf bound_ctrl:1
	s_nop 1
	v_add_f32_dpp v46, v46, v46 row_ror:4 row_mask:0xf bank_mask:0xf bound_ctrl:1
	s_nop 1
	v_mov_b32_dpp v47, v46 row_ror:8 row_mask:0xf bank_mask:0xf bound_ctrl:1
	s_and_saveexec_b64 s[0:1], s[6:7]
	v_add_f32_e32 v46, v46, v47
	v_add_f32_e32 v46, v110, v46
	ds_write_b32 v99, v46 offset:128
	s_or_b64 exec, exec, s[0:1]
	v_mul_f32_e32 v35, v35, v109
	v_fmac_f32_e32 v35, v34, v107
	v_fmac_f32_e32 v35, v36, v108
	v_fmac_f32_e32 v35, v37, v106
	s_nop 1
	v_add_f32_dpp v34, v35, v35 quad_perm:[1,0,3,2] row_mask:0xf bank_mask:0xf bound_ctrl:1
	s_nop 1
	v_add_f32_dpp v34, v34, v34 quad_perm:[2,3,0,1] row_mask:0xf bank_mask:0xf bound_ctrl:1
	s_nop 1
	v_add_f32_dpp v34, v34, v34 row_ror:4 row_mask:0xf bank_mask:0xf bound_ctrl:1
	s_nop 1
	v_mov_b32_dpp v35, v34 row_ror:8 row_mask:0xf bank_mask:0xf bound_ctrl:1
	s_and_saveexec_b64 s[0:1], s[6:7]
	v_add_f32_e32 v34, v34, v35
	v_add_f32_e32 v34, v110, v34
	ds_write_b32 v99, v34 offset:144
	s_or_b64 exec, exec, s[0:1]
	v_mul_f32_e32 v27, v27, v109
	v_fmac_f32_e32 v27, v26, v107
	v_fmac_f32_e32 v27, v28, v108
	v_fmac_f32_e32 v27, v29, v106
	s_nop 1
	v_add_f32_dpp v26, v27, v27 quad_perm:[1,0,3,2] row_mask:0xf bank_mask:0xf bound_ctrl:1
	s_nop 1
	v_add_f32_dpp v26, v26, v26 quad_perm:[2,3,0,1] row_mask:0xf bank_mask:0xf bound_ctrl:1
	s_nop 1
	v_add_f32_dpp v26, v26, v26 row_ror:4 row_mask:0xf bank_mask:0xf bound_ctrl:1
	s_nop 1
	v_mov_b32_dpp v27, v26 row_ror:8 row_mask:0xf bank_mask:0xf bound_ctrl:1
	s_and_saveexec_b64 s[0:1], s[6:7]
	v_add_f32_e32 v26, v26, v27
	v_add_f32_e32 v26, v110, v26
	ds_write_b32 v99, v26 offset:160
	s_or_b64 exec, exec, s[0:1]
	s_waitcnt vmcnt(11)
; template <int NB>
; __device__ __forceinline__ void sb_decode_task(const Params& P, float* lds, int task) {
;     ...
;     for (int kb = 0; kb < NBT; ++kb) {
;         const float* np = (kb + 1 < NBT) ? Kp + (size_t)(4 * NB * (kb + 1)) * (SH * HD) : Vp;
; #pragma unroll
;         for (int i = 0; i < NB; ++i) nx[i] = *(const float4*)(np + (size_t)(4 * i + g) * (SH * HD));
; #pragma unroll
;         for (int i = 0; i < NB; ++i) { const int s = 4 * NB * kb + 4 * i + g;
;             float part = q0 * cur[i].x + q1 * cur[i].y + q2 * cur[i].z + q3 * cur[i].w; part = sum16(part);
;             if (c == 0) zl[s] = part + bias; }
	v_mul_f32_e32 v15, v15, v109
	v_fmac_f32_e32 v15, v14, v107
	v_fmac_f32_e32 v15, v16, v108
	v_fmac_f32_e32 v15, v17, v106
	s_nop 1
	v_add_f32_dpp v14, v15, v15 quad_perm:[1,0,3,2] row_mask:0xf bank_mask:0xf bound_ctrl:1
	s_nop 1
	v_add_f32_dpp v14, v14, v14 quad_perm:[2,3,0,1] row_mask:0xf bank_mask:0xf bound_ctrl:1
	s_nop 1
	v_add_f32_dpp v14, v14, v14 row_ror:4 row_mask:0xf bank_mask:0xf bound_ctrl:1
	s_nop 1
	v_mov_b32_dpp v15, v14 row_ror:8 row_mask:0xf bank_mask:0xf bound_ctrl:1
	s_and_saveexec_b64 s[0:1], s[6:7]
	v_add_f32_e32 v14, v14, v15
	v_add_f32_e32 v14, v110, v14
	ds_write_b32 v99, v14 offset:176
	s_or_b64 exec, exec, s[0:1]
	v_mul_f32_e32 v14, v23, v109
	v_fmac_f32_e32 v14, v22, v107
	v_fmac_f32_e32 v14, v24, v108
	v_fmac_f32_e32 v14, v25, v106
	s_nop 1
	v_add_f32_dpp v14, v14, v14 quad_perm:[1,0,3,2] row_mask:0xf bank_mask:0xf bound_ctrl:1
	s_nop 1
	v_add_f32_dpp v14, v14, v14 quad_perm:[2,3,0,1] row_mask:0xf bank_mask:0xf bound_ctrl:1
	s_nop 1
	v_add_f32_dpp v14, v14, v14 row_ror:4 row_mask:0xf bank_mask:0xf bound_ctrl:1
	s_nop 1
	v_mov_b32_dpp v15, v14 row_ror:8 row_mask:0xf bank_mask:0xf bound_ctrl:1
	s_and_saveexec_b64 s[0:1], s[6:7]
	v_add_f32_e32 v14, v14, v15
	v_add_f32_e32 v14, v110, v14
	ds_write_b32 v99, v14 offset:192
	s_or_b64 exec, exec, s[0:1]
	s_waitcnt vmcnt(10)
	v_mul_f32_e32 v14, v39, v109
	v_fmac_f32_e32 v14, v38, v107
	v_fmac_f32_e32 v14, v40, v108
	v_fmac_f32_e32 v14, v41, v106
	s_nop 1
	v_add_f32_dpp v14, v14, v14 quad_perm:[1,0,3,2] row_mask:0xf bank_mask:0xf bound_ctrl:1
	s_nop 1
	v_add_f32_dpp v14, v14, v14 quad_perm:[2,3,0,1] row_mask:0xf bank_mask:0xf bound_ctrl:1
	s_nop 1
	v_add_f32_dpp v14, v14, v14 row_ror:4 row_mask:0xf bank_mask:0xf bound_ctrl:1
	s_nop 1
	v_mov_b32_dpp v15, v14 row_ror:8 row_mask:0xf bank_mask:0xf bound_ctrl:1
	s_and_saveexec_b64 s[0:1], s[6:7]
	v_add_f32_e32 v14, v14, v15
	v_add_f32_e32 v14, v110, v14
	ds_write_b32 v99, v14 offset:208
	s_or_b64 exec, exec, s[0:1]
	s_waitcnt vmcnt(9)
	v_mul_f32_e32 v14, v43, v109
	v_fmac_f32_e32 v14, v42, v107
	v_fmac_f32_e32 v14, v44, v108
	v_fmac_f32_e32 v14, v45, v106
	s_nop 1
	v_add_f32_dpp v14, v14, v14 quad_perm:[1,0,3,2] row_mask:0xf bank_mask:0xf bound_ctrl:1
	s_nop 1
	v_add_f32_dpp v14, v14, v14 quad_perm:[2,3,0,1] row_mask:0xf bank_mask:0xf bound_ctrl:1
	s_nop 1
	v_add_f32_dpp v14, v14, v14 row_ror:4 row_mask:0xf bank_mask:0xf bound_ctrl:1
	s_nop 1
	v_mov_b32_dpp v15, v14 row_ror:8 row_mask:0xf bank_mask:0xf bound_ctrl:1
	s_and_saveexec_b64 s[0:1], s[6:7]
	v_add_f32_e32 v14, v14, v15
	v_add_f32_e32 v14, v110, v14
	ds_write_b32 v99, v14 offset:224
	s_or_b64 exec, exec, s[0:1]
	s_waitcnt vmcnt(8)
	v_mul_f32_e32 v14, v31, v109
	v_fmac_f32_e32 v14, v30, v107
	v_fmac_f32_e32 v14, v32, v108
	v_fmac_f32_e32 v14, v33, v106
	s_nop 1
	v_add_f32_dpp v14, v14, v14 quad_perm:[1,0,3,2] row_mask:0xf bank_mask:0xf bound_ctrl:1
	s_nop 1
	v_add_f32_dpp v14, v14, v14 quad_perm:[2,3,0,1] row_mask:0xf bank_mask:0xf bound_ctrl:1
	s_nop 1
	v_add_f32_dpp v14, v14, v14 row_ror:4 row_mask:0xf bank_mask:0xf bound_ctrl:1
	s_nop 1
	v_mov_b32_dpp v15, v14 row_ror:8 row_mask:0xf bank_mask:0xf bound_ctrl:1
	s_and_saveexec_b64 s[0:1], s[6:7]
	v_add_f32_e32 v14, v14, v15
	v_add_f32_e32 v14, v110, v14
	ds_write_b32 v99, v14 offset:240
	s_or_b64 exec, exec, s[0:1]
	s_mov_b64 s[0:1], 0x24000
	v_lshl_add_u64 v[14:15], v[70:71], 0, s[0:1]
	v_lshl_add_u64 v[16:17], v[14:15], 0, v[82:83]
	v_add_co_u32_e32 v22, vcc, 0x1000, v16
	v_mov_b32_e32 v93, v83
	s_nop 0
	v_addc_co_u32_e32 v23, vcc, 0, v17, vcc
	global_load_dwordx4 v[78:81], v[16:17], off nt
	global_load_dwordx4 v[70:73], v[22:23], off offset:2048 nt
	v_add_co_u32_e32 v22, vcc, 0x3000, v16
	v_lshl_add_u64 v[14:15], v[14:15], 0, v[92:93]
	s_nop 0
	v_addc_co_u32_e32 v23, vcc, 0, v17, vcc
	v_add_co_u32_e32 v24, vcc, s49, v16
	s_nop 1
	v_addc_co_u32_e32 v25, vcc, 0, v17, vcc
	global_load_dwordx4 v[62:65], v[22:23], off nt
	global_load_dwordx4 v[54:57], v[24:25], off offset:2048 nt
	v_add_co_u32_e32 v22, vcc, 0x7000, v16
	s_nop 1
	v_addc_co_u32_e32 v23, vcc, 0, v17, vcc
	global_load_dwordx4 v[46:49], v[14:15], off nt
	global_load_dwordx4 v[42:45], v[22:23], off offset:2048 nt
	v_add_co_u32_e32 v14, vcc, 0x9000, v16
	s_nop 1
	v_addc_co_u32_e32 v15, vcc, 0, v17, vcc
	v_add_co_u32_e32 v16, vcc, 0xa000, v16
	s_nop 1
	v_addc_co_u32_e32 v17, vcc, 0, v17, vcc
	global_load_dwordx4 v[38:41], v[14:15], off nt
	global_load_dwordx4 v[34:37], v[16:17], off offset:2048 nt
	s_waitcnt vmcnt(15)
	v_mul_f32_e32 v14, v75, v109
	v_fmac_f32_e32 v14, v74, v107
	v_fmac_f32_e32 v14, v76, v108
	v_fmac_f32_e32 v14, v77, v106
	s_nop 1
	v_add_f32_dpp v14, v14, v14 quad_perm:[1,0,3,2] row_mask:0xf bank_mask:0xf bound_ctrl:1
	s_nop 1
	v_add_f32_dpp v14, v14, v14 quad_perm:[2,3,0,1] row_mask:0xf bank_mask:0xf bound_ctrl:1
	s_nop 1
	v_add_f32_dpp v14, v14, v14 row_ror:4 row_mask:0xf bank_mask:0xf bound_ctrl:1
	s_nop 1
	v_mov_b32_dpp v15, v14 row_ror:8 row_mask:0xf bank_mask:0xf bound_ctrl:1
	s_and_saveexec_b64 s[0:1], s[6:7]
	v_add_f32_e32 v14, v14, v15
	v_add_f32_e32 v14, v110, v14
	ds_write_b32 v99, v14 offset:256
	s_or_b64 exec, exec, s[0:1]
	s_waitcnt vmcnt(14)
	v_mul_f32_e32 v14, v67, v109
	v_fmac_f32_e32 v14, v66, v107
	v_fmac_f32_e32 v14, v68, v108
	v_fmac_f32_e32 v14, v69, v106
	s_nop 1
	v_add_f32_dpp v14, v14, v14 quad_perm:[1,0,3,2] row_mask:0xf bank_mask:0xf bound_ctrl:1
	s_nop 1
	v_add_f32_dpp v14, v14, v14 quad_perm:[2,3,0,1] row_mask:0xf bank_mask:0xf bound_ctrl:1
	s_nop 1
	v_add_f32_dpp v14, v14, v14 row_ror:4 row_mask:0xf bank_mask:0xf bound_ctrl:1
	s_nop 1
	v_mov_b32_dpp v15, v14 row_ror:8 row_mask:0xf bank_mask:0xf bound_ctrl:1
	s_and_saveexec_b64 s[0:1], s[6:7]
	v_add_f32_e32 v14, v14, v15
	v_add_f32_e32 v14, v110, v14
	ds_write_b32 v99, v14 offset:272
	s_or_b64 exec, exec, s[0:1]
	s_waitcnt vmcnt(13)
; template <int NB>
; __device__ __forceinline__ void sb_decode_task(const Params& P, float* lds, int task) {
;     ...
;     for (int kb = 0; kb < NBT; ++kb) {
;         const float* np = (kb + 1 < NBT) ? Kp + (size_t)(4 * NB * (kb + 1)) * (SH * HD) : Vp;
; #pragma unroll
;         for (int i = 0; i < NB; ++i) nx[i] = *(const float4*)(np + (size_t)(4 * i + g) * (SH * HD));
; #pragma unroll
;         for (int i = 0; i < NB; ++i) { const int s = 4 * NB * kb + 4 * i + g;
;             float part = q0 * cur[i].x + q1 * cur[i].y + q2 * cur[i].z + q3 * cur[i].w; part = sum16(part);
;             if (c == 0) zl[s] = part + bias; }
	v_mul_f32_e32 v14, v59, v109
	v_fmac_f32_e32 v14, v58, v107
	v_fmac_f32_e32 v14, v60, v108
	v_fmac_f32_e32 v14, v61, v106
	s_nop 1
	v_add_f32_dpp v14, v14, v14 quad_perm:[1,0,3,2] row_mask:0xf bank_mask:0xf bound_ctrl:1
	s_nop 1
	v_add_f32_dpp v14, v14, v14 quad_perm:[2,3,0,1] row_mask:0xf bank_mask:0xf bound_ctrl:1
	s_nop 1
	v_add_f32_dpp v14, v14, v14 row_ror:4 row_mask:0xf bank_mask:0xf bound_ctrl:1
	s_nop 1
	v_mov_b32_dpp v15, v14 row_ror:8 row_mask:0xf bank_mask:0xf bound_ctrl:1
	s_and_saveexec_b64 s[0:1], s[6:7]
	v_add_f32_e32 v14, v14, v15
	v_add_f32_e32 v14, v110, v14
	ds_write_b32 v99, v14 offset:288
	s_or_b64 exec, exec, s[0:1]
	s_waitcnt vmcnt(12)
	v_mul_f32_e32 v14, v51, v109
	v_fmac_f32_e32 v14, v50, v107
	v_fmac_f32_e32 v14, v52, v108
	v_fmac_f32_e32 v14, v53, v106
	s_nop 1
	v_add_f32_dpp v14, v14, v14 quad_perm:[1,0,3,2] row_mask:0xf bank_mask:0xf bound_ctrl:1
	s_nop 1
	v_add_f32_dpp v14, v14, v14 quad_perm:[2,3,0,1] row_mask:0xf bank_mask:0xf bound_ctrl:1
	s_nop 1
	v_add_f32_dpp v14, v14, v14 row_ror:4 row_mask:0xf bank_mask:0xf bound_ctrl:1
	s_nop 1
	v_mov_b32_dpp v15, v14 row_ror:8 row_mask:0xf bank_mask:0xf bound_ctrl:1
	s_and_saveexec_b64 s[0:1], s[6:7]
	v_add_f32_e32 v14, v14, v15
	v_add_f32_e32 v14, v110, v14
	ds_write_b32 v99, v14 offset:304
	s_or_b64 exec, exec, s[0:1]
	s_waitcnt vmcnt(11)
	v_mul_f32_e32 v14, v19, v109
	v_fmac_f32_e32 v14, v18, v107
	v_fmac_f32_e32 v14, v20, v108
	v_fmac_f32_e32 v14, v21, v106
	s_nop 1
	v_add_f32_dpp v14, v14, v14 quad_perm:[1,0,3,2] row_mask:0xf bank_mask:0xf bound_ctrl:1
	s_nop 1
	v_add_f32_dpp v14, v14, v14 quad_perm:[2,3,0,1] row_mask:0xf bank_mask:0xf bound_ctrl:1
	s_nop 1
	v_add_f32_dpp v14, v14, v14 row_ror:4 row_mask:0xf bank_mask:0xf bound_ctrl:1
	s_nop 1
	v_mov_b32_dpp v15, v14 row_ror:8 row_mask:0xf bank_mask:0xf bound_ctrl:1
	s_and_saveexec_b64 s[0:1], s[6:7]
	v_add_f32_e32 v14, v14, v15
	v_add_f32_e32 v14, v110, v14
	ds_write_b32 v99, v14 offset:320
	s_or_b64 exec, exec, s[0:1]
	s_waitcnt vmcnt(10)
	v_mul_f32_e32 v11, v11, v109
	v_fmac_f32_e32 v11, v10, v107
	v_fmac_f32_e32 v11, v12, v108
	v_fmac_f32_e32 v11, v13, v106
	s_nop 1
	v_add_f32_dpp v10, v11, v11 quad_perm:[1,0,3,2] row_mask:0xf bank_mask:0xf bound_ctrl:1
	s_nop 1
	v_add_f32_dpp v10, v10, v10 quad_perm:[2,3,0,1] row_mask:0xf bank_mask:0xf bound_ctrl:1
	s_nop 1
	v_add_f32_dpp v10, v10, v10 row_ror:4 row_mask:0xf bank_mask:0xf bound_ctrl:1
	s_nop 1
	v_mov_b32_dpp v11, v10 row_ror:8 row_mask:0xf bank_mask:0xf bound_ctrl:1
	s_and_saveexec_b64 s[0:1], s[6:7]
	v_add_f32_e32 v10, v10, v11
	v_add_f32_e32 v10, v110, v10
	ds_write_b32 v99, v10 offset:336
	s_or_b64 exec, exec, s[0:1]
	s_waitcnt vmcnt(9)
	v_mul_f32_e32 v7, v7, v109
	v_fmac_f32_e32 v7, v6, v107
	v_fmac_f32_e32 v7, v8, v108
	v_fmac_f32_e32 v7, v9, v106
	s_nop 1
	v_add_f32_dpp v6, v7, v7 quad_perm:[1,0,3,2] row_mask:0xf bank_mask:0xf bound_ctrl:1
	s_nop 1
	v_add_f32_dpp v6, v6, v6 quad_perm:[2,3,0,1] row_mask:0xf bank_mask:0xf bound_ctrl:1
	s_nop 1
	v_add_f32_dpp v6, v6, v6 row_ror:4 row_mask:0xf bank_mask:0xf bound_ctrl:1
	s_nop 1
	v_mov_b32_dpp v7, v6 row_ror:8 row_mask:0xf bank_mask:0xf bound_ctrl:1
	s_and_saveexec_b64 s[0:1], s[6:7]
	v_add_f32_e32 v6, v6, v7
	v_add_f32_e32 v6, v110, v6
	ds_write_b32 v99, v6 offset:352
	s_or_b64 exec, exec, s[0:1]
	s_waitcnt vmcnt(8)
	v_mul_f32_e32 v3, v3, v109
	v_fmac_f32_e32 v3, v2, v107
	v_fmac_f32_e32 v3, v4, v108
	v_fmac_f32_e32 v3, v5, v106
	s_nop 1
	v_add_f32_dpp v2, v3, v3 quad_perm:[1,0,3,2] row_mask:0xf bank_mask:0xf bound_ctrl:1
	s_nop 1
	v_add_f32_dpp v2, v2, v2 quad_perm:[2,3,0,1] row_mask:0xf bank_mask:0xf bound_ctrl:1
	s_nop 1
	v_add_f32_dpp v2, v2, v2 row_ror:4 row_mask:0xf bank_mask:0xf bound_ctrl:1
	s_nop 1
	v_mov_b32_dpp v3, v2 row_ror:8 row_mask:0xf bank_mask:0xf bound_ctrl:1
	s_and_saveexec_b64 s[0:1], s[6:7]
	v_add_f32_e32 v2, v2, v3
	v_add_f32_e32 v2, v110, v2
	ds_write_b32 v99, v2 offset:368
	s_or_b64 exec, exec, s[0:1]
	v_lshlrev_b64 v[2:3], 6, v[94:95]
	v_lshl_add_u64 v[6:7], v[2:3], 2, v[86:87]
	v_lshl_add_u64 v[50:51], v[6:7], 0, v[82:83]
	v_add_co_u32_e32 v2, vcc, 0x1000, v50
	v_mov_b32_e32 v93, v83
	s_nop 0
	v_addc_co_u32_e32 v3, vcc, 0, v51, vcc
	v_add_co_u32_e32 v8, vcc, 0x3000, v50
	v_lshl_add_u64 v[10:11], v[6:7], 0, v[92:93]
	s_nop 0
	v_addc_co_u32_e32 v9, vcc, 0, v51, vcc
	v_add_co_u32_e32 v14, vcc, s49, v50
	global_load_dwordx4 v[30:33], v[50:51], off nt
	s_nop 0
	global_load_dwordx4 v[2:5], v[2:3], off offset:2048 nt
	v_addc_co_u32_e32 v15, vcc, 0, v51, vcc
	v_add_co_u32_e32 v18, vcc, 0x7000, v50
	global_load_dwordx4 v[6:9], v[8:9], off nt
	s_nop 0
	global_load_dwordx4 v[10:13], v[10:11], off nt
	v_addc_co_u32_e32 v19, vcc, 0, v51, vcc
	v_add_co_u32_e32 v22, vcc, 0x9000, v50
	global_load_dwordx4 v[14:17], v[14:15], off offset:2048 nt
	s_nop 0
	global_load_dwordx4 v[18:21], v[18:19], off offset:2048 nt
	v_addc_co_u32_e32 v23, vcc, 0, v51, vcc
	v_add_co_u32_e32 v26, vcc, 0xa000, v50
	s_waitcnt vmcnt(13)
	v_mul_f32_e32 v52, v79, v109
	v_addc_co_u32_e32 v27, vcc, 0, v51, vcc
	global_load_dwordx4 v[22:25], v[22:23], off nt
	s_nop 0
	global_load_dwordx4 v[26:29], v[26:27], off offset:2048 nt
	v_fmac_f32_e32 v52, v78, v107
	v_fmac_f32_e32 v52, v80, v108
	v_fmac_f32_e32 v52, v81, v106
	s_nop 1
	v_add_f32_dpp v52, v52, v52 quad_perm:[1,0,3,2] row_mask:0xf bank_mask:0xf bound_ctrl:1
	s_nop 1
	v_add_f32_dpp v52, v52, v52 quad_perm:[2,3,0,1] row_mask:0xf bank_mask:0xf bound_ctrl:1
	s_nop 1
	v_add_f32_dpp v52, v52, v52 row_ror:4 row_mask:0xf bank_mask:0xf bound_ctrl:1
	s_nop 1
	v_mov_b32_dpp v53, v52 row_ror:8 row_mask:0xf bank_mask:0xf bound_ctrl:1
	s_and_saveexec_b64 s[0:1], s[6:7]
	v_add_f32_e32 v52, v52, v53
	v_add_f32_e32 v52, v110, v52
	ds_write_b32 v99, v52 offset:384
	s_or_b64 exec, exec, s[0:1]
	s_waitcnt vmcnt(14)
; template <int NB>
; __device__ __forceinline__ void sb_decode_task(const Params& P, float* lds, int task) {
;     ...
;         for (int i = 0; i < NB; ++i) { const int s = 4 * NB * kb + 4 * i + g;
;             float part = q0 * cur[i].x + q1 * cur[i].y + q2 * cur[i].z + q3 * cur[i].w; part = sum16(part);
;             if (c == 0) zl[s] = part + bias; }
; #pragma unroll
;         for (int i = 0; i < NB; ++i) cur[i] = nx[i];
;     }
;     asm volatile("s_waitcnt lgkmcnt(0)" ::: "memory");
;     __builtin_amdgcn_wave_barrier();
;     const float z0 = zl[2 * lane], z1 = zl[2 * lane + 1];
	v_mul_f32_e32 v52, v71, v109
	v_fmac_f32_e32 v52, v70, v107
	v_fmac_f32_e32 v52, v72, v108
	v_fmac_f32_e32 v52, v73, v106
	s_nop 1
	v_add_f32_dpp v52, v52, v52 quad_perm:[1,0,3,2] row_mask:0xf bank_mask:0xf bound_ctrl:1
	s_nop 1
	v_add_f32_dpp v52, v52, v52 quad_perm:[2,3,0,1] row_mask:0xf bank_mask:0xf bound_ctrl:1
	s_nop 1
	v_add_f32_dpp v52, v52, v52 row_ror:4 row_mask:0xf bank_mask:0xf bound_ctrl:1
	s_nop 1
	v_mov_b32_dpp v53, v52 row_ror:8 row_mask:0xf bank_mask:0xf bound_ctrl:1
	s_and_saveexec_b64 s[0:1], s[6:7]
	v_add_f32_e32 v52, v52, v53
	v_add_f32_e32 v52, v110, v52
	ds_write_b32 v99, v52 offset:400
	s_or_b64 exec, exec, s[0:1]
	s_waitcnt vmcnt(13)
	v_mul_f32_e32 v52, v63, v109
	v_fmac_f32_e32 v52, v62, v107
	v_fmac_f32_e32 v52, v64, v108
	v_fmac_f32_e32 v52, v65, v106
	s_nop 1
	v_add_f32_dpp v52, v52, v52 quad_perm:[1,0,3,2] row_mask:0xf bank_mask:0xf bound_ctrl:1
	s_nop 1
	v_add_f32_dpp v52, v52, v52 quad_perm:[2,3,0,1] row_mask:0xf bank_mask:0xf bound_ctrl:1
	s_nop 1
	v_add_f32_dpp v52, v52, v52 row_ror:4 row_mask:0xf bank_mask:0xf bound_ctrl:1
	s_nop 1
	v_mov_b32_dpp v53, v52 row_ror:8 row_mask:0xf bank_mask:0xf bound_ctrl:1
	s_and_saveexec_b64 s[0:1], s[6:7]
	v_add_f32_e32 v52, v52, v53
	v_add_f32_e32 v52, v110, v52
	ds_write_b32 v99, v52 offset:416
	s_or_b64 exec, exec, s[0:1]
	s_waitcnt vmcnt(12)
	v_mul_f32_e32 v52, v55, v109
	v_fmac_f32_e32 v52, v54, v107
	v_fmac_f32_e32 v52, v56, v108
	v_fmac_f32_e32 v52, v57, v106
	s_nop 1
	v_add_f32_dpp v52, v52, v52 quad_perm:[1,0,3,2] row_mask:0xf bank_mask:0xf bound_ctrl:1
	s_nop 1
	v_add_f32_dpp v52, v52, v52 quad_perm:[2,3,0,1] row_mask:0xf bank_mask:0xf bound_ctrl:1
	s_nop 1
	v_add_f32_dpp v52, v52, v52 row_ror:4 row_mask:0xf bank_mask:0xf bound_ctrl:1
	s_nop 1
	v_mov_b32_dpp v53, v52 row_ror:8 row_mask:0xf bank_mask:0xf bound_ctrl:1
	s_and_saveexec_b64 s[0:1], s[6:7]
	v_add_f32_e32 v52, v52, v53
	v_add_f32_e32 v52, v110, v52
	ds_write_b32 v99, v52 offset:432
	s_or_b64 exec, exec, s[0:1]
	s_waitcnt vmcnt(11)
	v_mul_f32_e32 v47, v47, v109
	v_fmac_f32_e32 v47, v46, v107
	v_fmac_f32_e32 v47, v48, v108
	v_fmac_f32_e32 v47, v49, v106
	s_nop 1
	v_add_f32_dpp v46, v47, v47 quad_perm:[1,0,3,2] row_mask:0xf bank_mask:0xf bound_ctrl:1
	s_nop 1
	v_add_f32_dpp v46, v46, v46 quad_perm:[2,3,0,1] row_mask:0xf bank_mask:0xf bound_ctrl:1
	s_nop 1
	v_add_f32_dpp v46, v46, v46 row_ror:4 row_mask:0xf bank_mask:0xf bound_ctrl:1
	s_nop 1
	v_mov_b32_dpp v47, v46 row_ror:8 row_mask:0xf bank_mask:0xf bound_ctrl:1
	s_and_saveexec_b64 s[0:1], s[6:7]
	v_add_f32_e32 v46, v46, v47
	v_add_f32_e32 v46, v110, v46
	ds_write_b32 v99, v46 offset:448
	s_or_b64 exec, exec, s[0:1]
	s_waitcnt vmcnt(10)
	v_mul_f32_e32 v43, v43, v109
	v_fmac_f32_e32 v43, v42, v107
	v_fmac_f32_e32 v43, v44, v108
	v_fmac_f32_e32 v43, v45, v106
	s_nop 1
	v_add_f32_dpp v42, v43, v43 quad_perm:[1,0,3,2] row_mask:0xf bank_mask:0xf bound_ctrl:1
	s_nop 1
	v_add_f32_dpp v42, v42, v42 quad_perm:[2,3,0,1] row_mask:0xf bank_mask:0xf bound_ctrl:1
	s_nop 1
	v_add_f32_dpp v42, v42, v42 row_ror:4 row_mask:0xf bank_mask:0xf bound_ctrl:1
	s_nop 1
	v_mov_b32_dpp v43, v42 row_ror:8 row_mask:0xf bank_mask:0xf bound_ctrl:1
	s_and_saveexec_b64 s[0:1], s[6:7]
	v_add_f32_e32 v42, v42, v43
	v_add_f32_e32 v42, v110, v42
	ds_write_b32 v99, v42 offset:464
	s_or_b64 exec, exec, s[0:1]
	s_waitcnt vmcnt(9)
	v_mul_f32_e32 v39, v39, v109
	v_fmac_f32_e32 v39, v38, v107
	v_fmac_f32_e32 v39, v40, v108
	v_fmac_f32_e32 v39, v41, v106
	s_nop 1
	v_add_f32_dpp v38, v39, v39 quad_perm:[1,0,3,2] row_mask:0xf bank_mask:0xf bound_ctrl:1
	s_nop 1
	v_add_f32_dpp v38, v38, v38 quad_perm:[2,3,0,1] row_mask:0xf bank_mask:0xf bound_ctrl:1
	s_nop 1
	v_add_f32_dpp v38, v38, v38 row_ror:4 row_mask:0xf bank_mask:0xf bound_ctrl:1
	s_nop 1
	v_mov_b32_dpp v39, v38 row_ror:8 row_mask:0xf bank_mask:0xf bound_ctrl:1
	s_and_saveexec_b64 s[0:1], s[6:7]
	v_add_f32_e32 v38, v38, v39
	v_add_f32_e32 v38, v110, v38
	ds_write_b32 v99, v38 offset:480
	s_or_b64 exec, exec, s[0:1]
	s_waitcnt vmcnt(8)
	v_mul_f32_e32 v35, v35, v109
	v_fmac_f32_e32 v35, v34, v107
	v_fmac_f32_e32 v35, v36, v108
	v_fmac_f32_e32 v35, v37, v106
	s_nop 1
	v_add_f32_dpp v34, v35, v35 quad_perm:[1,0,3,2] row_mask:0xf bank_mask:0xf bound_ctrl:1
	s_nop 1
	v_add_f32_dpp v34, v34, v34 quad_perm:[2,3,0,1] row_mask:0xf bank_mask:0xf bound_ctrl:1
	s_nop 1
	v_add_f32_dpp v34, v34, v34 row_ror:4 row_mask:0xf bank_mask:0xf bound_ctrl:1
	s_nop 1
	v_mov_b32_dpp v35, v34 row_ror:8 row_mask:0xf bank_mask:0xf bound_ctrl:1
	s_and_saveexec_b64 s[0:1], s[6:7]
	v_add_f32_e32 v34, v34, v35
	v_add_f32_e32 v34, v110, v34
	ds_write_b32 v99, v34 offset:496
	s_or_b64 exec, exec, s[0:1]
	s_waitcnt lgkmcnt(0)
	ds_read_b64 v[34:35], v100
	s_waitcnt lgkmcnt(0)
; __device__ __forceinline__ float softplus2_(float z2) { return fmaxf(z2, 0.f) + log1pf(exp2f(-fabsf(z2))) * LOG2E; }
; template <int NB>
; __device__ __forceinline__ void sb_decode_task(const Params& P, float* lds, int task) {
;     ...
;     const float z0 = zl[2 * lane], z1 = zl[2 * lane + 1];
;     const float sp0 = softplus2_(z0), sp1 = softplus2_(z1);
;     float incl = sp0 + sp1;
	v_cmp_gt_f32_e64 vcc, |v34|, s97
	s_nop 1
	v_cndmask_b32_e32 v37, 0, v103, vcc
	v_sub_f32_e64 v37, v37, |v34|
	v_exp_f32_e32 v37, v37
	v_max_f32_e32 v36, v34, v34
	v_max_f32_e32 v38, 0, v36
	v_cndmask_b32_e32 v36, 0, v102, vcc
	v_ldexp_f32 v39, v37, v36
	v_add_f32_e32 v40, 1.0, v39
	v_add_f32_e32 v36, -1.0, v40
	v_sub_f32_e32 v37, v36, v40
	v_add_f32_e32 v37, 1.0, v37
	v_sub_f32_e32 v36, v39, v36
	v_add_f32_e32 v41, v36, v37
	v_frexp_mant_f32_e32 v36, v40
	v_cmp_gt_f32_e32 vcc, s47, v36
	v_cvt_f64_f32_e32 v[36:37], v40
	v_frexp_exp_i32_f64_e32 v36, v[36:37]
	v_subbrev_co_u32_e32 v36, vcc, 0, v36, vcc
	v_sub_u32_e32 v37, 0, v36
	v_ldexp_f32 v40, v40, v37
	v_ldexp_f32 v37, v41, v37
	v_add_f32_e32 v41, -1.0, v40
	v_add_f32_e32 v42, 1.0, v41
	v_sub_f32_e32 v42, v40, v42
	v_add_f32_e32 v42, v37, v42
	v_add_f32_e32 v43, v41, v42
	v_sub_f32_e32 v41, v41, v43
	v_add_f32_e32 v41, v42, v41
	v_add_f32_e32 v42, 1.0, v40
	v_add_f32_e32 v44, -1.0, v42
	v_sub_f32_e32 v40, v40, v44
	v_add_f32_e32 v37, v37, v40
	v_add_f32_e32 v40, v42, v37
	v_sub_f32_e32 v42, v42, v40
	v_add_f32_e32 v37, v37, v42
	v_rcp_f32_e32 v42, v40
	v_cvt_f32_i32_e32 v36, v36
	v_cmp_neq_f32_e32 vcc, s46, v39
	v_mul_f32_e32 v44, v43, v42
	v_mul_f32_e32 v45, v40, v44
	v_fma_f32 v46, v44, v40, -v45
	v_fmac_f32_e32 v46, v44, v37
	v_add_f32_e32 v47, v45, v46
	v_sub_f32_e32 v48, v43, v47
	v_sub_f32_e32 v43, v43, v48
	v_sub_f32_e32 v45, v47, v45
	v_sub_f32_e32 v43, v43, v47
	v_add_f32_e32 v41, v41, v43
	v_sub_f32_e32 v43, v45, v46
	v_add_f32_e32 v41, v43, v41
	v_add_f32_e32 v43, v48, v41
	v_mul_f32_e32 v45, v42, v43
	v_mul_f32_e32 v46, v40, v45
	v_fma_f32 v40, v45, v40, -v46
	v_fmac_f32_e32 v40, v45, v37
	v_sub_f32_e32 v37, v48, v43
	v_add_f32_e32 v37, v41, v37
	v_add_f32_e32 v41, v46, v40
	v_sub_f32_e32 v47, v43, v41
	v_sub_f32_e32 v43, v43, v47
	v_sub_f32_e32 v46, v41, v46
	v_sub_f32_e32 v41, v43, v41
	v_add_f32_e32 v37, v37, v41
	v_sub_f32_e32 v40, v46, v40
	v_add_f32_e32 v37, v40, v37
	v_add_f32_e32 v40, v44, v45
	v_add_f32_e32 v37, v47, v37
	v_sub_f32_e32 v41, v40, v44
	v_mul_f32_e32 v37, v42, v37
	v_sub_f32_e32 v41, v45, v41
	v_add_f32_e32 v37, v41, v37
	v_mul_f32_e32 v44, 0x3f317218, v36
	v_add_f32_e32 v41, v40, v37
	v_fma_f32 v45, v36, s95, -v44
	v_mul_f32_e32 v42, v41, v41
	v_fmac_f32_e32 v45, 0xb102e308, v36
	v_sub_f32_e32 v36, v41, v40
	v_fmamk_f32 v43, v42, 0x3e9b6dac, v1
	v_sub_f32_e32 v36, v37, v36
	v_add_f32_e32 v37, v44, v45
	v_fmaak_f32 v43, v42, v43, 0x3f2aaada
	v_sub_f32_e32 v40, v37, v44
	v_ldexp_f32 v44, v41, 1
	v_mul_f32_e32 v41, v41, v42
	v_mul_f32_e32 v41, v41, v43
	v_add_f32_e32 v42, v44, v41
	v_sub_f32_e32 v43, v42, v44
	v_ldexp_f32 v36, v36, 1
	v_sub_f32_e32 v41, v41, v43
	v_add_f32_e32 v36, v36, v41
	v_add_f32_e32 v41, v42, v36
	v_sub_f32_e32 v42, v41, v42
	v_sub_f32_e32 v36, v36, v42
	v_add_f32_e32 v42, v37, v41
	v_sub_f32_e32 v43, v42, v37
	v_sub_f32_e32 v44, v42, v43
	v_sub_f32_e32 v40, v45, v40
	v_sub_f32_e32 v37, v37, v44
	v_sub_f32_e32 v41, v41, v43
	v_add_f32_e32 v37, v41, v37
	v_add_f32_e32 v41, v40, v36
	v_sub_f32_e32 v43, v41, v40
	v_sub_f32_e32 v44, v41, v43
	v_sub_f32_e32 v40, v40, v44
	v_sub_f32_e32 v36, v36, v43
	v_add_f32_e32 v37, v41, v37
	v_add_f32_e32 v36, v36, v40
	v_add_f32_e32 v40, v42, v37
	v_sub_f32_e32 v41, v40, v42
	v_sub_f32_e32 v37, v37, v41
	v_add_f32_e32 v36, v36, v37
	v_add_f32_e32 v36, v40, v36
	v_cndmask_b32_e32 v36, v104, v36, vcc
	v_cmp_lt_f32_e64 vcc, |v39|, s45
	s_nop 1
	v_cndmask_b32_e32 v36, v36, v39, vcc
	v_cmp_gt_f32_e64 vcc, |v35|, s97
	v_fmac_f32_e32 v38, 0x3fb8aa3b, v36
	v_max_f32_e32 v36, v35, v35
	v_cndmask_b32_e32 v37, 0, v103, vcc
	v_sub_f32_e64 v37, v37, |v35|
	v_exp_f32_e32 v37, v37
	v_max_f32_e32 v39, 0, v36
	v_cndmask_b32_e32 v36, 0, v102, vcc
	v_sub_f32_e32 v34, v34, v38
	v_ldexp_f32 v40, v37, v36
	v_add_f32_e32 v41, 1.0, v40
	v_add_f32_e32 v36, -1.0, v41
	v_sub_f32_e32 v37, v36, v41
	v_add_f32_e32 v37, 1.0, v37
	v_sub_f32_e32 v36, v40, v36
	v_add_f32_e32 v42, v36, v37
	v_frexp_mant_f32_e32 v36, v41
	v_cmp_gt_f32_e32 vcc, s47, v36
	v_cvt_f64_f32_e32 v[36:37], v41
	v_frexp_exp_i32_f64_e32 v36, v[36:37]
	v_subbrev_co_u32_e32 v36, vcc, 0, v36, vcc
	v_sub_u32_e32 v37, 0, v36
	v_ldexp_f32 v41, v41, v37
	v_ldexp_f32 v37, v42, v37
	v_add_f32_e32 v42, -1.0, v41
	v_add_f32_e32 v43, 1.0, v42
	v_sub_f32_e32 v43, v41, v43
	v_add_f32_e32 v43, v37, v43
	v_add_f32_e32 v44, v42, v43
	v_sub_f32_e32 v42, v42, v44
	v_add_f32_e32 v42, v43, v42
	v_add_f32_e32 v43, 1.0, v41
	v_add_f32_e32 v45, -1.0, v43
	v_sub_f32_e32 v41, v41, v45
	v_add_f32_e32 v37, v37, v41
	v_add_f32_e32 v41, v43, v37
	v_sub_f32_e32 v43, v43, v41
	v_add_f32_e32 v37, v37, v43
	v_rcp_f32_e32 v43, v41
	v_cvt_f32_i32_e32 v36, v36
	v_cmp_neq_f32_e32 vcc, s46, v40
	v_mul_f32_e32 v45, v44, v43
	v_mul_f32_e32 v46, v41, v45
	v_fma_f32 v47, v45, v41, -v46
	v_fmac_f32_e32 v47, v45, v37
	v_add_f32_e32 v48, v46, v47
	v_sub_f32_e32 v49, v44, v48
	v_sub_f32_e32 v44, v44, v49
	v_sub_f32_e32 v46, v48, v46
	v_sub_f32_e32 v44, v44, v48
	v_add_f32_e32 v42, v42, v44
	v_sub_f32_e32 v44, v46, v47
	v_add_f32_e32 v42, v44, v42
	v_add_f32_e32 v44, v49, v42
	v_mul_f32_e32 v46, v43, v44
	v_mul_f32_e32 v47, v41, v46
	v_fma_f32 v41, v46, v41, -v47
	v_fmac_f32_e32 v41, v46, v37
	v_sub_f32_e32 v37, v49, v44
	v_add_f32_e32 v37, v42, v37
	v_add_f32_e32 v42, v47, v41
	v_sub_f32_e32 v48, v44, v42
	v_sub_f32_e32 v44, v44, v48
	v_sub_f32_e32 v47, v42, v47
	v_sub_f32_e32 v42, v44, v42
	v_add_f32_e32 v37, v37, v42
	v_sub_f32_e32 v41, v47, v41
	v_add_f32_e32 v37, v41, v37
	v_add_f32_e32 v41, v45, v46
	v_add_f32_e32 v37, v48, v37
	v_sub_f32_e32 v42, v41, v45
	v_mul_f32_e32 v37, v43, v37
; template <int NB>
; __device__ __forceinline__ void sb_decode_task(const Params& P, float* lds, int task) {
;     ...
;     float incl = sp0 + sp1;
; #pragma unroll
;     for (int off = 1; off < 64; off <<= 1) { const float t = __shfl_down(incl, off); if (lane + off < 64) incl += t; }
;     const float excl = incl - (sp0 + sp1);
;     wl[2 * lane] = exp2f(z0 - sp0 - (excl + sp1));
;     wl[2 * lane + 1] = exp2f(z1 - sp1 - excl);
;     const float Ltot = __shfl(incl, 0);
;     asm volatile("s_waitcnt lgkmcnt(0)" ::: "memory");
;     __builtin_amdgcn_wave_barrier();
;     float4 o4 = make_float4(0.f, 0.f, 0.f, 0.f);
; #pragma unroll
;     for (int vb = 0; vb < NBT; ++vb) {
;         if (vb + 1 < NBT) {
; #pragma unroll
;             for (int i = 0; i < NB; ++i) nx[i] = *(const float4*)(Vp + (size_t)(4 * NB * (vb + 1) + 4 * i + g) * (SH * HD)); }
; #pragma unroll
;         for (int i = 0; i < NB; ++i) { const float w = wl[4 * NB * vb + 4 * i + g]; o4.x += w * cur[i].x; o4.y += w * cur[i].y; o4.z += w * cur[i].z; o4.w += w * cur[i].w; }
	v_sub_f32_e32 v42, v46, v42
	v_add_f32_e32 v37, v42, v37
	v_mul_f32_e32 v45, 0x3f317218, v36
	v_add_f32_e32 v42, v41, v37
	v_fma_f32 v46, v36, s95, -v45
	v_mul_f32_e32 v43, v42, v42
	v_fmac_f32_e32 v46, 0xb102e308, v36
	v_sub_f32_e32 v36, v42, v41
	v_fmamk_f32 v44, v43, 0x3e9b6dac, v1
	v_sub_f32_e32 v36, v37, v36
	v_add_f32_e32 v37, v45, v46
	v_fmaak_f32 v44, v43, v44, 0x3f2aaada
	v_sub_f32_e32 v41, v37, v45
	v_ldexp_f32 v45, v42, 1
	v_mul_f32_e32 v42, v42, v43
	v_mul_f32_e32 v42, v42, v44
	v_add_f32_e32 v43, v45, v42
	v_sub_f32_e32 v44, v43, v45
	v_ldexp_f32 v36, v36, 1
	v_sub_f32_e32 v42, v42, v44
	v_add_f32_e32 v36, v36, v42
	v_add_f32_e32 v42, v43, v36
	v_sub_f32_e32 v43, v42, v43
	v_sub_f32_e32 v36, v36, v43
	v_add_f32_e32 v43, v37, v42
	v_sub_f32_e32 v44, v43, v37
	v_sub_f32_e32 v45, v43, v44
	v_sub_f32_e32 v41, v46, v41
	v_sub_f32_e32 v37, v37, v45
	v_sub_f32_e32 v42, v42, v44
	v_add_f32_e32 v37, v42, v37
	v_add_f32_e32 v42, v41, v36
	v_sub_f32_e32 v44, v42, v41
	v_sub_f32_e32 v45, v42, v44
	v_sub_f32_e32 v41, v41, v45
	v_sub_f32_e32 v36, v36, v44
	v_add_f32_e32 v37, v42, v37
	v_add_f32_e32 v36, v36, v41
	v_add_f32_e32 v41, v43, v37
	v_sub_f32_e32 v42, v41, v43
	v_sub_f32_e32 v37, v37, v42
	v_add_f32_e32 v36, v36, v37
	v_add_f32_e32 v36, v41, v36
	v_cndmask_b32_e32 v36, v104, v36, vcc
	v_cmp_lt_f32_e64 vcc, |v40|, s45
	v_and_b32_e32 v37, 63, v105
	s_nop 0
	v_cndmask_b32_e32 v36, v36, v40, vcc
	v_cmp_ne_u32_e32 vcc, 63, v37
	v_fmac_f32_e32 v39, 0x3fb8aa3b, v36
	v_add_f32_e32 v36, v38, v39
	v_addc_co_u32_e32 v40, vcc, 0, v105, vcc
	v_lshlrev_b32_e32 v108, 2, v40
	ds_bpermute_b32 v40, v108, v36
	v_cmp_gt_u32_e32 vcc, 62, v37
	v_sub_f32_e32 v35, v35, v39
	s_waitcnt lgkmcnt(0)
	v_add_f32_e32 v40, v36, v40
	v_cndmask_b32_e64 v41, 0, 2, vcc
	v_cndmask_b32_e64 v40, v40, v36, s[8:9]
	v_add_lshl_u32 v109, v41, v105, 2
	ds_bpermute_b32 v41, v109, v40
	v_cmp_gt_u32_e32 vcc, 60, v37
	s_waitcnt lgkmcnt(0)
	v_add_f32_e32 v41, v40, v41
	v_cndmask_b32_e64 v40, v40, v41, s[10:11]
	v_cndmask_b32_e64 v41, 0, 4, vcc
	v_add_lshl_u32 v110, v41, v105, 2
	ds_bpermute_b32 v41, v110, v40
	v_cmp_gt_u32_e32 vcc, 56, v37
	s_waitcnt lgkmcnt(0)
	v_add_f32_e32 v41, v40, v41
	v_cndmask_b32_e64 v40, v40, v41, s[12:13]
	v_cndmask_b32_e64 v41, 0, 8, vcc
	v_add_lshl_u32 v111, v41, v105, 2
	ds_bpermute_b32 v41, v111, v40
	v_cmp_gt_u32_e32 vcc, 48, v37
	s_waitcnt lgkmcnt(0)
	v_add_f32_e32 v41, v40, v41
	v_cndmask_b32_e64 v37, 0, 16, vcc
	v_cndmask_b32_e64 v40, v40, v41, s[14:15]
	v_add_lshl_u32 v112, v37, v105, 2
	ds_bpermute_b32 v37, v112, v40
	s_waitcnt lgkmcnt(0)
	v_add_f32_e32 v37, v40, v37
	v_cndmask_b32_e64 v37, v40, v37, s[16:17]
	v_lshlrev_b32_e32 v40, 2, v105
	v_or_b32_e32 v113, 0x80, v40
	ds_bpermute_b32 v41, v113, v37
	v_and_b32_e32 v106, 0x100, v40
	s_waitcnt lgkmcnt(0)
	v_add_f32_e32 v41, v37, v41
	v_cndmask_b32_e64 v44, v37, v41, s[18:19]
	v_sub_f32_e32 v36, v44, v36
	v_add_f32_e32 v37, v39, v36
	v_sub_f32_e32 v34, v34, v37
	v_cmp_gt_f32_e32 vcc, s24, v34
	v_sub_f32_e32 v35, v35, v36
	s_nop 0
	v_cndmask_b32_e32 v37, 0, v103, vcc
	v_add_f32_e32 v34, v34, v37
	v_cndmask_b32_e32 v37, 0, v102, vcc
	v_cmp_gt_f32_e32 vcc, s24, v35
	v_exp_f32_e32 v34, v34
	s_nop 0
	v_cndmask_b32_e32 v36, 0, v103, vcc
	v_add_f32_e32 v35, v35, v36
	v_exp_f32_e32 v35, v35
	v_cndmask_b32_e32 v36, 0, v102, vcc
	v_ldexp_f32 v34, v34, v37
	v_ldexp_f32 v35, v35, v36
	ds_write_b64 v100, v[34:35] offset:512
	s_waitcnt lgkmcnt(0)
	ds_read2_b32 v[34:35], v99 offset0:128 offset1:132
	ds_read2_b32 v[42:43], v99 offset0:136 offset1:140
	ds_read2_b32 v[66:67], v99 offset0:144 offset1:148
	ds_read2_b32 v[68:69], v99 offset0:152 offset1:156
	ds_read2_b32 v[74:75], v99 offset0:160 offset1:164
	ds_read2_b32 v[76:77], v99 offset0:168 offset1:172
	ds_read2_b32 v[38:39], v99 offset0:176 offset1:180
	ds_read2_b32 v[40:41], v99 offset0:184 offset1:188
	s_waitcnt vmcnt(7) lgkmcnt(7)
	v_pk_fma_f32 v[70:71], v[30:31], v[34:35], 0 op_sel_hi:[1,0,0]
	v_add_co_u32_e32 v30, vcc, s25, v50
	v_pk_fma_f32 v[72:73], v[32:33], v[34:35], 0 op_sel_hi:[1,0,0]
	s_nop 0
	v_addc_co_u32_e32 v31, vcc, 0, v51, vcc
	v_add_co_u32_e32 v34, vcc, s43, v50
	v_mov_b32_e32 v64, v35
	s_nop 0
	v_addc_co_u32_e32 v35, vcc, 0, v51, vcc
	v_add_co_u32_e32 v46, vcc, s44, v50
	s_waitcnt vmcnt(6)
	v_pk_fma_f32 v[2:3], v[2:3], v[64:65], v[70:71] op_sel_hi:[1,0,1]
	v_addc_co_u32_e32 v47, vcc, 0, v51, vcc
	v_add_co_u32_e32 v52, vcc, s26, v50
	global_load_dwordx4 v[46:49], v[46:47], off nt
	s_nop 0
	v_addc_co_u32_e32 v53, vcc, 0, v51, vcc
	v_add_co_u32_e32 v56, vcc, s27, v50
	global_load_dwordx4 v[52:55], v[52:53], off offset:2048 nt
	s_nop 0
	v_addc_co_u32_e32 v57, vcc, 0, v51, vcc
	v_add_co_u32_e32 v60, vcc, s28, v50
	global_load_dwordx4 v[56:59], v[56:57], off nt
	s_nop 0
	v_addc_co_u32_e32 v61, vcc, 0, v51, vcc
	global_load_dwordx4 v[60:63], v[60:61], off offset:2048 nt
	s_waitcnt lgkmcnt(6)
	v_mov_b32_e32 v78, v43
	s_waitcnt vmcnt(9)
	v_pk_fma_f32 v[2:3], v[6:7], v[42:43], v[2:3] op_sel_hi:[1,0,1]
	s_waitcnt lgkmcnt(5)
	v_mov_b32_e32 v80, v67
	s_waitcnt vmcnt(7)
	v_pk_fma_f32 v[2:3], v[14:15], v[78:79], v[2:3] op_sel_hi:[1,0,1]
	s_waitcnt lgkmcnt(4)
	v_mov_b32_e32 v94, v69
	v_pk_fma_f32 v[2:3], v[10:11], v[66:67], v[2:3] op_sel_hi:[1,0,1]
	s_waitcnt lgkmcnt(3)
	v_mov_b32_e32 v10, v75
	s_waitcnt vmcnt(6)
	v_pk_fma_f32 v[2:3], v[18:19], v[80:81], v[2:3] op_sel_hi:[1,0,1]
	s_waitcnt lgkmcnt(2)
	v_mov_b32_e32 v14, v77
	s_waitcnt vmcnt(5)
	v_pk_fma_f32 v[2:3], v[22:23], v[68:69], v[2:3] op_sel_hi:[1,0,1]
	global_load_dwordx4 v[30:33], v[30:31], off nt
	s_waitcnt vmcnt(5)
; template <int NB>
; __device__ __forceinline__ void sb_decode_task(const Params& P, float* lds, int task) {
;     ...
;     for (int vb = 0; vb < NBT; ++vb) {
;         if (vb + 1 < NBT) {
; #pragma unroll
;             for (int i = 0; i < NB; ++i) nx[i] = *(const float4*)(Vp + (size_t)(4 * NB * (vb + 1) + 4 * i + g) * (SH * HD)); }
; #pragma unroll
;         for (int i = 0; i < NB; ++i) { const float w = wl[4 * NB * vb + 4 * i + g]; o4.x += w * cur[i].x; o4.y += w * cur[i].y; o4.z += w * cur[i].z; o4.w += w * cur[i].w; }
; #pragma unroll
;         for (int i = 0; i < NB; ++i) cur[i] = nx[i];
	v_pk_fma_f32 v[2:3], v[26:27], v[94:95], v[2:3] op_sel_hi:[1,0,1]
	global_load_dwordx4 v[34:37], v[34:35], off offset:2048 nt
	s_waitcnt vmcnt(5)
	v_pk_fma_f32 v[2:3], v[46:47], v[74:75], v[2:3] op_sel_hi:[1,0,1]
	s_waitcnt vmcnt(4)
	v_pk_fma_f32 v[2:3], v[52:53], v[10:11], v[2:3] op_sel_hi:[1,0,1]
	s_waitcnt vmcnt(3)
	v_pk_fma_f32 v[2:3], v[56:57], v[76:77], v[2:3] op_sel_hi:[1,0,1]
	s_waitcnt vmcnt(2)
	v_pk_fma_f32 v[6:7], v[60:61], v[14:15], v[2:3] op_sel_hi:[1,0,1]
	v_pk_fma_f32 v[2:3], v[4:5], v[64:65], v[72:73] op_sel_hi:[1,0,1]
	v_add_co_u32_e32 v4, vcc, s29, v50
	v_pk_fma_f32 v[2:3], v[8:9], v[42:43], v[2:3] op_sel_hi:[1,0,1]
	s_nop 0
	v_addc_co_u32_e32 v5, vcc, 0, v51, vcc
	v_pk_fma_f32 v[2:3], v[16:17], v[78:79], v[2:3] op_sel_hi:[1,0,1]
	s_waitcnt lgkmcnt(0)
	v_mov_b32_e32 v42, v41
	v_pk_fma_f32 v[2:3], v[12:13], v[66:67], v[2:3] op_sel_hi:[1,0,1]
	s_waitcnt vmcnt(1)
	v_pk_fma_f32 v[6:7], v[30:31], v[38:39], v[6:7] op_sel_hi:[1,0,1]
	v_pk_fma_f32 v[2:3], v[20:21], v[80:81], v[2:3] op_sel_hi:[1,0,1]
	s_nop 0
	v_pk_fma_f32 v[2:3], v[24:25], v[68:69], v[2:3] op_sel_hi:[1,0,1]
	s_nop 0
	v_pk_fma_f32 v[2:3], v[28:29], v[94:95], v[2:3] op_sel_hi:[1,0,1]
	v_mov_b32_e32 v28, v39
	v_pk_fma_f32 v[2:3], v[48:49], v[74:75], v[2:3] op_sel_hi:[1,0,1]
	s_waitcnt vmcnt(0)
	v_pk_fma_f32 v[6:7], v[34:35], v[28:29], v[6:7] op_sel_hi:[1,0,1]
	v_pk_fma_f32 v[2:3], v[54:55], v[10:11], v[2:3] op_sel_hi:[1,0,1]
	s_nop 0
	v_pk_fma_f32 v[2:3], v[58:59], v[76:77], v[2:3] op_sel_hi:[1,0,1]
	s_nop 0
	v_pk_fma_f32 v[2:3], v[62:63], v[14:15], v[2:3] op_sel_hi:[1,0,1]
	ds_read2_b32 v[14:15], v99 offset0:192 offset1:196
	ds_read2_b32 v[12:13], v99 offset0:200 offset1:204
	ds_read2_b32 v[10:11], v99 offset0:208 offset1:212
	ds_read2_b32 v[8:9], v99 offset0:216 offset1:220
	global_load_dwordx4 v[16:19], v[4:5], off nt
	v_add_co_u32_e32 v4, vcc, s68, v50
	v_pk_fma_f32 v[2:3], v[32:33], v[38:39], v[2:3] op_sel_hi:[1,0,1]
	s_nop 0
	v_addc_co_u32_e32 v5, vcc, 0, v51, vcc
	global_load_dwordx4 v[20:23], v[4:5], off offset:2048 nt
	v_add_co_u32_e32 v4, vcc, s69, v50
	v_pk_fma_f32 v[2:3], v[36:37], v[28:29], v[2:3] op_sel_hi:[1,0,1]
	s_nop 0
	v_addc_co_u32_e32 v5, vcc, 0, v51, vcc
	global_load_dwordx4 v[24:27], v[4:5], off nt
	v_add_co_u32_e32 v4, vcc, s70, v50
	s_waitcnt lgkmcnt(0)
	v_mov_b32_e32 v36, v9
	v_addc_co_u32_e32 v5, vcc, 0, v51, vcc
	global_load_dwordx4 v[46:49], v[4:5], off offset:2048 nt
	v_add_co_u32_e32 v4, vcc, s71, v50
	ds_read2_b32 v[30:31], v99 offset0:224 offset1:228
	s_nop 0
	v_addc_co_u32_e32 v5, vcc, 0, v51, vcc
	global_load_dwordx4 v[52:55], v[4:5], off nt
	v_add_co_u32_e32 v4, vcc, s72, v50
	s_waitcnt vmcnt(4)
	v_pk_fma_f32 v[2:3], v[18:19], v[40:41], v[2:3] op_sel_hi:[1,0,1]
	v_addc_co_u32_e32 v5, vcc, 0, v51, vcc
	global_load_dwordx4 v[56:59], v[4:5], off offset:2048 nt
	v_add_co_u32_e32 v4, vcc, s73, v50
	s_waitcnt vmcnt(4)
	v_pk_fma_f32 v[2:3], v[22:23], v[42:43], v[2:3] op_sel_hi:[1,0,1]
	v_addc_co_u32_e32 v5, vcc, 0, v51, vcc
	global_load_dwordx4 v[60:63], v[4:5], off nt
	v_add_co_u32_e32 v4, vcc, s74, v50
	s_waitcnt vmcnt(4)
	v_pk_fma_f32 v[2:3], v[26:27], v[14:15], v[2:3] op_sel_hi:[1,0,1]
	v_addc_co_u32_e32 v5, vcc, 0, v51, vcc
	global_load_dwordx4 v[64:67], v[4:5], off offset:2048 nt
	v_add_co_u32_e32 v4, vcc, s75, v50
	v_mov_b32_e32 v18, v15
	s_nop 0
	v_addc_co_u32_e32 v5, vcc, 0, v51, vcc
	global_load_dwordx4 v[68:71], v[4:5], off nt
	v_pk_fma_f32 v[6:7], v[16:17], v[40:41], v[6:7] op_sel_hi:[1,0,1]
	s_waitcnt vmcnt(5)
	v_pk_fma_f32 v[2:3], v[48:49], v[18:19], v[2:3] op_sel_hi:[1,0,1]
	v_pk_fma_f32 v[6:7], v[20:21], v[42:43], v[6:7] op_sel_hi:[1,0,1]
	s_waitcnt vmcnt(4)
	v_pk_fma_f32 v[2:3], v[54:55], v[12:13], v[2:3] op_sel_hi:[1,0,1]
	v_mov_b32_e32 v22, v13
	v_pk_fma_f32 v[6:7], v[24:25], v[14:15], v[6:7] op_sel_hi:[1,0,1]
	v_mov_b32_e32 v26, v11
	v_pk_fma_f32 v[6:7], v[46:47], v[18:19], v[6:7] op_sel_hi:[1,0,1]
	s_waitcnt vmcnt(3)
	v_pk_fma_f32 v[2:3], v[58:59], v[22:23], v[2:3] op_sel_hi:[1,0,1]
	v_pk_fma_f32 v[6:7], v[52:53], v[12:13], v[6:7] op_sel_hi:[1,0,1]
	s_waitcnt vmcnt(2)
	v_pk_fma_f32 v[2:3], v[62:63], v[10:11], v[2:3] op_sel_hi:[1,0,1]
	v_pk_fma_f32 v[6:7], v[56:57], v[22:23], v[6:7] op_sel_hi:[1,0,1]
	s_waitcnt vmcnt(1)
; template <int NB>
; __device__ __forceinline__ void sb_decode_task(const Params& P, float* lds, int task) {
;     ...
;     for (int vb = 0; vb < NBT; ++vb) {
;         if (vb + 1 < NBT) {
; #pragma unroll
;             for (int i = 0; i < NB; ++i) nx[i] = *(const float4*)(Vp + (size_t)(4 * NB * (vb + 1) + 4 * i + g) * (SH * HD)); }
; #pragma unroll
;         for (int i = 0; i < NB; ++i) { const float w = wl[4 * NB * vb + 4 * i + g]; o4.x += w * cur[i].x; o4.y += w * cur[i].y; o4.z += w * cur[i].z; o4.w += w * cur[i].w; }
; #pragma unroll
;         for (int i = 0; i < NB; ++i) cur[i] = nx[i];
;     }
; #pragma unroll
;     for (int off = 16; off < 64; off <<= 1) { o4.x += __shfl_xor(o4.x, off); o4.y += __shfl_xor(o4.y, off); o4.z += __shfl_xor(o4.z, off); o4.w += __shfl_xor(o4.w, off); }
;     if (g == 0) *(float4*)(dpart + (size_t)task * HD + 4 * c) = o4;
	v_pk_fma_f32 v[2:3], v[66:67], v[26:27], v[2:3] op_sel_hi:[1,0,1]
	v_pk_fma_f32 v[6:7], v[60:61], v[10:11], v[6:7] op_sel_hi:[1,0,1]
	v_and_b32_e32 v10, 64, v105
	v_pk_fma_f32 v[6:7], v[64:65], v[26:27], v[6:7] op_sel_hi:[1,0,1]
	v_add_u32_e32 v37, 64, v10
	v_xor_b32_e32 v10, 16, v105
	s_waitcnt vmcnt(0)
	v_pk_fma_f32 v[32:33], v[70:71], v[8:9], v[2:3] op_sel_hi:[1,0,1]
	v_add_co_u32_e32 v2, vcc, s80, v50
	v_pk_fma_f32 v[34:35], v[68:69], v[8:9], v[6:7] op_sel_hi:[1,0,1]
	s_nop 0
	v_addc_co_u32_e32 v3, vcc, 0, v51, vcc
	v_add_co_u32_e32 v6, vcc, s81, v50
	global_load_dwordx4 v[2:5], v[2:3], off offset:2048 nt
	s_nop 0
	v_addc_co_u32_e32 v7, vcc, 0, v51, vcc
	v_cmp_lt_i32_e32 vcc, v10, v37
	global_load_dwordx4 v[6:9], v[6:7], off nt
	ds_read2_b32 v[42:43], v99 offset0:232 offset1:236
	ds_read2_b32 v[40:41], v99 offset0:240 offset1:244
	ds_read2_b32 v[38:39], v99 offset0:248 offset1:252
	v_cndmask_b32_e32 v10, v105, v10, vcc
	v_lshlrev_b32_e32 v107, 2, v10
	v_add_co_u32_e32 v10, vcc, s82, v50
	s_waitcnt lgkmcnt(2)
	v_mov_b32_e32 v54, v43
	v_addc_co_u32_e32 v11, vcc, 0, v51, vcc
	v_add_co_u32_e32 v14, vcc, s83, v50
	global_load_dwordx4 v[10:13], v[10:11], off offset:2048 nt
	s_nop 0
	v_addc_co_u32_e32 v15, vcc, 0, v51, vcc
	v_add_co_u32_e32 v18, vcc, s84, v50
	global_load_dwordx4 v[14:17], v[14:15], off nt
	s_nop 0
	v_addc_co_u32_e32 v19, vcc, 0, v51, vcc
	v_add_co_u32_e32 v22, vcc, s85, v50
	global_load_dwordx4 v[18:21], v[18:19], off offset:2048 nt
	s_nop 0
	v_addc_co_u32_e32 v23, vcc, 0, v51, vcc
	v_add_co_u32_e32 v26, vcc, s86, v50
	global_load_dwordx4 v[22:25], v[22:23], off nt
	s_nop 0
	v_addc_co_u32_e32 v27, vcc, 0, v51, vcc
	v_add_co_u32_e32 v46, vcc, s87, v50
	global_load_dwordx4 v[26:29], v[26:27], off offset:2048 nt
	s_nop 0
	v_addc_co_u32_e32 v47, vcc, 0, v51, vcc
	v_add_co_u32_e32 v50, vcc, s88, v50
	global_load_dwordx4 v[46:49], v[46:47], off nt
	s_nop 0
	v_addc_co_u32_e32 v51, vcc, 0, v51, vcc
	global_load_dwordx4 v[50:53], v[50:51], off offset:2048 nt
	s_waitcnt lgkmcnt(1)
	v_mov_b32_e32 v56, v41
	s_waitcnt lgkmcnt(0)
	v_mov_b32_e32 v58, v39
	s_waitcnt vmcnt(8)
	v_pk_fma_f32 v[2:3], v[2:3], v[36:37], v[34:35] op_sel_hi:[1,0,1]
	v_mov_b32_e32 v34, v31
	v_pk_fma_f32 v[4:5], v[4:5], v[36:37], v[32:33] op_sel_hi:[1,0,1]
	s_waitcnt vmcnt(7)
	v_pk_fma_f32 v[2:3], v[6:7], v[30:31], v[2:3] op_sel_hi:[1,0,1]
	v_pk_fma_f32 v[4:5], v[8:9], v[30:31], v[4:5] op_sel_hi:[1,0,1]
	s_waitcnt vmcnt(6)
	v_pk_fma_f32 v[2:3], v[10:11], v[34:35], v[2:3] op_sel_hi:[1,0,1]
	v_pk_fma_f32 v[4:5], v[12:13], v[34:35], v[4:5] op_sel_hi:[1,0,1]
	ds_bpermute_b32 v10, v106, v44
	s_waitcnt vmcnt(5)
	v_pk_fma_f32 v[2:3], v[14:15], v[42:43], v[2:3] op_sel_hi:[1,0,1]
	v_pk_fma_f32 v[4:5], v[16:17], v[42:43], v[4:5] op_sel_hi:[1,0,1]
	s_waitcnt vmcnt(4)
	v_pk_fma_f32 v[2:3], v[18:19], v[54:55], v[2:3] op_sel_hi:[1,0,1]
	v_pk_fma_f32 v[4:5], v[20:21], v[54:55], v[4:5] op_sel_hi:[1,0,1]
	s_waitcnt vmcnt(3)
	v_pk_fma_f32 v[2:3], v[22:23], v[40:41], v[2:3] op_sel_hi:[1,0,1]
	v_pk_fma_f32 v[4:5], v[24:25], v[40:41], v[4:5] op_sel_hi:[1,0,1]
	s_waitcnt vmcnt(2)
	v_pk_fma_f32 v[2:3], v[26:27], v[56:57], v[2:3] op_sel_hi:[1,0,1]
	v_pk_fma_f32 v[4:5], v[28:29], v[56:57], v[4:5] op_sel_hi:[1,0,1]
	s_waitcnt vmcnt(1)
	v_pk_fma_f32 v[2:3], v[46:47], v[38:39], v[2:3] op_sel_hi:[1,0,1]
	v_pk_fma_f32 v[4:5], v[48:49], v[38:39], v[4:5] op_sel_hi:[1,0,1]
	s_waitcnt vmcnt(0)
	v_pk_fma_f32 v[2:3], v[50:51], v[58:59], v[2:3] op_sel_hi:[1,0,1]
	ds_bpermute_b32 v6, v107, v2
	ds_bpermute_b32 v7, v107, v3
	v_pk_fma_f32 v[4:5], v[52:53], v[58:59], v[4:5] op_sel_hi:[1,0,1]
	s_waitcnt lgkmcnt(0)
	v_pk_add_f32 v[2:3], v[2:3], v[6:7]
	ds_bpermute_b32 v6, v107, v4
	ds_bpermute_b32 v7, v107, v5
	s_waitcnt lgkmcnt(0)
	v_pk_add_f32 v[4:5], v[4:5], v[6:7]
	v_xor_b32_e32 v6, 32, v105
	v_cmp_lt_i32_e32 vcc, v6, v37
	s_nop 1
	v_cndmask_b32_e32 v6, v105, v6, vcc
	v_lshlrev_b32_e32 v114, 2, v6
	ds_bpermute_b32 v6, v114, v2
	ds_bpermute_b32 v7, v114, v3
	ds_bpermute_b32 v8, v114, v4
	ds_bpermute_b32 v9, v114, v5
	s_and_saveexec_b64 s[0:1], s[20:21]
	s_cbranch_execz .LBB0_1347
	s_ashr_i32 s35, s34, 31
	s_lshl_b64 s[36:37], s[34:35], 8
	v_lshl_add_u64 v[12:13], v[88:89], 0, s[36:37]
	s_waitcnt lgkmcnt(2)
	v_pk_add_f32 v[2:3], v[2:3], v[6:7]
	s_waitcnt lgkmcnt(0)
	v_pk_add_f32 v[4:5], v[4:5], v[8:9]
	global_store_dwordx4 v[12:13], v[2:5], off

; __device__ __forceinline__ float bf2f(bf16_t b) { return __uint_as_float(((unsigned)b) << 16); }
; template <int NB>
; __device__ __forceinline__ void sb_decode_task(const Params& P, float* lds, int task) {
;     ...
;     constexpr int NBT = 32 / NB;
;     const int h = task % SH, bj = task / SH, b = bj / NPAGES;
;     const int page = P.page_table[bj];
;     const float* Kp = P.cache_k + ((size_t)page * PAGE * SH + h) * HD + 4 * c;
;     const float* Vp = P.cache_v + ((size_t)page * PAGE * SH + h) * HD + 4 * c;
;     const bf16_t* qp = qb + (size_t)(NTOK + b) * SBW + h * 64 + 4 * c;
;     const float q0 = bf2f(qp[0]), q1 = bf2f(qp[1]), q2 = bf2f(qp[2]), q3 = bf2f(qp[3]);
;     const float bias = P.sb_bias[h] * LOG2E;
;     float4 cur[NB], nx[NB];
; #pragma unroll
;     for (int i = 0; i < NB; ++i) cur[i] = *(const float4*)(Kp + (size_t)(4 * i + g) * (SH * HD));
; #pragma unroll
;     for (int kb = 0; kb < NBT; ++kb) {
;         const float* np = (kb + 1 < NBT) ? Kp + (size_t)(4 * NB * (kb + 1)) * (SH * HD) : Vp;
; #pragma unroll
;         for (int i = 0; i < NB; ++i) nx[i] = *(const float4*)(np + (size_t)(4 * i + g) * (SH * HD));
; #pragma unroll
;         for (int i = 0; i < NB; ++i) { const int s = 4 * NB * kb + 4 * i + g;
;             float part = q0 * cur[i].x + q1 * cur[i].y + q2 * cur[i].z + q3 * cur[i].w; part = sum16(part);
;             if (c == 0) zl[s] = part + bias; }
.LBB0_1349:
	s_or_b64 exec, exec, s[0:1]
	v_readlane_b32 s30, v252, 48
	s_add_i32 s36, s34, 1
	v_readlane_b32 s31, v252, 49
	s_mul_hi_i32 s1, s36, 0x2aaaaaab
	s_load_dwordx16 s[52:67], s[30:31], 0x0
	s_lshr_b32 s3, s1, 31
	s_add_i32 s0, s1, s3
	s_ashr_i32 s1, s1, 7
	s_mul_i32 s33, s0, 6
	s_add_i32 s3, s1, s3
	s_ashr_i32 s1, s0, 31
	s_sub_i32 s90, s36, s33
	s_lshl_b64 s[0:1], s[0:1], 2
	s_waitcnt lgkmcnt(0)
	s_add_u32 s0, s62, s0
	s_addc_u32 s1, s63, s1
	v_mov_b32_e32 v2, v253
	s_add_i32 s0, s3, 0x4000
	s_ashr_i32 s91, s90, 31
	s_mul_hi_i32 s1, s0, 0x300
	s_mulk_i32 s0, 0x300
	s_add_u32 s3, s38, s0
	s_addc_u32 s33, s39, s1
	s_lshl_b32 s0, s90, 6
	s_ashr_i32 s1, s0, 31
	s_lshl_b64 s[0:1], s[0:1], 1
	s_add_u32 s0, s3, s0
	s_addc_u32 s1, s33, s1
	v_readlane_b32 s52, v252, 16
	v_readlane_b32 s53, v252, 17
	v_readlane_b32 s60, v252, 24
	v_readlane_b32 s61, v252, 25
	s_mov_b64 s[52:53], s[60:61]
	v_mov_b32_e32 v93, v83
	v_readlane_b32 s54, v252, 18
	v_readlane_b32 s55, v252, 19
	v_readlane_b32 s56, v252, 20
	v_readlane_b32 s57, v252, 21
	v_readlane_b32 s58, v252, 22
	v_readlane_b32 s59, v252, 23
	v_readlane_b32 s62, v252, 26
	v_readlane_b32 s63, v252, 27
	v_readlane_b32 s64, v252, 28
	v_readlane_b32 s65, v252, 29
	v_readlane_b32 s66, v252, 30
	v_readlane_b32 s67, v252, 31
	v_mul_hi_i32 v3, v2, s48
	v_mul_lo_u32 v2, v2, s48
	v_lshl_add_u64 v[94:95], v[2:3], 0, s[90:91]
	v_lshlrev_b64 v[2:3], 8, v[94:95]
	v_lshl_add_u64 v[70:71], v[84:85], 0, v[2:3]
	global_load_dwordx2 v[2:3], v101, s[0:1]
	s_lshl_b64 s[0:1], s[90:91], 2
	s_add_u32 s0, s52, s0
	s_addc_u32 s1, s53, s1
	global_load_dword v22, v83, s[0:1]
	v_lshl_add_u64 v[18:19], v[70:71], 0, v[82:83]
	v_lshl_add_u64 v[20:21], v[70:71], 0, v[92:93]
	global_load_dwordx4 v[14:17], v[18:19], off nt
	s_mov_b64 s[0:1], 0xc000
	global_load_dwordx4 v[62:65], v[20:21], off nt
	s_waitcnt vmcnt(3)
	v_lshlrev_b32_e32 v116, 16, v2
	v_and_b32_e32 v118, 0xffff0000, v2
	v_add_co_u32_e32 v2, vcc, s50, v18
	v_lshlrev_b32_e32 v117, 16, v3
	v_and_b32_e32 v115, 0xffff0000, v3
	v_addc_co_u32_e32 v3, vcc, 0, v19, vcc
	global_load_dwordx4 v[10:13], v[2:3], off offset:2048 nt
	v_add_co_u32_e32 v2, vcc, s51, v18
	s_waitcnt vmcnt(3)
	v_mul_f32_e32 v119, 0x3fb8aa3b, v22
	v_addc_co_u32_e32 v3, vcc, 0, v19, vcc
	global_load_dwordx4 v[6:9], v[2:3], off nt
	v_add_co_u32_e32 v2, vcc, s49, v18
	v_lshl_add_u64 v[22:23], v[70:71], 0, s[0:1]
	s_nop 0
	v_addc_co_u32_e32 v3, vcc, 0, v19, vcc
	v_add_co_u32_e32 v20, vcc, s92, v18
	v_lshl_add_u64 v[30:31], v[22:23], 0, v[82:83]
	s_nop 0
	v_addc_co_u32_e32 v21, vcc, 0, v19, vcc
	global_load_dwordx4 v[58:61], v[20:21], off offset:2048 nt
	v_add_co_u32_e32 v20, vcc, s93, v18
	v_lshl_add_u64 v[22:23], v[22:23], 0, v[92:93]
	s_nop 0
	v_addc_co_u32_e32 v21, vcc, 0, v19, vcc
	v_add_co_u32_e32 v18, vcc, s96, v18
	global_load_dwordx4 v[54:57], v[20:21], off nt
	s_nop 0
	v_addc_co_u32_e32 v19, vcc, 0, v19, vcc
	global_load_dwordx4 v[50:53], v[18:19], off offset:2048 nt
	v_add_co_u32_e32 v18, vcc, s50, v30
	global_load_dwordx4 v[22:25], v[22:23], off nt
	s_nop 0
	v_addc_co_u32_e32 v19, vcc, 0, v31, vcc
	global_load_dwordx4 v[34:37], v[18:19], off offset:2048 nt
	v_add_co_u32_e32 v18, vcc, s51, v30
	global_load_dwordx4 v[2:5], v[2:3], off offset:2048 nt
	s_nop 0
	v_addc_co_u32_e32 v19, vcc, 0, v31, vcc
	global_load_dwordx4 v[26:29], v[18:19], off nt
	v_add_co_u32_e32 v18, vcc, s49, v30
	global_load_dwordx4 v[46:49], v[30:31], off nt
	s_nop 0
	v_addc_co_u32_e32 v19, vcc, 0, v31, vcc
	v_add_co_u32_e32 v32, vcc, s92, v30
	global_load_dwordx4 v[18:21], v[18:19], off offset:2048 nt
	s_nop 0
	v_addc_co_u32_e32 v33, vcc, 0, v31, vcc
	global_load_dwordx4 v[38:41], v[32:33], off offset:2048 nt
	v_add_co_u32_e32 v32, vcc, s93, v30
	s_waitcnt vmcnt(13)
	v_mul_f32_e32 v15, v15, v118
	v_addc_co_u32_e32 v33, vcc, 0, v31, vcc
	v_add_co_u32_e32 v30, vcc, s96, v30
	global_load_dwordx4 v[42:45], v[32:33], off nt
	s_nop 0
	v_addc_co_u32_e32 v31, vcc, 0, v31, vcc
	global_load_dwordx4 v[30:33], v[30:31], off offset:2048 nt
	v_fmac_f32_e32 v15, v14, v116
	v_fmac_f32_e32 v15, v16, v117
	v_fmac_f32_e32 v15, v17, v115
	s_nop 1
	v_add_f32_dpp v14, v15, v15 quad_perm:[1,0,3,2] row_mask:0xf bank_mask:0xf bound_ctrl:1
	s_nop 1
	v_add_f32_dpp v14, v14, v14 quad_perm:[2,3,0,1] row_mask:0xf bank_mask:0xf bound_ctrl:1
	s_nop 1
	v_add_f32_dpp v14, v14, v14 row_ror:4 row_mask:0xf bank_mask:0xf bound_ctrl:1
	s_nop 1
	v_mov_b32_dpp v15, v14 row_ror:8 row_mask:0xf bank_mask:0xf bound_ctrl:1
	s_and_saveexec_b64 s[0:1], s[6:7]
	v_add_f32_e32 v14, v14, v15
	v_add_f32_e32 v14, v119, v14
	ds_write_b32 v99, v14
	s_or_b64 exec, exec, s[0:1]
	s_waitcnt vmcnt(13)
	v_mul_f32_e32 v11, v11, v118
	v_fmac_f32_e32 v11, v10, v116
	v_fmac_f32_e32 v11, v12, v117
	v_fmac_f32_e32 v11, v13, v115
	s_nop 1
	v_add_f32_dpp v10, v11, v11 quad_perm:[1,0,3,2] row_mask:0xf bank_mask:0xf bound_ctrl:1
	s_nop 1
	v_add_f32_dpp v10, v10, v10 quad_perm:[2,3,0,1] row_mask:0xf bank_mask:0xf bound_ctrl:1
	s_nop 1
	v_add_f32_dpp v10, v10, v10 row_ror:4 row_mask:0xf bank_mask:0xf bound_ctrl:1
	s_nop 1
	v_mov_b32_dpp v11, v10 row_ror:8 row_mask:0xf bank_mask:0xf bound_ctrl:1
	s_and_saveexec_b64 s[0:1], s[6:7]
	v_add_f32_e32 v10, v10, v11
	v_add_f32_e32 v10, v119, v10
	ds_write_b32 v99, v10 offset:16
	s_or_b64 exec, exec, s[0:1]
	s_waitcnt vmcnt(12)
	v_mul_f32_e32 v7, v7, v118
	v_fmac_f32_e32 v7, v6, v116
	v_fmac_f32_e32 v7, v8, v117
	v_fmac_f32_e32 v7, v9, v115
	s_nop 1
	v_add_f32_dpp v6, v7, v7 quad_perm:[1,0,3,2] row_mask:0xf bank_mask:0xf bound_ctrl:1
	s_nop 1
	v_add_f32_dpp v6, v6, v6 quad_perm:[2,3,0,1] row_mask:0xf bank_mask:0xf bound_ctrl:1
	s_nop 1
	v_add_f32_dpp v6, v6, v6 row_ror:4 row_mask:0xf bank_mask:0xf bound_ctrl:1
	s_nop 1
	v_mov_b32_dpp v7, v6 row_ror:8 row_mask:0xf bank_mask:0xf bound_ctrl:1
	s_and_saveexec_b64 s[0:1], s[6:7]
	v_add_f32_e32 v6, v6, v7
	v_add_f32_e32 v6, v119, v6
	ds_write_b32 v99, v6 offset:32
	s_or_b64 exec, exec, s[0:1]
	s_waitcnt vmcnt(6)
; template <int NB>
; __device__ __forceinline__ void sb_decode_task(const Params& P, float* lds, int task) {
;     ...
;     for (int kb = 0; kb < NBT; ++kb) {
;         const float* np = (kb + 1 < NBT) ? Kp + (size_t)(4 * NB * (kb + 1)) * (SH * HD) : Vp;
; #pragma unroll
;         for (int i = 0; i < NB; ++i) nx[i] = *(const float4*)(np + (size_t)(4 * i + g) * (SH * HD));
; #pragma unroll
;         for (int i = 0; i < NB; ++i) { const int s = 4 * NB * kb + 4 * i + g;
;             float part = q0 * cur[i].x + q1 * cur[i].y + q2 * cur[i].z + q3 * cur[i].w; part = sum16(part);
;             if (c == 0) zl[s] = part + bias; }
	v_mul_f32_e32 v3, v3, v118
	v_fmac_f32_e32 v3, v2, v116
	v_fmac_f32_e32 v3, v4, v117
	v_fmac_f32_e32 v3, v5, v115
	s_nop 1
	v_add_f32_dpp v2, v3, v3 quad_perm:[1,0,3,2] row_mask:0xf bank_mask:0xf bound_ctrl:1
	s_nop 1
	v_add_f32_dpp v2, v2, v2 quad_perm:[2,3,0,1] row_mask:0xf bank_mask:0xf bound_ctrl:1
	s_nop 1
	v_add_f32_dpp v2, v2, v2 row_ror:4 row_mask:0xf bank_mask:0xf bound_ctrl:1
	s_nop 1
	v_mov_b32_dpp v3, v2 row_ror:8 row_mask:0xf bank_mask:0xf bound_ctrl:1
	s_and_saveexec_b64 s[0:1], s[6:7]
	v_add_f32_e32 v2, v2, v3
	v_add_f32_e32 v2, v119, v2
	ds_write_b32 v99, v2 offset:48
	s_or_b64 exec, exec, s[0:1]
	v_mul_f32_e32 v2, v63, v118
	v_fmac_f32_e32 v2, v62, v116
	v_fmac_f32_e32 v2, v64, v117
	v_fmac_f32_e32 v2, v65, v115
	s_nop 1
	v_add_f32_dpp v2, v2, v2 quad_perm:[1,0,3,2] row_mask:0xf bank_mask:0xf bound_ctrl:1
	s_nop 1
	v_add_f32_dpp v2, v2, v2 quad_perm:[2,3,0,1] row_mask:0xf bank_mask:0xf bound_ctrl:1
	s_nop 1
	v_add_f32_dpp v2, v2, v2 row_ror:4 row_mask:0xf bank_mask:0xf bound_ctrl:1
	s_nop 1
	v_mov_b32_dpp v3, v2 row_ror:8 row_mask:0xf bank_mask:0xf bound_ctrl:1
	s_and_saveexec_b64 s[0:1], s[6:7]
	v_add_f32_e32 v2, v2, v3
	v_add_f32_e32 v2, v119, v2
	ds_write_b32 v99, v2 offset:64
	s_or_b64 exec, exec, s[0:1]
	v_mul_f32_e32 v2, v59, v118
	v_fmac_f32_e32 v2, v58, v116
	v_fmac_f32_e32 v2, v60, v117
	v_fmac_f32_e32 v2, v61, v115
	s_nop 1
	v_add_f32_dpp v2, v2, v2 quad_perm:[1,0,3,2] row_mask:0xf bank_mask:0xf bound_ctrl:1
	s_nop 1
	v_add_f32_dpp v2, v2, v2 quad_perm:[2,3,0,1] row_mask:0xf bank_mask:0xf bound_ctrl:1
	s_nop 1
	v_add_f32_dpp v2, v2, v2 row_ror:4 row_mask:0xf bank_mask:0xf bound_ctrl:1
	s_nop 1
	v_mov_b32_dpp v3, v2 row_ror:8 row_mask:0xf bank_mask:0xf bound_ctrl:1
	s_and_saveexec_b64 s[0:1], s[6:7]
	v_add_f32_e32 v2, v2, v3
	v_add_f32_e32 v2, v119, v2
	ds_write_b32 v99, v2 offset:80
	s_or_b64 exec, exec, s[0:1]
	v_mul_f32_e32 v2, v55, v118
	v_fmac_f32_e32 v2, v54, v116
	v_fmac_f32_e32 v2, v56, v117
	v_fmac_f32_e32 v2, v57, v115
	s_nop 1
	v_add_f32_dpp v2, v2, v2 quad_perm:[1,0,3,2] row_mask:0xf bank_mask:0xf bound_ctrl:1
	s_nop 1
	v_add_f32_dpp v2, v2, v2 quad_perm:[2,3,0,1] row_mask:0xf bank_mask:0xf bound_ctrl:1
	s_nop 1
	v_add_f32_dpp v2, v2, v2 row_ror:4 row_mask:0xf bank_mask:0xf bound_ctrl:1
	s_nop 1
	v_mov_b32_dpp v3, v2 row_ror:8 row_mask:0xf bank_mask:0xf bound_ctrl:1
	s_and_saveexec_b64 s[0:1], s[6:7]
	v_add_f32_e32 v2, v2, v3
	v_add_f32_e32 v2, v119, v2
	ds_write_b32 v99, v2 offset:96
	s_or_b64 exec, exec, s[0:1]
	v_mul_f32_e32 v2, v51, v118
	v_fmac_f32_e32 v2, v50, v116
	v_fmac_f32_e32 v2, v52, v117
	v_fmac_f32_e32 v2, v53, v115
	s_nop 1
	v_add_f32_dpp v2, v2, v2 quad_perm:[1,0,3,2] row_mask:0xf bank_mask:0xf bound_ctrl:1
	s_nop 1
	v_add_f32_dpp v2, v2, v2 quad_perm:[2,3,0,1] row_mask:0xf bank_mask:0xf bound_ctrl:1
	s_nop 1
	v_add_f32_dpp v2, v2, v2 row_ror:4 row_mask:0xf bank_mask:0xf bound_ctrl:1
	s_nop 1
	v_mov_b32_dpp v3, v2 row_ror:8 row_mask:0xf bank_mask:0xf bound_ctrl:1
	s_and_saveexec_b64 s[0:1], s[6:7]
	v_add_f32_e32 v2, v2, v3
	v_add_f32_e32 v2, v119, v2
	ds_write_b32 v99, v2 offset:112
	s_or_b64 exec, exec, s[0:1]
	s_mov_b64 s[0:1], 0x18000
	v_lshl_add_u64 v[2:3], v[70:71], 0, s[0:1]
	v_lshl_add_u64 v[4:5], v[2:3], 0, v[82:83]
	v_add_co_u32_e32 v6, vcc, 0x1000, v4
	v_mov_b32_e32 v93, v83
	s_nop 0
	v_addc_co_u32_e32 v7, vcc, 0, v5, vcc
	global_load_dwordx4 v[74:77], v[4:5], off nt
	global_load_dwordx4 v[66:69], v[6:7], off offset:2048 nt
	v_add_co_u32_e32 v6, vcc, 0x3000, v4
	v_lshl_add_u64 v[2:3], v[2:3], 0, v[92:93]
	s_nop 0
	v_addc_co_u32_e32 v7, vcc, 0, v5, vcc
	v_add_co_u32_e32 v8, vcc, s49, v4
	s_waitcnt vmcnt(6)
	v_mul_f32_e32 v47, v47, v118
	v_addc_co_u32_e32 v9, vcc, 0, v5, vcc
	global_load_dwordx4 v[58:61], v[6:7], off nt
	global_load_dwordx4 v[50:53], v[8:9], off offset:2048 nt
	v_add_co_u32_e32 v6, vcc, 0x7000, v4
	v_fmac_f32_e32 v47, v46, v116
	s_nop 0
	v_addc_co_u32_e32 v7, vcc, 0, v5, vcc
	global_load_dwordx4 v[14:17], v[2:3], off nt
	global_load_dwordx4 v[10:13], v[6:7], off offset:2048 nt
	v_add_co_u32_e32 v2, vcc, 0x9000, v4
	v_fmac_f32_e32 v47, v48, v117
	s_nop 0
	v_addc_co_u32_e32 v3, vcc, 0, v5, vcc
	v_add_co_u32_e32 v4, vcc, 0xa000, v4
	v_fmac_f32_e32 v47, v49, v115
	s_nop 0
	v_addc_co_u32_e32 v5, vcc, 0, v5, vcc
	global_load_dwordx4 v[6:9], v[2:3], off nt
	s_nop 0
	global_load_dwordx4 v[2:5], v[4:5], off offset:2048 nt
	v_add_f32_dpp v46, v47, v47 quad_perm:[1,0,3,2] row_mask:0xf bank_mask:0xf bound_ctrl:1
	s_nop 1
	v_add_f32_dpp v46, v46, v46 quad_perm:[2,3,0,1] row_mask:0xf bank_mask:0xf bound_ctrl:1
	s_nop 1
	v_add_f32_dpp v46, v46, v46 row_ror:4 row_mask:0xf bank_mask:0xf bound_ctrl:1
	s_nop 1
	v_mov_b32_dpp v47, v46 row_ror:8 row_mask:0xf bank_mask:0xf bound_ctrl:1
	s_and_saveexec_b64 s[0:1], s[6:7]
	v_add_f32_e32 v46, v46, v47
	v_add_f32_e32 v46, v119, v46
	ds_write_b32 v99, v46 offset:128
	s_or_b64 exec, exec, s[0:1]
	v_mul_f32_e32 v35, v35, v118
	v_fmac_f32_e32 v35, v34, v116
	v_fmac_f32_e32 v35, v36, v117
	v_fmac_f32_e32 v35, v37, v115
	s_nop 1
	v_add_f32_dpp v34, v35, v35 quad_perm:[1,0,3,2] row_mask:0xf bank_mask:0xf bound_ctrl:1
	s_nop 1
	v_add_f32_dpp v34, v34, v34 quad_perm:[2,3,0,1] row_mask:0xf bank_mask:0xf bound_ctrl:1
	s_nop 1
	v_add_f32_dpp v34, v34, v34 row_ror:4 row_mask:0xf bank_mask:0xf bound_ctrl:1
	s_nop 1
	v_mov_b32_dpp v35, v34 row_ror:8 row_mask:0xf bank_mask:0xf bound_ctrl:1
	s_and_saveexec_b64 s[0:1], s[6:7]
	v_add_f32_e32 v34, v34, v35
	v_add_f32_e32 v34, v119, v34
	ds_write_b32 v99, v34 offset:144
	s_or_b64 exec, exec, s[0:1]
	v_mul_f32_e32 v27, v27, v118
	v_fmac_f32_e32 v27, v26, v116
	v_fmac_f32_e32 v27, v28, v117
	v_fmac_f32_e32 v27, v29, v115
	s_nop 1
	v_add_f32_dpp v26, v27, v27 quad_perm:[1,0,3,2] row_mask:0xf bank_mask:0xf bound_ctrl:1
	s_nop 1
	v_add_f32_dpp v26, v26, v26 quad_perm:[2,3,0,1] row_mask:0xf bank_mask:0xf bound_ctrl:1
	s_nop 1
	v_add_f32_dpp v26, v26, v26 row_ror:4 row_mask:0xf bank_mask:0xf bound_ctrl:1
	s_nop 1
	v_mov_b32_dpp v27, v26 row_ror:8 row_mask:0xf bank_mask:0xf bound_ctrl:1
	s_and_saveexec_b64 s[0:1], s[6:7]
	v_add_f32_e32 v26, v26, v27
	v_add_f32_e32 v26, v119, v26
	ds_write_b32 v99, v26 offset:160
	s_or_b64 exec, exec, s[0:1]
	s_waitcnt vmcnt(11)
; template <int NB>
; __device__ __forceinline__ void sb_decode_task(const Params& P, float* lds, int task) {
;     ...
;     for (int kb = 0; kb < NBT; ++kb) {
;         const float* np = (kb + 1 < NBT) ? Kp + (size_t)(4 * NB * (kb + 1)) * (SH * HD) : Vp;
; #pragma unroll
;         for (int i = 0; i < NB; ++i) nx[i] = *(const float4*)(np + (size_t)(4 * i + g) * (SH * HD));
; #pragma unroll
;         for (int i = 0; i < NB; ++i) { const int s = 4 * NB * kb + 4 * i + g;
;             float part = q0 * cur[i].x + q1 * cur[i].y + q2 * cur[i].z + q3 * cur[i].w; part = sum16(part);
;             if (c == 0) zl[s] = part + bias; }
; #pragma unroll
;         for (int i = 0; i < NB; ++i) cur[i] = nx[i];
;     }
	v_mul_f32_e32 v19, v19, v118
	v_fmac_f32_e32 v19, v18, v116
	v_fmac_f32_e32 v19, v20, v117
	v_fmac_f32_e32 v19, v21, v115
	s_nop 1
	v_add_f32_dpp v18, v19, v19 quad_perm:[1,0,3,2] row_mask:0xf bank_mask:0xf bound_ctrl:1
	s_nop 1
	v_add_f32_dpp v18, v18, v18 quad_perm:[2,3,0,1] row_mask:0xf bank_mask:0xf bound_ctrl:1
	s_nop 1
	v_add_f32_dpp v18, v18, v18 row_ror:4 row_mask:0xf bank_mask:0xf bound_ctrl:1
	s_nop 1
	v_mov_b32_dpp v19, v18 row_ror:8 row_mask:0xf bank_mask:0xf bound_ctrl:1
	s_and_saveexec_b64 s[0:1], s[6:7]
	v_add_f32_e32 v18, v18, v19
	v_add_f32_e32 v18, v119, v18
	ds_write_b32 v99, v18 offset:176
	s_or_b64 exec, exec, s[0:1]
	v_mul_f32_e32 v18, v23, v118
	v_fmac_f32_e32 v18, v22, v116
	v_fmac_f32_e32 v18, v24, v117
	v_fmac_f32_e32 v18, v25, v115
	s_nop 1
	v_add_f32_dpp v18, v18, v18 quad_perm:[1,0,3,2] row_mask:0xf bank_mask:0xf bound_ctrl:1
	s_nop 1
	v_add_f32_dpp v18, v18, v18 quad_perm:[2,3,0,1] row_mask:0xf bank_mask:0xf bound_ctrl:1
	s_nop 1
	v_add_f32_dpp v18, v18, v18 row_ror:4 row_mask:0xf bank_mask:0xf bound_ctrl:1
	s_nop 1
	v_mov_b32_dpp v19, v18 row_ror:8 row_mask:0xf bank_mask:0xf bound_ctrl:1
	s_and_saveexec_b64 s[0:1], s[6:7]
	v_add_f32_e32 v18, v18, v19
	v_add_f32_e32 v18, v119, v18
	ds_write_b32 v99, v18 offset:192
	s_or_b64 exec, exec, s[0:1]
	s_waitcnt vmcnt(10)
	v_mul_f32_e32 v18, v39, v118
	v_fmac_f32_e32 v18, v38, v116
	v_fmac_f32_e32 v18, v40, v117
	v_fmac_f32_e32 v18, v41, v115
	s_nop 1
	v_add_f32_dpp v18, v18, v18 quad_perm:[1,0,3,2] row_mask:0xf bank_mask:0xf bound_ctrl:1
	s_nop 1
	v_add_f32_dpp v18, v18, v18 quad_perm:[2,3,0,1] row_mask:0xf bank_mask:0xf bound_ctrl:1
	s_nop 1
	v_add_f32_dpp v18, v18, v18 row_ror:4 row_mask:0xf bank_mask:0xf bound_ctrl:1
	s_nop 1
	v_mov_b32_dpp v19, v18 row_ror:8 row_mask:0xf bank_mask:0xf bound_ctrl:1
	s_and_saveexec_b64 s[0:1], s[6:7]
	v_add_f32_e32 v18, v18, v19
	v_add_f32_e32 v18, v119, v18
	ds_write_b32 v99, v18 offset:208
	s_or_b64 exec, exec, s[0:1]
	s_waitcnt vmcnt(9)
	v_mul_f32_e32 v18, v43, v118
	v_fmac_f32_e32 v18, v42, v116
	v_fmac_f32_e32 v18, v44, v117
	v_fmac_f32_e32 v18, v45, v115
	s_nop 1
	v_add_f32_dpp v18, v18, v18 quad_perm:[1,0,3,2] row_mask:0xf bank_mask:0xf bound_ctrl:1
	s_nop 1
	v_add_f32_dpp v18, v18, v18 quad_perm:[2,3,0,1] row_mask:0xf bank_mask:0xf bound_ctrl:1
	s_nop 1
	v_add_f32_dpp v18, v18, v18 row_ror:4 row_mask:0xf bank_mask:0xf bound_ctrl:1
	s_nop 1
	v_mov_b32_dpp v19, v18 row_ror:8 row_mask:0xf bank_mask:0xf bound_ctrl:1
	s_and_saveexec_b64 s[0:1], s[6:7]
	v_add_f32_e32 v18, v18, v19
	v_add_f32_e32 v18, v119, v18
	ds_write_b32 v99, v18 offset:224
	s_or_b64 exec, exec, s[0:1]
	s_waitcnt vmcnt(8)
	v_mul_f32_e32 v18, v31, v118
	v_fmac_f32_e32 v18, v30, v116
	v_fmac_f32_e32 v18, v32, v117
	v_fmac_f32_e32 v18, v33, v115
	s_nop 1
	v_add_f32_dpp v18, v18, v18 quad_perm:[1,0,3,2] row_mask:0xf bank_mask:0xf bound_ctrl:1
	s_nop 1
	v_add_f32_dpp v18, v18, v18 quad_perm:[2,3,0,1] row_mask:0xf bank_mask:0xf bound_ctrl:1
	s_nop 1
	v_add_f32_dpp v18, v18, v18 row_ror:4 row_mask:0xf bank_mask:0xf bound_ctrl:1
	s_nop 1
	v_mov_b32_dpp v19, v18 row_ror:8 row_mask:0xf bank_mask:0xf bound_ctrl:1
	s_and_saveexec_b64 s[0:1], s[6:7]
	v_add_f32_e32 v18, v18, v19
	v_add_f32_e32 v18, v119, v18
	ds_write_b32 v99, v18 offset:240
	s_or_b64 exec, exec, s[0:1]
	s_mov_b64 s[0:1], 0x24000
	v_lshl_add_u64 v[18:19], v[70:71], 0, s[0:1]
	v_lshl_add_u64 v[20:21], v[18:19], 0, v[82:83]
	v_add_co_u32_e32 v22, vcc, 0x1000, v20
	v_mov_b32_e32 v93, v83
	s_nop 0
	v_addc_co_u32_e32 v23, vcc, 0, v21, vcc
	global_load_dwordx4 v[78:81], v[20:21], off nt
	global_load_dwordx4 v[70:73], v[22:23], off offset:2048 nt
	v_add_co_u32_e32 v22, vcc, 0x3000, v20
	v_lshl_add_u64 v[18:19], v[18:19], 0, v[92:93]
	s_nop 0
	v_addc_co_u32_e32 v23, vcc, 0, v21, vcc
	v_add_co_u32_e32 v24, vcc, s49, v20
	s_nop 1
	v_addc_co_u32_e32 v25, vcc, 0, v21, vcc
	global_load_dwordx4 v[62:65], v[22:23], off nt
	global_load_dwordx4 v[54:57], v[24:25], off offset:2048 nt
	v_add_co_u32_e32 v22, vcc, 0x7000, v20
	s_nop 1
	v_addc_co_u32_e32 v23, vcc, 0, v21, vcc
	global_load_dwordx4 v[46:49], v[18:19], off nt
	global_load_dwordx4 v[42:45], v[22:23], off offset:2048 nt
	v_add_co_u32_e32 v18, vcc, 0x9000, v20
	s_nop 1
	v_addc_co_u32_e32 v19, vcc, 0, v21, vcc
	v_add_co_u32_e32 v20, vcc, 0xa000, v20
	s_nop 1
	v_addc_co_u32_e32 v21, vcc, 0, v21, vcc
	global_load_dwordx4 v[38:41], v[18:19], off nt
	global_load_dwordx4 v[34:37], v[20:21], off offset:2048 nt
	s_waitcnt vmcnt(15)
	v_mul_f32_e32 v18, v75, v118
	v_fmac_f32_e32 v18, v74, v116
	v_fmac_f32_e32 v18, v76, v117
	v_fmac_f32_e32 v18, v77, v115
	s_nop 1
	v_add_f32_dpp v18, v18, v18 quad_perm:[1,0,3,2] row_mask:0xf bank_mask:0xf bound_ctrl:1
	s_nop 1
	v_add_f32_dpp v18, v18, v18 quad_perm:[2,3,0,1] row_mask:0xf bank_mask:0xf bound_ctrl:1
	s_nop 1
	v_add_f32_dpp v18, v18, v18 row_ror:4 row_mask:0xf bank_mask:0xf bound_ctrl:1
	s_nop 1
	v_mov_b32_dpp v19, v18 row_ror:8 row_mask:0xf bank_mask:0xf bound_ctrl:1
	s_and_saveexec_b64 s[0:1], s[6:7]
	v_add_f32_e32 v18, v18, v19
	v_add_f32_e32 v18, v119, v18
	ds_write_b32 v99, v18 offset:256
	s_or_b64 exec, exec, s[0:1]
	s_waitcnt vmcnt(14)
	v_mul_f32_e32 v18, v67, v118
	v_fmac_f32_e32 v18, v66, v116
	v_fmac_f32_e32 v18, v68, v117
	v_fmac_f32_e32 v18, v69, v115
	s_nop 1
	v_add_f32_dpp v18, v18, v18 quad_perm:[1,0,3,2] row_mask:0xf bank_mask:0xf bound_ctrl:1
	s_nop 1
	v_add_f32_dpp v18, v18, v18 quad_perm:[2,3,0,1] row_mask:0xf bank_mask:0xf bound_ctrl:1
	s_nop 1
	v_add_f32_dpp v18, v18, v18 row_ror:4 row_mask:0xf bank_mask:0xf bound_ctrl:1
	s_nop 1
	v_mov_b32_dpp v19, v18 row_ror:8 row_mask:0xf bank_mask:0xf bound_ctrl:1
	s_and_saveexec_b64 s[0:1], s[6:7]
	v_add_f32_e32 v18, v18, v19
	v_add_f32_e32 v18, v119, v18
	ds_write_b32 v99, v18 offset:272
	s_or_b64 exec, exec, s[0:1]
	s_waitcnt vmcnt(13)
; template <int NB>
; __device__ __forceinline__ void sb_decode_task(const Params& P, float* lds, int task) {
;     ...
;     for (int kb = 0; kb < NBT; ++kb) {
;         const float* np = (kb + 1 < NBT) ? Kp + (size_t)(4 * NB * (kb + 1)) * (SH * HD) : Vp;
; #pragma unroll
;         for (int i = 0; i < NB; ++i) nx[i] = *(const float4*)(np + (size_t)(4 * i + g) * (SH * HD));
; #pragma unroll
;         for (int i = 0; i < NB; ++i) { const int s = 4 * NB * kb + 4 * i + g;
;             float part = q0 * cur[i].x + q1 * cur[i].y + q2 * cur[i].z + q3 * cur[i].w; part = sum16(part);
;             if (c == 0) zl[s] = part + bias; }
; #pragma unroll
;         for (int i = 0; i < NB; ++i) cur[i] = nx[i];
;     }
;     ...
;     for (int vb = 0; vb < NBT; ++vb) {
;         if (vb + 1 < NBT) {
; #pragma unroll
;             for (int i = 0; i < NB; ++i) nx[i] = *(const float4*)(Vp + (size_t)(4 * NB * (vb + 1) + 4 * i + g) * (SH * HD)); }
	v_mul_f32_e32 v18, v59, v118
	v_fmac_f32_e32 v18, v58, v116
	v_fmac_f32_e32 v18, v60, v117
	v_fmac_f32_e32 v18, v61, v115
	s_nop 1
	v_add_f32_dpp v18, v18, v18 quad_perm:[1,0,3,2] row_mask:0xf bank_mask:0xf bound_ctrl:1
	s_nop 1
	v_add_f32_dpp v18, v18, v18 quad_perm:[2,3,0,1] row_mask:0xf bank_mask:0xf bound_ctrl:1
	s_nop 1
	v_add_f32_dpp v18, v18, v18 row_ror:4 row_mask:0xf bank_mask:0xf bound_ctrl:1
	s_nop 1
	v_mov_b32_dpp v19, v18 row_ror:8 row_mask:0xf bank_mask:0xf bound_ctrl:1
	s_and_saveexec_b64 s[0:1], s[6:7]
	v_add_f32_e32 v18, v18, v19
	v_add_f32_e32 v18, v119, v18
	ds_write_b32 v99, v18 offset:288
	s_or_b64 exec, exec, s[0:1]
	s_waitcnt vmcnt(12)
	v_mul_f32_e32 v18, v51, v118
	v_fmac_f32_e32 v18, v50, v116
	v_fmac_f32_e32 v18, v52, v117
	v_fmac_f32_e32 v18, v53, v115
	s_nop 1
	v_add_f32_dpp v18, v18, v18 quad_perm:[1,0,3,2] row_mask:0xf bank_mask:0xf bound_ctrl:1
	s_nop 1
	v_add_f32_dpp v18, v18, v18 quad_perm:[2,3,0,1] row_mask:0xf bank_mask:0xf bound_ctrl:1
	s_nop 1
	v_add_f32_dpp v18, v18, v18 row_ror:4 row_mask:0xf bank_mask:0xf bound_ctrl:1
	s_nop 1
	v_mov_b32_dpp v19, v18 row_ror:8 row_mask:0xf bank_mask:0xf bound_ctrl:1
	s_and_saveexec_b64 s[0:1], s[6:7]
	v_add_f32_e32 v18, v18, v19
	v_add_f32_e32 v18, v119, v18
	ds_write_b32 v99, v18 offset:304
	s_or_b64 exec, exec, s[0:1]
	s_waitcnt vmcnt(11)
	v_mul_f32_e32 v15, v15, v118
	v_fmac_f32_e32 v15, v14, v116
	v_fmac_f32_e32 v15, v16, v117
	v_fmac_f32_e32 v15, v17, v115
	s_nop 1
	v_add_f32_dpp v14, v15, v15 quad_perm:[1,0,3,2] row_mask:0xf bank_mask:0xf bound_ctrl:1
	s_nop 1
	v_add_f32_dpp v14, v14, v14 quad_perm:[2,3,0,1] row_mask:0xf bank_mask:0xf bound_ctrl:1
	s_nop 1
	v_add_f32_dpp v14, v14, v14 row_ror:4 row_mask:0xf bank_mask:0xf bound_ctrl:1
	s_nop 1
	v_mov_b32_dpp v15, v14 row_ror:8 row_mask:0xf bank_mask:0xf bound_ctrl:1
	s_and_saveexec_b64 s[0:1], s[6:7]
	v_add_f32_e32 v14, v14, v15
	v_add_f32_e32 v14, v119, v14
	ds_write_b32 v99, v14 offset:320
	s_or_b64 exec, exec, s[0:1]
	s_waitcnt vmcnt(10)
	v_mul_f32_e32 v11, v11, v118
	v_fmac_f32_e32 v11, v10, v116
	v_fmac_f32_e32 v11, v12, v117
	v_fmac_f32_e32 v11, v13, v115
	s_nop 1
	v_add_f32_dpp v10, v11, v11 quad_perm:[1,0,3,2] row_mask:0xf bank_mask:0xf bound_ctrl:1
	s_nop 1
	v_add_f32_dpp v10, v10, v10 quad_perm:[2,3,0,1] row_mask:0xf bank_mask:0xf bound_ctrl:1
	s_nop 1
	v_add_f32_dpp v10, v10, v10 row_ror:4 row_mask:0xf bank_mask:0xf bound_ctrl:1
	s_nop 1
	v_mov_b32_dpp v11, v10 row_ror:8 row_mask:0xf bank_mask:0xf bound_ctrl:1
	s_and_saveexec_b64 s[0:1], s[6:7]
	v_add_f32_e32 v10, v10, v11
	v_add_f32_e32 v10, v119, v10
	ds_write_b32 v99, v10 offset:336
	s_or_b64 exec, exec, s[0:1]
	s_waitcnt vmcnt(9)
	v_mul_f32_e32 v7, v7, v118
	v_fmac_f32_e32 v7, v6, v116
	v_fmac_f32_e32 v7, v8, v117
	v_fmac_f32_e32 v7, v9, v115
	s_nop 1
	v_add_f32_dpp v6, v7, v7 quad_perm:[1,0,3,2] row_mask:0xf bank_mask:0xf bound_ctrl:1
	s_nop 1
	v_add_f32_dpp v6, v6, v6 quad_perm:[2,3,0,1] row_mask:0xf bank_mask:0xf bound_ctrl:1
	s_nop 1
	v_add_f32_dpp v6, v6, v6 row_ror:4 row_mask:0xf bank_mask:0xf bound_ctrl:1
	s_nop 1
	v_mov_b32_dpp v7, v6 row_ror:8 row_mask:0xf bank_mask:0xf bound_ctrl:1
	s_and_saveexec_b64 s[0:1], s[6:7]
	v_add_f32_e32 v6, v6, v7
	v_add_f32_e32 v6, v119, v6
	ds_write_b32 v99, v6 offset:352
	s_or_b64 exec, exec, s[0:1]
	s_waitcnt vmcnt(8)
	v_mul_f32_e32 v3, v3, v118
	v_fmac_f32_e32 v3, v2, v116
	v_fmac_f32_e32 v3, v4, v117
	v_fmac_f32_e32 v3, v5, v115
	s_nop 1
	v_add_f32_dpp v2, v3, v3 quad_perm:[1,0,3,2] row_mask:0xf bank_mask:0xf bound_ctrl:1
	s_nop 1
	v_add_f32_dpp v2, v2, v2 quad_perm:[2,3,0,1] row_mask:0xf bank_mask:0xf bound_ctrl:1
	s_nop 1
	v_add_f32_dpp v2, v2, v2 row_ror:4 row_mask:0xf bank_mask:0xf bound_ctrl:1
	s_nop 1
	v_mov_b32_dpp v3, v2 row_ror:8 row_mask:0xf bank_mask:0xf bound_ctrl:1
	s_and_saveexec_b64 s[0:1], s[6:7]
	v_add_f32_e32 v2, v2, v3
	v_add_f32_e32 v2, v119, v2
	ds_write_b32 v99, v2 offset:368
	s_or_b64 exec, exec, s[0:1]
	v_lshlrev_b64 v[2:3], 6, v[94:95]
	v_lshl_add_u64 v[6:7], v[2:3], 2, v[86:87]
	v_lshl_add_u64 v[50:51], v[6:7], 0, v[82:83]
	v_add_co_u32_e32 v2, vcc, 0x1000, v50
	v_mov_b32_e32 v93, v83
	s_nop 0
	v_addc_co_u32_e32 v3, vcc, 0, v51, vcc
	v_add_co_u32_e32 v8, vcc, 0x3000, v50
	v_lshl_add_u64 v[10:11], v[6:7], 0, v[92:93]
	s_nop 0
	v_addc_co_u32_e32 v9, vcc, 0, v51, vcc
	v_add_co_u32_e32 v14, vcc, s49, v50
	global_load_dwordx4 v[30:33], v[50:51], off nt
	s_nop 0
	global_load_dwordx4 v[2:5], v[2:3], off offset:2048 nt
	v_addc_co_u32_e32 v15, vcc, 0, v51, vcc
	v_add_co_u32_e32 v18, vcc, 0x7000, v50
	global_load_dwordx4 v[6:9], v[8:9], off nt
	s_nop 0
	global_load_dwordx4 v[10:13], v[10:11], off nt
	v_addc_co_u32_e32 v19, vcc, 0, v51, vcc
	v_add_co_u32_e32 v22, vcc, 0x9000, v50
	global_load_dwordx4 v[14:17], v[14:15], off offset:2048 nt
	s_nop 0
	global_load_dwordx4 v[18:21], v[18:19], off offset:2048 nt
	v_addc_co_u32_e32 v23, vcc, 0, v51, vcc
	v_add_co_u32_e32 v26, vcc, 0xa000, v50
	s_waitcnt vmcnt(13)
	v_mul_f32_e32 v52, v79, v118
	v_addc_co_u32_e32 v27, vcc, 0, v51, vcc
	global_load_dwordx4 v[22:25], v[22:23], off nt
	s_nop 0
	global_load_dwordx4 v[26:29], v[26:27], off offset:2048 nt
	v_fmac_f32_e32 v52, v78, v116
	v_fmac_f32_e32 v52, v80, v117
	v_fmac_f32_e32 v52, v81, v115
	s_nop 1
	v_add_f32_dpp v52, v52, v52 quad_perm:[1,0,3,2] row_mask:0xf bank_mask:0xf bound_ctrl:1
	s_nop 1
	v_add_f32_dpp v52, v52, v52 quad_perm:[2,3,0,1] row_mask:0xf bank_mask:0xf bound_ctrl:1
	s_nop 1
	v_add_f32_dpp v52, v52, v52 row_ror:4 row_mask:0xf bank_mask:0xf bound_ctrl:1
	s_nop 1
	v_mov_b32_dpp v53, v52 row_ror:8 row_mask:0xf bank_mask:0xf bound_ctrl:1
	s_and_saveexec_b64 s[0:1], s[6:7]
	v_add_f32_e32 v52, v52, v53
	v_add_f32_e32 v52, v119, v52
	ds_write_b32 v99, v52 offset:384
	s_or_b64 exec, exec, s[0:1]
	s_waitcnt vmcnt(14)
; template <int NB>
; __device__ __forceinline__ void sb_decode_task(const Params& P, float* lds, int task) {
;     ...
;         for (int i = 0; i < NB; ++i) { const int s = 4 * NB * kb + 4 * i + g;
;             float part = q0 * cur[i].x + q1 * cur[i].y + q2 * cur[i].z + q3 * cur[i].w; part = sum16(part);
;             if (c == 0) zl[s] = part + bias; }
; #pragma unroll
;         for (int i = 0; i < NB; ++i) cur[i] = nx[i];
;     }
;     asm volatile("s_waitcnt lgkmcnt(0)" ::: "memory");
;     __builtin_amdgcn_wave_barrier();
;     const float z0 = zl[2 * lane], z1 = zl[2 * lane + 1];
	v_mul_f32_e32 v52, v71, v118
	v_fmac_f32_e32 v52, v70, v116
	v_fmac_f32_e32 v52, v72, v117
	v_fmac_f32_e32 v52, v73, v115
	s_nop 1
	v_add_f32_dpp v52, v52, v52 quad_perm:[1,0,3,2] row_mask:0xf bank_mask:0xf bound_ctrl:1
	s_nop 1
	v_add_f32_dpp v52, v52, v52 quad_perm:[2,3,0,1] row_mask:0xf bank_mask:0xf bound_ctrl:1
	s_nop 1
	v_add_f32_dpp v52, v52, v52 row_ror:4 row_mask:0xf bank_mask:0xf bound_ctrl:1
	s_nop 1
	v_mov_b32_dpp v53, v52 row_ror:8 row_mask:0xf bank_mask:0xf bound_ctrl:1
	s_and_saveexec_b64 s[0:1], s[6:7]
	v_add_f32_e32 v52, v52, v53
	v_add_f32_e32 v52, v119, v52
	ds_write_b32 v99, v52 offset:400
	s_or_b64 exec, exec, s[0:1]
	s_waitcnt vmcnt(13)
	v_mul_f32_e32 v52, v63, v118
	v_fmac_f32_e32 v52, v62, v116
	v_fmac_f32_e32 v52, v64, v117
	v_fmac_f32_e32 v52, v65, v115
	s_nop 1
	v_add_f32_dpp v52, v52, v52 quad_perm:[1,0,3,2] row_mask:0xf bank_mask:0xf bound_ctrl:1
	s_nop 1
	v_add_f32_dpp v52, v52, v52 quad_perm:[2,3,0,1] row_mask:0xf bank_mask:0xf bound_ctrl:1
	s_nop 1
	v_add_f32_dpp v52, v52, v52 row_ror:4 row_mask:0xf bank_mask:0xf bound_ctrl:1
	s_nop 1
	v_mov_b32_dpp v53, v52 row_ror:8 row_mask:0xf bank_mask:0xf bound_ctrl:1
	s_and_saveexec_b64 s[0:1], s[6:7]
	v_add_f32_e32 v52, v52, v53
	v_add_f32_e32 v52, v119, v52
	ds_write_b32 v99, v52 offset:416
	s_or_b64 exec, exec, s[0:1]
	s_waitcnt vmcnt(12)
	v_mul_f32_e32 v52, v55, v118
	v_fmac_f32_e32 v52, v54, v116
	v_fmac_f32_e32 v52, v56, v117
	v_fmac_f32_e32 v52, v57, v115
	s_nop 1
	v_add_f32_dpp v52, v52, v52 quad_perm:[1,0,3,2] row_mask:0xf bank_mask:0xf bound_ctrl:1
	s_nop 1
	v_add_f32_dpp v52, v52, v52 quad_perm:[2,3,0,1] row_mask:0xf bank_mask:0xf bound_ctrl:1
	s_nop 1
	v_add_f32_dpp v52, v52, v52 row_ror:4 row_mask:0xf bank_mask:0xf bound_ctrl:1
	s_nop 1
	v_mov_b32_dpp v53, v52 row_ror:8 row_mask:0xf bank_mask:0xf bound_ctrl:1
	s_and_saveexec_b64 s[0:1], s[6:7]
	v_add_f32_e32 v52, v52, v53
	v_add_f32_e32 v52, v119, v52
	ds_write_b32 v99, v52 offset:432
	s_or_b64 exec, exec, s[0:1]
	s_waitcnt vmcnt(11)
	v_mul_f32_e32 v47, v47, v118
	v_fmac_f32_e32 v47, v46, v116
	v_fmac_f32_e32 v47, v48, v117
	v_fmac_f32_e32 v47, v49, v115
	s_nop 1
	v_add_f32_dpp v46, v47, v47 quad_perm:[1,0,3,2] row_mask:0xf bank_mask:0xf bound_ctrl:1
	s_nop 1
	v_add_f32_dpp v46, v46, v46 quad_perm:[2,3,0,1] row_mask:0xf bank_mask:0xf bound_ctrl:1
	s_nop 1
	v_add_f32_dpp v46, v46, v46 row_ror:4 row_mask:0xf bank_mask:0xf bound_ctrl:1
	s_nop 1
	v_mov_b32_dpp v47, v46 row_ror:8 row_mask:0xf bank_mask:0xf bound_ctrl:1
	s_and_saveexec_b64 s[0:1], s[6:7]
	v_add_f32_e32 v46, v46, v47
	v_add_f32_e32 v46, v119, v46
	ds_write_b32 v99, v46 offset:448
	s_or_b64 exec, exec, s[0:1]
	s_waitcnt vmcnt(10)
	v_mul_f32_e32 v43, v43, v118
	v_fmac_f32_e32 v43, v42, v116
	v_fmac_f32_e32 v43, v44, v117
	v_fmac_f32_e32 v43, v45, v115
	s_nop 1
	v_add_f32_dpp v42, v43, v43 quad_perm:[1,0,3,2] row_mask:0xf bank_mask:0xf bound_ctrl:1
	s_nop 1
	v_add_f32_dpp v42, v42, v42 quad_perm:[2,3,0,1] row_mask:0xf bank_mask:0xf bound_ctrl:1
	s_nop 1
	v_add_f32_dpp v42, v42, v42 row_ror:4 row_mask:0xf bank_mask:0xf bound_ctrl:1
	s_nop 1
	v_mov_b32_dpp v43, v42 row_ror:8 row_mask:0xf bank_mask:0xf bound_ctrl:1
	s_and_saveexec_b64 s[0:1], s[6:7]
	v_add_f32_e32 v42, v42, v43
	v_add_f32_e32 v42, v119, v42
	ds_write_b32 v99, v42 offset:464
	s_or_b64 exec, exec, s[0:1]
	s_waitcnt vmcnt(9)
	v_mul_f32_e32 v39, v39, v118
	v_fmac_f32_e32 v39, v38, v116
	v_fmac_f32_e32 v39, v40, v117
	v_fmac_f32_e32 v39, v41, v115
	s_nop 1
	v_add_f32_dpp v38, v39, v39 quad_perm:[1,0,3,2] row_mask:0xf bank_mask:0xf bound_ctrl:1
	s_nop 1
	v_add_f32_dpp v38, v38, v38 quad_perm:[2,3,0,1] row_mask:0xf bank_mask:0xf bound_ctrl:1
	s_nop 1
	v_add_f32_dpp v38, v38, v38 row_ror:4 row_mask:0xf bank_mask:0xf bound_ctrl:1
	s_nop 1
	v_mov_b32_dpp v39, v38 row_ror:8 row_mask:0xf bank_mask:0xf bound_ctrl:1
	s_and_saveexec_b64 s[0:1], s[6:7]
	v_add_f32_e32 v38, v38, v39
	v_add_f32_e32 v38, v119, v38
	ds_write_b32 v99, v38 offset:480
	s_or_b64 exec, exec, s[0:1]
	s_waitcnt vmcnt(8)
	v_mul_f32_e32 v35, v35, v118
	v_fmac_f32_e32 v35, v34, v116
	v_fmac_f32_e32 v35, v36, v117
	v_fmac_f32_e32 v35, v37, v115
	s_nop 1
	v_add_f32_dpp v34, v35, v35 quad_perm:[1,0,3,2] row_mask:0xf bank_mask:0xf bound_ctrl:1
	s_nop 1
	v_add_f32_dpp v34, v34, v34 quad_perm:[2,3,0,1] row_mask:0xf bank_mask:0xf bound_ctrl:1
	s_nop 1
	v_add_f32_dpp v34, v34, v34 row_ror:4 row_mask:0xf bank_mask:0xf bound_ctrl:1
	s_nop 1
	v_mov_b32_dpp v35, v34 row_ror:8 row_mask:0xf bank_mask:0xf bound_ctrl:1
	s_and_saveexec_b64 s[0:1], s[6:7]
	v_add_f32_e32 v34, v34, v35
	v_add_f32_e32 v34, v119, v34
	ds_write_b32 v99, v34 offset:496
	s_or_b64 exec, exec, s[0:1]
	s_waitcnt lgkmcnt(0)
	ds_read_b64 v[34:35], v100
	s_waitcnt lgkmcnt(0)
; __device__ __forceinline__ float softplus2_(float z2) { return fmaxf(z2, 0.f) + log1pf(exp2f(-fabsf(z2))) * LOG2E; }
; template <int NB>
; __device__ __forceinline__ void sb_decode_task(const Params& P, float* lds, int task) {
;     ...
;     const float z0 = zl[2 * lane], z1 = zl[2 * lane + 1];
;     const float sp0 = softplus2_(z0), sp1 = softplus2_(z1);
;     float incl = sp0 + sp1;
	v_cmp_gt_f32_e64 vcc, |v34|, s97
	s_nop 1
	v_cndmask_b32_e32 v37, 0, v103, vcc
	v_sub_f32_e64 v37, v37, |v34|
	v_exp_f32_e32 v37, v37
	v_max_f32_e32 v36, v34, v34
	v_max_f32_e32 v38, 0, v36
	v_cndmask_b32_e32 v36, 0, v102, vcc
	v_ldexp_f32 v39, v37, v36
	v_add_f32_e32 v40, 1.0, v39
	v_add_f32_e32 v36, -1.0, v40
	v_sub_f32_e32 v37, v36, v40
	v_add_f32_e32 v37, 1.0, v37
	v_sub_f32_e32 v36, v39, v36
	v_add_f32_e32 v41, v36, v37
	v_frexp_mant_f32_e32 v36, v40
	v_cmp_gt_f32_e32 vcc, s47, v36
	v_cvt_f64_f32_e32 v[36:37], v40
	v_frexp_exp_i32_f64_e32 v36, v[36:37]
	v_subbrev_co_u32_e32 v36, vcc, 0, v36, vcc
	v_sub_u32_e32 v37, 0, v36
	v_ldexp_f32 v40, v40, v37
	v_ldexp_f32 v37, v41, v37
	v_add_f32_e32 v41, -1.0, v40
	v_add_f32_e32 v42, 1.0, v41
	v_sub_f32_e32 v42, v40, v42
	v_add_f32_e32 v42, v37, v42
	v_add_f32_e32 v43, v41, v42
	v_sub_f32_e32 v41, v41, v43
	v_add_f32_e32 v41, v42, v41
	v_add_f32_e32 v42, 1.0, v40
	v_add_f32_e32 v44, -1.0, v42
	v_sub_f32_e32 v40, v40, v44
	v_add_f32_e32 v37, v37, v40
	v_add_f32_e32 v40, v42, v37
	v_sub_f32_e32 v42, v42, v40
	v_add_f32_e32 v37, v37, v42
	v_rcp_f32_e32 v42, v40
	v_cvt_f32_i32_e32 v36, v36
	v_cmp_neq_f32_e32 vcc, s46, v39
	v_mul_f32_e32 v44, v43, v42
	v_mul_f32_e32 v45, v40, v44
	v_fma_f32 v46, v44, v40, -v45
	v_fmac_f32_e32 v46, v44, v37
	v_add_f32_e32 v47, v45, v46
	v_sub_f32_e32 v48, v43, v47
	v_sub_f32_e32 v43, v43, v48
	v_sub_f32_e32 v45, v47, v45
	v_sub_f32_e32 v43, v43, v47
	v_add_f32_e32 v41, v41, v43
	v_sub_f32_e32 v43, v45, v46
	v_add_f32_e32 v41, v43, v41
	v_add_f32_e32 v43, v48, v41
	v_mul_f32_e32 v45, v42, v43
	v_mul_f32_e32 v46, v40, v45
	v_fma_f32 v40, v45, v40, -v46
	v_fmac_f32_e32 v40, v45, v37
	v_sub_f32_e32 v37, v48, v43
	v_add_f32_e32 v37, v41, v37
	v_add_f32_e32 v41, v46, v40
	v_sub_f32_e32 v47, v43, v41
	v_sub_f32_e32 v43, v43, v47
	v_sub_f32_e32 v46, v41, v46
	v_sub_f32_e32 v41, v43, v41
	v_add_f32_e32 v37, v37, v41
	v_sub_f32_e32 v40, v46, v40
	v_add_f32_e32 v37, v40, v37
	v_add_f32_e32 v40, v44, v45
	v_add_f32_e32 v37, v47, v37
	v_sub_f32_e32 v41, v40, v44
	v_mul_f32_e32 v37, v42, v37
	v_sub_f32_e32 v41, v45, v41
	v_add_f32_e32 v37, v41, v37
	v_mul_f32_e32 v44, 0x3f317218, v36
	v_add_f32_e32 v41, v40, v37
	v_fma_f32 v45, v36, s95, -v44
	v_mul_f32_e32 v42, v41, v41
	v_fmac_f32_e32 v45, 0xb102e308, v36
	v_sub_f32_e32 v36, v41, v40
	v_fmamk_f32 v43, v42, 0x3e9b6dac, v1
	v_sub_f32_e32 v36, v37, v36
	v_add_f32_e32 v37, v44, v45
	v_fmaak_f32 v43, v42, v43, 0x3f2aaada
	v_sub_f32_e32 v40, v37, v44
	v_ldexp_f32 v44, v41, 1
	v_mul_f32_e32 v41, v41, v42
	v_mul_f32_e32 v41, v41, v43
	v_add_f32_e32 v42, v44, v41
	v_sub_f32_e32 v43, v42, v44
	v_ldexp_f32 v36, v36, 1
	v_sub_f32_e32 v41, v41, v43
	v_add_f32_e32 v36, v36, v41
	v_add_f32_e32 v41, v42, v36
	v_sub_f32_e32 v42, v41, v42
	v_sub_f32_e32 v36, v36, v42
	v_add_f32_e32 v42, v37, v41
	v_sub_f32_e32 v43, v42, v37
	v_sub_f32_e32 v44, v42, v43
	v_sub_f32_e32 v40, v45, v40
	v_sub_f32_e32 v37, v37, v44
	v_sub_f32_e32 v41, v41, v43
	v_add_f32_e32 v37, v41, v37
	v_add_f32_e32 v41, v40, v36
	v_sub_f32_e32 v43, v41, v40
	v_sub_f32_e32 v44, v41, v43
	v_sub_f32_e32 v40, v40, v44
	v_sub_f32_e32 v36, v36, v43
	v_add_f32_e32 v37, v41, v37
	v_add_f32_e32 v36, v36, v40
	v_add_f32_e32 v40, v42, v37
	v_sub_f32_e32 v41, v40, v42
	v_sub_f32_e32 v37, v37, v41
	v_add_f32_e32 v36, v36, v37
	v_add_f32_e32 v36, v40, v36
	v_cndmask_b32_e32 v36, v104, v36, vcc
	v_cmp_lt_f32_e64 vcc, |v39|, s45
	s_nop 1
	v_cndmask_b32_e32 v36, v36, v39, vcc
	v_cmp_gt_f32_e64 vcc, |v35|, s97
	v_fmac_f32_e32 v38, 0x3fb8aa3b, v36
	v_max_f32_e32 v36, v35, v35
	v_cndmask_b32_e32 v37, 0, v103, vcc
	v_sub_f32_e64 v37, v37, |v35|
	v_exp_f32_e32 v37, v37
	v_max_f32_e32 v39, 0, v36
	v_cndmask_b32_e32 v36, 0, v102, vcc
	v_sub_f32_e32 v34, v34, v38
	v_ldexp_f32 v40, v37, v36
	v_add_f32_e32 v41, 1.0, v40
	v_add_f32_e32 v36, -1.0, v41
	v_sub_f32_e32 v37, v36, v41
	v_add_f32_e32 v37, 1.0, v37
	v_sub_f32_e32 v36, v40, v36
	v_add_f32_e32 v42, v36, v37
	v_frexp_mant_f32_e32 v36, v41
	v_cmp_gt_f32_e32 vcc, s47, v36
	v_cvt_f64_f32_e32 v[36:37], v41
	v_frexp_exp_i32_f64_e32 v36, v[36:37]
	v_subbrev_co_u32_e32 v36, vcc, 0, v36, vcc
	v_sub_u32_e32 v37, 0, v36
	v_ldexp_f32 v41, v41, v37
	v_ldexp_f32 v37, v42, v37
	v_add_f32_e32 v42, -1.0, v41
	v_add_f32_e32 v43, 1.0, v42
	v_sub_f32_e32 v43, v41, v43
	v_add_f32_e32 v43, v37, v43
	v_add_f32_e32 v44, v42, v43
	v_sub_f32_e32 v42, v42, v44
	v_add_f32_e32 v42, v43, v42
	v_add_f32_e32 v43, 1.0, v41
	v_add_f32_e32 v45, -1.0, v43
	v_sub_f32_e32 v41, v41, v45
	v_add_f32_e32 v37, v37, v41
	v_add_f32_e32 v41, v43, v37
	v_sub_f32_e32 v43, v43, v41
	v_add_f32_e32 v37, v37, v43
	v_rcp_f32_e32 v43, v41
	v_cvt_f32_i32_e32 v36, v36
	v_cmp_neq_f32_e32 vcc, s46, v40
	v_mul_f32_e32 v45, v44, v43
	v_mul_f32_e32 v46, v41, v45
	v_fma_f32 v47, v45, v41, -v46
	v_fmac_f32_e32 v47, v45, v37
	v_add_f32_e32 v48, v46, v47
	v_sub_f32_e32 v49, v44, v48
	v_sub_f32_e32 v44, v44, v49
	v_sub_f32_e32 v46, v48, v46
	v_sub_f32_e32 v44, v44, v48
	v_add_f32_e32 v42, v42, v44
	v_sub_f32_e32 v44, v46, v47
	v_add_f32_e32 v42, v44, v42
	v_add_f32_e32 v44, v49, v42
	v_mul_f32_e32 v46, v43, v44
	v_mul_f32_e32 v47, v41, v46
	v_fma_f32 v41, v46, v41, -v47
	v_fmac_f32_e32 v41, v46, v37
	v_sub_f32_e32 v37, v49, v44
	v_add_f32_e32 v37, v42, v37
	v_add_f32_e32 v42, v47, v41
	v_sub_f32_e32 v48, v44, v42
	v_sub_f32_e32 v44, v44, v48
	v_sub_f32_e32 v47, v42, v47
	v_sub_f32_e32 v42, v44, v42
	v_add_f32_e32 v37, v37, v42
	v_sub_f32_e32 v41, v47, v41
	v_add_f32_e32 v37, v41, v37
	v_add_f32_e32 v41, v45, v46
	v_add_f32_e32 v37, v48, v37
	v_sub_f32_e32 v42, v41, v45
	v_mul_f32_e32 v37, v43, v37
; template <int NB>
; __device__ __forceinline__ void sb_decode_task(const Params& P, float* lds, int task) {
;     ...
; #pragma unroll
;     for (int off = 1; off < 64; off <<= 1) { const float t = __shfl_down(incl, off); if (lane + off < 64) incl += t; }
;     const float excl = incl - (sp0 + sp1);
;     wl[2 * lane] = exp2f(z0 - sp0 - (excl + sp1));
;     wl[2 * lane + 1] = exp2f(z1 - sp1 - excl);
;     const float Ltot = __shfl(incl, 0);
;     asm volatile("s_waitcnt lgkmcnt(0)" ::: "memory");
;     __builtin_amdgcn_wave_barrier();
;     float4 o4 = make_float4(0.f, 0.f, 0.f, 0.f);
; #pragma unroll
;     for (int vb = 0; vb < NBT; ++vb) {
;         if (vb + 1 < NBT) {
; #pragma unroll
;             for (int i = 0; i < NB; ++i) nx[i] = *(const float4*)(Vp + (size_t)(4 * NB * (vb + 1) + 4 * i + g) * (SH * HD)); }
; #pragma unroll
;         for (int i = 0; i < NB; ++i) { const float w = wl[4 * NB * vb + 4 * i + g]; o4.x += w * cur[i].x; o4.y += w * cur[i].y; o4.z += w * cur[i].z; o4.w += w * cur[i].w; }
	v_sub_f32_e32 v42, v46, v42
	v_add_f32_e32 v37, v42, v37
	v_mul_f32_e32 v45, 0x3f317218, v36
	v_add_f32_e32 v42, v41, v37
	v_fma_f32 v46, v36, s95, -v45
	v_mul_f32_e32 v43, v42, v42
	v_fmac_f32_e32 v46, 0xb102e308, v36
	v_sub_f32_e32 v36, v42, v41
	v_fmamk_f32 v44, v43, 0x3e9b6dac, v1
	v_sub_f32_e32 v36, v37, v36
	v_add_f32_e32 v37, v45, v46
	v_fmaak_f32 v44, v43, v44, 0x3f2aaada
	v_sub_f32_e32 v41, v37, v45
	v_ldexp_f32 v45, v42, 1
	v_mul_f32_e32 v42, v42, v43
	v_mul_f32_e32 v42, v42, v44
	v_add_f32_e32 v43, v45, v42
	v_sub_f32_e32 v44, v43, v45
	v_ldexp_f32 v36, v36, 1
	v_sub_f32_e32 v42, v42, v44
	v_add_f32_e32 v36, v36, v42
	v_add_f32_e32 v42, v43, v36
	v_sub_f32_e32 v43, v42, v43
	v_sub_f32_e32 v36, v36, v43
	v_add_f32_e32 v43, v37, v42
	v_sub_f32_e32 v44, v43, v37
	v_sub_f32_e32 v45, v43, v44
	v_sub_f32_e32 v41, v46, v41
	v_sub_f32_e32 v37, v37, v45
	v_sub_f32_e32 v42, v42, v44
	v_add_f32_e32 v37, v42, v37
	v_add_f32_e32 v42, v41, v36
	v_sub_f32_e32 v44, v42, v41
	v_sub_f32_e32 v45, v42, v44
	v_sub_f32_e32 v41, v41, v45
	v_sub_f32_e32 v36, v36, v44
	v_add_f32_e32 v37, v42, v37
	v_add_f32_e32 v36, v36, v41
	v_add_f32_e32 v41, v43, v37
	v_sub_f32_e32 v42, v41, v43
	v_sub_f32_e32 v37, v37, v42
	v_add_f32_e32 v36, v36, v37
	v_add_f32_e32 v36, v41, v36
	v_cndmask_b32_e32 v36, v104, v36, vcc
	v_cmp_lt_f32_e64 vcc, |v40|, s45
	s_nop 1
	v_cndmask_b32_e32 v36, v36, v40, vcc
	v_fmac_f32_e32 v39, 0x3fb8aa3b, v36
	v_add_f32_e32 v36, v38, v39
	ds_bpermute_b32 v37, v108, v36
	v_sub_f32_e32 v35, v35, v39
	s_waitcnt lgkmcnt(0)
	v_add_f32_e32 v37, v36, v37
	v_cndmask_b32_e64 v37, v37, v36, s[8:9]
	ds_bpermute_b32 v40, v109, v37
	s_waitcnt lgkmcnt(0)
	v_add_f32_e32 v40, v37, v40
	v_cndmask_b32_e64 v37, v37, v40, s[10:11]
	ds_bpermute_b32 v40, v110, v37
	s_waitcnt lgkmcnt(0)
	v_add_f32_e32 v40, v37, v40
	v_cndmask_b32_e64 v37, v37, v40, s[12:13]
	ds_bpermute_b32 v40, v111, v37
	s_waitcnt lgkmcnt(0)
	v_add_f32_e32 v40, v37, v40
	v_cndmask_b32_e64 v37, v37, v40, s[14:15]
	ds_bpermute_b32 v40, v112, v37
	s_waitcnt lgkmcnt(0)
	v_add_f32_e32 v40, v37, v40
	v_cndmask_b32_e64 v37, v37, v40, s[16:17]
	ds_bpermute_b32 v40, v113, v37
	s_waitcnt lgkmcnt(0)
	v_add_f32_e32 v40, v37, v40
	v_cndmask_b32_e64 v44, v37, v40, s[18:19]
	v_sub_f32_e32 v36, v44, v36
	v_add_f32_e32 v37, v39, v36
	v_sub_f32_e32 v34, v34, v37
	v_cmp_gt_f32_e32 vcc, s24, v34
	v_sub_f32_e32 v35, v35, v36
	s_nop 0
	v_cndmask_b32_e32 v37, 0, v103, vcc
	v_add_f32_e32 v34, v34, v37
	v_cndmask_b32_e32 v37, 0, v102, vcc
	v_cmp_gt_f32_e32 vcc, s24, v35
	v_exp_f32_e32 v34, v34
	s_nop 0
	v_cndmask_b32_e32 v36, 0, v103, vcc
	v_add_f32_e32 v35, v35, v36
	v_exp_f32_e32 v35, v35
	v_cndmask_b32_e32 v36, 0, v102, vcc
	v_ldexp_f32 v34, v34, v37
	v_ldexp_f32 v35, v35, v36
	ds_write_b64 v100, v[34:35] offset:512
	s_waitcnt lgkmcnt(0)
	ds_read2_b32 v[34:35], v99 offset0:128 offset1:132
	ds_read2_b32 v[42:43], v99 offset0:136 offset1:140
	ds_read2_b32 v[66:67], v99 offset0:144 offset1:148
	ds_read2_b32 v[68:69], v99 offset0:152 offset1:156
	ds_read2_b32 v[74:75], v99 offset0:160 offset1:164
	ds_read2_b32 v[76:77], v99 offset0:168 offset1:172
	ds_read2_b32 v[38:39], v99 offset0:176 offset1:180
	ds_read2_b32 v[40:41], v99 offset0:184 offset1:188
	s_waitcnt vmcnt(7) lgkmcnt(7)
	v_pk_fma_f32 v[70:71], v[30:31], v[34:35], 0 op_sel_hi:[1,0,0]
	v_add_co_u32_e32 v30, vcc, s25, v50
	v_pk_fma_f32 v[72:73], v[32:33], v[34:35], 0 op_sel_hi:[1,0,0]
	s_nop 0
	v_addc_co_u32_e32 v31, vcc, 0, v51, vcc
	v_add_co_u32_e32 v34, vcc, s43, v50
	v_mov_b32_e32 v64, v35
	s_nop 0
	v_addc_co_u32_e32 v35, vcc, 0, v51, vcc
	v_add_co_u32_e32 v46, vcc, s44, v50
	s_waitcnt vmcnt(6)
	v_pk_fma_f32 v[2:3], v[2:3], v[64:65], v[70:71] op_sel_hi:[1,0,1]
	v_addc_co_u32_e32 v47, vcc, 0, v51, vcc
	v_add_co_u32_e32 v52, vcc, s26, v50
	global_load_dwordx4 v[46:49], v[46:47], off nt
	s_nop 0
	v_addc_co_u32_e32 v53, vcc, 0, v51, vcc
	v_add_co_u32_e32 v56, vcc, s27, v50
	global_load_dwordx4 v[52:55], v[52:53], off offset:2048 nt
	s_nop 0
	v_addc_co_u32_e32 v57, vcc, 0, v51, vcc
	v_add_co_u32_e32 v60, vcc, s28, v50
	global_load_dwordx4 v[56:59], v[56:57], off nt
	s_nop 0
	v_addc_co_u32_e32 v61, vcc, 0, v51, vcc
	global_load_dwordx4 v[60:63], v[60:61], off offset:2048 nt
	s_waitcnt lgkmcnt(6)
	v_mov_b32_e32 v78, v43
	s_waitcnt vmcnt(9)
	v_pk_fma_f32 v[2:3], v[6:7], v[42:43], v[2:3] op_sel_hi:[1,0,1]
	s_waitcnt lgkmcnt(5)
	v_mov_b32_e32 v80, v67
	s_waitcnt vmcnt(7)
	v_pk_fma_f32 v[2:3], v[14:15], v[78:79], v[2:3] op_sel_hi:[1,0,1]
	s_waitcnt lgkmcnt(4)
	v_mov_b32_e32 v94, v69
	v_pk_fma_f32 v[2:3], v[10:11], v[66:67], v[2:3] op_sel_hi:[1,0,1]
	s_waitcnt lgkmcnt(3)
	v_mov_b32_e32 v10, v75
	s_waitcnt vmcnt(6)
	v_pk_fma_f32 v[2:3], v[18:19], v[80:81], v[2:3] op_sel_hi:[1,0,1]
	s_waitcnt lgkmcnt(2)
	v_mov_b32_e32 v14, v77
	s_waitcnt vmcnt(5)
	v_pk_fma_f32 v[2:3], v[22:23], v[68:69], v[2:3] op_sel_hi:[1,0,1]
	global_load_dwordx4 v[30:33], v[30:31], off nt
	s_waitcnt vmcnt(5)
	v_pk_fma_f32 v[2:3], v[26:27], v[94:95], v[2:3] op_sel_hi:[1,0,1]
	global_load_dwordx4 v[34:37], v[34:35], off offset:2048 nt
	s_waitcnt vmcnt(5)
	v_pk_fma_f32 v[2:3], v[46:47], v[74:75], v[2:3] op_sel_hi:[1,0,1]
	s_waitcnt vmcnt(4)
	v_pk_fma_f32 v[2:3], v[52:53], v[10:11], v[2:3] op_sel_hi:[1,0,1]
	s_waitcnt vmcnt(3)
	v_pk_fma_f32 v[2:3], v[56:57], v[76:77], v[2:3] op_sel_hi:[1,0,1]
	s_waitcnt vmcnt(2)
	v_pk_fma_f32 v[6:7], v[60:61], v[14:15], v[2:3] op_sel_hi:[1,0,1]
	v_pk_fma_f32 v[2:3], v[4:5], v[64:65], v[72:73] op_sel_hi:[1,0,1]
	v_add_co_u32_e32 v4, vcc, s29, v50
	v_pk_fma_f32 v[2:3], v[8:9], v[42:43], v[2:3] op_sel_hi:[1,0,1]
	s_nop 0
	v_addc_co_u32_e32 v5, vcc, 0, v51, vcc
	v_pk_fma_f32 v[2:3], v[16:17], v[78:79], v[2:3] op_sel_hi:[1,0,1]
	s_waitcnt lgkmcnt(0)
; template <int NB>
; __device__ __forceinline__ void sb_decode_task(const Params& P, float* lds, int task) {
;     ...
;     for (int vb = 0; vb < NBT; ++vb) {
;         if (vb + 1 < NBT) {
; #pragma unroll
;             for (int i = 0; i < NB; ++i) nx[i] = *(const float4*)(Vp + (size_t)(4 * NB * (vb + 1) + 4 * i + g) * (SH * HD)); }
; #pragma unroll
;         for (int i = 0; i < NB; ++i) { const float w = wl[4 * NB * vb + 4 * i + g]; o4.x += w * cur[i].x; o4.y += w * cur[i].y; o4.z += w * cur[i].z; o4.w += w * cur[i].w; }
; #pragma unroll
;         for (int i = 0; i < NB; ++i) cur[i] = nx[i];
	v_mov_b32_e32 v42, v41
	v_pk_fma_f32 v[2:3], v[12:13], v[66:67], v[2:3] op_sel_hi:[1,0,1]
	s_waitcnt vmcnt(1)
	v_pk_fma_f32 v[6:7], v[30:31], v[38:39], v[6:7] op_sel_hi:[1,0,1]
	v_pk_fma_f32 v[2:3], v[20:21], v[80:81], v[2:3] op_sel_hi:[1,0,1]
	s_nop 0
	v_pk_fma_f32 v[2:3], v[24:25], v[68:69], v[2:3] op_sel_hi:[1,0,1]
	s_nop 0
	v_pk_fma_f32 v[2:3], v[28:29], v[94:95], v[2:3] op_sel_hi:[1,0,1]
	v_mov_b32_e32 v28, v39
	v_pk_fma_f32 v[2:3], v[48:49], v[74:75], v[2:3] op_sel_hi:[1,0,1]
	s_waitcnt vmcnt(0)
	v_pk_fma_f32 v[6:7], v[34:35], v[28:29], v[6:7] op_sel_hi:[1,0,1]
	v_pk_fma_f32 v[2:3], v[54:55], v[10:11], v[2:3] op_sel_hi:[1,0,1]
	s_nop 0
	v_pk_fma_f32 v[2:3], v[58:59], v[76:77], v[2:3] op_sel_hi:[1,0,1]
	s_nop 0
	v_pk_fma_f32 v[2:3], v[62:63], v[14:15], v[2:3] op_sel_hi:[1,0,1]
	ds_read2_b32 v[14:15], v99 offset0:192 offset1:196
	ds_read2_b32 v[12:13], v99 offset0:200 offset1:204
	ds_read2_b32 v[10:11], v99 offset0:208 offset1:212
	ds_read2_b32 v[8:9], v99 offset0:216 offset1:220
	global_load_dwordx4 v[16:19], v[4:5], off nt
	v_add_co_u32_e32 v4, vcc, s68, v50
	v_pk_fma_f32 v[2:3], v[32:33], v[38:39], v[2:3] op_sel_hi:[1,0,1]
	s_nop 0
	v_addc_co_u32_e32 v5, vcc, 0, v51, vcc
	global_load_dwordx4 v[20:23], v[4:5], off offset:2048 nt
	v_add_co_u32_e32 v4, vcc, s69, v50
	v_pk_fma_f32 v[2:3], v[36:37], v[28:29], v[2:3] op_sel_hi:[1,0,1]
	s_nop 0
	v_addc_co_u32_e32 v5, vcc, 0, v51, vcc
	global_load_dwordx4 v[24:27], v[4:5], off nt
	v_add_co_u32_e32 v4, vcc, s70, v50
	s_waitcnt lgkmcnt(0)
	v_mov_b32_e32 v36, v9
	v_addc_co_u32_e32 v5, vcc, 0, v51, vcc
	global_load_dwordx4 v[46:49], v[4:5], off offset:2048 nt
	v_add_co_u32_e32 v4, vcc, s71, v50
	ds_read2_b32 v[30:31], v99 offset0:224 offset1:228
	s_nop 0
	v_addc_co_u32_e32 v5, vcc, 0, v51, vcc
	global_load_dwordx4 v[52:55], v[4:5], off nt
	v_add_co_u32_e32 v4, vcc, s72, v50
	s_waitcnt vmcnt(4)
	v_pk_fma_f32 v[2:3], v[18:19], v[40:41], v[2:3] op_sel_hi:[1,0,1]
	v_addc_co_u32_e32 v5, vcc, 0, v51, vcc
	global_load_dwordx4 v[56:59], v[4:5], off offset:2048 nt
	v_add_co_u32_e32 v4, vcc, s73, v50
	s_waitcnt vmcnt(4)
	v_pk_fma_f32 v[2:3], v[22:23], v[42:43], v[2:3] op_sel_hi:[1,0,1]
	v_addc_co_u32_e32 v5, vcc, 0, v51, vcc
	global_load_dwordx4 v[60:63], v[4:5], off nt
	v_add_co_u32_e32 v4, vcc, s74, v50
	s_waitcnt vmcnt(4)
	v_pk_fma_f32 v[2:3], v[26:27], v[14:15], v[2:3] op_sel_hi:[1,0,1]
	v_addc_co_u32_e32 v5, vcc, 0, v51, vcc
	global_load_dwordx4 v[64:67], v[4:5], off offset:2048 nt
	v_add_co_u32_e32 v4, vcc, s75, v50
	v_mov_b32_e32 v18, v15
	s_nop 0
	v_addc_co_u32_e32 v5, vcc, 0, v51, vcc
	global_load_dwordx4 v[68:71], v[4:5], off nt
	v_pk_fma_f32 v[6:7], v[16:17], v[40:41], v[6:7] op_sel_hi:[1,0,1]
	s_waitcnt vmcnt(5)
	v_pk_fma_f32 v[2:3], v[48:49], v[18:19], v[2:3] op_sel_hi:[1,0,1]
	v_pk_fma_f32 v[6:7], v[20:21], v[42:43], v[6:7] op_sel_hi:[1,0,1]
	s_waitcnt vmcnt(4)
	v_pk_fma_f32 v[2:3], v[54:55], v[12:13], v[2:3] op_sel_hi:[1,0,1]
	v_mov_b32_e32 v22, v13
	v_pk_fma_f32 v[6:7], v[24:25], v[14:15], v[6:7] op_sel_hi:[1,0,1]
	v_mov_b32_e32 v26, v11
	v_pk_fma_f32 v[6:7], v[46:47], v[18:19], v[6:7] op_sel_hi:[1,0,1]
	s_waitcnt vmcnt(3)
	v_pk_fma_f32 v[2:3], v[58:59], v[22:23], v[2:3] op_sel_hi:[1,0,1]
	v_pk_fma_f32 v[6:7], v[52:53], v[12:13], v[6:7] op_sel_hi:[1,0,1]
	s_waitcnt vmcnt(2)
	v_pk_fma_f32 v[2:3], v[62:63], v[10:11], v[2:3] op_sel_hi:[1,0,1]
	v_pk_fma_f32 v[6:7], v[56:57], v[22:23], v[6:7] op_sel_hi:[1,0,1]
	s_waitcnt vmcnt(1)
	v_pk_fma_f32 v[2:3], v[66:67], v[26:27], v[2:3] op_sel_hi:[1,0,1]
	v_pk_fma_f32 v[6:7], v[60:61], v[10:11], v[6:7] op_sel_hi:[1,0,1]
	s_waitcnt vmcnt(0)
; template <int NB>
; __device__ __forceinline__ void sb_decode_task(const Params& P, float* lds, int task) {
;     ...
;     for (int vb = 0; vb < NBT; ++vb) {
;         if (vb + 1 < NBT) {
; #pragma unroll
;             for (int i = 0; i < NB; ++i) nx[i] = *(const float4*)(Vp + (size_t)(4 * NB * (vb + 1) + 4 * i + g) * (SH * HD)); }
; #pragma unroll
;         for (int i = 0; i < NB; ++i) { const float w = wl[4 * NB * vb + 4 * i + g]; o4.x += w * cur[i].x; o4.y += w * cur[i].y; o4.z += w * cur[i].z; o4.w += w * cur[i].w; }
; #pragma unroll
;         for (int i = 0; i < NB; ++i) cur[i] = nx[i];
;     }
; #pragma unroll
;     for (int off = 16; off < 64; off <<= 1) { o4.x += __shfl_xor(o4.x, off); o4.y += __shfl_xor(o4.y, off); o4.z += __shfl_xor(o4.z, off); o4.w += __shfl_xor(o4.w, off); }
;     if (g == 0) *(float4*)(dpart + (size_t)task * HD + 4 * c) = o4;
;     if (lane == 0) dl[task] = Ltot;
;     __builtin_amdgcn_wave_barrier();
	v_pk_fma_f32 v[32:33], v[70:71], v[8:9], v[2:3] op_sel_hi:[1,0,1]
	v_add_co_u32_e32 v2, vcc, s80, v50
	v_pk_fma_f32 v[6:7], v[64:65], v[26:27], v[6:7] op_sel_hi:[1,0,1]
	s_nop 0
	v_addc_co_u32_e32 v3, vcc, 0, v51, vcc
	v_pk_fma_f32 v[34:35], v[68:69], v[8:9], v[6:7] op_sel_hi:[1,0,1]
	v_add_co_u32_e32 v6, vcc, s81, v50
	global_load_dwordx4 v[2:5], v[2:3], off offset:2048 nt
	s_nop 0
	v_addc_co_u32_e32 v7, vcc, 0, v51, vcc
	v_add_co_u32_e32 v10, vcc, s82, v50
	global_load_dwordx4 v[6:9], v[6:7], off nt
	s_nop 0
	v_addc_co_u32_e32 v11, vcc, 0, v51, vcc
	v_add_co_u32_e32 v14, vcc, s83, v50
	ds_read2_b32 v[42:43], v99 offset0:232 offset1:236
	ds_read2_b32 v[40:41], v99 offset0:240 offset1:244
	ds_read2_b32 v[38:39], v99 offset0:248 offset1:252
	v_addc_co_u32_e32 v15, vcc, 0, v51, vcc
	v_add_co_u32_e32 v18, vcc, s84, v50
	global_load_dwordx4 v[10:13], v[10:11], off offset:2048 nt
	s_nop 0
	v_addc_co_u32_e32 v19, vcc, 0, v51, vcc
	v_add_co_u32_e32 v22, vcc, s85, v50
	global_load_dwordx4 v[14:17], v[14:15], off nt
	s_nop 0
	v_addc_co_u32_e32 v23, vcc, 0, v51, vcc
	v_add_co_u32_e32 v26, vcc, s86, v50
	global_load_dwordx4 v[18:21], v[18:19], off offset:2048 nt
	s_nop 0
	v_addc_co_u32_e32 v27, vcc, 0, v51, vcc
	v_add_co_u32_e32 v46, vcc, s87, v50
	global_load_dwordx4 v[22:25], v[22:23], off nt
	s_nop 0
	v_addc_co_u32_e32 v47, vcc, 0, v51, vcc
	global_load_dwordx4 v[26:29], v[26:27], off offset:2048 nt
	v_add_co_u32_e32 v50, vcc, s88, v50
	global_load_dwordx4 v[46:49], v[46:47], off nt
	s_nop 0
	v_addc_co_u32_e32 v51, vcc, 0, v51, vcc
	global_load_dwordx4 v[50:53], v[50:51], off offset:2048 nt
	s_waitcnt lgkmcnt(2)
	v_mov_b32_e32 v54, v43
	s_waitcnt lgkmcnt(1)
	v_mov_b32_e32 v56, v41
	s_waitcnt lgkmcnt(0)
	v_mov_b32_e32 v58, v39
	s_waitcnt vmcnt(8)
	v_pk_fma_f32 v[2:3], v[2:3], v[36:37], v[34:35] op_sel_hi:[1,0,1]
	v_mov_b32_e32 v34, v31
	v_pk_fma_f32 v[4:5], v[4:5], v[36:37], v[32:33] op_sel_hi:[1,0,1]
	s_waitcnt vmcnt(7)
	v_pk_fma_f32 v[2:3], v[6:7], v[30:31], v[2:3] op_sel_hi:[1,0,1]
	v_pk_fma_f32 v[4:5], v[8:9], v[30:31], v[4:5] op_sel_hi:[1,0,1]
	s_waitcnt vmcnt(6)
	v_pk_fma_f32 v[2:3], v[10:11], v[34:35], v[2:3] op_sel_hi:[1,0,1]
	v_pk_fma_f32 v[4:5], v[12:13], v[34:35], v[4:5] op_sel_hi:[1,0,1]
	ds_bpermute_b32 v10, v106, v44
	s_waitcnt vmcnt(5)
	v_pk_fma_f32 v[2:3], v[14:15], v[42:43], v[2:3] op_sel_hi:[1,0,1]
	v_pk_fma_f32 v[4:5], v[16:17], v[42:43], v[4:5] op_sel_hi:[1,0,1]
	s_waitcnt vmcnt(4)
	v_pk_fma_f32 v[2:3], v[18:19], v[54:55], v[2:3] op_sel_hi:[1,0,1]
	v_pk_fma_f32 v[4:5], v[20:21], v[54:55], v[4:5] op_sel_hi:[1,0,1]
	s_waitcnt vmcnt(3)
	v_pk_fma_f32 v[2:3], v[22:23], v[40:41], v[2:3] op_sel_hi:[1,0,1]
	v_pk_fma_f32 v[4:5], v[24:25], v[40:41], v[4:5] op_sel_hi:[1,0,1]
	s_waitcnt vmcnt(2)
	v_pk_fma_f32 v[2:3], v[26:27], v[56:57], v[2:3] op_sel_hi:[1,0,1]
	v_pk_fma_f32 v[4:5], v[28:29], v[56:57], v[4:5] op_sel_hi:[1,0,1]
	s_waitcnt vmcnt(1)
	v_pk_fma_f32 v[2:3], v[46:47], v[38:39], v[2:3] op_sel_hi:[1,0,1]
	v_pk_fma_f32 v[4:5], v[48:49], v[38:39], v[4:5] op_sel_hi:[1,0,1]
	s_waitcnt vmcnt(0)
	v_pk_fma_f32 v[2:3], v[50:51], v[58:59], v[2:3] op_sel_hi:[1,0,1]
	ds_bpermute_b32 v6, v107, v2
	ds_bpermute_b32 v7, v107, v3
	v_pk_fma_f32 v[4:5], v[52:53], v[58:59], v[4:5] op_sel_hi:[1,0,1]
	s_waitcnt lgkmcnt(0)
	v_pk_add_f32 v[2:3], v[2:3], v[6:7]
	ds_bpermute_b32 v6, v107, v4
	ds_bpermute_b32 v7, v107, v5
	s_waitcnt lgkmcnt(0)
	v_pk_add_f32 v[4:5], v[4:5], v[6:7]
	ds_bpermute_b32 v6, v114, v2
	ds_bpermute_b32 v7, v114, v3
	ds_bpermute_b32 v8, v114, v4
	ds_bpermute_b32 v9, v114, v5
	s_and_saveexec_b64 s[0:1], s[20:21]
	s_cbranch_execz .LBB0_1415
	s_ashr_i32 s37, s36, 31
	s_lshl_b64 s[90:91], s[36:37], 8
	v_lshl_add_u64 v[12:13], v[88:89], 0, s[90:91]
	s_waitcnt lgkmcnt(2)
	v_pk_add_f32 v[2:3], v[2:3], v[6:7]
	s_waitcnt lgkmcnt(0)
	v_pk_add_f32 v[4:5], v[4:5], v[8:9]
	global_store_dwordx4 v[12:13], v[2:5], off

; __device__ __forceinline__ float bf2f(bf16_t b) { return __uint_as_float(((unsigned)b) << 16); }
; template <int NB>
; __device__ __forceinline__ void sb_decode_task(const Params& P, float* lds, int task) {
;     ...
;     const int h = task % SH, bj = task / SH, b = bj / NPAGES;
;     const int page = P.page_table[bj];
;     const float* Kp = P.cache_k + ((size_t)page * PAGE * SH + h) * HD + 4 * c;
;     const float* Vp = P.cache_v + ((size_t)page * PAGE * SH + h) * HD + 4 * c;
;     const bf16_t* qp = qb + (size_t)(NTOK + b) * SBW + h * 64 + 4 * c;
;     const float q0 = bf2f(qp[0]), q1 = bf2f(qp[1]), q2 = bf2f(qp[2]), q3 = bf2f(qp[3]);
;     const float bias = P.sb_bias[h] * LOG2E;
;     float4 cur[NB], nx[NB];
; #pragma unroll
;     for (int i = 0; i < NB; ++i) cur[i] = *(const float4*)(Kp + (size_t)(4 * i + g) * (SH * HD));
; #pragma unroll
;     for (int kb = 0; kb < NBT; ++kb) {
;         const float* np = (kb + 1 < NBT) ? Kp + (size_t)(4 * NB * (kb + 1)) * (SH * HD) : Vp;
; #pragma unroll
;         for (int i = 0; i < NB; ++i) nx[i] = *(const float4*)(np + (size_t)(4 * i + g) * (SH * HD));
; #pragma unroll
;         for (int i = 0; i < NB; ++i) { const int s = 4 * NB * kb + 4 * i + g;
;             float part = q0 * cur[i].x + q1 * cur[i].y + q2 * cur[i].z + q3 * cur[i].w; part = sum16(part);
;             if (c == 0) zl[s] = part + bias; }
.LBB0_1418:
	s_and_b64 vcc, exec, s[0:1]
	s_cbranch_vccz .LBB0_1267
	v_readlane_b32 s90, v252, 48
	v_readlane_b32 s91, v252, 49
	s_load_dwordx16 s[52:67], s[90:91], 0x0
	s_lshr_b32 s1, s2, 31
	s_add_i32 s0, s2, s1
	s_ashr_i32 s2, s2, 7
	s_mul_i32 s3, s0, 6
	s_add_i32 s2, s2, s1
	s_ashr_i32 s1, s0, 31
	s_sub_i32 s36, s34, s3
	s_lshl_b64 s[0:1], s[0:1], 2
	s_waitcnt lgkmcnt(0)
	s_add_u32 s0, s62, s0
	s_addc_u32 s1, s63, s1
	global_load_dword v2, v83, s[0:1]
	s_add_i32 s0, s2, 0x4000
	s_ashr_i32 s37, s36, 31
	s_mul_hi_i32 s1, s0, 0x300
	s_mulk_i32 s0, 0x300
	s_add_u32 s2, s38, s0
	s_addc_u32 s3, s39, s1
	s_lshl_b32 s0, s36, 6
	s_ashr_i32 s1, s0, 31
	s_lshl_b64 s[0:1], s[0:1], 1
	s_add_u32 s0, s2, s0
	s_addc_u32 s1, s3, s1
	v_readlane_b32 s52, v252, 16
	v_readlane_b32 s53, v252, 17
	v_readlane_b32 s60, v252, 24
	v_readlane_b32 s61, v252, 25
	s_mov_b64 s[52:53], s[60:61]
	v_readlane_b32 s54, v252, 18
	v_readlane_b32 s55, v252, 19
	v_readlane_b32 s56, v252, 20
	v_readlane_b32 s57, v252, 21
	v_readlane_b32 s58, v252, 22
	v_readlane_b32 s59, v252, 23
	v_readlane_b32 s62, v252, 26
	v_readlane_b32 s63, v252, 27
	v_readlane_b32 s64, v252, 28
	v_readlane_b32 s65, v252, 29
	v_readlane_b32 s66, v252, 30
	v_readlane_b32 s67, v252, 31
	s_waitcnt vmcnt(0)
	v_mov_b32_e32 v253, v2
	v_mul_hi_i32 v3, v2, s48
	v_mul_lo_u32 v2, v2, s48
	v_lshl_add_u64 v[42:43], v[2:3], 0, s[36:37]
	v_lshlrev_b64 v[2:3], 8, v[42:43]
	v_lshl_add_u64 v[38:39], v[84:85], 0, v[2:3]
	global_load_dwordx2 v[2:3], v101, s[0:1]
	s_lshl_b64 s[0:1], s[36:37], 2
	s_add_u32 s0, s52, s0
	s_addc_u32 s1, s53, s1
	global_load_dword v6, v83, s[0:1]
	s_waitcnt vmcnt(1)
	v_lshlrev_b32_e32 v45, 16, v2
	v_and_b32_e32 v47, 0xffff0000, v2
	v_lshlrev_b32_e32 v46, 16, v3
	v_and_b32_e32 v44, 0xffff0000, v3
	v_lshl_add_u64 v[2:3], v[38:39], 0, v[82:83]
	v_add_co_u32_e32 v4, vcc, s50, v2
	global_load_dwordx4 v[30:33], v[2:3], off nt
	s_nop 0
	v_addc_co_u32_e32 v5, vcc, 0, v3, vcc
	global_load_dwordx4 v[26:29], v[4:5], off offset:2048 nt
	v_add_co_u32_e32 v4, vcc, s51, v2
	s_waitcnt vmcnt(2)
	v_mul_f32_e32 v48, 0x3fb8aa3b, v6
	v_addc_co_u32_e32 v5, vcc, 0, v3, vcc
	global_load_dwordx4 v[22:25], v[4:5], off nt
	v_add_co_u32_e32 v4, vcc, s49, v2
	s_waitcnt vmcnt(2)
	v_mul_f32_e32 v31, v31, v47
	v_addc_co_u32_e32 v5, vcc, 0, v3, vcc
	global_load_dwordx4 v[14:17], v[4:5], off offset:2048 nt
	v_add_co_u32_e32 v4, vcc, s89, v2
	v_fmac_f32_e32 v31, v30, v45
	s_nop 0
	v_addc_co_u32_e32 v5, vcc, 0, v3, vcc
	global_load_dwordx4 v[18:21], v[4:5], off nt
	v_add_co_u32_e32 v4, vcc, s92, v2
	v_fmac_f32_e32 v31, v32, v46
	s_nop 0
	v_addc_co_u32_e32 v5, vcc, 0, v3, vcc
	global_load_dwordx4 v[6:9], v[4:5], off offset:2048 nt
	v_add_co_u32_e32 v4, vcc, s93, v2
	v_fmac_f32_e32 v31, v33, v44
	s_nop 0
	v_addc_co_u32_e32 v5, vcc, 0, v3, vcc
	v_add_co_u32_e32 v2, vcc, s96, v2
	global_load_dwordx4 v[10:13], v[4:5], off nt
	s_nop 0
	v_addc_co_u32_e32 v3, vcc, 0, v3, vcc
	global_load_dwordx4 v[2:5], v[2:3], off offset:2048 nt
	v_add_f32_dpp v30, v31, v31 quad_perm:[1,0,3,2] row_mask:0xf bank_mask:0xf bound_ctrl:1
	s_nop 1
	v_add_f32_dpp v30, v30, v30 quad_perm:[2,3,0,1] row_mask:0xf bank_mask:0xf bound_ctrl:1
	s_nop 1
	v_add_f32_dpp v30, v30, v30 row_ror:4 row_mask:0xf bank_mask:0xf bound_ctrl:1
	s_nop 1
	v_mov_b32_dpp v31, v30 row_ror:8 row_mask:0xf bank_mask:0xf bound_ctrl:1
	s_and_saveexec_b64 s[0:1], s[6:7]
	v_add_f32_e32 v30, v30, v31
	v_add_f32_e32 v30, v48, v30
	ds_write_b32 v99, v30
	s_or_b64 exec, exec, s[0:1]
	s_waitcnt vmcnt(6)
	v_mul_f32_e32 v27, v27, v47
	v_fmac_f32_e32 v27, v26, v45
	v_fmac_f32_e32 v27, v28, v46
	v_fmac_f32_e32 v27, v29, v44
	s_nop 1
	v_add_f32_dpp v26, v27, v27 quad_perm:[1,0,3,2] row_mask:0xf bank_mask:0xf bound_ctrl:1
	s_nop 1
	v_add_f32_dpp v26, v26, v26 quad_perm:[2,3,0,1] row_mask:0xf bank_mask:0xf bound_ctrl:1
	s_nop 1
	v_add_f32_dpp v26, v26, v26 row_ror:4 row_mask:0xf bank_mask:0xf bound_ctrl:1
	s_nop 1
	v_mov_b32_dpp v27, v26 row_ror:8 row_mask:0xf bank_mask:0xf bound_ctrl:1
	s_and_saveexec_b64 s[0:1], s[6:7]
	v_add_f32_e32 v26, v26, v27
	v_add_f32_e32 v26, v48, v26
	ds_write_b32 v99, v26 offset:16
	s_or_b64 exec, exec, s[0:1]
	s_waitcnt vmcnt(5)
	v_mul_f32_e32 v23, v23, v47
	v_fmac_f32_e32 v23, v22, v45
	v_fmac_f32_e32 v23, v24, v46
	v_fmac_f32_e32 v23, v25, v44
	s_nop 1
	v_add_f32_dpp v22, v23, v23 quad_perm:[1,0,3,2] row_mask:0xf bank_mask:0xf bound_ctrl:1
	s_nop 1
	v_add_f32_dpp v22, v22, v22 quad_perm:[2,3,0,1] row_mask:0xf bank_mask:0xf bound_ctrl:1
	s_nop 1
	v_add_f32_dpp v22, v22, v22 row_ror:4 row_mask:0xf bank_mask:0xf bound_ctrl:1
	s_nop 1
	v_mov_b32_dpp v23, v22 row_ror:8 row_mask:0xf bank_mask:0xf bound_ctrl:1
	s_and_saveexec_b64 s[0:1], s[6:7]
	v_add_f32_e32 v22, v22, v23
	v_add_f32_e32 v22, v48, v22
	ds_write_b32 v99, v22 offset:32
	s_or_b64 exec, exec, s[0:1]
	s_waitcnt vmcnt(4)
	v_mul_f32_e32 v15, v15, v47
	v_fmac_f32_e32 v15, v14, v45
	v_fmac_f32_e32 v15, v16, v46
	v_fmac_f32_e32 v15, v17, v44
	s_nop 1
	v_add_f32_dpp v14, v15, v15 quad_perm:[1,0,3,2] row_mask:0xf bank_mask:0xf bound_ctrl:1
	s_nop 1
	v_add_f32_dpp v14, v14, v14 quad_perm:[2,3,0,1] row_mask:0xf bank_mask:0xf bound_ctrl:1
	s_nop 1
	v_add_f32_dpp v14, v14, v14 row_ror:4 row_mask:0xf bank_mask:0xf bound_ctrl:1
	s_nop 1
	v_mov_b32_dpp v15, v14 row_ror:8 row_mask:0xf bank_mask:0xf bound_ctrl:1
	s_and_saveexec_b64 s[0:1], s[6:7]
	v_add_f32_e32 v14, v14, v15
	v_add_f32_e32 v14, v48, v14
	ds_write_b32 v99, v14 offset:48
	s_or_b64 exec, exec, s[0:1]
	v_lshl_add_u64 v[14:15], v[38:39], 0, v[82:83]
	v_add_co_u32_e32 v16, vcc, 0xc000, v14
	s_waitcnt vmcnt(3)
; template <int NB>
; __device__ __forceinline__ void sb_decode_task(const Params& P, float* lds, int task) {
;     ...
;     for (int kb = 0; kb < NBT; ++kb) {
;         const float* np = (kb + 1 < NBT) ? Kp + (size_t)(4 * NB * (kb + 1)) * (SH * HD) : Vp;
; #pragma unroll
;         for (int i = 0; i < NB; ++i) nx[i] = *(const float4*)(np + (size_t)(4 * i + g) * (SH * HD));
; #pragma unroll
;         for (int i = 0; i < NB; ++i) { const int s = 4 * NB * kb + 4 * i + g;
;             float part = q0 * cur[i].x + q1 * cur[i].y + q2 * cur[i].z + q3 * cur[i].w; part = sum16(part);
;             if (c == 0) zl[s] = part + bias; }
; #pragma unroll
;         for (int i = 0; i < NB; ++i) cur[i] = nx[i];
;     }
	v_mul_f32_e32 v19, v19, v47
	v_addc_co_u32_e32 v17, vcc, 0, v15, vcc
	v_add_co_u32_e32 v22, vcc, 0xd000, v14
	v_fmac_f32_e32 v19, v18, v45
	s_nop 0
	v_addc_co_u32_e32 v23, vcc, 0, v15, vcc
	global_load_dwordx4 v[30:33], v[16:17], off nt
	global_load_dwordx4 v[26:29], v[22:23], off offset:2048 nt
	v_add_co_u32_e32 v16, vcc, 0xf000, v14
	v_fmac_f32_e32 v19, v20, v46
	s_nop 0
	v_addc_co_u32_e32 v17, vcc, 0, v15, vcc
	v_add_co_u32_e32 v14, vcc, 0x10000, v14
	v_fmac_f32_e32 v19, v21, v44
	s_nop 0
	v_addc_co_u32_e32 v15, vcc, 0, v15, vcc
	global_load_dwordx4 v[22:25], v[16:17], off nt
	s_nop 0
	global_load_dwordx4 v[14:17], v[14:15], off offset:2048 nt
	v_add_f32_dpp v18, v19, v19 quad_perm:[1,0,3,2] row_mask:0xf bank_mask:0xf bound_ctrl:1
	s_nop 1
	v_add_f32_dpp v18, v18, v18 quad_perm:[2,3,0,1] row_mask:0xf bank_mask:0xf bound_ctrl:1
	s_nop 1
	v_add_f32_dpp v18, v18, v18 row_ror:4 row_mask:0xf bank_mask:0xf bound_ctrl:1
	s_nop 1
	v_mov_b32_dpp v19, v18 row_ror:8 row_mask:0xf bank_mask:0xf bound_ctrl:1
	s_and_saveexec_b64 s[0:1], s[6:7]
	v_add_f32_e32 v18, v18, v19
	v_add_f32_e32 v18, v48, v18
	ds_write_b32 v99, v18 offset:64
	s_or_b64 exec, exec, s[0:1]
	s_waitcnt vmcnt(6)
	v_mul_f32_e32 v7, v7, v47
	v_fmac_f32_e32 v7, v6, v45
	v_fmac_f32_e32 v7, v8, v46
	v_fmac_f32_e32 v7, v9, v44
	s_nop 1
	v_add_f32_dpp v6, v7, v7 quad_perm:[1,0,3,2] row_mask:0xf bank_mask:0xf bound_ctrl:1
	s_nop 1
	v_add_f32_dpp v6, v6, v6 quad_perm:[2,3,0,1] row_mask:0xf bank_mask:0xf bound_ctrl:1
	s_nop 1
	v_add_f32_dpp v6, v6, v6 row_ror:4 row_mask:0xf bank_mask:0xf bound_ctrl:1
	s_nop 1
	v_mov_b32_dpp v7, v6 row_ror:8 row_mask:0xf bank_mask:0xf bound_ctrl:1
	s_and_saveexec_b64 s[0:1], s[6:7]
	v_add_f32_e32 v6, v6, v7
	v_add_f32_e32 v6, v48, v6
	ds_write_b32 v99, v6 offset:80
	s_or_b64 exec, exec, s[0:1]
	s_waitcnt vmcnt(5)
	v_mul_f32_e32 v6, v11, v47
	v_fmac_f32_e32 v6, v10, v45
	v_fmac_f32_e32 v6, v12, v46
	v_fmac_f32_e32 v6, v13, v44
	s_nop 1
	v_add_f32_dpp v6, v6, v6 quad_perm:[1,0,3,2] row_mask:0xf bank_mask:0xf bound_ctrl:1
	s_nop 1
	v_add_f32_dpp v6, v6, v6 quad_perm:[2,3,0,1] row_mask:0xf bank_mask:0xf bound_ctrl:1
	s_nop 1
	v_add_f32_dpp v6, v6, v6 row_ror:4 row_mask:0xf bank_mask:0xf bound_ctrl:1
	s_nop 1
	v_mov_b32_dpp v7, v6 row_ror:8 row_mask:0xf bank_mask:0xf bound_ctrl:1
	s_and_saveexec_b64 s[0:1], s[6:7]
	v_add_f32_e32 v6, v6, v7
	v_add_f32_e32 v6, v48, v6
	ds_write_b32 v99, v6 offset:96
	s_or_b64 exec, exec, s[0:1]
	s_waitcnt vmcnt(4)
	v_mul_f32_e32 v3, v3, v47
	v_fmac_f32_e32 v3, v2, v45
	v_fmac_f32_e32 v3, v4, v46
	v_fmac_f32_e32 v3, v5, v44
	s_nop 1
	v_add_f32_dpp v2, v3, v3 quad_perm:[1,0,3,2] row_mask:0xf bank_mask:0xf bound_ctrl:1
	s_nop 1
	v_add_f32_dpp v2, v2, v2 quad_perm:[2,3,0,1] row_mask:0xf bank_mask:0xf bound_ctrl:1
	s_nop 1
	v_add_f32_dpp v2, v2, v2 row_ror:4 row_mask:0xf bank_mask:0xf bound_ctrl:1
	s_nop 1
	v_mov_b32_dpp v3, v2 row_ror:8 row_mask:0xf bank_mask:0xf bound_ctrl:1
	s_and_saveexec_b64 s[0:1], s[6:7]
	v_add_f32_e32 v2, v2, v3
	v_add_f32_e32 v2, v48, v2
	ds_write_b32 v99, v2 offset:112
	s_or_b64 exec, exec, s[0:1]
	v_lshl_add_u64 v[2:3], v[38:39], 0, v[82:83]
	v_add_co_u32_e32 v4, vcc, 0x12000, v2
	s_nop 1
	v_addc_co_u32_e32 v5, vcc, 0, v3, vcc
	v_add_co_u32_e32 v6, vcc, 0x13000, v2
	s_nop 1
	v_addc_co_u32_e32 v7, vcc, 0, v3, vcc
	global_load_dwordx4 v[34:37], v[4:5], off nt
	global_load_dwordx4 v[18:21], v[6:7], off offset:2048 nt
	v_add_co_u32_e32 v4, vcc, 0x15000, v2
	s_waitcnt vmcnt(5)
	v_mul_f32_e32 v6, v31, v47
	v_addc_co_u32_e32 v5, vcc, 0, v3, vcc
	v_add_co_u32_e32 v2, vcc, 0x16000, v2
	v_fmac_f32_e32 v6, v30, v45
	s_nop 0
	v_addc_co_u32_e32 v3, vcc, 0, v3, vcc
	global_load_dwordx4 v[10:13], v[4:5], off nt
	s_nop 0
	global_load_dwordx4 v[2:5], v[2:3], off offset:2048 nt
	v_fmac_f32_e32 v6, v32, v46
	v_fmac_f32_e32 v6, v33, v44
	s_nop 1
	v_add_f32_dpp v6, v6, v6 quad_perm:[1,0,3,2] row_mask:0xf bank_mask:0xf bound_ctrl:1
	s_nop 1
	v_add_f32_dpp v6, v6, v6 quad_perm:[2,3,0,1] row_mask:0xf bank_mask:0xf bound_ctrl:1
	s_nop 1
	v_add_f32_dpp v6, v6, v6 row_ror:4 row_mask:0xf bank_mask:0xf bound_ctrl:1
	s_nop 1
	v_mov_b32_dpp v7, v6 row_ror:8 row_mask:0xf bank_mask:0xf bound_ctrl:1
	s_and_saveexec_b64 s[0:1], s[6:7]
	v_add_f32_e32 v6, v6, v7
	v_add_f32_e32 v6, v48, v6
	ds_write_b32 v99, v6 offset:128
	s_or_b64 exec, exec, s[0:1]
	s_waitcnt vmcnt(6)
	v_mul_f32_e32 v6, v27, v47
	v_fmac_f32_e32 v6, v26, v45
	v_fmac_f32_e32 v6, v28, v46
	v_fmac_f32_e32 v6, v29, v44
	s_nop 1
	v_add_f32_dpp v6, v6, v6 quad_perm:[1,0,3,2] row_mask:0xf bank_mask:0xf bound_ctrl:1
	s_nop 1
	v_add_f32_dpp v6, v6, v6 quad_perm:[2,3,0,1] row_mask:0xf bank_mask:0xf bound_ctrl:1
	s_nop 1
	v_add_f32_dpp v6, v6, v6 row_ror:4 row_mask:0xf bank_mask:0xf bound_ctrl:1
	s_nop 1
	v_mov_b32_dpp v7, v6 row_ror:8 row_mask:0xf bank_mask:0xf bound_ctrl:1
	s_and_saveexec_b64 s[0:1], s[6:7]
	v_add_f32_e32 v6, v6, v7
	v_add_f32_e32 v6, v48, v6
	ds_write_b32 v99, v6 offset:144
	s_or_b64 exec, exec, s[0:1]
	s_waitcnt vmcnt(5)
	v_mul_f32_e32 v6, v23, v47
	v_fmac_f32_e32 v6, v22, v45
	v_fmac_f32_e32 v6, v24, v46
	v_fmac_f32_e32 v6, v25, v44
	s_nop 1
	v_add_f32_dpp v6, v6, v6 quad_perm:[1,0,3,2] row_mask:0xf bank_mask:0xf bound_ctrl:1
	s_nop 1
	v_add_f32_dpp v6, v6, v6 quad_perm:[2,3,0,1] row_mask:0xf bank_mask:0xf bound_ctrl:1
	s_nop 1
	v_add_f32_dpp v6, v6, v6 row_ror:4 row_mask:0xf bank_mask:0xf bound_ctrl:1
	s_nop 1
	v_mov_b32_dpp v7, v6 row_ror:8 row_mask:0xf bank_mask:0xf bound_ctrl:1
	s_and_saveexec_b64 s[0:1], s[6:7]
	v_add_f32_e32 v6, v6, v7
	v_add_f32_e32 v6, v48, v6
	ds_write_b32 v99, v6 offset:160
	s_or_b64 exec, exec, s[0:1]
	s_waitcnt vmcnt(4)
; template <int NB>
; __device__ __forceinline__ void sb_decode_task(const Params& P, float* lds, int task) {
;     ...
;     for (int kb = 0; kb < NBT; ++kb) {
;         const float* np = (kb + 1 < NBT) ? Kp + (size_t)(4 * NB * (kb + 1)) * (SH * HD) : Vp;
; #pragma unroll
;         for (int i = 0; i < NB; ++i) nx[i] = *(const float4*)(np + (size_t)(4 * i + g) * (SH * HD));
; #pragma unroll
;         for (int i = 0; i < NB; ++i) { const int s = 4 * NB * kb + 4 * i + g;
;             float part = q0 * cur[i].x + q1 * cur[i].y + q2 * cur[i].z + q3 * cur[i].w; part = sum16(part);
;             if (c == 0) zl[s] = part + bias; }
; #pragma unroll
;         for (int i = 0; i < NB; ++i) cur[i] = nx[i];
;     }
	v_mul_f32_e32 v6, v15, v47
	v_fmac_f32_e32 v6, v14, v45
	v_fmac_f32_e32 v6, v16, v46
	v_fmac_f32_e32 v6, v17, v44
	s_nop 1
	v_add_f32_dpp v6, v6, v6 quad_perm:[1,0,3,2] row_mask:0xf bank_mask:0xf bound_ctrl:1
	s_nop 1
	v_add_f32_dpp v6, v6, v6 quad_perm:[2,3,0,1] row_mask:0xf bank_mask:0xf bound_ctrl:1
	s_nop 1
	v_add_f32_dpp v6, v6, v6 row_ror:4 row_mask:0xf bank_mask:0xf bound_ctrl:1
	s_nop 1
	v_mov_b32_dpp v7, v6 row_ror:8 row_mask:0xf bank_mask:0xf bound_ctrl:1
	s_and_saveexec_b64 s[0:1], s[6:7]
	v_add_f32_e32 v6, v6, v7
	v_add_f32_e32 v6, v48, v6
	ds_write_b32 v99, v6 offset:176
	s_or_b64 exec, exec, s[0:1]
	v_lshl_add_u64 v[6:7], v[38:39], 0, v[82:83]
	v_add_co_u32_e32 v8, vcc, 0x18000, v6
	s_waitcnt vmcnt(3)
	v_mul_f32_e32 v30, v35, v47
	v_addc_co_u32_e32 v9, vcc, 0, v7, vcc
	v_add_co_u32_e32 v14, vcc, 0x19000, v6
	v_fmac_f32_e32 v30, v34, v45
	s_nop 0
	v_addc_co_u32_e32 v15, vcc, 0, v7, vcc
	global_load_dwordx4 v[26:29], v[8:9], off nt
	global_load_dwordx4 v[22:25], v[14:15], off offset:2048 nt
	v_add_co_u32_e32 v8, vcc, 0x1b000, v6
	v_fmac_f32_e32 v30, v36, v46
	s_nop 0
	v_addc_co_u32_e32 v9, vcc, 0, v7, vcc
	v_add_co_u32_e32 v6, vcc, 0x1c000, v6
	v_fmac_f32_e32 v30, v37, v44
	s_nop 0
	v_addc_co_u32_e32 v7, vcc, 0, v7, vcc
	global_load_dwordx4 v[14:17], v[8:9], off nt
	s_nop 0
	global_load_dwordx4 v[6:9], v[6:7], off offset:2048 nt
	v_add_f32_dpp v30, v30, v30 quad_perm:[1,0,3,2] row_mask:0xf bank_mask:0xf bound_ctrl:1
	s_nop 1
	v_add_f32_dpp v30, v30, v30 quad_perm:[2,3,0,1] row_mask:0xf bank_mask:0xf bound_ctrl:1
	s_nop 1
	v_add_f32_dpp v30, v30, v30 row_ror:4 row_mask:0xf bank_mask:0xf bound_ctrl:1
	s_nop 1
	v_mov_b32_dpp v31, v30 row_ror:8 row_mask:0xf bank_mask:0xf bound_ctrl:1
	s_and_saveexec_b64 s[0:1], s[6:7]
	v_add_f32_e32 v30, v30, v31
	v_add_f32_e32 v30, v48, v30
	ds_write_b32 v99, v30 offset:192
	s_or_b64 exec, exec, s[0:1]
	s_waitcnt vmcnt(6)
	v_mul_f32_e32 v19, v19, v47
	v_fmac_f32_e32 v19, v18, v45
	v_fmac_f32_e32 v19, v20, v46
	v_fmac_f32_e32 v19, v21, v44
	s_nop 1
	v_add_f32_dpp v18, v19, v19 quad_perm:[1,0,3,2] row_mask:0xf bank_mask:0xf bound_ctrl:1
	s_nop 1
	v_add_f32_dpp v18, v18, v18 quad_perm:[2,3,0,1] row_mask:0xf bank_mask:0xf bound_ctrl:1
	s_nop 1
	v_add_f32_dpp v18, v18, v18 row_ror:4 row_mask:0xf bank_mask:0xf bound_ctrl:1
	s_nop 1
	v_mov_b32_dpp v19, v18 row_ror:8 row_mask:0xf bank_mask:0xf bound_ctrl:1
	s_and_saveexec_b64 s[0:1], s[6:7]
	v_add_f32_e32 v18, v18, v19
	v_add_f32_e32 v18, v48, v18
	ds_write_b32 v99, v18 offset:208
	s_or_b64 exec, exec, s[0:1]
	s_waitcnt vmcnt(5)
	v_mul_f32_e32 v11, v11, v47
	v_fmac_f32_e32 v11, v10, v45
	v_fmac_f32_e32 v11, v12, v46
	v_fmac_f32_e32 v11, v13, v44
	s_nop 1
	v_add_f32_dpp v10, v11, v11 quad_perm:[1,0,3,2] row_mask:0xf bank_mask:0xf bound_ctrl:1
	s_nop 1
	v_add_f32_dpp v10, v10, v10 quad_perm:[2,3,0,1] row_mask:0xf bank_mask:0xf bound_ctrl:1
	s_nop 1
	v_add_f32_dpp v10, v10, v10 row_ror:4 row_mask:0xf bank_mask:0xf bound_ctrl:1
	s_nop 1
	v_mov_b32_dpp v11, v10 row_ror:8 row_mask:0xf bank_mask:0xf bound_ctrl:1
	s_and_saveexec_b64 s[0:1], s[6:7]
	v_add_f32_e32 v10, v10, v11
	v_add_f32_e32 v10, v48, v10
	ds_write_b32 v99, v10 offset:224
	s_or_b64 exec, exec, s[0:1]
	s_waitcnt vmcnt(4)
	v_mul_f32_e32 v3, v3, v47
	v_fmac_f32_e32 v3, v2, v45
	v_fmac_f32_e32 v3, v4, v46
	v_fmac_f32_e32 v3, v5, v44
	s_nop 1
	v_add_f32_dpp v2, v3, v3 quad_perm:[1,0,3,2] row_mask:0xf bank_mask:0xf bound_ctrl:1
	s_nop 1
	v_add_f32_dpp v2, v2, v2 quad_perm:[2,3,0,1] row_mask:0xf bank_mask:0xf bound_ctrl:1
	s_nop 1
	v_add_f32_dpp v2, v2, v2 row_ror:4 row_mask:0xf bank_mask:0xf bound_ctrl:1
	s_nop 1
	v_mov_b32_dpp v3, v2 row_ror:8 row_mask:0xf bank_mask:0xf bound_ctrl:1
	s_and_saveexec_b64 s[0:1], s[6:7]
	v_add_f32_e32 v2, v2, v3
	v_add_f32_e32 v2, v48, v2
	ds_write_b32 v99, v2 offset:240
	s_or_b64 exec, exec, s[0:1]
	v_lshl_add_u64 v[2:3], v[38:39], 0, v[82:83]
	v_add_co_u32_e32 v4, vcc, 0x1e000, v2
	s_waitcnt vmcnt(3)
	v_mul_f32_e32 v27, v27, v47
	v_addc_co_u32_e32 v5, vcc, 0, v3, vcc
	v_add_co_u32_e32 v10, vcc, 0x1f000, v2
	v_fmac_f32_e32 v27, v26, v45
	s_nop 0
	v_addc_co_u32_e32 v11, vcc, 0, v3, vcc
	global_load_dwordx4 v[30:33], v[4:5], off nt
	global_load_dwordx4 v[18:21], v[10:11], off offset:2048 nt
	v_add_co_u32_e32 v4, vcc, 0x21000, v2
	v_fmac_f32_e32 v27, v28, v46
	s_nop 0
	v_addc_co_u32_e32 v5, vcc, 0, v3, vcc
	v_add_co_u32_e32 v2, vcc, 0x22000, v2
	v_fmac_f32_e32 v27, v29, v44
	s_nop 0
	v_addc_co_u32_e32 v3, vcc, 0, v3, vcc
	global_load_dwordx4 v[10:13], v[4:5], off nt
	s_nop 0
	global_load_dwordx4 v[2:5], v[2:3], off offset:2048 nt
	v_add_f32_dpp v26, v27, v27 quad_perm:[1,0,3,2] row_mask:0xf bank_mask:0xf bound_ctrl:1
	s_nop 1
	v_add_f32_dpp v26, v26, v26 quad_perm:[2,3,0,1] row_mask:0xf bank_mask:0xf bound_ctrl:1
	s_nop 1
	v_add_f32_dpp v26, v26, v26 row_ror:4 row_mask:0xf bank_mask:0xf bound_ctrl:1
	s_nop 1
	v_mov_b32_dpp v27, v26 row_ror:8 row_mask:0xf bank_mask:0xf bound_ctrl:1
	s_and_saveexec_b64 s[0:1], s[6:7]
	v_add_f32_e32 v26, v26, v27
	v_add_f32_e32 v26, v48, v26
	ds_write_b32 v99, v26 offset:256
	s_or_b64 exec, exec, s[0:1]
	s_waitcnt vmcnt(6)
	v_mul_f32_e32 v23, v23, v47
	v_fmac_f32_e32 v23, v22, v45
	v_fmac_f32_e32 v23, v24, v46
	v_fmac_f32_e32 v23, v25, v44
	s_nop 1
	v_add_f32_dpp v22, v23, v23 quad_perm:[1,0,3,2] row_mask:0xf bank_mask:0xf bound_ctrl:1
	s_nop 1
	v_add_f32_dpp v22, v22, v22 quad_perm:[2,3,0,1] row_mask:0xf bank_mask:0xf bound_ctrl:1
	s_nop 1
	v_add_f32_dpp v22, v22, v22 row_ror:4 row_mask:0xf bank_mask:0xf bound_ctrl:1
	s_nop 1
	v_mov_b32_dpp v23, v22 row_ror:8 row_mask:0xf bank_mask:0xf bound_ctrl:1
	s_and_saveexec_b64 s[0:1], s[6:7]
	v_add_f32_e32 v22, v22, v23
	v_add_f32_e32 v22, v48, v22
	ds_write_b32 v99, v22 offset:272
	s_or_b64 exec, exec, s[0:1]
	s_waitcnt vmcnt(5)
; template <int NB>
; __device__ __forceinline__ void sb_decode_task(const Params& P, float* lds, int task) {
;     ...
;     for (int kb = 0; kb < NBT; ++kb) {
;         const float* np = (kb + 1 < NBT) ? Kp + (size_t)(4 * NB * (kb + 1)) * (SH * HD) : Vp;
; #pragma unroll
;         for (int i = 0; i < NB; ++i) nx[i] = *(const float4*)(np + (size_t)(4 * i + g) * (SH * HD));
; #pragma unroll
;         for (int i = 0; i < NB; ++i) { const int s = 4 * NB * kb + 4 * i + g;
;             float part = q0 * cur[i].x + q1 * cur[i].y + q2 * cur[i].z + q3 * cur[i].w; part = sum16(part);
;             if (c == 0) zl[s] = part + bias; }
; #pragma unroll
;         for (int i = 0; i < NB; ++i) cur[i] = nx[i];
;     }
	v_mul_f32_e32 v15, v15, v47
	v_fmac_f32_e32 v15, v14, v45
	v_fmac_f32_e32 v15, v16, v46
	v_fmac_f32_e32 v15, v17, v44
	s_nop 1
	v_add_f32_dpp v14, v15, v15 quad_perm:[1,0,3,2] row_mask:0xf bank_mask:0xf bound_ctrl:1
	s_nop 1
	v_add_f32_dpp v14, v14, v14 quad_perm:[2,3,0,1] row_mask:0xf bank_mask:0xf bound_ctrl:1
	s_nop 1
	v_add_f32_dpp v14, v14, v14 row_ror:4 row_mask:0xf bank_mask:0xf bound_ctrl:1
	s_nop 1
	v_mov_b32_dpp v15, v14 row_ror:8 row_mask:0xf bank_mask:0xf bound_ctrl:1
	s_and_saveexec_b64 s[0:1], s[6:7]
	v_add_f32_e32 v14, v14, v15
	v_add_f32_e32 v14, v48, v14
	ds_write_b32 v99, v14 offset:288
	s_or_b64 exec, exec, s[0:1]
	s_waitcnt vmcnt(4)
	v_mul_f32_e32 v7, v7, v47
	v_fmac_f32_e32 v7, v6, v45
	v_fmac_f32_e32 v7, v8, v46
	v_fmac_f32_e32 v7, v9, v44
	s_nop 1
	v_add_f32_dpp v6, v7, v7 quad_perm:[1,0,3,2] row_mask:0xf bank_mask:0xf bound_ctrl:1
	s_nop 1
	v_add_f32_dpp v6, v6, v6 quad_perm:[2,3,0,1] row_mask:0xf bank_mask:0xf bound_ctrl:1
	s_nop 1
	v_add_f32_dpp v6, v6, v6 row_ror:4 row_mask:0xf bank_mask:0xf bound_ctrl:1
	s_nop 1
	v_mov_b32_dpp v7, v6 row_ror:8 row_mask:0xf bank_mask:0xf bound_ctrl:1
	s_and_saveexec_b64 s[0:1], s[6:7]
	v_add_f32_e32 v6, v6, v7
	v_add_f32_e32 v6, v48, v6
	ds_write_b32 v99, v6 offset:304
	s_or_b64 exec, exec, s[0:1]
	v_lshl_add_u64 v[6:7], v[38:39], 0, v[82:83]
	v_add_co_u32_e32 v8, vcc, 0x24000, v6
	s_waitcnt vmcnt(3)
	v_mul_f32_e32 v22, v31, v47
	v_addc_co_u32_e32 v9, vcc, 0, v7, vcc
	v_add_co_u32_e32 v14, vcc, 0x25000, v6
	v_fmac_f32_e32 v22, v30, v45
	s_nop 0
	v_addc_co_u32_e32 v15, vcc, 0, v7, vcc
	global_load_dwordx4 v[34:37], v[8:9], off nt
	global_load_dwordx4 v[26:29], v[14:15], off offset:2048 nt
	v_add_co_u32_e32 v8, vcc, 0x27000, v6
	v_fmac_f32_e32 v22, v32, v46
	s_nop 0
	v_addc_co_u32_e32 v9, vcc, 0, v7, vcc
	v_add_co_u32_e32 v6, vcc, 0x28000, v6
	v_fmac_f32_e32 v22, v33, v44
	s_nop 0
	v_addc_co_u32_e32 v7, vcc, 0, v7, vcc
	global_load_dwordx4 v[14:17], v[8:9], off nt
	s_nop 0
	global_load_dwordx4 v[6:9], v[6:7], off offset:2048 nt
	v_add_f32_dpp v22, v22, v22 quad_perm:[1,0,3,2] row_mask:0xf bank_mask:0xf bound_ctrl:1
	s_nop 1
	v_add_f32_dpp v22, v22, v22 quad_perm:[2,3,0,1] row_mask:0xf bank_mask:0xf bound_ctrl:1
	s_nop 1
	v_add_f32_dpp v22, v22, v22 row_ror:4 row_mask:0xf bank_mask:0xf bound_ctrl:1
	s_nop 1
	v_mov_b32_dpp v23, v22 row_ror:8 row_mask:0xf bank_mask:0xf bound_ctrl:1
	s_and_saveexec_b64 s[0:1], s[6:7]
	v_add_f32_e32 v22, v22, v23
	v_add_f32_e32 v22, v48, v22
	ds_write_b32 v99, v22 offset:320
	s_or_b64 exec, exec, s[0:1]
	s_waitcnt vmcnt(6)
	v_mul_f32_e32 v19, v19, v47
	v_fmac_f32_e32 v19, v18, v45
	v_fmac_f32_e32 v19, v20, v46
	v_fmac_f32_e32 v19, v21, v44
	s_nop 1
	v_add_f32_dpp v18, v19, v19 quad_perm:[1,0,3,2] row_mask:0xf bank_mask:0xf bound_ctrl:1
	s_nop 1
	v_add_f32_dpp v18, v18, v18 quad_perm:[2,3,0,1] row_mask:0xf bank_mask:0xf bound_ctrl:1
	s_nop 1
	v_add_f32_dpp v18, v18, v18 row_ror:4 row_mask:0xf bank_mask:0xf bound_ctrl:1
	s_nop 1
	v_mov_b32_dpp v19, v18 row_ror:8 row_mask:0xf bank_mask:0xf bound_ctrl:1
	s_and_saveexec_b64 s[0:1], s[6:7]
	v_add_f32_e32 v18, v18, v19
	v_add_f32_e32 v18, v48, v18
	ds_write_b32 v99, v18 offset:336
	s_or_b64 exec, exec, s[0:1]
	s_waitcnt vmcnt(5)
	v_mul_f32_e32 v11, v11, v47
	v_fmac_f32_e32 v11, v10, v45
	v_fmac_f32_e32 v11, v12, v46
	v_fmac_f32_e32 v11, v13, v44
	s_nop 1
	v_add_f32_dpp v10, v11, v11 quad_perm:[1,0,3,2] row_mask:0xf bank_mask:0xf bound_ctrl:1
	s_nop 1
	v_add_f32_dpp v10, v10, v10 quad_perm:[2,3,0,1] row_mask:0xf bank_mask:0xf bound_ctrl:1
	s_nop 1
	v_add_f32_dpp v10, v10, v10 row_ror:4 row_mask:0xf bank_mask:0xf bound_ctrl:1
	s_nop 1
	v_mov_b32_dpp v11, v10 row_ror:8 row_mask:0xf bank_mask:0xf bound_ctrl:1
	s_and_saveexec_b64 s[0:1], s[6:7]
	v_add_f32_e32 v10, v10, v11
	v_add_f32_e32 v10, v48, v10
	ds_write_b32 v99, v10 offset:352
	s_or_b64 exec, exec, s[0:1]
	s_waitcnt vmcnt(4)
	v_mul_f32_e32 v3, v3, v47
	v_fmac_f32_e32 v3, v2, v45
	v_fmac_f32_e32 v3, v4, v46
	v_fmac_f32_e32 v3, v5, v44
	s_nop 1
	v_add_f32_dpp v2, v3, v3 quad_perm:[1,0,3,2] row_mask:0xf bank_mask:0xf bound_ctrl:1
	s_nop 1
	v_add_f32_dpp v2, v2, v2 quad_perm:[2,3,0,1] row_mask:0xf bank_mask:0xf bound_ctrl:1
	s_nop 1
	v_add_f32_dpp v2, v2, v2 row_ror:4 row_mask:0xf bank_mask:0xf bound_ctrl:1
	s_nop 1
	v_mov_b32_dpp v3, v2 row_ror:8 row_mask:0xf bank_mask:0xf bound_ctrl:1
	s_and_saveexec_b64 s[0:1], s[6:7]
	v_add_f32_e32 v2, v2, v3
	v_add_f32_e32 v2, v48, v2
	ds_write_b32 v99, v2 offset:368
	s_or_b64 exec, exec, s[0:1]
	v_lshl_add_u64 v[2:3], v[38:39], 0, v[82:83]
	v_add_co_u32_e32 v4, vcc, 0x2a000, v2
	s_nop 1
	v_addc_co_u32_e32 v5, vcc, 0, v3, vcc
	v_add_co_u32_e32 v10, vcc, 0x2b000, v2
	s_nop 1
	v_addc_co_u32_e32 v11, vcc, 0, v3, vcc
	global_load_dwordx4 v[38:41], v[4:5], off nt
	global_load_dwordx4 v[30:33], v[10:11], off offset:2048 nt
	v_add_co_u32_e32 v4, vcc, 0x2d000, v2
	s_nop 1
	v_addc_co_u32_e32 v5, vcc, 0, v3, vcc
	v_add_co_u32_e32 v2, vcc, 0x2e000, v2
	s_nop 1
	v_addc_co_u32_e32 v3, vcc, 0, v3, vcc
	global_load_dwordx4 v[22:25], v[4:5], off nt
	global_load_dwordx4 v[18:21], v[2:3], off offset:2048 nt
	s_waitcnt vmcnt(7)
	v_mul_f32_e32 v2, v35, v47
	v_fmac_f32_e32 v2, v34, v45
	v_fmac_f32_e32 v2, v36, v46
	v_fmac_f32_e32 v2, v37, v44
	s_nop 1
	v_add_f32_dpp v2, v2, v2 quad_perm:[1,0,3,2] row_mask:0xf bank_mask:0xf bound_ctrl:1
	s_nop 1
	v_add_f32_dpp v2, v2, v2 quad_perm:[2,3,0,1] row_mask:0xf bank_mask:0xf bound_ctrl:1
	s_nop 1
	v_add_f32_dpp v2, v2, v2 row_ror:4 row_mask:0xf bank_mask:0xf bound_ctrl:1
	s_nop 1
	v_mov_b32_dpp v3, v2 row_ror:8 row_mask:0xf bank_mask:0xf bound_ctrl:1
	s_and_saveexec_b64 s[0:1], s[6:7]
	v_add_f32_e32 v2, v2, v3
	v_add_f32_e32 v2, v48, v2
	ds_write_b32 v99, v2 offset:384
	s_or_b64 exec, exec, s[0:1]
	s_waitcnt vmcnt(6)
; template <int NB>
; __device__ __forceinline__ void sb_decode_task(const Params& P, float* lds, int task) {
;     ...
;         for (int i = 0; i < NB; ++i) { const int s = 4 * NB * kb + 4 * i + g;
;             float part = q0 * cur[i].x + q1 * cur[i].y + q2 * cur[i].z + q3 * cur[i].w; part = sum16(part);
;             if (c == 0) zl[s] = part + bias; }
; #pragma unroll
;         for (int i = 0; i < NB; ++i) cur[i] = nx[i];
;     }
;     asm volatile("s_waitcnt lgkmcnt(0)" ::: "memory");
;     __builtin_amdgcn_wave_barrier();
;     const float z0 = zl[2 * lane], z1 = zl[2 * lane + 1];
;     ...
;     for (int vb = 0; vb < NBT; ++vb) {
;         if (vb + 1 < NBT) {
; #pragma unroll
;             for (int i = 0; i < NB; ++i) nx[i] = *(const float4*)(Vp + (size_t)(4 * NB * (vb + 1) + 4 * i + g) * (SH * HD)); }
	v_mul_f32_e32 v2, v27, v47
	v_fmac_f32_e32 v2, v26, v45
	v_fmac_f32_e32 v2, v28, v46
	v_fmac_f32_e32 v2, v29, v44
	s_nop 1
	v_add_f32_dpp v2, v2, v2 quad_perm:[1,0,3,2] row_mask:0xf bank_mask:0xf bound_ctrl:1
	s_nop 1
	v_add_f32_dpp v2, v2, v2 quad_perm:[2,3,0,1] row_mask:0xf bank_mask:0xf bound_ctrl:1
	s_nop 1
	v_add_f32_dpp v2, v2, v2 row_ror:4 row_mask:0xf bank_mask:0xf bound_ctrl:1
	s_nop 1
	v_mov_b32_dpp v3, v2 row_ror:8 row_mask:0xf bank_mask:0xf bound_ctrl:1
	s_and_saveexec_b64 s[0:1], s[6:7]
	v_add_f32_e32 v2, v2, v3
	v_add_f32_e32 v2, v48, v2
	ds_write_b32 v99, v2 offset:400
	s_or_b64 exec, exec, s[0:1]
	s_waitcnt vmcnt(5)
	v_mul_f32_e32 v2, v15, v47
	v_fmac_f32_e32 v2, v14, v45
	v_fmac_f32_e32 v2, v16, v46
	v_fmac_f32_e32 v2, v17, v44
	s_nop 1
	v_add_f32_dpp v2, v2, v2 quad_perm:[1,0,3,2] row_mask:0xf bank_mask:0xf bound_ctrl:1
	s_nop 1
	v_add_f32_dpp v2, v2, v2 quad_perm:[2,3,0,1] row_mask:0xf bank_mask:0xf bound_ctrl:1
	s_nop 1
	v_add_f32_dpp v2, v2, v2 row_ror:4 row_mask:0xf bank_mask:0xf bound_ctrl:1
	s_nop 1
	v_mov_b32_dpp v3, v2 row_ror:8 row_mask:0xf bank_mask:0xf bound_ctrl:1
	s_and_saveexec_b64 s[0:1], s[6:7]
	v_add_f32_e32 v2, v2, v3
	v_add_f32_e32 v2, v48, v2
	ds_write_b32 v99, v2 offset:416
	s_or_b64 exec, exec, s[0:1]
	s_waitcnt vmcnt(4)
	v_mul_f32_e32 v2, v7, v47
	v_fmac_f32_e32 v2, v6, v45
	v_fmac_f32_e32 v2, v8, v46
	v_fmac_f32_e32 v2, v9, v44
	s_nop 1
	v_add_f32_dpp v2, v2, v2 quad_perm:[1,0,3,2] row_mask:0xf bank_mask:0xf bound_ctrl:1
	s_nop 1
	v_add_f32_dpp v2, v2, v2 quad_perm:[2,3,0,1] row_mask:0xf bank_mask:0xf bound_ctrl:1
	s_nop 1
	v_add_f32_dpp v2, v2, v2 row_ror:4 row_mask:0xf bank_mask:0xf bound_ctrl:1
	s_nop 1
	v_mov_b32_dpp v3, v2 row_ror:8 row_mask:0xf bank_mask:0xf bound_ctrl:1
	s_and_saveexec_b64 s[0:1], s[6:7]
	v_add_f32_e32 v2, v2, v3
	v_add_f32_e32 v2, v48, v2
	ds_write_b32 v99, v2 offset:432
	s_or_b64 exec, exec, s[0:1]
	v_lshlrev_b64 v[2:3], 6, v[42:43]
	v_lshl_add_u64 v[34:35], v[2:3], 2, v[90:91]
	v_add_co_u32_e32 v2, vcc, 0x1000, v34
	s_waitcnt vmcnt(3)
	v_mul_f32_e32 v26, v39, v47
	v_addc_co_u32_e32 v3, vcc, 0, v35, vcc
	v_add_co_u32_e32 v6, vcc, 0x3000, v34
	global_load_dwordx4 v[14:17], v[34:35], off nt
	s_nop 0
	global_load_dwordx4 v[2:5], v[2:3], off offset:2048 nt
	v_addc_co_u32_e32 v7, vcc, 0, v35, vcc
	v_add_co_u32_e32 v10, vcc, s49, v34
	v_fmac_f32_e32 v26, v38, v45
	s_nop 0
	v_addc_co_u32_e32 v11, vcc, 0, v35, vcc
	global_load_dwordx4 v[6:9], v[6:7], off nt
	s_nop 0
	global_load_dwordx4 v[10:13], v[10:11], off offset:2048 nt
	v_fmac_f32_e32 v26, v40, v46
	v_fmac_f32_e32 v26, v41, v44
	s_nop 1
	v_add_f32_dpp v26, v26, v26 quad_perm:[1,0,3,2] row_mask:0xf bank_mask:0xf bound_ctrl:1
	s_nop 1
	v_add_f32_dpp v26, v26, v26 quad_perm:[2,3,0,1] row_mask:0xf bank_mask:0xf bound_ctrl:1
	s_nop 1
	v_add_f32_dpp v26, v26, v26 row_ror:4 row_mask:0xf bank_mask:0xf bound_ctrl:1
	s_nop 1
	v_mov_b32_dpp v27, v26 row_ror:8 row_mask:0xf bank_mask:0xf bound_ctrl:1
	s_and_saveexec_b64 s[0:1], s[6:7]
	v_add_f32_e32 v26, v26, v27
	v_add_f32_e32 v26, v48, v26
	ds_write_b32 v99, v26 offset:448
	s_or_b64 exec, exec, s[0:1]
	s_waitcnt vmcnt(6)
	v_mul_f32_e32 v26, v31, v47
	v_fmac_f32_e32 v26, v30, v45
	v_fmac_f32_e32 v26, v32, v46
	v_fmac_f32_e32 v26, v33, v44
	s_nop 1
	v_add_f32_dpp v26, v26, v26 quad_perm:[1,0,3,2] row_mask:0xf bank_mask:0xf bound_ctrl:1
	s_nop 1
	v_add_f32_dpp v26, v26, v26 quad_perm:[2,3,0,1] row_mask:0xf bank_mask:0xf bound_ctrl:1
	s_nop 1
	v_add_f32_dpp v26, v26, v26 row_ror:4 row_mask:0xf bank_mask:0xf bound_ctrl:1
	s_nop 1
	v_mov_b32_dpp v27, v26 row_ror:8 row_mask:0xf bank_mask:0xf bound_ctrl:1
	s_and_saveexec_b64 s[0:1], s[6:7]
	v_add_f32_e32 v26, v26, v27
	v_add_f32_e32 v26, v48, v26
	ds_write_b32 v99, v26 offset:464
	s_or_b64 exec, exec, s[0:1]
	s_waitcnt vmcnt(5)
	v_mul_f32_e32 v23, v23, v47
	v_fmac_f32_e32 v23, v22, v45
	v_fmac_f32_e32 v23, v24, v46
	v_fmac_f32_e32 v23, v25, v44
	s_nop 1
	v_add_f32_dpp v22, v23, v23 quad_perm:[1,0,3,2] row_mask:0xf bank_mask:0xf bound_ctrl:1
	s_nop 1
	v_add_f32_dpp v22, v22, v22 quad_perm:[2,3,0,1] row_mask:0xf bank_mask:0xf bound_ctrl:1
	s_nop 1
	v_add_f32_dpp v22, v22, v22 row_ror:4 row_mask:0xf bank_mask:0xf bound_ctrl:1
	s_nop 1
	v_mov_b32_dpp v23, v22 row_ror:8 row_mask:0xf bank_mask:0xf bound_ctrl:1
	s_and_saveexec_b64 s[0:1], s[6:7]
	v_add_f32_e32 v22, v22, v23
	v_add_f32_e32 v22, v48, v22
	ds_write_b32 v99, v22 offset:480
	s_or_b64 exec, exec, s[0:1]
	s_waitcnt vmcnt(4)
	v_mul_f32_e32 v19, v19, v47
	v_fmac_f32_e32 v19, v18, v45
	v_fmac_f32_e32 v19, v20, v46
	v_fmac_f32_e32 v19, v21, v44
	s_nop 1
	v_add_f32_dpp v18, v19, v19 quad_perm:[1,0,3,2] row_mask:0xf bank_mask:0xf bound_ctrl:1
	s_nop 1
	v_add_f32_dpp v18, v18, v18 quad_perm:[2,3,0,1] row_mask:0xf bank_mask:0xf bound_ctrl:1
	s_nop 1
	v_add_f32_dpp v18, v18, v18 row_ror:4 row_mask:0xf bank_mask:0xf bound_ctrl:1
	s_nop 1
	v_mov_b32_dpp v19, v18 row_ror:8 row_mask:0xf bank_mask:0xf bound_ctrl:1
	s_and_saveexec_b64 s[0:1], s[6:7]
	v_add_f32_e32 v18, v18, v19
	v_add_f32_e32 v18, v48, v18
	ds_write_b32 v99, v18 offset:496
	s_or_b64 exec, exec, s[0:1]
	s_waitcnt lgkmcnt(0)
	ds_read_b64 v[18:19], v100
	s_waitcnt lgkmcnt(0)
; __device__ __forceinline__ float softplus2_(float z2) { return fmaxf(z2, 0.f) + log1pf(exp2f(-fabsf(z2))) * LOG2E; }
; template <int NB>
; __device__ __forceinline__ void sb_decode_task(const Params& P, float* lds, int task) {
;     ...
;     const float sp0 = softplus2_(z0), sp1 = softplus2_(z1);
;     float incl = sp0 + sp1;
	v_cmp_gt_f32_e64 vcc, |v18|, s97
	s_nop 1
	v_cndmask_b32_e32 v21, 0, v103, vcc
	v_sub_f32_e64 v21, v21, |v18|
	v_exp_f32_e32 v21, v21
	v_max_f32_e32 v20, v18, v18
	v_max_f32_e32 v22, 0, v20
	v_cndmask_b32_e32 v20, 0, v102, vcc
	v_ldexp_f32 v23, v21, v20
	v_add_f32_e32 v24, 1.0, v23
	v_add_f32_e32 v20, -1.0, v24
	v_sub_f32_e32 v21, v20, v24
	v_add_f32_e32 v21, 1.0, v21
	v_sub_f32_e32 v20, v23, v20
	v_add_f32_e32 v25, v20, v21
	v_frexp_mant_f32_e32 v20, v24
	v_cmp_gt_f32_e32 vcc, s47, v20
	v_cvt_f64_f32_e32 v[20:21], v24
	v_frexp_exp_i32_f64_e32 v20, v[20:21]
	v_subbrev_co_u32_e32 v20, vcc, 0, v20, vcc
	v_sub_u32_e32 v21, 0, v20
	v_ldexp_f32 v24, v24, v21
	v_ldexp_f32 v21, v25, v21
	v_add_f32_e32 v25, -1.0, v24
	v_add_f32_e32 v26, 1.0, v25
	v_sub_f32_e32 v26, v24, v26
	v_add_f32_e32 v26, v21, v26
	v_add_f32_e32 v27, v25, v26
	v_sub_f32_e32 v25, v25, v27
	v_add_f32_e32 v25, v26, v25
	v_add_f32_e32 v26, 1.0, v24
	v_add_f32_e32 v28, -1.0, v26
	v_sub_f32_e32 v24, v24, v28
	v_add_f32_e32 v21, v21, v24
	v_add_f32_e32 v24, v26, v21
	v_sub_f32_e32 v26, v26, v24
	v_add_f32_e32 v21, v21, v26
	v_rcp_f32_e32 v26, v24
	v_cvt_f32_i32_e32 v20, v20
	v_cmp_neq_f32_e32 vcc, s46, v23
	v_mul_f32_e32 v28, v27, v26
	v_mul_f32_e32 v29, v24, v28
	v_fma_f32 v30, v28, v24, -v29
	v_fmac_f32_e32 v30, v28, v21
	v_add_f32_e32 v31, v29, v30
	v_sub_f32_e32 v32, v27, v31
	v_sub_f32_e32 v27, v27, v32
	v_sub_f32_e32 v29, v31, v29
	v_sub_f32_e32 v27, v27, v31
	v_add_f32_e32 v25, v25, v27
	v_sub_f32_e32 v27, v29, v30
	v_add_f32_e32 v25, v27, v25
	v_add_f32_e32 v27, v32, v25
	v_mul_f32_e32 v29, v26, v27
	v_mul_f32_e32 v30, v24, v29
	v_fma_f32 v24, v29, v24, -v30
	v_fmac_f32_e32 v24, v29, v21
	v_sub_f32_e32 v21, v32, v27
	v_add_f32_e32 v21, v25, v21
	v_add_f32_e32 v25, v30, v24
	v_sub_f32_e32 v31, v27, v25
	v_sub_f32_e32 v27, v27, v31
	v_sub_f32_e32 v30, v25, v30
	v_sub_f32_e32 v25, v27, v25
	v_add_f32_e32 v21, v21, v25
	v_sub_f32_e32 v24, v30, v24
	v_add_f32_e32 v21, v24, v21
	v_add_f32_e32 v24, v28, v29
	v_add_f32_e32 v21, v31, v21
	v_sub_f32_e32 v25, v24, v28
	v_mul_f32_e32 v21, v26, v21
	v_sub_f32_e32 v25, v29, v25
	v_add_f32_e32 v21, v25, v21
	v_mul_f32_e32 v28, 0x3f317218, v20
	v_add_f32_e32 v25, v24, v21
	v_fma_f32 v29, v20, s95, -v28
	v_mul_f32_e32 v26, v25, v25
	v_fmac_f32_e32 v29, 0xb102e308, v20
	v_sub_f32_e32 v20, v25, v24
	v_fmamk_f32 v27, v26, 0x3e9b6dac, v1
	v_sub_f32_e32 v20, v21, v20
	v_add_f32_e32 v21, v28, v29
	v_fmaak_f32 v27, v26, v27, 0x3f2aaada
	v_sub_f32_e32 v24, v21, v28
	v_ldexp_f32 v28, v25, 1
	v_mul_f32_e32 v25, v25, v26
	v_mul_f32_e32 v25, v25, v27
	v_add_f32_e32 v26, v28, v25
	v_sub_f32_e32 v27, v26, v28
	v_ldexp_f32 v20, v20, 1
	v_sub_f32_e32 v25, v25, v27
	v_add_f32_e32 v20, v20, v25
	v_add_f32_e32 v25, v26, v20
	v_sub_f32_e32 v26, v25, v26
	v_sub_f32_e32 v20, v20, v26
	v_add_f32_e32 v26, v21, v25
	v_sub_f32_e32 v27, v26, v21
	v_sub_f32_e32 v28, v26, v27
	v_sub_f32_e32 v24, v29, v24
	v_sub_f32_e32 v21, v21, v28
	v_sub_f32_e32 v25, v25, v27
	v_add_f32_e32 v21, v25, v21
	v_add_f32_e32 v25, v24, v20
	v_sub_f32_e32 v27, v25, v24
	v_sub_f32_e32 v28, v25, v27
	v_sub_f32_e32 v24, v24, v28
	v_sub_f32_e32 v20, v20, v27
	v_add_f32_e32 v21, v25, v21
	v_add_f32_e32 v20, v20, v24
	v_add_f32_e32 v24, v26, v21
	v_sub_f32_e32 v25, v24, v26
	v_sub_f32_e32 v21, v21, v25
	v_add_f32_e32 v20, v20, v21
	v_add_f32_e32 v20, v24, v20
	v_cndmask_b32_e32 v20, v104, v20, vcc
	v_cmp_lt_f32_e64 vcc, |v23|, s45
	s_nop 1
	v_cndmask_b32_e32 v20, v20, v23, vcc
	v_cmp_gt_f32_e64 vcc, |v19|, s97
	v_fmac_f32_e32 v22, 0x3fb8aa3b, v20
	v_max_f32_e32 v20, v19, v19
	v_cndmask_b32_e32 v21, 0, v103, vcc
	v_sub_f32_e64 v21, v21, |v19|
	v_exp_f32_e32 v21, v21
	v_max_f32_e32 v23, 0, v20
	v_cndmask_b32_e32 v20, 0, v102, vcc
	v_sub_f32_e32 v18, v18, v22
	v_ldexp_f32 v24, v21, v20
	v_add_f32_e32 v25, 1.0, v24
	v_add_f32_e32 v20, -1.0, v25
	v_sub_f32_e32 v21, v20, v25
	v_add_f32_e32 v21, 1.0, v21
	v_sub_f32_e32 v20, v24, v20
	v_add_f32_e32 v26, v20, v21
	v_frexp_mant_f32_e32 v20, v25
	v_cmp_gt_f32_e32 vcc, s47, v20
	v_cvt_f64_f32_e32 v[20:21], v25
	v_frexp_exp_i32_f64_e32 v20, v[20:21]
	v_subbrev_co_u32_e32 v20, vcc, 0, v20, vcc
	v_sub_u32_e32 v21, 0, v20
	v_ldexp_f32 v25, v25, v21
	v_ldexp_f32 v21, v26, v21
	v_add_f32_e32 v26, -1.0, v25
	v_add_f32_e32 v27, 1.0, v26
	v_sub_f32_e32 v27, v25, v27
	v_add_f32_e32 v27, v21, v27
	v_add_f32_e32 v28, v26, v27
	v_sub_f32_e32 v26, v26, v28
	v_add_f32_e32 v26, v27, v26
	v_add_f32_e32 v27, 1.0, v25
	v_add_f32_e32 v29, -1.0, v27
	v_sub_f32_e32 v25, v25, v29
	v_add_f32_e32 v21, v21, v25
	v_add_f32_e32 v25, v27, v21
	v_sub_f32_e32 v27, v27, v25
	v_add_f32_e32 v21, v21, v27
	v_rcp_f32_e32 v27, v25
	v_cvt_f32_i32_e32 v20, v20
	v_cmp_neq_f32_e32 vcc, s46, v24
	v_mul_f32_e32 v29, v28, v27
	v_mul_f32_e32 v30, v25, v29
	v_fma_f32 v31, v29, v25, -v30
	v_fmac_f32_e32 v31, v29, v21
	v_add_f32_e32 v32, v30, v31
	v_sub_f32_e32 v33, v28, v32
	v_sub_f32_e32 v28, v28, v33
	v_sub_f32_e32 v30, v32, v30
	v_sub_f32_e32 v28, v28, v32
	v_add_f32_e32 v26, v26, v28
	v_sub_f32_e32 v28, v30, v31
	v_add_f32_e32 v26, v28, v26
	v_add_f32_e32 v28, v33, v26
	v_mul_f32_e32 v30, v27, v28
	v_mul_f32_e32 v31, v25, v30
	v_fma_f32 v25, v30, v25, -v31
	v_fmac_f32_e32 v25, v30, v21
	v_sub_f32_e32 v21, v33, v28
	v_add_f32_e32 v21, v26, v21
	v_add_f32_e32 v26, v31, v25
	v_sub_f32_e32 v32, v28, v26
	v_sub_f32_e32 v28, v28, v32
	v_sub_f32_e32 v31, v26, v31
	v_sub_f32_e32 v26, v28, v26
	v_add_f32_e32 v21, v21, v26
	v_sub_f32_e32 v25, v31, v25
	v_add_f32_e32 v21, v25, v21
	v_add_f32_e32 v25, v29, v30
	v_add_f32_e32 v21, v32, v21
	v_sub_f32_e32 v26, v25, v29
	v_mul_f32_e32 v21, v27, v21
; template <int NB>
; __device__ __forceinline__ void sb_decode_task(const Params& P, float* lds, int task) {
;     ...
; #pragma unroll
;     for (int off = 1; off < 64; off <<= 1) { const float t = __shfl_down(incl, off); if (lane + off < 64) incl += t; }
;     const float excl = incl - (sp0 + sp1);
;     wl[2 * lane] = exp2f(z0 - sp0 - (excl + sp1));
;     wl[2 * lane + 1] = exp2f(z1 - sp1 - excl);
;     const float Ltot = __shfl(incl, 0);
;     asm volatile("s_waitcnt lgkmcnt(0)" ::: "memory");
;     __builtin_amdgcn_wave_barrier();
;     float4 o4 = make_float4(0.f, 0.f, 0.f, 0.f);
; #pragma unroll
;     for (int vb = 0; vb < NBT; ++vb) {
;         if (vb + 1 < NBT) {
; #pragma unroll
;             for (int i = 0; i < NB; ++i) nx[i] = *(const float4*)(Vp + (size_t)(4 * NB * (vb + 1) + 4 * i + g) * (SH * HD)); }
; #pragma unroll
;         for (int i = 0; i < NB; ++i) { const float w = wl[4 * NB * vb + 4 * i + g]; o4.x += w * cur[i].x; o4.y += w * cur[i].y; o4.z += w * cur[i].z; o4.w += w * cur[i].w; }
	v_sub_f32_e32 v26, v30, v26
	v_add_f32_e32 v21, v26, v21
	v_mul_f32_e32 v29, 0x3f317218, v20
	v_add_f32_e32 v26, v25, v21
	v_fma_f32 v30, v20, s95, -v29
	v_mul_f32_e32 v27, v26, v26
	v_fmac_f32_e32 v30, 0xb102e308, v20
	v_sub_f32_e32 v20, v26, v25
	v_fmamk_f32 v28, v27, 0x3e9b6dac, v1
	v_sub_f32_e32 v20, v21, v20
	v_add_f32_e32 v21, v29, v30
	v_fmaak_f32 v28, v27, v28, 0x3f2aaada
	v_sub_f32_e32 v25, v21, v29
	v_ldexp_f32 v29, v26, 1
	v_mul_f32_e32 v26, v26, v27
	v_mul_f32_e32 v26, v26, v28
	v_add_f32_e32 v27, v29, v26
	v_sub_f32_e32 v28, v27, v29
	v_ldexp_f32 v20, v20, 1
	v_sub_f32_e32 v26, v26, v28
	v_add_f32_e32 v20, v20, v26
	v_add_f32_e32 v26, v27, v20
	v_sub_f32_e32 v27, v26, v27
	v_sub_f32_e32 v20, v20, v27
	v_add_f32_e32 v27, v21, v26
	v_sub_f32_e32 v28, v27, v21
	v_sub_f32_e32 v29, v27, v28
	v_sub_f32_e32 v25, v30, v25
	v_sub_f32_e32 v21, v21, v29
	v_sub_f32_e32 v26, v26, v28
	v_add_f32_e32 v21, v26, v21
	v_add_f32_e32 v26, v25, v20
	v_sub_f32_e32 v28, v26, v25
	v_sub_f32_e32 v29, v26, v28
	v_sub_f32_e32 v25, v25, v29
	v_sub_f32_e32 v20, v20, v28
	v_add_f32_e32 v21, v26, v21
	v_add_f32_e32 v20, v20, v25
	v_add_f32_e32 v25, v27, v21
	v_sub_f32_e32 v26, v25, v27
	v_sub_f32_e32 v21, v21, v26
	v_add_f32_e32 v20, v20, v21
	v_add_f32_e32 v20, v25, v20
	v_cndmask_b32_e32 v20, v104, v20, vcc
	v_cmp_lt_f32_e64 vcc, |v24|, s45
	v_and_b32_e32 v21, 63, v105
	s_nop 0
	v_cndmask_b32_e32 v20, v20, v24, vcc
	v_cmp_ne_u32_e32 vcc, 63, v21
	v_fmac_f32_e32 v23, 0x3fb8aa3b, v20
	v_add_f32_e32 v20, v22, v23
	v_addc_co_u32_e32 v24, vcc, 0, v105, vcc
	v_lshlrev_b32_e32 v46, 2, v24
	ds_bpermute_b32 v24, v46, v20
	v_cmp_gt_u32_e32 vcc, 62, v21
	v_sub_f32_e32 v19, v19, v23
	s_waitcnt lgkmcnt(0)
	v_add_f32_e32 v24, v20, v24
	v_cndmask_b32_e64 v25, 0, 2, vcc
	v_cndmask_b32_e64 v24, v24, v20, s[8:9]
	v_add_lshl_u32 v47, v25, v105, 2
	ds_bpermute_b32 v25, v47, v24
	v_cmp_gt_u32_e32 vcc, 60, v21
	s_waitcnt lgkmcnt(0)
	v_add_f32_e32 v25, v24, v25
	v_cndmask_b32_e64 v24, v24, v25, s[10:11]
	v_cndmask_b32_e64 v25, 0, 4, vcc
	v_add_lshl_u32 v48, v25, v105, 2
	ds_bpermute_b32 v25, v48, v24
	v_cmp_gt_u32_e32 vcc, 56, v21
	s_waitcnt lgkmcnt(0)
	v_add_f32_e32 v25, v24, v25
	v_cndmask_b32_e64 v24, v24, v25, s[12:13]
	v_cndmask_b32_e64 v25, 0, 8, vcc
	v_add_lshl_u32 v49, v25, v105, 2
	ds_bpermute_b32 v25, v49, v24
	v_cmp_gt_u32_e32 vcc, 48, v21
	s_waitcnt lgkmcnt(0)
	v_add_f32_e32 v25, v24, v25
	v_cndmask_b32_e64 v21, 0, 16, vcc
	v_cndmask_b32_e64 v24, v24, v25, s[14:15]
	v_add_lshl_u32 v50, v21, v105, 2
	ds_bpermute_b32 v21, v50, v24
	s_waitcnt lgkmcnt(0)
	v_add_f32_e32 v21, v24, v21
	v_cndmask_b32_e64 v21, v24, v21, s[16:17]
	v_lshlrev_b32_e32 v24, 2, v105
	v_or_b32_e32 v51, 0x80, v24
	ds_bpermute_b32 v25, v51, v21
	v_and_b32_e32 v44, 0x100, v24
	s_waitcnt lgkmcnt(0)
	v_add_f32_e32 v25, v21, v25
	v_cndmask_b32_e64 v31, v21, v25, s[18:19]
	v_sub_f32_e32 v20, v31, v20
	v_add_f32_e32 v21, v23, v20
	v_sub_f32_e32 v18, v18, v21
	v_cmp_gt_f32_e32 vcc, s24, v18
	v_sub_f32_e32 v19, v19, v20
	s_nop 0
	v_cndmask_b32_e32 v21, 0, v103, vcc
	v_add_f32_e32 v18, v18, v21
	v_cndmask_b32_e32 v21, 0, v102, vcc
	v_cmp_gt_f32_e32 vcc, s24, v19
	v_exp_f32_e32 v18, v18
	s_nop 0
	v_cndmask_b32_e32 v20, 0, v103, vcc
	v_add_f32_e32 v19, v19, v20
	v_exp_f32_e32 v19, v19
	v_cndmask_b32_e32 v20, 0, v102, vcc
	v_ldexp_f32 v18, v18, v21
	v_ldexp_f32 v19, v19, v20
	ds_write_b64 v100, v[18:19] offset:512
	s_waitcnt lgkmcnt(0)
	ds_read2_b32 v[18:19], v99 offset0:128 offset1:132
	ds_read2_b32 v[32:33], v99 offset0:136 offset1:140
	ds_read2_b32 v[62:63], v99 offset0:144 offset1:148
	ds_read2_b32 v[64:65], v99 offset0:152 offset1:156
	ds_read2_b32 v[66:67], v99 offset0:160 offset1:164
	ds_read2_b32 v[68:69], v99 offset0:168 offset1:172
	s_waitcnt vmcnt(3) lgkmcnt(5)
	v_pk_fma_f32 v[36:37], v[14:15], v[18:19], 0 op_sel_hi:[1,0,0]
	v_add_co_u32_e32 v14, vcc, s89, v34
	v_pk_fma_f32 v[60:61], v[16:17], v[18:19], 0 op_sel_hi:[1,0,0]
	s_nop 0
	v_addc_co_u32_e32 v15, vcc, 0, v35, vcc
	v_add_co_u32_e32 v18, vcc, s92, v34
	v_mov_b32_e32 v30, v19
	s_nop 0
	v_addc_co_u32_e32 v19, vcc, 0, v35, vcc
	v_add_co_u32_e32 v22, vcc, s93, v34
	s_waitcnt vmcnt(2)
	v_pk_fma_f32 v[2:3], v[2:3], v[30:31], v[36:37] op_sel_hi:[1,0,1]
	v_addc_co_u32_e32 v23, vcc, 0, v35, vcc
	v_add_co_u32_e32 v26, vcc, s96, v34
	s_waitcnt vmcnt(1) lgkmcnt(4)
	v_pk_fma_f32 v[2:3], v[6:7], v[32:33], v[2:3] op_sel_hi:[1,0,1]
	v_addc_co_u32_e32 v27, vcc, 0, v35, vcc
	v_add_co_u32_e32 v6, vcc, s44, v34
	global_load_dwordx4 v[14:17], v[14:15], off nt
	s_nop 0
	v_addc_co_u32_e32 v7, vcc, 0, v35, vcc
	global_load_dwordx4 v[18:21], v[18:19], off offset:2048 nt
	v_mov_b32_e32 v70, v33
	global_load_dwordx4 v[36:39], v[6:7], off nt
	v_add_co_u32_e32 v6, vcc, s26, v34
	global_load_dwordx4 v[22:25], v[22:23], off nt
	s_nop 0
	v_addc_co_u32_e32 v7, vcc, 0, v35, vcc
	global_load_dwordx4 v[26:29], v[26:27], off offset:2048 nt
	s_waitcnt vmcnt(5)
	v_pk_fma_f32 v[2:3], v[10:11], v[70:71], v[2:3] op_sel_hi:[1,0,1]
	global_load_dwordx4 v[40:43], v[6:7], off offset:2048 nt
	v_add_co_u32_e32 v6, vcc, s27, v34
	s_waitcnt lgkmcnt(2)
	v_mov_b32_e32 v10, v65
	v_addc_co_u32_e32 v7, vcc, 0, v35, vcc
	global_load_dwordx4 v[52:55], v[6:7], off nt
	v_add_co_u32_e32 v6, vcc, s28, v34
	s_waitcnt vmcnt(6)
	v_pk_fma_f32 v[2:3], v[14:15], v[62:63], v[2:3] op_sel_hi:[1,0,1]
	v_addc_co_u32_e32 v7, vcc, 0, v35, vcc
	global_load_dwordx4 v[56:59], v[6:7], off offset:2048 nt
	v_mov_b32_e32 v6, v63
	s_waitcnt vmcnt(6)
	v_pk_fma_f32 v[2:3], v[18:19], v[6:7], v[2:3] op_sel_hi:[1,0,1]
	s_waitcnt lgkmcnt(1)
	v_mov_b32_e32 v14, v67
	s_waitcnt lgkmcnt(0)
	v_mov_b32_e32 v18, v69
	s_waitcnt vmcnt(4)
; template <int NB>
; __device__ __forceinline__ void sb_decode_task(const Params& P, float* lds, int task) {
;     ...
;     for (int vb = 0; vb < NBT; ++vb) {
;         if (vb + 1 < NBT) {
; #pragma unroll
;             for (int i = 0; i < NB; ++i) nx[i] = *(const float4*)(Vp + (size_t)(4 * NB * (vb + 1) + 4 * i + g) * (SH * HD)); }
; #pragma unroll
;         for (int i = 0; i < NB; ++i) { const float w = wl[4 * NB * vb + 4 * i + g]; o4.x += w * cur[i].x; o4.y += w * cur[i].y; o4.z += w * cur[i].z; o4.w += w * cur[i].w; }
; #pragma unroll
;         for (int i = 0; i < NB; ++i) cur[i] = nx[i];
	v_pk_fma_f32 v[2:3], v[22:23], v[64:65], v[2:3] op_sel_hi:[1,0,1]
	s_waitcnt vmcnt(3)
	v_pk_fma_f32 v[2:3], v[26:27], v[10:11], v[2:3] op_sel_hi:[1,0,1]
	s_nop 0
	v_pk_fma_f32 v[2:3], v[36:37], v[66:67], v[2:3] op_sel_hi:[1,0,1]
	s_waitcnt vmcnt(2)
	v_pk_fma_f32 v[2:3], v[40:41], v[14:15], v[2:3] op_sel_hi:[1,0,1]
	s_waitcnt vmcnt(1)
	v_pk_fma_f32 v[2:3], v[52:53], v[68:69], v[2:3] op_sel_hi:[1,0,1]
	s_waitcnt vmcnt(0)
	v_pk_fma_f32 v[56:57], v[56:57], v[18:19], v[2:3] op_sel_hi:[1,0,1]
	v_pk_fma_f32 v[2:3], v[4:5], v[30:31], v[60:61] op_sel_hi:[1,0,1]
	s_nop 0
	v_pk_fma_f32 v[2:3], v[8:9], v[32:33], v[2:3] op_sel_hi:[1,0,1]
	ds_read2_b32 v[8:9], v99 offset0:176 offset1:180
	v_pk_fma_f32 v[2:3], v[12:13], v[70:71], v[2:3] op_sel_hi:[1,0,1]
	s_waitcnt lgkmcnt(0)
	v_mov_b32_e32 v76, v9
	v_pk_fma_f32 v[2:3], v[16:17], v[62:63], v[2:3] op_sel_hi:[1,0,1]
	s_nop 0
	v_pk_fma_f32 v[2:3], v[20:21], v[6:7], v[2:3] op_sel_hi:[1,0,1]
	s_nop 0
	v_pk_fma_f32 v[2:3], v[24:25], v[64:65], v[2:3] op_sel_hi:[1,0,1]
	s_nop 0
	v_pk_fma_f32 v[2:3], v[28:29], v[10:11], v[2:3] op_sel_hi:[1,0,1]
	s_nop 0
	v_pk_fma_f32 v[2:3], v[38:39], v[66:67], v[2:3] op_sel_hi:[1,0,1]
	s_nop 0
	v_pk_fma_f32 v[2:3], v[42:43], v[14:15], v[2:3] op_sel_hi:[1,0,1]
	s_nop 0
	v_pk_fma_f32 v[2:3], v[54:55], v[68:69], v[2:3] op_sel_hi:[1,0,1]
	s_nop 0
	v_pk_fma_f32 v[6:7], v[58:59], v[18:19], v[2:3] op_sel_hi:[1,0,1]
	v_add_co_u32_e32 v2, vcc, s25, v34
	s_nop 1
	v_addc_co_u32_e32 v3, vcc, 0, v35, vcc
	global_load_dwordx4 v[10:13], v[2:3], off nt
	v_add_co_u32_e32 v2, vcc, s43, v34
	s_waitcnt vmcnt(0)
	v_pk_fma_f32 v[10:11], v[10:11], v[8:9], v[56:57] op_sel_hi:[1,0,1]
	v_addc_co_u32_e32 v3, vcc, 0, v35, vcc
	global_load_dwordx4 v[14:17], v[2:3], off offset:2048 nt
	v_add_co_u32_e32 v2, vcc, s80, v34
	ds_read2_b32 v[32:33], v99 offset0:184 offset1:188
	ds_read2_b32 v[68:69], v99 offset0:192 offset1:196
	ds_read2_b32 v[70:71], v99 offset0:200 offset1:204
	ds_read2_b32 v[72:73], v99 offset0:208 offset1:212
	ds_read2_b32 v[74:75], v99 offset0:216 offset1:220
	v_addc_co_u32_e32 v3, vcc, 0, v35, vcc
	v_add_co_u32_e32 v18, vcc, s29, v34
	global_load_dwordx4 v[2:5], v[2:3], off offset:2048 nt
	s_nop 0
	v_addc_co_u32_e32 v19, vcc, 0, v35, vcc
	v_add_co_u32_e32 v22, vcc, s68, v34
	global_load_dwordx4 v[18:21], v[18:19], off nt
	s_nop 0
	v_addc_co_u32_e32 v23, vcc, 0, v35, vcc
	v_add_co_u32_e32 v26, vcc, s69, v34
	global_load_dwordx4 v[22:25], v[22:23], off offset:2048 nt
	s_nop 0
	v_addc_co_u32_e32 v27, vcc, 0, v35, vcc
	v_add_co_u32_e32 v36, vcc, s70, v34
	global_load_dwordx4 v[26:29], v[26:27], off nt
	s_nop 0
	v_addc_co_u32_e32 v37, vcc, 0, v35, vcc
	v_add_co_u32_e32 v40, vcc, s71, v34
	global_load_dwordx4 v[36:39], v[36:37], off offset:2048 nt
	s_nop 0
	v_addc_co_u32_e32 v41, vcc, 0, v35, vcc
	v_add_co_u32_e32 v52, vcc, s72, v34
	global_load_dwordx4 v[40:43], v[40:41], off nt
	s_nop 0
	v_addc_co_u32_e32 v53, vcc, 0, v35, vcc
	global_load_dwordx4 v[52:55], v[52:53], off offset:2048 nt
	v_pk_fma_f32 v[6:7], v[12:13], v[8:9], v[6:7] op_sel_hi:[1,0,1]
	s_waitcnt lgkmcnt(4)
	v_mov_b32_e32 v78, v33
	s_waitcnt lgkmcnt(0)
	v_mov_b32_e32 v30, v75
	s_waitcnt vmcnt(7)
	v_pk_fma_f32 v[10:11], v[14:15], v[76:77], v[10:11] op_sel_hi:[1,0,1]
	v_add_co_u32_e32 v14, vcc, s73, v34
	v_pk_fma_f32 v[6:7], v[16:17], v[76:77], v[6:7] op_sel_hi:[1,0,1]
	s_nop 0
	v_addc_co_u32_e32 v15, vcc, 0, v35, vcc
	global_load_dwordx4 v[56:59], v[14:15], off nt
	v_add_co_u32_e32 v14, vcc, s74, v34
	s_nop 1
	v_addc_co_u32_e32 v15, vcc, 0, v35, vcc
	global_load_dwordx4 v[60:63], v[14:15], off offset:2048 nt
	v_add_co_u32_e32 v14, vcc, s75, v34
	s_nop 1
	v_addc_co_u32_e32 v15, vcc, 0, v35, vcc
	global_load_dwordx4 v[64:67], v[14:15], off nt
	s_waitcnt vmcnt(8)
	v_pk_fma_f32 v[10:11], v[18:19], v[32:33], v[10:11] op_sel_hi:[1,0,1]
	v_pk_fma_f32 v[6:7], v[20:21], v[32:33], v[6:7] op_sel_hi:[1,0,1]
	s_waitcnt vmcnt(7)
	v_pk_fma_f32 v[10:11], v[22:23], v[78:79], v[10:11] op_sel_hi:[1,0,1]
	v_pk_fma_f32 v[6:7], v[24:25], v[78:79], v[6:7] op_sel_hi:[1,0,1]
	v_mov_b32_e32 v14, v69
	s_waitcnt vmcnt(6)
	v_pk_fma_f32 v[10:11], v[26:27], v[68:69], v[10:11] op_sel_hi:[1,0,1]
	v_pk_fma_f32 v[6:7], v[28:29], v[68:69], v[6:7] op_sel_hi:[1,0,1]
	v_mov_b32_e32 v18, v71
	v_mov_b32_e32 v22, v73
	s_waitcnt vmcnt(5)
	v_pk_fma_f32 v[10:11], v[36:37], v[14:15], v[10:11] op_sel_hi:[1,0,1]
	v_pk_fma_f32 v[6:7], v[38:39], v[14:15], v[6:7] op_sel_hi:[1,0,1]
	ds_read2_b32 v[38:39], v99 offset0:224 offset1:228
	ds_read2_b32 v[32:33], v99 offset0:232 offset1:236
	s_waitcnt vmcnt(4)
; template <int NB>
; __device__ __forceinline__ void sb_decode_task(const Params& P, float* lds, int task) {
;     ...
;     for (int vb = 0; vb < NBT; ++vb) {
;         if (vb + 1 < NBT) {
; #pragma unroll
;             for (int i = 0; i < NB; ++i) nx[i] = *(const float4*)(Vp + (size_t)(4 * NB * (vb + 1) + 4 * i + g) * (SH * HD)); }
; #pragma unroll
;         for (int i = 0; i < NB; ++i) { const float w = wl[4 * NB * vb + 4 * i + g]; o4.x += w * cur[i].x; o4.y += w * cur[i].y; o4.z += w * cur[i].z; o4.w += w * cur[i].w; }
; #pragma unroll
;         for (int i = 0; i < NB; ++i) cur[i] = nx[i];
;     }
; #pragma unroll
;     for (int off = 16; off < 64; off <<= 1) { o4.x += __shfl_xor(o4.x, off); o4.y += __shfl_xor(o4.y, off); o4.z += __shfl_xor(o4.z, off); o4.w += __shfl_xor(o4.w, off); }
;     if (g == 0) *(float4*)(dpart + (size_t)task * HD + 4 * c) = o4;
;     if (lane == 0) dl[task] = Ltot;
;     __builtin_amdgcn_wave_barrier();
	v_pk_fma_f32 v[10:11], v[40:41], v[70:71], v[10:11] op_sel_hi:[1,0,1]
	v_pk_fma_f32 v[6:7], v[42:43], v[70:71], v[6:7] op_sel_hi:[1,0,1]
	s_waitcnt vmcnt(3)
	v_pk_fma_f32 v[10:11], v[52:53], v[18:19], v[10:11] op_sel_hi:[1,0,1]
	v_pk_fma_f32 v[6:7], v[54:55], v[18:19], v[6:7] op_sel_hi:[1,0,1]
	s_waitcnt vmcnt(2)
	v_pk_fma_f32 v[10:11], v[56:57], v[72:73], v[10:11] op_sel_hi:[1,0,1]
	v_pk_fma_f32 v[6:7], v[58:59], v[72:73], v[6:7] op_sel_hi:[1,0,1]
	s_waitcnt vmcnt(1)
	v_pk_fma_f32 v[10:11], v[60:61], v[22:23], v[10:11] op_sel_hi:[1,0,1]
	v_pk_fma_f32 v[6:7], v[62:63], v[22:23], v[6:7] op_sel_hi:[1,0,1]
	s_waitcnt vmcnt(0)
	v_pk_fma_f32 v[26:27], v[64:65], v[74:75], v[10:11] op_sel_hi:[1,0,1]
	v_pk_fma_f32 v[36:37], v[66:67], v[74:75], v[6:7] op_sel_hi:[1,0,1]
	v_add_co_u32_e32 v6, vcc, s81, v34
	v_and_b32_e32 v10, 64, v105
	s_nop 0
	v_addc_co_u32_e32 v7, vcc, 0, v35, vcc
	v_add_u32_e32 v60, 64, v10
	v_xor_b32_e32 v10, 16, v105
	v_cmp_lt_i32_e32 vcc, v10, v60
	global_load_dwordx4 v[6:9], v[6:7], off nt
	ds_read2_b32 v[42:43], v99 offset0:240 offset1:244
	ds_read2_b32 v[40:41], v99 offset0:248 offset1:252
	v_cndmask_b32_e32 v10, v105, v10, vcc
	v_lshlrev_b32_e32 v45, 2, v10
	v_add_co_u32_e32 v10, vcc, s82, v34
	v_pk_fma_f32 v[2:3], v[2:3], v[30:31], v[26:27] op_sel_hi:[1,0,1]
	s_nop 0
	v_addc_co_u32_e32 v11, vcc, 0, v35, vcc
	v_add_co_u32_e32 v14, vcc, s83, v34
	global_load_dwordx4 v[10:13], v[10:11], off offset:2048 nt
	s_nop 0
	v_addc_co_u32_e32 v15, vcc, 0, v35, vcc
	v_add_co_u32_e32 v18, vcc, s84, v34
	global_load_dwordx4 v[14:17], v[14:15], off nt
	s_nop 0
	v_addc_co_u32_e32 v19, vcc, 0, v35, vcc
	v_add_co_u32_e32 v22, vcc, s85, v34
	global_load_dwordx4 v[18:21], v[18:19], off offset:2048 nt
	s_nop 0
	v_addc_co_u32_e32 v23, vcc, 0, v35, vcc
	v_add_co_u32_e32 v26, vcc, s86, v34
	global_load_dwordx4 v[22:25], v[22:23], off nt
	s_nop 0
	v_addc_co_u32_e32 v27, vcc, 0, v35, vcc
	v_add_co_u32_e32 v52, vcc, s87, v34
	global_load_dwordx4 v[26:29], v[26:27], off offset:2048 nt
	s_nop 0
	v_addc_co_u32_e32 v53, vcc, 0, v35, vcc
	v_add_co_u32_e32 v34, vcc, s88, v34
	global_load_dwordx4 v[52:55], v[52:53], off nt
	s_nop 0
	v_addc_co_u32_e32 v35, vcc, 0, v35, vcc
	global_load_dwordx4 v[56:59], v[34:35], off offset:2048 nt
	v_pk_fma_f32 v[4:5], v[4:5], v[30:31], v[36:37] op_sel_hi:[1,0,1]
	s_waitcnt vmcnt(7) lgkmcnt(3)
	v_pk_fma_f32 v[2:3], v[6:7], v[38:39], v[2:3] op_sel_hi:[1,0,1]
	v_mov_b32_e32 v6, v39
	v_pk_fma_f32 v[4:5], v[8:9], v[38:39], v[4:5] op_sel_hi:[1,0,1]
	s_waitcnt vmcnt(6)
	v_pk_fma_f32 v[2:3], v[10:11], v[6:7], v[2:3] op_sel_hi:[1,0,1]
	v_pk_fma_f32 v[4:5], v[12:13], v[6:7], v[4:5] op_sel_hi:[1,0,1]
	s_waitcnt lgkmcnt(2)
	v_mov_b32_e32 v10, v33
	s_waitcnt vmcnt(5)
	v_pk_fma_f32 v[4:5], v[16:17], v[32:33], v[4:5] op_sel_hi:[1,0,1]
	v_pk_fma_f32 v[2:3], v[14:15], v[32:33], v[2:3] op_sel_hi:[1,0,1]
	s_waitcnt lgkmcnt(1)
	v_mov_b32_e32 v14, v43
	s_waitcnt vmcnt(4)
	v_pk_fma_f32 v[4:5], v[20:21], v[10:11], v[4:5] op_sel_hi:[1,0,1]
	v_pk_fma_f32 v[2:3], v[18:19], v[10:11], v[2:3] op_sel_hi:[1,0,1]
	s_waitcnt lgkmcnt(0)
	v_mov_b32_e32 v18, v41
	ds_bpermute_b32 v10, v44, v31
	s_waitcnt vmcnt(3)
	v_pk_fma_f32 v[4:5], v[24:25], v[42:43], v[4:5] op_sel_hi:[1,0,1]
	v_pk_fma_f32 v[2:3], v[22:23], v[42:43], v[2:3] op_sel_hi:[1,0,1]
	s_waitcnt vmcnt(2)
	v_pk_fma_f32 v[4:5], v[28:29], v[14:15], v[4:5] op_sel_hi:[1,0,1]
	v_pk_fma_f32 v[2:3], v[26:27], v[14:15], v[2:3] op_sel_hi:[1,0,1]
	s_waitcnt vmcnt(1)
	v_pk_fma_f32 v[4:5], v[54:55], v[40:41], v[4:5] op_sel_hi:[1,0,1]
	v_pk_fma_f32 v[2:3], v[52:53], v[40:41], v[2:3] op_sel_hi:[1,0,1]
	s_waitcnt vmcnt(0)
	v_pk_fma_f32 v[4:5], v[58:59], v[18:19], v[4:5] op_sel_hi:[1,0,1]
	ds_bpermute_b32 v6, v45, v4
	ds_bpermute_b32 v7, v45, v5
	v_pk_fma_f32 v[2:3], v[56:57], v[18:19], v[2:3] op_sel_hi:[1,0,1]
	ds_bpermute_b32 v22, v45, v2
	ds_bpermute_b32 v23, v45, v3
	s_waitcnt lgkmcnt(2)
	v_pk_add_f32 v[4:5], v[4:5], v[6:7]
	v_xor_b32_e32 v6, 32, v105
	v_cmp_lt_i32_e32 vcc, v6, v60
	s_waitcnt lgkmcnt(0)
	v_pk_add_f32 v[2:3], v[2:3], v[22:23]
	v_cndmask_b32_e32 v6, v105, v6, vcc
	v_lshlrev_b32_e32 v52, 2, v6
	ds_bpermute_b32 v6, v52, v2
	ds_bpermute_b32 v7, v52, v3
	ds_bpermute_b32 v8, v52, v4
	ds_bpermute_b32 v9, v52, v5
	s_and_saveexec_b64 s[0:1], s[20:21]
	s_cbranch_execz .LBB0_1485
	s_ashr_i32 s35, s34, 31
	s_lshl_b64 s[2:3], s[34:35], 8
	v_lshl_add_u64 v[12:13], v[88:89], 0, s[2:3]
	s_waitcnt lgkmcnt(2)
	v_pk_add_f32 v[2:3], v[2:3], v[6:7]
	s_waitcnt lgkmcnt(0)
	v_pk_add_f32 v[4:5], v[4:5], v[8:9]
	global_store_dwordx4 v[12:13], v[2:5], off

; __device__ __forceinline__ float bf2f(bf16_t b) { return __uint_as_float(((unsigned)b) << 16); }
; template <int NB>
; __device__ __forceinline__ void sb_decode_task(const Params& P, float* lds, int task) {
;     ...
;     constexpr int NBT = 32 / NB;
;     const int h = task % SH, bj = task / SH, b = bj / NPAGES;
;     const int page = P.page_table[bj];
;     const float* Kp = P.cache_k + ((size_t)page * PAGE * SH + h) * HD + 4 * c;
;     const float* Vp = P.cache_v + ((size_t)page * PAGE * SH + h) * HD + 4 * c;
;     const bf16_t* qp = qb + (size_t)(NTOK + b) * SBW + h * 64 + 4 * c;
;     const float q0 = bf2f(qp[0]), q1 = bf2f(qp[1]), q2 = bf2f(qp[2]), q3 = bf2f(qp[3]);
;     const float bias = P.sb_bias[h] * LOG2E;
;     float4 cur[NB], nx[NB];
; #pragma unroll
;     for (int i = 0; i < NB; ++i) cur[i] = *(const float4*)(Kp + (size_t)(4 * i + g) * (SH * HD));
; #pragma unroll
;     for (int kb = 0; kb < NBT; ++kb) {
;         const float* np = (kb + 1 < NBT) ? Kp + (size_t)(4 * NB * (kb + 1)) * (SH * HD) : Vp;
; #pragma unroll
;         for (int i = 0; i < NB; ++i) nx[i] = *(const float4*)(np + (size_t)(4 * i + g) * (SH * HD));
; #pragma unroll
;         for (int i = 0; i < NB; ++i) { const int s = 4 * NB * kb + 4 * i + g;
;             float part = q0 * cur[i].x + q1 * cur[i].y + q2 * cur[i].z + q3 * cur[i].w; part = sum16(part);
;             if (c == 0) zl[s] = part + bias; }
.LBB0_1487:
	s_or_b64 exec, exec, s[0:1]
	v_readlane_b32 s36, v252, 48
	s_add_i32 s34, s34, 1
	v_readlane_b32 s37, v252, 49
	s_mul_hi_i32 s1, s34, 0x2aaaaaab
	s_load_dwordx16 s[52:67], s[36:37], 0x0
	s_lshr_b32 s3, s1, 31
	s_add_i32 s0, s1, s3
	s_ashr_i32 s1, s1, 7
	s_mul_i32 s2, s0, 6
	s_add_i32 s33, s1, s3
	s_ashr_i32 s1, s0, 31
	s_sub_i32 s2, s34, s2
	s_lshl_b64 s[0:1], s[0:1], 2
	s_waitcnt lgkmcnt(0)
	s_add_u32 s0, s62, s0
	s_addc_u32 s1, s63, s1
	v_mov_b32_e32 v2, v253
	s_add_i32 s0, s33, 0x4000
	s_ashr_i32 s3, s2, 31
	s_mul_hi_i32 s1, s0, 0x300
	s_mulk_i32 s0, 0x300
	s_add_u32 s33, s38, s0
	s_addc_u32 s35, s39, s1
	s_lshl_b32 s0, s2, 6
	s_ashr_i32 s1, s0, 31
	s_lshl_b64 s[0:1], s[0:1], 1
	s_add_u32 s0, s33, s0
	s_addc_u32 s1, s35, s1
	v_readlane_b32 s52, v252, 16
	v_readlane_b32 s53, v252, 17
	v_readlane_b32 s60, v252, 24
	v_readlane_b32 s61, v252, 25
	s_mov_b64 s[52:53], s[60:61]
	v_readlane_b32 s54, v252, 18
	v_readlane_b32 s55, v252, 19
	v_readlane_b32 s56, v252, 20
	v_readlane_b32 s57, v252, 21
	v_readlane_b32 s58, v252, 22
	v_readlane_b32 s59, v252, 23
	v_readlane_b32 s62, v252, 26
	v_readlane_b32 s63, v252, 27
	v_readlane_b32 s64, v252, 28
	v_readlane_b32 s65, v252, 29
	v_readlane_b32 s66, v252, 30
	v_readlane_b32 s67, v252, 31
	v_mul_hi_i32 v3, v2, s48
	v_mul_lo_u32 v2, v2, s48
	v_lshl_add_u64 v[42:43], v[2:3], 0, s[2:3]
	v_lshlrev_b64 v[2:3], 8, v[42:43]
	v_lshl_add_u64 v[38:39], v[84:85], 0, v[2:3]
	global_load_dwordx2 v[2:3], v101, s[0:1]
	s_lshl_b64 s[0:1], s[2:3], 2
	s_add_u32 s0, s52, s0
	s_addc_u32 s1, s53, s1
	global_load_dword v6, v83, s[0:1]
	s_waitcnt vmcnt(1)
	v_lshlrev_b32_e32 v54, 16, v2
	v_and_b32_e32 v56, 0xffff0000, v2
	v_lshlrev_b32_e32 v55, 16, v3
	v_and_b32_e32 v53, 0xffff0000, v3
	v_lshl_add_u64 v[2:3], v[38:39], 0, v[82:83]
	v_add_co_u32_e32 v4, vcc, s50, v2
	global_load_dwordx4 v[30:33], v[2:3], off nt
	s_nop 0
	v_addc_co_u32_e32 v5, vcc, 0, v3, vcc
	global_load_dwordx4 v[26:29], v[4:5], off offset:2048 nt
	v_add_co_u32_e32 v4, vcc, s51, v2
	s_waitcnt vmcnt(2)
	v_mul_f32_e32 v57, 0x3fb8aa3b, v6
	v_addc_co_u32_e32 v5, vcc, 0, v3, vcc
	global_load_dwordx4 v[22:25], v[4:5], off nt
	v_add_co_u32_e32 v4, vcc, s49, v2
	s_waitcnt vmcnt(2)
	v_mul_f32_e32 v31, v31, v56
	v_addc_co_u32_e32 v5, vcc, 0, v3, vcc
	global_load_dwordx4 v[14:17], v[4:5], off offset:2048 nt
	v_add_co_u32_e32 v4, vcc, s89, v2
	v_fmac_f32_e32 v31, v30, v54
	s_nop 0
	v_addc_co_u32_e32 v5, vcc, 0, v3, vcc
	global_load_dwordx4 v[18:21], v[4:5], off nt
	v_add_co_u32_e32 v4, vcc, s92, v2
	v_fmac_f32_e32 v31, v32, v55
	s_nop 0
	v_addc_co_u32_e32 v5, vcc, 0, v3, vcc
	global_load_dwordx4 v[6:9], v[4:5], off offset:2048 nt
	v_add_co_u32_e32 v4, vcc, s93, v2
	v_fmac_f32_e32 v31, v33, v53
	s_nop 0
	v_addc_co_u32_e32 v5, vcc, 0, v3, vcc
	v_add_co_u32_e32 v2, vcc, s96, v2
	global_load_dwordx4 v[10:13], v[4:5], off nt
	s_nop 0
	v_addc_co_u32_e32 v3, vcc, 0, v3, vcc
	global_load_dwordx4 v[2:5], v[2:3], off offset:2048 nt
	v_add_f32_dpp v30, v31, v31 quad_perm:[1,0,3,2] row_mask:0xf bank_mask:0xf bound_ctrl:1
	s_nop 1
	v_add_f32_dpp v30, v30, v30 quad_perm:[2,3,0,1] row_mask:0xf bank_mask:0xf bound_ctrl:1
	s_nop 1
	v_add_f32_dpp v30, v30, v30 row_ror:4 row_mask:0xf bank_mask:0xf bound_ctrl:1
	s_nop 1
	v_mov_b32_dpp v31, v30 row_ror:8 row_mask:0xf bank_mask:0xf bound_ctrl:1
	s_and_saveexec_b64 s[0:1], s[6:7]
	v_add_f32_e32 v30, v30, v31
	v_add_f32_e32 v30, v57, v30
	ds_write_b32 v99, v30
	s_or_b64 exec, exec, s[0:1]
	s_waitcnt vmcnt(6)
	v_mul_f32_e32 v27, v27, v56
	v_fmac_f32_e32 v27, v26, v54
	v_fmac_f32_e32 v27, v28, v55
	v_fmac_f32_e32 v27, v29, v53
	s_nop 1
	v_add_f32_dpp v26, v27, v27 quad_perm:[1,0,3,2] row_mask:0xf bank_mask:0xf bound_ctrl:1
	s_nop 1
	v_add_f32_dpp v26, v26, v26 quad_perm:[2,3,0,1] row_mask:0xf bank_mask:0xf bound_ctrl:1
	s_nop 1
	v_add_f32_dpp v26, v26, v26 row_ror:4 row_mask:0xf bank_mask:0xf bound_ctrl:1
	s_nop 1
	v_mov_b32_dpp v27, v26 row_ror:8 row_mask:0xf bank_mask:0xf bound_ctrl:1
	s_and_saveexec_b64 s[0:1], s[6:7]
	v_add_f32_e32 v26, v26, v27
	v_add_f32_e32 v26, v57, v26
	ds_write_b32 v99, v26 offset:16
	s_or_b64 exec, exec, s[0:1]
	s_waitcnt vmcnt(5)
	v_mul_f32_e32 v23, v23, v56
	v_fmac_f32_e32 v23, v22, v54
	v_fmac_f32_e32 v23, v24, v55
	v_fmac_f32_e32 v23, v25, v53
	s_nop 1
	v_add_f32_dpp v22, v23, v23 quad_perm:[1,0,3,2] row_mask:0xf bank_mask:0xf bound_ctrl:1
	s_nop 1
	v_add_f32_dpp v22, v22, v22 quad_perm:[2,3,0,1] row_mask:0xf bank_mask:0xf bound_ctrl:1
	s_nop 1
	v_add_f32_dpp v22, v22, v22 row_ror:4 row_mask:0xf bank_mask:0xf bound_ctrl:1
	s_nop 1
	v_mov_b32_dpp v23, v22 row_ror:8 row_mask:0xf bank_mask:0xf bound_ctrl:1
	s_and_saveexec_b64 s[0:1], s[6:7]
	v_add_f32_e32 v22, v22, v23
	v_add_f32_e32 v22, v57, v22
	ds_write_b32 v99, v22 offset:32
	s_or_b64 exec, exec, s[0:1]
	s_waitcnt vmcnt(4)
	v_mul_f32_e32 v15, v15, v56
	v_fmac_f32_e32 v15, v14, v54
	v_fmac_f32_e32 v15, v16, v55
	v_fmac_f32_e32 v15, v17, v53
	s_nop 1
	v_add_f32_dpp v14, v15, v15 quad_perm:[1,0,3,2] row_mask:0xf bank_mask:0xf bound_ctrl:1
	s_nop 1
	v_add_f32_dpp v14, v14, v14 quad_perm:[2,3,0,1] row_mask:0xf bank_mask:0xf bound_ctrl:1
	s_nop 1
	v_add_f32_dpp v14, v14, v14 row_ror:4 row_mask:0xf bank_mask:0xf bound_ctrl:1
	s_nop 1
	v_mov_b32_dpp v15, v14 row_ror:8 row_mask:0xf bank_mask:0xf bound_ctrl:1
	s_and_saveexec_b64 s[0:1], s[6:7]
	v_add_f32_e32 v14, v14, v15
	v_add_f32_e32 v14, v57, v14
	ds_write_b32 v99, v14 offset:48
	s_or_b64 exec, exec, s[0:1]
	v_lshl_add_u64 v[14:15], v[38:39], 0, v[82:83]
	v_add_co_u32_e32 v16, vcc, 0xc000, v14
	s_waitcnt vmcnt(3)
; template <int NB>
; __device__ __forceinline__ void sb_decode_task(const Params& P, float* lds, int task) {
;     ...
;     for (int kb = 0; kb < NBT; ++kb) {
;         const float* np = (kb + 1 < NBT) ? Kp + (size_t)(4 * NB * (kb + 1)) * (SH * HD) : Vp;
; #pragma unroll
;         for (int i = 0; i < NB; ++i) nx[i] = *(const float4*)(np + (size_t)(4 * i + g) * (SH * HD));
; #pragma unroll
;         for (int i = 0; i < NB; ++i) { const int s = 4 * NB * kb + 4 * i + g;
;             float part = q0 * cur[i].x + q1 * cur[i].y + q2 * cur[i].z + q3 * cur[i].w; part = sum16(part);
;             if (c == 0) zl[s] = part + bias; }
; #pragma unroll
;         for (int i = 0; i < NB; ++i) cur[i] = nx[i];
;     }
	v_mul_f32_e32 v19, v19, v56
	v_addc_co_u32_e32 v17, vcc, 0, v15, vcc
	v_add_co_u32_e32 v22, vcc, 0xd000, v14
	v_fmac_f32_e32 v19, v18, v54
	s_nop 0
	v_addc_co_u32_e32 v23, vcc, 0, v15, vcc
	global_load_dwordx4 v[30:33], v[16:17], off nt
	global_load_dwordx4 v[26:29], v[22:23], off offset:2048 nt
	v_add_co_u32_e32 v16, vcc, 0xf000, v14
	v_fmac_f32_e32 v19, v20, v55
	s_nop 0
	v_addc_co_u32_e32 v17, vcc, 0, v15, vcc
	v_add_co_u32_e32 v14, vcc, 0x10000, v14
	v_fmac_f32_e32 v19, v21, v53
	s_nop 0
	v_addc_co_u32_e32 v15, vcc, 0, v15, vcc
	global_load_dwordx4 v[22:25], v[16:17], off nt
	s_nop 0
	global_load_dwordx4 v[14:17], v[14:15], off offset:2048 nt
	v_add_f32_dpp v18, v19, v19 quad_perm:[1,0,3,2] row_mask:0xf bank_mask:0xf bound_ctrl:1
	s_nop 1
	v_add_f32_dpp v18, v18, v18 quad_perm:[2,3,0,1] row_mask:0xf bank_mask:0xf bound_ctrl:1
	s_nop 1
	v_add_f32_dpp v18, v18, v18 row_ror:4 row_mask:0xf bank_mask:0xf bound_ctrl:1
	s_nop 1
	v_mov_b32_dpp v19, v18 row_ror:8 row_mask:0xf bank_mask:0xf bound_ctrl:1
	s_and_saveexec_b64 s[0:1], s[6:7]
	v_add_f32_e32 v18, v18, v19
	v_add_f32_e32 v18, v57, v18
	ds_write_b32 v99, v18 offset:64
	s_or_b64 exec, exec, s[0:1]
	s_waitcnt vmcnt(6)
	v_mul_f32_e32 v7, v7, v56
	v_fmac_f32_e32 v7, v6, v54
	v_fmac_f32_e32 v7, v8, v55
	v_fmac_f32_e32 v7, v9, v53
	s_nop 1
	v_add_f32_dpp v6, v7, v7 quad_perm:[1,0,3,2] row_mask:0xf bank_mask:0xf bound_ctrl:1
	s_nop 1
	v_add_f32_dpp v6, v6, v6 quad_perm:[2,3,0,1] row_mask:0xf bank_mask:0xf bound_ctrl:1
	s_nop 1
	v_add_f32_dpp v6, v6, v6 row_ror:4 row_mask:0xf bank_mask:0xf bound_ctrl:1
	s_nop 1
	v_mov_b32_dpp v7, v6 row_ror:8 row_mask:0xf bank_mask:0xf bound_ctrl:1
	s_and_saveexec_b64 s[0:1], s[6:7]
	v_add_f32_e32 v6, v6, v7
	v_add_f32_e32 v6, v57, v6
	ds_write_b32 v99, v6 offset:80
	s_or_b64 exec, exec, s[0:1]
	s_waitcnt vmcnt(5)
	v_mul_f32_e32 v6, v11, v56
	v_fmac_f32_e32 v6, v10, v54
	v_fmac_f32_e32 v6, v12, v55
	v_fmac_f32_e32 v6, v13, v53
	s_nop 1
	v_add_f32_dpp v6, v6, v6 quad_perm:[1,0,3,2] row_mask:0xf bank_mask:0xf bound_ctrl:1
	s_nop 1
	v_add_f32_dpp v6, v6, v6 quad_perm:[2,3,0,1] row_mask:0xf bank_mask:0xf bound_ctrl:1
	s_nop 1
	v_add_f32_dpp v6, v6, v6 row_ror:4 row_mask:0xf bank_mask:0xf bound_ctrl:1
	s_nop 1
	v_mov_b32_dpp v7, v6 row_ror:8 row_mask:0xf bank_mask:0xf bound_ctrl:1
	s_and_saveexec_b64 s[0:1], s[6:7]
	v_add_f32_e32 v6, v6, v7
	v_add_f32_e32 v6, v57, v6
	ds_write_b32 v99, v6 offset:96
	s_or_b64 exec, exec, s[0:1]
	s_waitcnt vmcnt(4)
	v_mul_f32_e32 v3, v3, v56
	v_fmac_f32_e32 v3, v2, v54
	v_fmac_f32_e32 v3, v4, v55
	v_fmac_f32_e32 v3, v5, v53
	s_nop 1
	v_add_f32_dpp v2, v3, v3 quad_perm:[1,0,3,2] row_mask:0xf bank_mask:0xf bound_ctrl:1
	s_nop 1
	v_add_f32_dpp v2, v2, v2 quad_perm:[2,3,0,1] row_mask:0xf bank_mask:0xf bound_ctrl:1
	s_nop 1
	v_add_f32_dpp v2, v2, v2 row_ror:4 row_mask:0xf bank_mask:0xf bound_ctrl:1
	s_nop 1
	v_mov_b32_dpp v3, v2 row_ror:8 row_mask:0xf bank_mask:0xf bound_ctrl:1
	s_and_saveexec_b64 s[0:1], s[6:7]
	v_add_f32_e32 v2, v2, v3
	v_add_f32_e32 v2, v57, v2
	ds_write_b32 v99, v2 offset:112
	s_or_b64 exec, exec, s[0:1]
	v_lshl_add_u64 v[2:3], v[38:39], 0, v[82:83]
	v_add_co_u32_e32 v4, vcc, 0x12000, v2
	s_nop 1
	v_addc_co_u32_e32 v5, vcc, 0, v3, vcc
	v_add_co_u32_e32 v6, vcc, 0x13000, v2
	s_nop 1
	v_addc_co_u32_e32 v7, vcc, 0, v3, vcc
	global_load_dwordx4 v[34:37], v[4:5], off nt
	global_load_dwordx4 v[18:21], v[6:7], off offset:2048 nt
	v_add_co_u32_e32 v4, vcc, 0x15000, v2
	s_waitcnt vmcnt(5)
	v_mul_f32_e32 v6, v31, v56
	v_addc_co_u32_e32 v5, vcc, 0, v3, vcc
	v_add_co_u32_e32 v2, vcc, 0x16000, v2
	v_fmac_f32_e32 v6, v30, v54
	s_nop 0
	v_addc_co_u32_e32 v3, vcc, 0, v3, vcc
	global_load_dwordx4 v[10:13], v[4:5], off nt
	s_nop 0
	global_load_dwordx4 v[2:5], v[2:3], off offset:2048 nt
	v_fmac_f32_e32 v6, v32, v55
	v_fmac_f32_e32 v6, v33, v53
	s_nop 1
	v_add_f32_dpp v6, v6, v6 quad_perm:[1,0,3,2] row_mask:0xf bank_mask:0xf bound_ctrl:1
	s_nop 1
	v_add_f32_dpp v6, v6, v6 quad_perm:[2,3,0,1] row_mask:0xf bank_mask:0xf bound_ctrl:1
	s_nop 1
	v_add_f32_dpp v6, v6, v6 row_ror:4 row_mask:0xf bank_mask:0xf bound_ctrl:1
	s_nop 1
	v_mov_b32_dpp v7, v6 row_ror:8 row_mask:0xf bank_mask:0xf bound_ctrl:1
	s_and_saveexec_b64 s[0:1], s[6:7]
	v_add_f32_e32 v6, v6, v7
	v_add_f32_e32 v6, v57, v6
	ds_write_b32 v99, v6 offset:128
	s_or_b64 exec, exec, s[0:1]
	s_waitcnt vmcnt(6)
	v_mul_f32_e32 v6, v27, v56
	v_fmac_f32_e32 v6, v26, v54
	v_fmac_f32_e32 v6, v28, v55
	v_fmac_f32_e32 v6, v29, v53
	s_nop 1
	v_add_f32_dpp v6, v6, v6 quad_perm:[1,0,3,2] row_mask:0xf bank_mask:0xf bound_ctrl:1
	s_nop 1
	v_add_f32_dpp v6, v6, v6 quad_perm:[2,3,0,1] row_mask:0xf bank_mask:0xf bound_ctrl:1
	s_nop 1
	v_add_f32_dpp v6, v6, v6 row_ror:4 row_mask:0xf bank_mask:0xf bound_ctrl:1
	s_nop 1
	v_mov_b32_dpp v7, v6 row_ror:8 row_mask:0xf bank_mask:0xf bound_ctrl:1
	s_and_saveexec_b64 s[0:1], s[6:7]
	v_add_f32_e32 v6, v6, v7
	v_add_f32_e32 v6, v57, v6
	ds_write_b32 v99, v6 offset:144
	s_or_b64 exec, exec, s[0:1]
	s_waitcnt vmcnt(5)
	v_mul_f32_e32 v6, v23, v56
	v_fmac_f32_e32 v6, v22, v54
	v_fmac_f32_e32 v6, v24, v55
	v_fmac_f32_e32 v6, v25, v53
	s_nop 1
	v_add_f32_dpp v6, v6, v6 quad_perm:[1,0,3,2] row_mask:0xf bank_mask:0xf bound_ctrl:1
	s_nop 1
	v_add_f32_dpp v6, v6, v6 quad_perm:[2,3,0,1] row_mask:0xf bank_mask:0xf bound_ctrl:1
	s_nop 1
	v_add_f32_dpp v6, v6, v6 row_ror:4 row_mask:0xf bank_mask:0xf bound_ctrl:1
	s_nop 1
	v_mov_b32_dpp v7, v6 row_ror:8 row_mask:0xf bank_mask:0xf bound_ctrl:1
	s_and_saveexec_b64 s[0:1], s[6:7]
	v_add_f32_e32 v6, v6, v7
	v_add_f32_e32 v6, v57, v6
	ds_write_b32 v99, v6 offset:160
	s_or_b64 exec, exec, s[0:1]
	s_waitcnt vmcnt(4)
; template <int NB>
; __device__ __forceinline__ void sb_decode_task(const Params& P, float* lds, int task) {
;     ...
;     for (int kb = 0; kb < NBT; ++kb) {
;         const float* np = (kb + 1 < NBT) ? Kp + (size_t)(4 * NB * (kb + 1)) * (SH * HD) : Vp;
; #pragma unroll
;         for (int i = 0; i < NB; ++i) nx[i] = *(const float4*)(np + (size_t)(4 * i + g) * (SH * HD));
; #pragma unroll
;         for (int i = 0; i < NB; ++i) { const int s = 4 * NB * kb + 4 * i + g;
;             float part = q0 * cur[i].x + q1 * cur[i].y + q2 * cur[i].z + q3 * cur[i].w; part = sum16(part);
;             if (c == 0) zl[s] = part + bias; }
; #pragma unroll
;         for (int i = 0; i < NB; ++i) cur[i] = nx[i];
;     }
	v_mul_f32_e32 v6, v15, v56
	v_fmac_f32_e32 v6, v14, v54
	v_fmac_f32_e32 v6, v16, v55
	v_fmac_f32_e32 v6, v17, v53
	s_nop 1
	v_add_f32_dpp v6, v6, v6 quad_perm:[1,0,3,2] row_mask:0xf bank_mask:0xf bound_ctrl:1
	s_nop 1
	v_add_f32_dpp v6, v6, v6 quad_perm:[2,3,0,1] row_mask:0xf bank_mask:0xf bound_ctrl:1
	s_nop 1
	v_add_f32_dpp v6, v6, v6 row_ror:4 row_mask:0xf bank_mask:0xf bound_ctrl:1
	s_nop 1
	v_mov_b32_dpp v7, v6 row_ror:8 row_mask:0xf bank_mask:0xf bound_ctrl:1
	s_and_saveexec_b64 s[0:1], s[6:7]
	v_add_f32_e32 v6, v6, v7
	v_add_f32_e32 v6, v57, v6
	ds_write_b32 v99, v6 offset:176
	s_or_b64 exec, exec, s[0:1]
	v_lshl_add_u64 v[6:7], v[38:39], 0, v[82:83]
	v_add_co_u32_e32 v8, vcc, 0x18000, v6
	s_waitcnt vmcnt(3)
	v_mul_f32_e32 v30, v35, v56
	v_addc_co_u32_e32 v9, vcc, 0, v7, vcc
	v_add_co_u32_e32 v14, vcc, 0x19000, v6
	v_fmac_f32_e32 v30, v34, v54
	s_nop 0
	v_addc_co_u32_e32 v15, vcc, 0, v7, vcc
	global_load_dwordx4 v[26:29], v[8:9], off nt
	global_load_dwordx4 v[22:25], v[14:15], off offset:2048 nt
	v_add_co_u32_e32 v8, vcc, 0x1b000, v6
	v_fmac_f32_e32 v30, v36, v55
	s_nop 0
	v_addc_co_u32_e32 v9, vcc, 0, v7, vcc
	v_add_co_u32_e32 v6, vcc, 0x1c000, v6
	v_fmac_f32_e32 v30, v37, v53
	s_nop 0
	v_addc_co_u32_e32 v7, vcc, 0, v7, vcc
	global_load_dwordx4 v[14:17], v[8:9], off nt
	s_nop 0
	global_load_dwordx4 v[6:9], v[6:7], off offset:2048 nt
	v_add_f32_dpp v30, v30, v30 quad_perm:[1,0,3,2] row_mask:0xf bank_mask:0xf bound_ctrl:1
	s_nop 1
	v_add_f32_dpp v30, v30, v30 quad_perm:[2,3,0,1] row_mask:0xf bank_mask:0xf bound_ctrl:1
	s_nop 1
	v_add_f32_dpp v30, v30, v30 row_ror:4 row_mask:0xf bank_mask:0xf bound_ctrl:1
	s_nop 1
	v_mov_b32_dpp v31, v30 row_ror:8 row_mask:0xf bank_mask:0xf bound_ctrl:1
	s_and_saveexec_b64 s[0:1], s[6:7]
	v_add_f32_e32 v30, v30, v31
	v_add_f32_e32 v30, v57, v30
	ds_write_b32 v99, v30 offset:192
	s_or_b64 exec, exec, s[0:1]
	s_waitcnt vmcnt(6)
	v_mul_f32_e32 v19, v19, v56
	v_fmac_f32_e32 v19, v18, v54
	v_fmac_f32_e32 v19, v20, v55
	v_fmac_f32_e32 v19, v21, v53
	s_nop 1
	v_add_f32_dpp v18, v19, v19 quad_perm:[1,0,3,2] row_mask:0xf bank_mask:0xf bound_ctrl:1
	s_nop 1
	v_add_f32_dpp v18, v18, v18 quad_perm:[2,3,0,1] row_mask:0xf bank_mask:0xf bound_ctrl:1
	s_nop 1
	v_add_f32_dpp v18, v18, v18 row_ror:4 row_mask:0xf bank_mask:0xf bound_ctrl:1
	s_nop 1
	v_mov_b32_dpp v19, v18 row_ror:8 row_mask:0xf bank_mask:0xf bound_ctrl:1
	s_and_saveexec_b64 s[0:1], s[6:7]
	v_add_f32_e32 v18, v18, v19
	v_add_f32_e32 v18, v57, v18
	ds_write_b32 v99, v18 offset:208
	s_or_b64 exec, exec, s[0:1]
	s_waitcnt vmcnt(5)
	v_mul_f32_e32 v11, v11, v56
	v_fmac_f32_e32 v11, v10, v54
	v_fmac_f32_e32 v11, v12, v55
	v_fmac_f32_e32 v11, v13, v53
	s_nop 1
	v_add_f32_dpp v10, v11, v11 quad_perm:[1,0,3,2] row_mask:0xf bank_mask:0xf bound_ctrl:1
	s_nop 1
	v_add_f32_dpp v10, v10, v10 quad_perm:[2,3,0,1] row_mask:0xf bank_mask:0xf bound_ctrl:1
	s_nop 1
	v_add_f32_dpp v10, v10, v10 row_ror:4 row_mask:0xf bank_mask:0xf bound_ctrl:1
	s_nop 1
	v_mov_b32_dpp v11, v10 row_ror:8 row_mask:0xf bank_mask:0xf bound_ctrl:1
	s_and_saveexec_b64 s[0:1], s[6:7]
	v_add_f32_e32 v10, v10, v11
	v_add_f32_e32 v10, v57, v10
	ds_write_b32 v99, v10 offset:224
	s_or_b64 exec, exec, s[0:1]
	s_waitcnt vmcnt(4)
	v_mul_f32_e32 v3, v3, v56
	v_fmac_f32_e32 v3, v2, v54
	v_fmac_f32_e32 v3, v4, v55
	v_fmac_f32_e32 v3, v5, v53
	s_nop 1
	v_add_f32_dpp v2, v3, v3 quad_perm:[1,0,3,2] row_mask:0xf bank_mask:0xf bound_ctrl:1
	s_nop 1
	v_add_f32_dpp v2, v2, v2 quad_perm:[2,3,0,1] row_mask:0xf bank_mask:0xf bound_ctrl:1
	s_nop 1
	v_add_f32_dpp v2, v2, v2 row_ror:4 row_mask:0xf bank_mask:0xf bound_ctrl:1
	s_nop 1
	v_mov_b32_dpp v3, v2 row_ror:8 row_mask:0xf bank_mask:0xf bound_ctrl:1
	s_and_saveexec_b64 s[0:1], s[6:7]
	v_add_f32_e32 v2, v2, v3
	v_add_f32_e32 v2, v57, v2
	ds_write_b32 v99, v2 offset:240
	s_or_b64 exec, exec, s[0:1]
	v_lshl_add_u64 v[2:3], v[38:39], 0, v[82:83]
	v_add_co_u32_e32 v4, vcc, 0x1e000, v2
	s_waitcnt vmcnt(3)
	v_mul_f32_e32 v27, v27, v56
	v_addc_co_u32_e32 v5, vcc, 0, v3, vcc
	v_add_co_u32_e32 v10, vcc, 0x1f000, v2
	v_fmac_f32_e32 v27, v26, v54
	s_nop 0
	v_addc_co_u32_e32 v11, vcc, 0, v3, vcc
	global_load_dwordx4 v[30:33], v[4:5], off nt
	global_load_dwordx4 v[18:21], v[10:11], off offset:2048 nt
	v_add_co_u32_e32 v4, vcc, 0x21000, v2
	v_fmac_f32_e32 v27, v28, v55
	s_nop 0
	v_addc_co_u32_e32 v5, vcc, 0, v3, vcc
	v_add_co_u32_e32 v2, vcc, 0x22000, v2
	v_fmac_f32_e32 v27, v29, v53
	s_nop 0
	v_addc_co_u32_e32 v3, vcc, 0, v3, vcc
	global_load_dwordx4 v[10:13], v[4:5], off nt
	s_nop 0
	global_load_dwordx4 v[2:5], v[2:3], off offset:2048 nt
	v_add_f32_dpp v26, v27, v27 quad_perm:[1,0,3,2] row_mask:0xf bank_mask:0xf bound_ctrl:1
	s_nop 1
	v_add_f32_dpp v26, v26, v26 quad_perm:[2,3,0,1] row_mask:0xf bank_mask:0xf bound_ctrl:1
	s_nop 1
	v_add_f32_dpp v26, v26, v26 row_ror:4 row_mask:0xf bank_mask:0xf bound_ctrl:1
	s_nop 1
	v_mov_b32_dpp v27, v26 row_ror:8 row_mask:0xf bank_mask:0xf bound_ctrl:1
	s_and_saveexec_b64 s[0:1], s[6:7]
	v_add_f32_e32 v26, v26, v27
	v_add_f32_e32 v26, v57, v26
	ds_write_b32 v99, v26 offset:256
	s_or_b64 exec, exec, s[0:1]
	s_waitcnt vmcnt(6)
	v_mul_f32_e32 v23, v23, v56
	v_fmac_f32_e32 v23, v22, v54
	v_fmac_f32_e32 v23, v24, v55
	v_fmac_f32_e32 v23, v25, v53
	s_nop 1
	v_add_f32_dpp v22, v23, v23 quad_perm:[1,0,3,2] row_mask:0xf bank_mask:0xf bound_ctrl:1
	s_nop 1
	v_add_f32_dpp v22, v22, v22 quad_perm:[2,3,0,1] row_mask:0xf bank_mask:0xf bound_ctrl:1
	s_nop 1
	v_add_f32_dpp v22, v22, v22 row_ror:4 row_mask:0xf bank_mask:0xf bound_ctrl:1
	s_nop 1
	v_mov_b32_dpp v23, v22 row_ror:8 row_mask:0xf bank_mask:0xf bound_ctrl:1
	s_and_saveexec_b64 s[0:1], s[6:7]
	v_add_f32_e32 v22, v22, v23
	v_add_f32_e32 v22, v57, v22
	ds_write_b32 v99, v22 offset:272
	s_or_b64 exec, exec, s[0:1]
	s_waitcnt vmcnt(5)
; template <int NB>
; __device__ __forceinline__ void sb_decode_task(const Params& P, float* lds, int task) {
;     ...
;     for (int kb = 0; kb < NBT; ++kb) {
;         const float* np = (kb + 1 < NBT) ? Kp + (size_t)(4 * NB * (kb + 1)) * (SH * HD) : Vp;
; #pragma unroll
;         for (int i = 0; i < NB; ++i) nx[i] = *(const float4*)(np + (size_t)(4 * i + g) * (SH * HD));
; #pragma unroll
;         for (int i = 0; i < NB; ++i) { const int s = 4 * NB * kb + 4 * i + g;
;             float part = q0 * cur[i].x + q1 * cur[i].y + q2 * cur[i].z + q3 * cur[i].w; part = sum16(part);
;             if (c == 0) zl[s] = part + bias; }
; #pragma unroll
;         for (int i = 0; i < NB; ++i) cur[i] = nx[i];
;     }
	v_mul_f32_e32 v15, v15, v56
	v_fmac_f32_e32 v15, v14, v54
	v_fmac_f32_e32 v15, v16, v55
	v_fmac_f32_e32 v15, v17, v53
	s_nop 1
	v_add_f32_dpp v14, v15, v15 quad_perm:[1,0,3,2] row_mask:0xf bank_mask:0xf bound_ctrl:1
	s_nop 1
	v_add_f32_dpp v14, v14, v14 quad_perm:[2,3,0,1] row_mask:0xf bank_mask:0xf bound_ctrl:1
	s_nop 1
	v_add_f32_dpp v14, v14, v14 row_ror:4 row_mask:0xf bank_mask:0xf bound_ctrl:1
	s_nop 1
	v_mov_b32_dpp v15, v14 row_ror:8 row_mask:0xf bank_mask:0xf bound_ctrl:1
	s_and_saveexec_b64 s[0:1], s[6:7]
	v_add_f32_e32 v14, v14, v15
	v_add_f32_e32 v14, v57, v14
	ds_write_b32 v99, v14 offset:288
	s_or_b64 exec, exec, s[0:1]
	s_waitcnt vmcnt(4)
	v_mul_f32_e32 v7, v7, v56
	v_fmac_f32_e32 v7, v6, v54
	v_fmac_f32_e32 v7, v8, v55
	v_fmac_f32_e32 v7, v9, v53
	s_nop 1
	v_add_f32_dpp v6, v7, v7 quad_perm:[1,0,3,2] row_mask:0xf bank_mask:0xf bound_ctrl:1
	s_nop 1
	v_add_f32_dpp v6, v6, v6 quad_perm:[2,3,0,1] row_mask:0xf bank_mask:0xf bound_ctrl:1
	s_nop 1
	v_add_f32_dpp v6, v6, v6 row_ror:4 row_mask:0xf bank_mask:0xf bound_ctrl:1
	s_nop 1
	v_mov_b32_dpp v7, v6 row_ror:8 row_mask:0xf bank_mask:0xf bound_ctrl:1
	s_and_saveexec_b64 s[0:1], s[6:7]
	v_add_f32_e32 v6, v6, v7
	v_add_f32_e32 v6, v57, v6
	ds_write_b32 v99, v6 offset:304
	s_or_b64 exec, exec, s[0:1]
	v_lshl_add_u64 v[6:7], v[38:39], 0, v[82:83]
	v_add_co_u32_e32 v8, vcc, 0x24000, v6
	s_waitcnt vmcnt(3)
	v_mul_f32_e32 v22, v31, v56
	v_addc_co_u32_e32 v9, vcc, 0, v7, vcc
	v_add_co_u32_e32 v14, vcc, 0x25000, v6
	v_fmac_f32_e32 v22, v30, v54
	s_nop 0
	v_addc_co_u32_e32 v15, vcc, 0, v7, vcc
	global_load_dwordx4 v[34:37], v[8:9], off nt
	global_load_dwordx4 v[26:29], v[14:15], off offset:2048 nt
	v_add_co_u32_e32 v8, vcc, 0x27000, v6
	v_fmac_f32_e32 v22, v32, v55
	s_nop 0
	v_addc_co_u32_e32 v9, vcc, 0, v7, vcc
	v_add_co_u32_e32 v6, vcc, 0x28000, v6
	v_fmac_f32_e32 v22, v33, v53
	s_nop 0
	v_addc_co_u32_e32 v7, vcc, 0, v7, vcc
	global_load_dwordx4 v[14:17], v[8:9], off nt
	s_nop 0
	global_load_dwordx4 v[6:9], v[6:7], off offset:2048 nt
	v_add_f32_dpp v22, v22, v22 quad_perm:[1,0,3,2] row_mask:0xf bank_mask:0xf bound_ctrl:1
	s_nop 1
	v_add_f32_dpp v22, v22, v22 quad_perm:[2,3,0,1] row_mask:0xf bank_mask:0xf bound_ctrl:1
	s_nop 1
	v_add_f32_dpp v22, v22, v22 row_ror:4 row_mask:0xf bank_mask:0xf bound_ctrl:1
	s_nop 1
	v_mov_b32_dpp v23, v22 row_ror:8 row_mask:0xf bank_mask:0xf bound_ctrl:1
	s_and_saveexec_b64 s[0:1], s[6:7]
	v_add_f32_e32 v22, v22, v23
	v_add_f32_e32 v22, v57, v22
	ds_write_b32 v99, v22 offset:320
	s_or_b64 exec, exec, s[0:1]
	s_waitcnt vmcnt(6)
	v_mul_f32_e32 v19, v19, v56
	v_fmac_f32_e32 v19, v18, v54
	v_fmac_f32_e32 v19, v20, v55
	v_fmac_f32_e32 v19, v21, v53
	s_nop 1
	v_add_f32_dpp v18, v19, v19 quad_perm:[1,0,3,2] row_mask:0xf bank_mask:0xf bound_ctrl:1
	s_nop 1
	v_add_f32_dpp v18, v18, v18 quad_perm:[2,3,0,1] row_mask:0xf bank_mask:0xf bound_ctrl:1
	s_nop 1
	v_add_f32_dpp v18, v18, v18 row_ror:4 row_mask:0xf bank_mask:0xf bound_ctrl:1
	s_nop 1
	v_mov_b32_dpp v19, v18 row_ror:8 row_mask:0xf bank_mask:0xf bound_ctrl:1
	s_and_saveexec_b64 s[0:1], s[6:7]
	v_add_f32_e32 v18, v18, v19
	v_add_f32_e32 v18, v57, v18
	ds_write_b32 v99, v18 offset:336
	s_or_b64 exec, exec, s[0:1]
	s_waitcnt vmcnt(5)
	v_mul_f32_e32 v11, v11, v56
	v_fmac_f32_e32 v11, v10, v54
	v_fmac_f32_e32 v11, v12, v55
	v_fmac_f32_e32 v11, v13, v53
	s_nop 1
	v_add_f32_dpp v10, v11, v11 quad_perm:[1,0,3,2] row_mask:0xf bank_mask:0xf bound_ctrl:1
	s_nop 1
	v_add_f32_dpp v10, v10, v10 quad_perm:[2,3,0,1] row_mask:0xf bank_mask:0xf bound_ctrl:1
	s_nop 1
	v_add_f32_dpp v10, v10, v10 row_ror:4 row_mask:0xf bank_mask:0xf bound_ctrl:1
	s_nop 1
	v_mov_b32_dpp v11, v10 row_ror:8 row_mask:0xf bank_mask:0xf bound_ctrl:1
	s_and_saveexec_b64 s[0:1], s[6:7]
	v_add_f32_e32 v10, v10, v11
	v_add_f32_e32 v10, v57, v10
	ds_write_b32 v99, v10 offset:352
	s_or_b64 exec, exec, s[0:1]
	s_waitcnt vmcnt(4)
	v_mul_f32_e32 v3, v3, v56
	v_fmac_f32_e32 v3, v2, v54
	v_fmac_f32_e32 v3, v4, v55
	v_fmac_f32_e32 v3, v5, v53
	s_nop 1
	v_add_f32_dpp v2, v3, v3 quad_perm:[1,0,3,2] row_mask:0xf bank_mask:0xf bound_ctrl:1
	s_nop 1
	v_add_f32_dpp v2, v2, v2 quad_perm:[2,3,0,1] row_mask:0xf bank_mask:0xf bound_ctrl:1
	s_nop 1
	v_add_f32_dpp v2, v2, v2 row_ror:4 row_mask:0xf bank_mask:0xf bound_ctrl:1
	s_nop 1
	v_mov_b32_dpp v3, v2 row_ror:8 row_mask:0xf bank_mask:0xf bound_ctrl:1
	s_and_saveexec_b64 s[0:1], s[6:7]
	v_add_f32_e32 v2, v2, v3
	v_add_f32_e32 v2, v57, v2
	ds_write_b32 v99, v2 offset:368
	s_or_b64 exec, exec, s[0:1]
	v_lshl_add_u64 v[2:3], v[38:39], 0, v[82:83]
	v_add_co_u32_e32 v4, vcc, 0x2a000, v2
	s_nop 1
	v_addc_co_u32_e32 v5, vcc, 0, v3, vcc
	v_add_co_u32_e32 v10, vcc, 0x2b000, v2
	s_nop 1
	v_addc_co_u32_e32 v11, vcc, 0, v3, vcc
	global_load_dwordx4 v[38:41], v[4:5], off nt
	global_load_dwordx4 v[30:33], v[10:11], off offset:2048 nt
	v_add_co_u32_e32 v4, vcc, 0x2d000, v2
	s_nop 1
	v_addc_co_u32_e32 v5, vcc, 0, v3, vcc
	v_add_co_u32_e32 v2, vcc, 0x2e000, v2
	s_nop 1
	v_addc_co_u32_e32 v3, vcc, 0, v3, vcc
	global_load_dwordx4 v[22:25], v[4:5], off nt
	global_load_dwordx4 v[18:21], v[2:3], off offset:2048 nt
	s_waitcnt vmcnt(7)
	v_mul_f32_e32 v2, v35, v56
	v_fmac_f32_e32 v2, v34, v54
	v_fmac_f32_e32 v2, v36, v55
	v_fmac_f32_e32 v2, v37, v53
	s_nop 1
	v_add_f32_dpp v2, v2, v2 quad_perm:[1,0,3,2] row_mask:0xf bank_mask:0xf bound_ctrl:1
	s_nop 1
	v_add_f32_dpp v2, v2, v2 quad_perm:[2,3,0,1] row_mask:0xf bank_mask:0xf bound_ctrl:1
	s_nop 1
	v_add_f32_dpp v2, v2, v2 row_ror:4 row_mask:0xf bank_mask:0xf bound_ctrl:1
	s_nop 1
	v_mov_b32_dpp v3, v2 row_ror:8 row_mask:0xf bank_mask:0xf bound_ctrl:1
	s_and_saveexec_b64 s[0:1], s[6:7]
	v_add_f32_e32 v2, v2, v3
	v_add_f32_e32 v2, v57, v2
	ds_write_b32 v99, v2 offset:384
	s_or_b64 exec, exec, s[0:1]
	s_waitcnt vmcnt(6)
; template <int NB>
; __device__ __forceinline__ void sb_decode_task(const Params& P, float* lds, int task) {
;     ...
;         for (int i = 0; i < NB; ++i) { const int s = 4 * NB * kb + 4 * i + g;
;             float part = q0 * cur[i].x + q1 * cur[i].y + q2 * cur[i].z + q3 * cur[i].w; part = sum16(part);
;             if (c == 0) zl[s] = part + bias; }
; #pragma unroll
;         for (int i = 0; i < NB; ++i) cur[i] = nx[i];
;     }
;     asm volatile("s_waitcnt lgkmcnt(0)" ::: "memory");
;     __builtin_amdgcn_wave_barrier();
;     const float z0 = zl[2 * lane], z1 = zl[2 * lane + 1];
;     ...
;     for (int vb = 0; vb < NBT; ++vb) {
;         if (vb + 1 < NBT) {
; #pragma unroll
;             for (int i = 0; i < NB; ++i) nx[i] = *(const float4*)(Vp + (size_t)(4 * NB * (vb + 1) + 4 * i + g) * (SH * HD)); }
	v_mul_f32_e32 v2, v27, v56
	v_fmac_f32_e32 v2, v26, v54
	v_fmac_f32_e32 v2, v28, v55
	v_fmac_f32_e32 v2, v29, v53
	s_nop 1
	v_add_f32_dpp v2, v2, v2 quad_perm:[1,0,3,2] row_mask:0xf bank_mask:0xf bound_ctrl:1
	s_nop 1
	v_add_f32_dpp v2, v2, v2 quad_perm:[2,3,0,1] row_mask:0xf bank_mask:0xf bound_ctrl:1
	s_nop 1
	v_add_f32_dpp v2, v2, v2 row_ror:4 row_mask:0xf bank_mask:0xf bound_ctrl:1
	s_nop 1
	v_mov_b32_dpp v3, v2 row_ror:8 row_mask:0xf bank_mask:0xf bound_ctrl:1
	s_and_saveexec_b64 s[0:1], s[6:7]
	v_add_f32_e32 v2, v2, v3
	v_add_f32_e32 v2, v57, v2
	ds_write_b32 v99, v2 offset:400
	s_or_b64 exec, exec, s[0:1]
	s_waitcnt vmcnt(5)
	v_mul_f32_e32 v2, v15, v56
	v_fmac_f32_e32 v2, v14, v54
	v_fmac_f32_e32 v2, v16, v55
	v_fmac_f32_e32 v2, v17, v53
	s_nop 1
	v_add_f32_dpp v2, v2, v2 quad_perm:[1,0,3,2] row_mask:0xf bank_mask:0xf bound_ctrl:1
	s_nop 1
	v_add_f32_dpp v2, v2, v2 quad_perm:[2,3,0,1] row_mask:0xf bank_mask:0xf bound_ctrl:1
	s_nop 1
	v_add_f32_dpp v2, v2, v2 row_ror:4 row_mask:0xf bank_mask:0xf bound_ctrl:1
	s_nop 1
	v_mov_b32_dpp v3, v2 row_ror:8 row_mask:0xf bank_mask:0xf bound_ctrl:1
	s_and_saveexec_b64 s[0:1], s[6:7]
	v_add_f32_e32 v2, v2, v3
	v_add_f32_e32 v2, v57, v2
	ds_write_b32 v99, v2 offset:416
	s_or_b64 exec, exec, s[0:1]
	s_waitcnt vmcnt(4)
	v_mul_f32_e32 v2, v7, v56
	v_fmac_f32_e32 v2, v6, v54
	v_fmac_f32_e32 v2, v8, v55
	v_fmac_f32_e32 v2, v9, v53
	s_nop 1
	v_add_f32_dpp v2, v2, v2 quad_perm:[1,0,3,2] row_mask:0xf bank_mask:0xf bound_ctrl:1
	s_nop 1
	v_add_f32_dpp v2, v2, v2 quad_perm:[2,3,0,1] row_mask:0xf bank_mask:0xf bound_ctrl:1
	s_nop 1
	v_add_f32_dpp v2, v2, v2 row_ror:4 row_mask:0xf bank_mask:0xf bound_ctrl:1
	s_nop 1
	v_mov_b32_dpp v3, v2 row_ror:8 row_mask:0xf bank_mask:0xf bound_ctrl:1
	s_and_saveexec_b64 s[0:1], s[6:7]
	v_add_f32_e32 v2, v2, v3
	v_add_f32_e32 v2, v57, v2
	ds_write_b32 v99, v2 offset:432
	s_or_b64 exec, exec, s[0:1]
	v_lshlrev_b64 v[2:3], 6, v[42:43]
	v_lshl_add_u64 v[34:35], v[2:3], 2, v[90:91]
	v_add_co_u32_e32 v2, vcc, 0x1000, v34
	s_waitcnt vmcnt(3)
	v_mul_f32_e32 v26, v39, v56
	v_addc_co_u32_e32 v3, vcc, 0, v35, vcc
	v_add_co_u32_e32 v6, vcc, 0x3000, v34
	global_load_dwordx4 v[14:17], v[34:35], off nt
	s_nop 0
	global_load_dwordx4 v[2:5], v[2:3], off offset:2048 nt
	v_addc_co_u32_e32 v7, vcc, 0, v35, vcc
	v_add_co_u32_e32 v10, vcc, s49, v34
	v_fmac_f32_e32 v26, v38, v54
	s_nop 0
	v_addc_co_u32_e32 v11, vcc, 0, v35, vcc
	global_load_dwordx4 v[6:9], v[6:7], off nt
	s_nop 0
	global_load_dwordx4 v[10:13], v[10:11], off offset:2048 nt
	v_fmac_f32_e32 v26, v40, v55
	v_fmac_f32_e32 v26, v41, v53
	s_nop 1
	v_add_f32_dpp v26, v26, v26 quad_perm:[1,0,3,2] row_mask:0xf bank_mask:0xf bound_ctrl:1
	s_nop 1
	v_add_f32_dpp v26, v26, v26 quad_perm:[2,3,0,1] row_mask:0xf bank_mask:0xf bound_ctrl:1
	s_nop 1
	v_add_f32_dpp v26, v26, v26 row_ror:4 row_mask:0xf bank_mask:0xf bound_ctrl:1
	s_nop 1
	v_mov_b32_dpp v27, v26 row_ror:8 row_mask:0xf bank_mask:0xf bound_ctrl:1
	s_and_saveexec_b64 s[0:1], s[6:7]
	v_add_f32_e32 v26, v26, v27
	v_add_f32_e32 v26, v57, v26
	ds_write_b32 v99, v26 offset:448
	s_or_b64 exec, exec, s[0:1]
	s_waitcnt vmcnt(6)
	v_mul_f32_e32 v26, v31, v56
	v_fmac_f32_e32 v26, v30, v54
	v_fmac_f32_e32 v26, v32, v55
	v_fmac_f32_e32 v26, v33, v53
	s_nop 1
	v_add_f32_dpp v26, v26, v26 quad_perm:[1,0,3,2] row_mask:0xf bank_mask:0xf bound_ctrl:1
	s_nop 1
	v_add_f32_dpp v26, v26, v26 quad_perm:[2,3,0,1] row_mask:0xf bank_mask:0xf bound_ctrl:1
	s_nop 1
	v_add_f32_dpp v26, v26, v26 row_ror:4 row_mask:0xf bank_mask:0xf bound_ctrl:1
	s_nop 1
	v_mov_b32_dpp v27, v26 row_ror:8 row_mask:0xf bank_mask:0xf bound_ctrl:1
	s_and_saveexec_b64 s[0:1], s[6:7]
	v_add_f32_e32 v26, v26, v27
	v_add_f32_e32 v26, v57, v26
	ds_write_b32 v99, v26 offset:464
	s_or_b64 exec, exec, s[0:1]
	s_waitcnt vmcnt(5)
	v_mul_f32_e32 v23, v23, v56
	v_fmac_f32_e32 v23, v22, v54
	v_fmac_f32_e32 v23, v24, v55
	v_fmac_f32_e32 v23, v25, v53
	s_nop 1
	v_add_f32_dpp v22, v23, v23 quad_perm:[1,0,3,2] row_mask:0xf bank_mask:0xf bound_ctrl:1
	s_nop 1
	v_add_f32_dpp v22, v22, v22 quad_perm:[2,3,0,1] row_mask:0xf bank_mask:0xf bound_ctrl:1
	s_nop 1
	v_add_f32_dpp v22, v22, v22 row_ror:4 row_mask:0xf bank_mask:0xf bound_ctrl:1
	s_nop 1
	v_mov_b32_dpp v23, v22 row_ror:8 row_mask:0xf bank_mask:0xf bound_ctrl:1
	s_and_saveexec_b64 s[0:1], s[6:7]
	v_add_f32_e32 v22, v22, v23
	v_add_f32_e32 v22, v57, v22
	ds_write_b32 v99, v22 offset:480
	s_or_b64 exec, exec, s[0:1]
	s_waitcnt vmcnt(4)
	v_mul_f32_e32 v19, v19, v56
	v_fmac_f32_e32 v19, v18, v54
	v_fmac_f32_e32 v19, v20, v55
	v_fmac_f32_e32 v19, v21, v53
	s_nop 1
	v_add_f32_dpp v18, v19, v19 quad_perm:[1,0,3,2] row_mask:0xf bank_mask:0xf bound_ctrl:1
	s_nop 1
	v_add_f32_dpp v18, v18, v18 quad_perm:[2,3,0,1] row_mask:0xf bank_mask:0xf bound_ctrl:1
	s_nop 1
	v_add_f32_dpp v18, v18, v18 row_ror:4 row_mask:0xf bank_mask:0xf bound_ctrl:1
	s_nop 1
	v_mov_b32_dpp v19, v18 row_ror:8 row_mask:0xf bank_mask:0xf bound_ctrl:1
	s_and_saveexec_b64 s[0:1], s[6:7]
	v_add_f32_e32 v18, v18, v19
	v_add_f32_e32 v18, v57, v18
	ds_write_b32 v99, v18 offset:496
	s_or_b64 exec, exec, s[0:1]
	s_waitcnt lgkmcnt(0)
	ds_read_b64 v[18:19], v100
	s_waitcnt lgkmcnt(0)
; __device__ __forceinline__ float softplus2_(float z2) { return fmaxf(z2, 0.f) + log1pf(exp2f(-fabsf(z2))) * LOG2E; }
; template <int NB>
; __device__ __forceinline__ void sb_decode_task(const Params& P, float* lds, int task) {
;     ...
;     const float z0 = zl[2 * lane], z1 = zl[2 * lane + 1];
;     const float sp0 = softplus2_(z0), sp1 = softplus2_(z1);
	v_cmp_gt_f32_e64 vcc, |v18|, s97
	s_nop 1
	v_cndmask_b32_e32 v21, 0, v103, vcc
	v_sub_f32_e64 v21, v21, |v18|
	v_exp_f32_e32 v21, v21
	v_max_f32_e32 v20, v18, v18
	v_max_f32_e32 v22, 0, v20
	v_cndmask_b32_e32 v20, 0, v102, vcc
	v_ldexp_f32 v23, v21, v20
	v_add_f32_e32 v24, 1.0, v23
	v_add_f32_e32 v20, -1.0, v24
	v_sub_f32_e32 v21, v20, v24
	v_add_f32_e32 v21, 1.0, v21
	v_sub_f32_e32 v20, v23, v20
	v_add_f32_e32 v25, v20, v21
	v_frexp_mant_f32_e32 v20, v24
	v_cmp_gt_f32_e32 vcc, s47, v20
	v_cvt_f64_f32_e32 v[20:21], v24
	v_frexp_exp_i32_f64_e32 v20, v[20:21]
	v_subbrev_co_u32_e32 v20, vcc, 0, v20, vcc
	v_sub_u32_e32 v21, 0, v20
	v_ldexp_f32 v24, v24, v21
	v_ldexp_f32 v21, v25, v21
	v_add_f32_e32 v25, -1.0, v24
	v_add_f32_e32 v26, 1.0, v25
	v_sub_f32_e32 v26, v24, v26
	v_add_f32_e32 v26, v21, v26
	v_add_f32_e32 v27, v25, v26
	v_sub_f32_e32 v25, v25, v27
	v_add_f32_e32 v25, v26, v25
	v_add_f32_e32 v26, 1.0, v24
	v_add_f32_e32 v28, -1.0, v26
	v_sub_f32_e32 v24, v24, v28
	v_add_f32_e32 v21, v21, v24
	v_add_f32_e32 v24, v26, v21
	v_sub_f32_e32 v26, v26, v24
	v_add_f32_e32 v21, v21, v26
	v_rcp_f32_e32 v26, v24
	v_cvt_f32_i32_e32 v20, v20
	v_cmp_neq_f32_e32 vcc, s46, v23
	v_mul_f32_e32 v28, v27, v26
	v_mul_f32_e32 v29, v24, v28
	v_fma_f32 v30, v28, v24, -v29
	v_fmac_f32_e32 v30, v28, v21
	v_add_f32_e32 v31, v29, v30
	v_sub_f32_e32 v32, v27, v31
	v_sub_f32_e32 v27, v27, v32
	v_sub_f32_e32 v29, v31, v29
	v_sub_f32_e32 v27, v27, v31
	v_add_f32_e32 v25, v25, v27
	v_sub_f32_e32 v27, v29, v30
	v_add_f32_e32 v25, v27, v25
	v_add_f32_e32 v27, v32, v25
	v_mul_f32_e32 v29, v26, v27
	v_mul_f32_e32 v30, v24, v29
	v_fma_f32 v24, v29, v24, -v30
	v_fmac_f32_e32 v24, v29, v21
	v_sub_f32_e32 v21, v32, v27
	v_add_f32_e32 v21, v25, v21
	v_add_f32_e32 v25, v30, v24
	v_sub_f32_e32 v31, v27, v25
	v_sub_f32_e32 v27, v27, v31
	v_sub_f32_e32 v30, v25, v30
	v_sub_f32_e32 v25, v27, v25
	v_add_f32_e32 v21, v21, v25
	v_sub_f32_e32 v24, v30, v24
	v_add_f32_e32 v21, v24, v21
	v_add_f32_e32 v24, v28, v29
	v_add_f32_e32 v21, v31, v21
	v_sub_f32_e32 v25, v24, v28
	v_mul_f32_e32 v21, v26, v21
	v_sub_f32_e32 v25, v29, v25
	v_add_f32_e32 v21, v25, v21
	v_mul_f32_e32 v28, 0x3f317218, v20
	v_add_f32_e32 v25, v24, v21
	v_fma_f32 v29, v20, s95, -v28
	v_mul_f32_e32 v26, v25, v25
	v_fmac_f32_e32 v29, 0xb102e308, v20
	v_sub_f32_e32 v20, v25, v24
	v_fmamk_f32 v27, v26, 0x3e9b6dac, v1
	v_sub_f32_e32 v20, v21, v20
	v_add_f32_e32 v21, v28, v29
	v_fmaak_f32 v27, v26, v27, 0x3f2aaada
	v_sub_f32_e32 v24, v21, v28
	v_ldexp_f32 v28, v25, 1
	v_mul_f32_e32 v25, v25, v26
	v_mul_f32_e32 v25, v25, v27
	v_add_f32_e32 v26, v28, v25
	v_sub_f32_e32 v27, v26, v28
	v_ldexp_f32 v20, v20, 1
	v_sub_f32_e32 v25, v25, v27
	v_add_f32_e32 v20, v20, v25
	v_add_f32_e32 v25, v26, v20
	v_sub_f32_e32 v26, v25, v26
	v_sub_f32_e32 v20, v20, v26
	v_add_f32_e32 v26, v21, v25
	v_sub_f32_e32 v27, v26, v21
	v_sub_f32_e32 v28, v26, v27
	v_sub_f32_e32 v24, v29, v24
	v_sub_f32_e32 v21, v21, v28
	v_sub_f32_e32 v25, v25, v27
	v_add_f32_e32 v21, v25, v21
	v_add_f32_e32 v25, v24, v20
	v_sub_f32_e32 v27, v25, v24
	v_sub_f32_e32 v28, v25, v27
	v_sub_f32_e32 v24, v24, v28
	v_sub_f32_e32 v20, v20, v27
	v_add_f32_e32 v21, v25, v21
	v_add_f32_e32 v20, v20, v24
	v_add_f32_e32 v24, v26, v21
	v_sub_f32_e32 v25, v24, v26
	v_sub_f32_e32 v21, v21, v25
	v_add_f32_e32 v20, v20, v21
	v_add_f32_e32 v20, v24, v20
	v_cndmask_b32_e32 v20, v104, v20, vcc
	v_cmp_lt_f32_e64 vcc, |v23|, s45
	s_nop 1
	v_cndmask_b32_e32 v20, v20, v23, vcc
	v_cmp_gt_f32_e64 vcc, |v19|, s97
	v_fmac_f32_e32 v22, 0x3fb8aa3b, v20
	v_max_f32_e32 v20, v19, v19
	v_cndmask_b32_e32 v21, 0, v103, vcc
	v_sub_f32_e64 v21, v21, |v19|
	v_exp_f32_e32 v21, v21
	v_max_f32_e32 v23, 0, v20
	v_cndmask_b32_e32 v20, 0, v102, vcc
	v_sub_f32_e32 v18, v18, v22
	v_ldexp_f32 v24, v21, v20
	v_add_f32_e32 v25, 1.0, v24
	v_add_f32_e32 v20, -1.0, v25
	v_sub_f32_e32 v21, v20, v25
	v_add_f32_e32 v21, 1.0, v21
	v_sub_f32_e32 v20, v24, v20
	v_add_f32_e32 v26, v20, v21
	v_frexp_mant_f32_e32 v20, v25
	v_cmp_gt_f32_e32 vcc, s47, v20
	v_cvt_f64_f32_e32 v[20:21], v25
	v_frexp_exp_i32_f64_e32 v20, v[20:21]
	v_subbrev_co_u32_e32 v20, vcc, 0, v20, vcc
	v_sub_u32_e32 v21, 0, v20
	v_ldexp_f32 v25, v25, v21
	v_ldexp_f32 v21, v26, v21
	v_add_f32_e32 v26, -1.0, v25
	v_add_f32_e32 v27, 1.0, v26
	v_sub_f32_e32 v27, v25, v27
	v_add_f32_e32 v27, v21, v27
	v_add_f32_e32 v28, v26, v27
	v_sub_f32_e32 v26, v26, v28
	v_add_f32_e32 v26, v27, v26
	v_add_f32_e32 v27, 1.0, v25
	v_add_f32_e32 v29, -1.0, v27
	v_sub_f32_e32 v25, v25, v29
	v_add_f32_e32 v21, v21, v25
	v_add_f32_e32 v25, v27, v21
	v_sub_f32_e32 v27, v27, v25
	v_add_f32_e32 v21, v21, v27
	v_rcp_f32_e32 v27, v25
	v_cvt_f32_i32_e32 v20, v20
	v_cmp_neq_f32_e32 vcc, s46, v24
	v_mul_f32_e32 v29, v28, v27
	v_mul_f32_e32 v30, v25, v29
	v_fma_f32 v31, v29, v25, -v30
	v_fmac_f32_e32 v31, v29, v21
	v_add_f32_e32 v32, v30, v31
	v_sub_f32_e32 v33, v28, v32
	v_sub_f32_e32 v28, v28, v33
	v_sub_f32_e32 v30, v32, v30
	v_sub_f32_e32 v28, v28, v32
	v_add_f32_e32 v26, v26, v28
	v_sub_f32_e32 v28, v30, v31
	v_add_f32_e32 v26, v28, v26
	v_add_f32_e32 v28, v33, v26
	v_mul_f32_e32 v30, v27, v28
	v_mul_f32_e32 v31, v25, v30
	v_fma_f32 v25, v30, v25, -v31
	v_fmac_f32_e32 v25, v30, v21
	v_sub_f32_e32 v21, v33, v28
	v_add_f32_e32 v21, v26, v21
	v_add_f32_e32 v26, v31, v25
	v_sub_f32_e32 v32, v28, v26
	v_sub_f32_e32 v28, v28, v32
	v_sub_f32_e32 v31, v26, v31
	v_sub_f32_e32 v26, v28, v26
	v_add_f32_e32 v21, v21, v26
	v_sub_f32_e32 v25, v31, v25
	v_add_f32_e32 v21, v25, v21
	v_add_f32_e32 v25, v29, v30
	v_add_f32_e32 v21, v32, v21
	v_sub_f32_e32 v26, v25, v29
	v_mul_f32_e32 v21, v27, v21
; __device__ __forceinline__ float softplus2_(float z2) { return fmaxf(z2, 0.f) + log1pf(exp2f(-fabsf(z2))) * LOG2E; }
; template <int NB>
; __device__ __forceinline__ void sb_decode_task(const Params& P, float* lds, int task) {
;     ...
;     const float sp0 = softplus2_(z0), sp1 = softplus2_(z1);
;     float incl = sp0 + sp1;
; #pragma unroll
;     for (int off = 1; off < 64; off <<= 1) { const float t = __shfl_down(incl, off); if (lane + off < 64) incl += t; }
;     const float excl = incl - (sp0 + sp1);
;     wl[2 * lane] = exp2f(z0 - sp0 - (excl + sp1));
;     wl[2 * lane + 1] = exp2f(z1 - sp1 - excl);
;     const float Ltot = __shfl(incl, 0);
;     asm volatile("s_waitcnt lgkmcnt(0)" ::: "memory");
;     __builtin_amdgcn_wave_barrier();
;     float4 o4 = make_float4(0.f, 0.f, 0.f, 0.f);
; #pragma unroll
;     for (int vb = 0; vb < NBT; ++vb) {
;         if (vb + 1 < NBT) {
; #pragma unroll
;             for (int i = 0; i < NB; ++i) nx[i] = *(const float4*)(Vp + (size_t)(4 * NB * (vb + 1) + 4 * i + g) * (SH * HD)); }
; #pragma unroll
;         for (int i = 0; i < NB; ++i) { const float w = wl[4 * NB * vb + 4 * i + g]; o4.x += w * cur[i].x; o4.y += w * cur[i].y; o4.z += w * cur[i].z; o4.w += w * cur[i].w; }
; #pragma unroll
;         for (int i = 0; i < NB; ++i) cur[i] = nx[i];
	v_sub_f32_e32 v26, v30, v26
	v_add_f32_e32 v21, v26, v21
	v_mul_f32_e32 v29, 0x3f317218, v20
	v_add_f32_e32 v26, v25, v21
	v_fma_f32 v30, v20, s95, -v29
	v_mul_f32_e32 v27, v26, v26
	v_fmac_f32_e32 v30, 0xb102e308, v20
	v_sub_f32_e32 v20, v26, v25
	v_fmamk_f32 v28, v27, 0x3e9b6dac, v1
	v_sub_f32_e32 v20, v21, v20
	v_add_f32_e32 v21, v29, v30
	v_fmaak_f32 v28, v27, v28, 0x3f2aaada
	v_sub_f32_e32 v25, v21, v29
	v_ldexp_f32 v29, v26, 1
	v_mul_f32_e32 v26, v26, v27
	v_mul_f32_e32 v26, v26, v28
	v_add_f32_e32 v27, v29, v26
	v_sub_f32_e32 v28, v27, v29
	v_ldexp_f32 v20, v20, 1
	v_sub_f32_e32 v26, v26, v28
	v_add_f32_e32 v20, v20, v26
	v_add_f32_e32 v26, v27, v20
	v_sub_f32_e32 v27, v26, v27
	v_sub_f32_e32 v20, v20, v27
	v_add_f32_e32 v27, v21, v26
	v_sub_f32_e32 v28, v27, v21
	v_sub_f32_e32 v29, v27, v28
	v_sub_f32_e32 v25, v30, v25
	v_sub_f32_e32 v21, v21, v29
	v_sub_f32_e32 v26, v26, v28
	v_add_f32_e32 v21, v26, v21
	v_add_f32_e32 v26, v25, v20
	v_sub_f32_e32 v28, v26, v25
	v_sub_f32_e32 v29, v26, v28
	v_sub_f32_e32 v25, v25, v29
	v_sub_f32_e32 v20, v20, v28
	v_add_f32_e32 v21, v26, v21
	v_add_f32_e32 v20, v20, v25
	v_add_f32_e32 v25, v27, v21
	v_sub_f32_e32 v26, v25, v27
	v_sub_f32_e32 v21, v21, v26
	v_add_f32_e32 v20, v20, v21
	v_add_f32_e32 v20, v25, v20
	v_cndmask_b32_e32 v20, v104, v20, vcc
	v_cmp_lt_f32_e64 vcc, |v24|, s45
	s_nop 1
	v_cndmask_b32_e32 v20, v20, v24, vcc
	v_fmac_f32_e32 v23, 0x3fb8aa3b, v20
	v_add_f32_e32 v20, v22, v23
	ds_bpermute_b32 v21, v46, v20
	v_sub_f32_e32 v19, v19, v23
	s_waitcnt lgkmcnt(0)
	v_add_f32_e32 v21, v20, v21
	v_cndmask_b32_e64 v21, v21, v20, s[8:9]
	ds_bpermute_b32 v24, v47, v21
	s_waitcnt lgkmcnt(0)
	v_add_f32_e32 v24, v21, v24
	v_cndmask_b32_e64 v21, v21, v24, s[10:11]
	ds_bpermute_b32 v24, v48, v21
	s_waitcnt lgkmcnt(0)
	v_add_f32_e32 v24, v21, v24
	v_cndmask_b32_e64 v21, v21, v24, s[12:13]
	ds_bpermute_b32 v24, v49, v21
	s_waitcnt lgkmcnt(0)
	v_add_f32_e32 v24, v21, v24
	v_cndmask_b32_e64 v21, v21, v24, s[14:15]
	ds_bpermute_b32 v24, v50, v21
	s_waitcnt lgkmcnt(0)
	v_add_f32_e32 v24, v21, v24
	v_cndmask_b32_e64 v21, v21, v24, s[16:17]
	ds_bpermute_b32 v24, v51, v21
	s_waitcnt lgkmcnt(0)
	v_add_f32_e32 v24, v21, v24
	v_cndmask_b32_e64 v31, v21, v24, s[18:19]
	v_sub_f32_e32 v20, v31, v20
	v_add_f32_e32 v21, v23, v20
	v_sub_f32_e32 v18, v18, v21
	v_cmp_gt_f32_e32 vcc, s24, v18
	v_sub_f32_e32 v19, v19, v20
	s_nop 0
	v_cndmask_b32_e32 v21, 0, v103, vcc
	v_add_f32_e32 v18, v18, v21
	v_cndmask_b32_e32 v21, 0, v102, vcc
	v_cmp_gt_f32_e32 vcc, s24, v19
	v_exp_f32_e32 v18, v18
	s_nop 0
	v_cndmask_b32_e32 v20, 0, v103, vcc
	v_add_f32_e32 v19, v19, v20
	v_exp_f32_e32 v19, v19
	v_cndmask_b32_e32 v20, 0, v102, vcc
	v_ldexp_f32 v18, v18, v21
	v_ldexp_f32 v19, v19, v20
	ds_write_b64 v100, v[18:19] offset:512
	s_waitcnt lgkmcnt(0)
	ds_read2_b32 v[18:19], v99 offset0:128 offset1:132
	ds_read2_b32 v[32:33], v99 offset0:136 offset1:140
	ds_read2_b32 v[58:59], v99 offset0:144 offset1:148
	ds_read2_b32 v[60:61], v99 offset0:152 offset1:156
	ds_read2_b32 v[62:63], v99 offset0:160 offset1:164
	ds_read2_b32 v[64:65], v99 offset0:168 offset1:172
	s_waitcnt vmcnt(3) lgkmcnt(5)
	v_pk_fma_f32 v[36:37], v[14:15], v[18:19], 0 op_sel_hi:[1,0,0]
	v_add_co_u32_e32 v14, vcc, s89, v34
	v_pk_fma_f32 v[50:51], v[16:17], v[18:19], 0 op_sel_hi:[1,0,0]
	s_nop 0
	v_addc_co_u32_e32 v15, vcc, 0, v35, vcc
	v_add_co_u32_e32 v18, vcc, s92, v34
	v_mov_b32_e32 v30, v19
	s_nop 0
	v_addc_co_u32_e32 v19, vcc, 0, v35, vcc
	v_add_co_u32_e32 v22, vcc, s93, v34
	s_waitcnt vmcnt(2)
	v_pk_fma_f32 v[2:3], v[2:3], v[30:31], v[36:37] op_sel_hi:[1,0,1]
	v_addc_co_u32_e32 v23, vcc, 0, v35, vcc
	v_add_co_u32_e32 v26, vcc, s96, v34
	s_waitcnt vmcnt(1) lgkmcnt(4)
	v_pk_fma_f32 v[2:3], v[6:7], v[32:33], v[2:3] op_sel_hi:[1,0,1]
	v_addc_co_u32_e32 v27, vcc, 0, v35, vcc
	v_add_co_u32_e32 v6, vcc, s44, v34
	global_load_dwordx4 v[14:17], v[14:15], off nt
	s_nop 0
	v_addc_co_u32_e32 v7, vcc, 0, v35, vcc
	global_load_dwordx4 v[18:21], v[18:19], off offset:2048 nt
	v_mov_b32_e32 v66, v33
	global_load_dwordx4 v[36:39], v[6:7], off nt
	v_add_co_u32_e32 v6, vcc, s26, v34
	global_load_dwordx4 v[22:25], v[22:23], off nt
	s_nop 0
	v_addc_co_u32_e32 v7, vcc, 0, v35, vcc
	global_load_dwordx4 v[26:29], v[26:27], off offset:2048 nt
	s_waitcnt vmcnt(5)
	v_pk_fma_f32 v[2:3], v[10:11], v[66:67], v[2:3] op_sel_hi:[1,0,1]
	global_load_dwordx4 v[40:43], v[6:7], off offset:2048 nt
	v_add_co_u32_e32 v6, vcc, s27, v34
	s_waitcnt lgkmcnt(2)
	v_mov_b32_e32 v10, v61
	v_addc_co_u32_e32 v7, vcc, 0, v35, vcc
	global_load_dwordx4 v[46:49], v[6:7], off nt
	v_add_co_u32_e32 v6, vcc, s28, v34
	s_waitcnt vmcnt(6)
	v_pk_fma_f32 v[2:3], v[14:15], v[58:59], v[2:3] op_sel_hi:[1,0,1]
	v_addc_co_u32_e32 v7, vcc, 0, v35, vcc
	global_load_dwordx4 v[54:57], v[6:7], off offset:2048 nt
	v_mov_b32_e32 v6, v59
	s_waitcnt vmcnt(6)
	v_pk_fma_f32 v[2:3], v[18:19], v[6:7], v[2:3] op_sel_hi:[1,0,1]
	s_waitcnt lgkmcnt(1)
	v_mov_b32_e32 v14, v63
	s_waitcnt lgkmcnt(0)
	v_mov_b32_e32 v18, v65
	s_waitcnt vmcnt(4)
	v_pk_fma_f32 v[2:3], v[22:23], v[60:61], v[2:3] op_sel_hi:[1,0,1]
	s_waitcnt vmcnt(3)
	v_pk_fma_f32 v[2:3], v[26:27], v[10:11], v[2:3] op_sel_hi:[1,0,1]
	s_nop 0
	v_pk_fma_f32 v[2:3], v[36:37], v[62:63], v[2:3] op_sel_hi:[1,0,1]
	s_waitcnt vmcnt(2)
	v_pk_fma_f32 v[2:3], v[40:41], v[14:15], v[2:3] op_sel_hi:[1,0,1]
	s_waitcnt vmcnt(1)
	v_pk_fma_f32 v[2:3], v[46:47], v[64:65], v[2:3] op_sel_hi:[1,0,1]
	s_waitcnt vmcnt(0)
	v_pk_fma_f32 v[54:55], v[54:55], v[18:19], v[2:3] op_sel_hi:[1,0,1]
	v_pk_fma_f32 v[2:3], v[4:5], v[30:31], v[50:51] op_sel_hi:[1,0,1]
	s_nop 0
	v_pk_fma_f32 v[2:3], v[8:9], v[32:33], v[2:3] op_sel_hi:[1,0,1]
	ds_read2_b32 v[8:9], v99 offset0:176 offset1:180
	v_pk_fma_f32 v[2:3], v[12:13], v[66:67], v[2:3] op_sel_hi:[1,0,1]
	s_waitcnt lgkmcnt(0)
; template <int NB>
; __device__ __forceinline__ void sb_decode_task(const Params& P, float* lds, int task) {
;     ...
;     for (int vb = 0; vb < NBT; ++vb) {
;         if (vb + 1 < NBT) {
; #pragma unroll
;             for (int i = 0; i < NB; ++i) nx[i] = *(const float4*)(Vp + (size_t)(4 * NB * (vb + 1) + 4 * i + g) * (SH * HD)); }
; #pragma unroll
;         for (int i = 0; i < NB; ++i) { const float w = wl[4 * NB * vb + 4 * i + g]; o4.x += w * cur[i].x; o4.y += w * cur[i].y; o4.z += w * cur[i].z; o4.w += w * cur[i].w; }
; #pragma unroll
;         for (int i = 0; i < NB; ++i) cur[i] = nx[i];
	v_mov_b32_e32 v72, v9
	v_pk_fma_f32 v[2:3], v[16:17], v[58:59], v[2:3] op_sel_hi:[1,0,1]
	s_nop 0
	v_pk_fma_f32 v[2:3], v[20:21], v[6:7], v[2:3] op_sel_hi:[1,0,1]
	s_nop 0
	v_pk_fma_f32 v[2:3], v[24:25], v[60:61], v[2:3] op_sel_hi:[1,0,1]
	s_nop 0
	v_pk_fma_f32 v[2:3], v[28:29], v[10:11], v[2:3] op_sel_hi:[1,0,1]
	s_nop 0
	v_pk_fma_f32 v[2:3], v[38:39], v[62:63], v[2:3] op_sel_hi:[1,0,1]
	s_nop 0
	v_pk_fma_f32 v[2:3], v[42:43], v[14:15], v[2:3] op_sel_hi:[1,0,1]
	s_nop 0
	v_pk_fma_f32 v[2:3], v[48:49], v[64:65], v[2:3] op_sel_hi:[1,0,1]
	s_nop 0
	v_pk_fma_f32 v[6:7], v[56:57], v[18:19], v[2:3] op_sel_hi:[1,0,1]
	v_add_co_u32_e32 v2, vcc, s25, v34
	s_nop 1
	v_addc_co_u32_e32 v3, vcc, 0, v35, vcc
	global_load_dwordx4 v[10:13], v[2:3], off nt
	v_add_co_u32_e32 v2, vcc, s43, v34
	s_waitcnt vmcnt(0)
	v_pk_fma_f32 v[10:11], v[10:11], v[8:9], v[54:55] op_sel_hi:[1,0,1]
	v_addc_co_u32_e32 v3, vcc, 0, v35, vcc
	global_load_dwordx4 v[14:17], v[2:3], off offset:2048 nt
	v_add_co_u32_e32 v2, vcc, s80, v34
	ds_read2_b32 v[32:33], v99 offset0:184 offset1:188
	ds_read2_b32 v[50:51], v99 offset0:192 offset1:196
	ds_read2_b32 v[66:67], v99 offset0:200 offset1:204
	ds_read2_b32 v[68:69], v99 offset0:208 offset1:212
	ds_read2_b32 v[70:71], v99 offset0:216 offset1:220
	v_addc_co_u32_e32 v3, vcc, 0, v35, vcc
	v_add_co_u32_e32 v18, vcc, s29, v34
	global_load_dwordx4 v[2:5], v[2:3], off offset:2048 nt
	s_nop 0
	v_addc_co_u32_e32 v19, vcc, 0, v35, vcc
	v_add_co_u32_e32 v22, vcc, s68, v34
	global_load_dwordx4 v[18:21], v[18:19], off nt
	s_nop 0
	v_addc_co_u32_e32 v23, vcc, 0, v35, vcc
	v_add_co_u32_e32 v26, vcc, s69, v34
	global_load_dwordx4 v[22:25], v[22:23], off offset:2048 nt
	s_nop 0
	v_addc_co_u32_e32 v27, vcc, 0, v35, vcc
	v_add_co_u32_e32 v36, vcc, s70, v34
	global_load_dwordx4 v[26:29], v[26:27], off nt
	s_nop 0
	v_addc_co_u32_e32 v37, vcc, 0, v35, vcc
	v_add_co_u32_e32 v40, vcc, s71, v34
	global_load_dwordx4 v[36:39], v[36:37], off offset:2048 nt
	s_nop 0
	v_addc_co_u32_e32 v41, vcc, 0, v35, vcc
	v_add_co_u32_e32 v46, vcc, s72, v34
	global_load_dwordx4 v[40:43], v[40:41], off nt
	s_nop 0
	v_addc_co_u32_e32 v47, vcc, 0, v35, vcc
	global_load_dwordx4 v[46:49], v[46:47], off offset:2048 nt
	v_pk_fma_f32 v[6:7], v[12:13], v[8:9], v[6:7] op_sel_hi:[1,0,1]
	s_waitcnt lgkmcnt(4)
	v_mov_b32_e32 v74, v33
	s_waitcnt lgkmcnt(0)
	v_mov_b32_e32 v30, v71
	s_waitcnt vmcnt(7)
	v_pk_fma_f32 v[10:11], v[14:15], v[72:73], v[10:11] op_sel_hi:[1,0,1]
	v_add_co_u32_e32 v14, vcc, s73, v34
	v_pk_fma_f32 v[6:7], v[16:17], v[72:73], v[6:7] op_sel_hi:[1,0,1]
	s_nop 0
	v_addc_co_u32_e32 v15, vcc, 0, v35, vcc
	global_load_dwordx4 v[54:57], v[14:15], off nt
	v_add_co_u32_e32 v14, vcc, s74, v34
	s_nop 1
	v_addc_co_u32_e32 v15, vcc, 0, v35, vcc
	global_load_dwordx4 v[58:61], v[14:15], off offset:2048 nt
	v_add_co_u32_e32 v14, vcc, s75, v34
	s_nop 1
	v_addc_co_u32_e32 v15, vcc, 0, v35, vcc
	global_load_dwordx4 v[62:65], v[14:15], off nt
	s_waitcnt vmcnt(8)
	v_pk_fma_f32 v[6:7], v[20:21], v[32:33], v[6:7] op_sel_hi:[1,0,1]
	v_pk_fma_f32 v[10:11], v[18:19], v[32:33], v[10:11] op_sel_hi:[1,0,1]
	s_waitcnt vmcnt(7)
	v_pk_fma_f32 v[6:7], v[24:25], v[74:75], v[6:7] op_sel_hi:[1,0,1]
	v_mov_b32_e32 v14, v51
	s_waitcnt vmcnt(6)
	v_pk_fma_f32 v[6:7], v[28:29], v[50:51], v[6:7] op_sel_hi:[1,0,1]
	v_pk_fma_f32 v[10:11], v[22:23], v[74:75], v[10:11] op_sel_hi:[1,0,1]
	v_mov_b32_e32 v18, v67
	v_pk_fma_f32 v[10:11], v[26:27], v[50:51], v[10:11] op_sel_hi:[1,0,1]
	v_mov_b32_e32 v22, v69
	s_waitcnt vmcnt(5)
	v_pk_fma_f32 v[6:7], v[38:39], v[14:15], v[6:7] op_sel_hi:[1,0,1]
	v_pk_fma_f32 v[10:11], v[36:37], v[14:15], v[10:11] op_sel_hi:[1,0,1]
	ds_read2_b32 v[38:39], v99 offset0:224 offset1:228
	ds_read2_b32 v[32:33], v99 offset0:232 offset1:236
	s_waitcnt vmcnt(4)
	v_pk_fma_f32 v[6:7], v[42:43], v[66:67], v[6:7] op_sel_hi:[1,0,1]
	v_pk_fma_f32 v[10:11], v[40:41], v[66:67], v[10:11] op_sel_hi:[1,0,1]
	s_waitcnt vmcnt(3)
; template <int NB>
; __device__ __forceinline__ void sb_decode_task(const Params& P, float* lds, int task) {
;     ...
;     for (int vb = 0; vb < NBT; ++vb) {
;         if (vb + 1 < NBT) {
; #pragma unroll
;             for (int i = 0; i < NB; ++i) nx[i] = *(const float4*)(Vp + (size_t)(4 * NB * (vb + 1) + 4 * i + g) * (SH * HD)); }
; #pragma unroll
;         for (int i = 0; i < NB; ++i) { const float w = wl[4 * NB * vb + 4 * i + g]; o4.x += w * cur[i].x; o4.y += w * cur[i].y; o4.z += w * cur[i].z; o4.w += w * cur[i].w; }
; #pragma unroll
;         for (int i = 0; i < NB; ++i) cur[i] = nx[i];
;     }
; #pragma unroll
;     for (int off = 16; off < 64; off <<= 1) { o4.x += __shfl_xor(o4.x, off); o4.y += __shfl_xor(o4.y, off); o4.z += __shfl_xor(o4.z, off); o4.w += __shfl_xor(o4.w, off); }
;     if (g == 0) *(float4*)(dpart + (size_t)task * HD + 4 * c) = o4;
;     if (lane == 0) dl[task] = Ltot;
	v_pk_fma_f32 v[6:7], v[48:49], v[18:19], v[6:7] op_sel_hi:[1,0,1]
	v_pk_fma_f32 v[10:11], v[46:47], v[18:19], v[10:11] op_sel_hi:[1,0,1]
	s_waitcnt vmcnt(2)
	v_pk_fma_f32 v[6:7], v[56:57], v[68:69], v[6:7] op_sel_hi:[1,0,1]
	v_pk_fma_f32 v[10:11], v[54:55], v[68:69], v[10:11] op_sel_hi:[1,0,1]
	s_waitcnt vmcnt(1)
	v_pk_fma_f32 v[6:7], v[60:61], v[22:23], v[6:7] op_sel_hi:[1,0,1]
	v_pk_fma_f32 v[10:11], v[58:59], v[22:23], v[10:11] op_sel_hi:[1,0,1]
	s_waitcnt vmcnt(0)
	v_pk_fma_f32 v[36:37], v[64:65], v[70:71], v[6:7] op_sel_hi:[1,0,1]
	v_add_co_u32_e32 v6, vcc, s81, v34
	v_pk_fma_f32 v[26:27], v[62:63], v[70:71], v[10:11] op_sel_hi:[1,0,1]
	s_nop 0
	v_addc_co_u32_e32 v7, vcc, 0, v35, vcc
	v_add_co_u32_e32 v10, vcc, s82, v34
	global_load_dwordx4 v[6:9], v[6:7], off nt
	s_nop 0
	v_addc_co_u32_e32 v11, vcc, 0, v35, vcc
	v_add_co_u32_e32 v14, vcc, s83, v34
	ds_read2_b32 v[42:43], v99 offset0:240 offset1:244
	ds_read2_b32 v[40:41], v99 offset0:248 offset1:252
	v_addc_co_u32_e32 v15, vcc, 0, v35, vcc
	v_add_co_u32_e32 v18, vcc, s84, v34
	global_load_dwordx4 v[10:13], v[10:11], off offset:2048 nt
	s_nop 0
	v_addc_co_u32_e32 v19, vcc, 0, v35, vcc
	v_add_co_u32_e32 v22, vcc, s85, v34
	v_pk_fma_f32 v[2:3], v[2:3], v[30:31], v[26:27] op_sel_hi:[1,0,1]
	s_nop 0
	v_addc_co_u32_e32 v23, vcc, 0, v35, vcc
	v_add_co_u32_e32 v26, vcc, s86, v34
	global_load_dwordx4 v[14:17], v[14:15], off nt
	s_nop 0
	v_addc_co_u32_e32 v27, vcc, 0, v35, vcc
	global_load_dwordx4 v[18:21], v[18:19], off offset:2048 nt
	v_add_co_u32_e32 v46, vcc, s87, v34
	global_load_dwordx4 v[22:25], v[22:23], off nt
	s_nop 0
	v_addc_co_u32_e32 v47, vcc, 0, v35, vcc
	global_load_dwordx4 v[26:29], v[26:27], off offset:2048 nt
	v_add_co_u32_e32 v34, vcc, s88, v34
	global_load_dwordx4 v[46:49], v[46:47], off nt
	s_nop 0
	v_addc_co_u32_e32 v35, vcc, 0, v35, vcc
	global_load_dwordx4 v[54:57], v[34:35], off offset:2048 nt
	v_pk_fma_f32 v[4:5], v[4:5], v[30:31], v[36:37] op_sel_hi:[1,0,1]
	s_waitcnt vmcnt(7) lgkmcnt(3)
	v_pk_fma_f32 v[2:3], v[6:7], v[38:39], v[2:3] op_sel_hi:[1,0,1]
	v_mov_b32_e32 v6, v39
	v_pk_fma_f32 v[4:5], v[8:9], v[38:39], v[4:5] op_sel_hi:[1,0,1]
	s_waitcnt vmcnt(6)
	v_pk_fma_f32 v[2:3], v[10:11], v[6:7], v[2:3] op_sel_hi:[1,0,1]
	v_pk_fma_f32 v[4:5], v[12:13], v[6:7], v[4:5] op_sel_hi:[1,0,1]
	s_waitcnt lgkmcnt(2)
	v_mov_b32_e32 v10, v33
	s_waitcnt vmcnt(5)
	v_pk_fma_f32 v[2:3], v[14:15], v[32:33], v[2:3] op_sel_hi:[1,0,1]
	v_pk_fma_f32 v[4:5], v[16:17], v[32:33], v[4:5] op_sel_hi:[1,0,1]
	s_waitcnt lgkmcnt(1)
	v_mov_b32_e32 v14, v43
	s_waitcnt vmcnt(4)
	v_pk_fma_f32 v[2:3], v[18:19], v[10:11], v[2:3] op_sel_hi:[1,0,1]
	v_pk_fma_f32 v[4:5], v[20:21], v[10:11], v[4:5] op_sel_hi:[1,0,1]
	s_waitcnt lgkmcnt(0)
	v_mov_b32_e32 v18, v41
	s_waitcnt vmcnt(3)
	v_pk_fma_f32 v[2:3], v[22:23], v[42:43], v[2:3] op_sel_hi:[1,0,1]
	v_pk_fma_f32 v[4:5], v[24:25], v[42:43], v[4:5] op_sel_hi:[1,0,1]
	ds_bpermute_b32 v10, v44, v31
	s_waitcnt vmcnt(2)
	v_pk_fma_f32 v[2:3], v[26:27], v[14:15], v[2:3] op_sel_hi:[1,0,1]
	v_pk_fma_f32 v[4:5], v[28:29], v[14:15], v[4:5] op_sel_hi:[1,0,1]
	s_waitcnt vmcnt(1)
	v_pk_fma_f32 v[2:3], v[46:47], v[40:41], v[2:3] op_sel_hi:[1,0,1]
	v_pk_fma_f32 v[4:5], v[48:49], v[40:41], v[4:5] op_sel_hi:[1,0,1]
	s_waitcnt vmcnt(0)
	v_pk_fma_f32 v[2:3], v[54:55], v[18:19], v[2:3] op_sel_hi:[1,0,1]
	v_pk_fma_f32 v[4:5], v[56:57], v[18:19], v[4:5] op_sel_hi:[1,0,1]
	ds_bpermute_b32 v22, v45, v2
	ds_bpermute_b32 v23, v45, v3
	ds_bpermute_b32 v6, v45, v4
	ds_bpermute_b32 v7, v45, v5
	s_waitcnt lgkmcnt(2)
	v_pk_add_f32 v[2:3], v[2:3], v[22:23]
	s_waitcnt lgkmcnt(0)
	v_pk_add_f32 v[4:5], v[4:5], v[6:7]
	ds_bpermute_b32 v6, v52, v2
	ds_bpermute_b32 v7, v52, v3
	ds_bpermute_b32 v8, v52, v4
	ds_bpermute_b32 v9, v52, v5
	s_and_saveexec_b64 s[0:1], s[20:21]
	s_cbranch_execz .LBB0_1553
	s_ashr_i32 s35, s34, 31
	s_lshl_b64 s[2:3], s[34:35], 8
	v_lshl_add_u64 v[12:13], v[88:89], 0, s[2:3]
	s_waitcnt lgkmcnt(2)
	v_pk_add_f32 v[2:3], v[2:3], v[6:7]
	s_waitcnt lgkmcnt(0)
	v_pk_add_f32 v[4:5], v[4:5], v[8:9]
	global_store_dwordx4 v[12:13], v[2:5], off
